# GEMM phases: adjacent vmcnt / lgkmcnt waits merged into one s_waitcnt (104 sites)
# speedup vs baseline: 1.0050x; 1.0050x over previous
.LBB0_271:
	s_ashr_i32 s37, s36, 31
	s_lshl_b64 s[38:39], s[36:37], 19
	s_add_u32 s38, s58, s38
	s_addc_u32 s39, s59, s39
	s_and_b64 s[40:41], s[4:5], exec
	s_cselect_b32 s37, s39, s61
	s_cselect_b32 s43, s38, s60
	s_ashr_i32 s35, s34, 31
	s_lshl_b64 s[40:41], s[34:35], 19
	s_add_u32 s40, s66, s40
	s_addc_u32 s41, s67, s41
	s_and_b64 s[64:65], s[4:5], exec
	s_cselect_b32 s35, s41, s63
	s_cselect_b32 s55, s40, s62
	s_add_u32 s60, s60, 0x40080
	s_addc_u32 s61, s61, 0
	s_add_u32 s84, s62, 0x100
	s_addc_u32 s85, s63, 0
	s_mov_b32 s86, -2
	ds_read_b128 v[146:149], v153
	ds_read_b128 v[156:159], v153 offset:1024
	ds_read_b128 v[160:163], v153 offset:2048
	ds_read_b128 v[164:167], v153 offset:3072
	ds_read_b128 v[168:171], v154
	ds_read_b128 v[172:175], v154 offset:1024
	ds_read_b128 v[176:179], v154 offset:2048
	ds_read_b128 v[180:183], v154 offset:3072
	s_add_u32 s62, s60, 0xfffc0080
	s_addc_u32 s63, s61, -1
	s_cmp_eq_u32 s86, 12
	s_cselect_b32 s65, s37, s63
	s_cselect_b32 s64, s43, s62
	s_cselect_b32 s63, s35, s85
	s_cselect_b32 s62, s55, s84
	s_add_i32 m0, s69, 0xc000
	ds_read_b128 v[184:187], v155
	ds_read_b128 v[192:195], v155 offset:1024
	ds_read_b128 v[196:199], v155 offset:2048
	ds_read_b128 v[200:203], v155 offset:3072
	ds_read_b128 v[204:207], v155 offset:4096
	ds_read_b128 v[208:211], v155 offset:5120
	ds_read_b128 v[212:215], v155 offset:6144
	ds_read_b128 v[216:219], v155 offset:7168
	global_load_lds_dwordx4 v138, s[60:61]
	v_lshl_add_u64 v[188:189], s[60:61], 0, v[140:141]
	s_add_i32 m0, s69, 0xe000
	s_nop 0
	global_load_lds_dwordx4 v[188:189], off
	s_waitcnt vmcnt(8) lgkmcnt(0)
	s_barrier
	v_mfma_f32_16x16x32_bf16 v[124:127], v[146:149], v[184:187], 0
	v_mfma_f32_16x16x32_bf16 v[120:123], v[160:163], v[184:187], 0
	v_mfma_f32_16x16x32_bf16 v[116:119], v[146:149], v[196:199], 0
	v_mfma_f32_16x16x32_bf16 v[108:111], v[160:163], v[196:199], 0
	v_mfma_f32_16x16x32_bf16 v[100:103], v[146:149], v[204:207], 0
	v_mfma_f32_16x16x32_bf16 v[92:95], v[160:163], v[204:207], 0
	v_mfma_f32_16x16x32_bf16 v[84:87], v[146:149], v[212:215], 0
	v_mfma_f32_16x16x32_bf16 v[76:79], v[160:163], v[212:215], 0
	v_mfma_f32_16x16x32_bf16 v[124:127], v[156:159], v[192:195], v[124:127]
	v_mfma_f32_16x16x32_bf16 v[120:123], v[164:167], v[192:195], v[120:123]
	v_mfma_f32_16x16x32_bf16 v[116:119], v[156:159], v[200:203], v[116:119]
	v_mfma_f32_16x16x32_bf16 v[108:111], v[164:167], v[200:203], v[108:111]
	v_mfma_f32_16x16x32_bf16 v[100:103], v[156:159], v[208:211], v[100:103]
	v_mfma_f32_16x16x32_bf16 v[92:95], v[164:167], v[208:211], v[92:95]
	v_mfma_f32_16x16x32_bf16 v[84:87], v[156:159], v[216:219], v[84:87]
	v_mfma_f32_16x16x32_bf16 v[76:79], v[164:167], v[216:219], v[76:79]
	v_mfma_f32_16x16x32_bf16 v[112:115], v[168:171], v[184:187], 0
	v_mfma_f32_16x16x32_bf16 v[104:107], v[176:179], v[184:187], 0
	v_mfma_f32_16x16x32_bf16 v[96:99], v[168:171], v[196:199], 0
	v_mfma_f32_16x16x32_bf16 v[88:91], v[176:179], v[196:199], 0
	v_mfma_f32_16x16x32_bf16 v[80:83], v[168:171], v[204:207], 0
	v_mfma_f32_16x16x32_bf16 v[72:75], v[176:179], v[204:207], 0
	v_mfma_f32_16x16x32_bf16 v[68:71], v[168:171], v[212:215], 0
	v_mfma_f32_16x16x32_bf16 v[64:67], v[176:179], v[212:215], 0
	v_mfma_f32_16x16x32_bf16 v[112:115], v[172:175], v[192:195], v[112:115]
	v_mfma_f32_16x16x32_bf16 v[104:107], v[180:183], v[192:195], v[104:107]
	v_mfma_f32_16x16x32_bf16 v[96:99], v[172:175], v[200:203], v[96:99]
	v_mfma_f32_16x16x32_bf16 v[88:91], v[180:183], v[200:203], v[88:91]
	v_mfma_f32_16x16x32_bf16 v[80:83], v[172:175], v[208:211], v[80:83]
	v_mfma_f32_16x16x32_bf16 v[72:75], v[180:183], v[208:211], v[72:75]
	v_mfma_f32_16x16x32_bf16 v[68:71], v[172:175], v[216:219], v[68:71]
	v_mfma_f32_16x16x32_bf16 v[64:67], v[180:183], v[216:219], v[64:67]
	s_barrier
	s_add_i32 s87, s76, s68
	v_lshl_add_u64 v[188:189], s[62:63], 0, v[132:133]
	s_mov_b32 m0, s87
	ds_read_b128 v[184:187], v155 offset:16384
	ds_read_b128 v[192:195], v155 offset:17408
	ds_read_b128 v[196:199], v155 offset:18432
	ds_read_b128 v[200:203], v155 offset:19456
	ds_read_b128 v[204:207], v155 offset:20480
	ds_read_b128 v[208:211], v155 offset:21504
	ds_read_b128 v[212:215], v155 offset:22528
	ds_read_b128 v[216:219], v155 offset:23552
	global_load_lds_dwordx4 v[188:189], off
	s_add_i32 m0, s87, 0x2000
	s_add_u32 s88, s62, 0x40000
	v_lshl_add_u64 v[220:221], s[62:63], 0, v[128:129]
	s_addc_u32 s89, s63, 0
	s_add_i32 s87, s77, s68
	global_load_lds_dwordx4 v[220:221], off
	s_mov_b32 m0, s87
	v_lshl_add_u64 v[224:225], s[64:65], 0, v[130:131]
	global_load_lds_dwordx4 v132, s[88:89]
	s_add_i32 m0, s87, 0x2000
	s_nop 0
	global_load_lds_dwordx4 v128, s[88:89]
	v_lshl_add_u64 v[222:223], s[64:65], 0, v[134:135]
	s_mov_b32 m0, s69
	s_nop 0
	global_load_lds_dwordx4 v[222:223], off
	s_mov_b32 m0, s70
	s_nop 0
	global_load_lds_dwordx4 v[224:225], off
	s_waitcnt vmcnt(8) lgkmcnt(0)
	s_barrier
	v_mfma_f32_16x16x32_bf16 v[60:63], v[146:149], v[184:187], 0
	v_mfma_f32_16x16x32_bf16 v[56:59], v[160:163], v[184:187], 0
	v_mfma_f32_16x16x32_bf16 v[52:55], v[146:149], v[196:199], 0
	v_mfma_f32_16x16x32_bf16 v[44:47], v[160:163], v[196:199], 0
	v_mfma_f32_16x16x32_bf16 v[36:39], v[146:149], v[204:207], 0
	v_mfma_f32_16x16x32_bf16 v[28:31], v[160:163], v[204:207], 0
	v_mfma_f32_16x16x32_bf16 v[20:23], v[146:149], v[212:215], 0
	v_mfma_f32_16x16x32_bf16 v[12:15], v[160:163], v[212:215], 0
	v_mfma_f32_16x16x32_bf16 v[60:63], v[156:159], v[192:195], v[60:63]
	v_mfma_f32_16x16x32_bf16 v[56:59], v[164:167], v[192:195], v[56:59]
	v_mfma_f32_16x16x32_bf16 v[52:55], v[156:159], v[200:203], v[52:55]
	v_mfma_f32_16x16x32_bf16 v[44:47], v[164:167], v[200:203], v[44:47]
	v_mfma_f32_16x16x32_bf16 v[36:39], v[156:159], v[208:211], v[36:39]
	v_mfma_f32_16x16x32_bf16 v[28:31], v[164:167], v[208:211], v[28:31]
	v_mfma_f32_16x16x32_bf16 v[20:23], v[156:159], v[216:219], v[20:23]
	v_mfma_f32_16x16x32_bf16 v[12:15], v[164:167], v[216:219], v[12:15]
	v_mfma_f32_16x16x32_bf16 v[48:51], v[168:171], v[184:187], 0
	v_mfma_f32_16x16x32_bf16 v[40:43], v[176:179], v[184:187], 0
	v_mfma_f32_16x16x32_bf16 v[32:35], v[168:171], v[196:199], 0
	v_mfma_f32_16x16x32_bf16 v[24:27], v[176:179], v[196:199], 0
	v_mfma_f32_16x16x32_bf16 v[16:19], v[168:171], v[204:207], 0
	v_mfma_f32_16x16x32_bf16 v[8:11], v[176:179], v[204:207], 0
	v_mfma_f32_16x16x32_bf16 v[4:7], v[168:171], v[212:215], 0
	v_mfma_f32_16x16x32_bf16 v[0:3], v[176:179], v[212:215], 0
	v_mfma_f32_16x16x32_bf16 v[48:51], v[172:175], v[192:195], v[48:51]
	v_mfma_f32_16x16x32_bf16 v[40:43], v[180:183], v[192:195], v[40:43]
	v_mfma_f32_16x16x32_bf16 v[32:35], v[172:175], v[200:203], v[32:35]
	v_mfma_f32_16x16x32_bf16 v[24:27], v[180:183], v[200:203], v[24:27]
	v_mfma_f32_16x16x32_bf16 v[16:19], v[172:175], v[208:211], v[16:19]
	v_mfma_f32_16x16x32_bf16 v[8:11], v[180:183], v[208:211], v[8:11]
	v_mfma_f32_16x16x32_bf16 v[4:7], v[172:175], v[216:219], v[4:7]
	v_mfma_f32_16x16x32_bf16 v[0:3], v[180:183], v[216:219], v[0:3]
	s_barrier
	s_add_i32 s87, 0, 0x18000
	s_add_i32 s88, 0, 0x1c000
	v_add_u32_e32 v164, s87, v151
	v_add_u32_e32 v180, s88, v151
	ds_read_b128 v[146:149], v164
	ds_read_b128 v[156:159], v164 offset:1024
	ds_read_b128 v[160:163], v164 offset:2048
	ds_read_b128 v[164:167], v164 offset:3072
	ds_read_b128 v[168:171], v180
	ds_read_b128 v[172:175], v180 offset:1024
	ds_read_b128 v[176:179], v180 offset:2048
	ds_read_b128 v[180:183], v180 offset:3072
	s_add_u32 s64, s64, 0x40000
	s_addc_u32 s65, s65, 0
	s_mov_b32 m0, s71
	ds_read_b128 v[184:187], v155 offset:32768
	ds_read_b128 v[192:195], v155 offset:33792
	ds_read_b128 v[196:199], v155 offset:34816
	ds_read_b128 v[200:203], v155 offset:35840
	ds_read_b128 v[204:207], v155 offset:36864
	ds_read_b128 v[208:211], v155 offset:37888
	ds_read_b128 v[212:215], v155 offset:38912
	ds_read_b128 v[216:219], v155 offset:39936
	global_load_lds_dwordx4 v134, s[64:65]
	s_mov_b32 m0, s72
	s_nop 0
	global_load_lds_dwordx4 v130, s[64:65]
	s_waitcnt vmcnt(8) lgkmcnt(0)
	s_barrier
	v_mfma_f32_16x16x32_bf16 v[124:127], v[146:149], v[184:187], v[124:127]
	v_mfma_f32_16x16x32_bf16 v[120:123], v[160:163], v[184:187], v[120:123]
	v_mfma_f32_16x16x32_bf16 v[116:119], v[146:149], v[196:199], v[116:119]
	v_mfma_f32_16x16x32_bf16 v[108:111], v[160:163], v[196:199], v[108:111]
	v_mfma_f32_16x16x32_bf16 v[100:103], v[146:149], v[204:207], v[100:103]
	v_mfma_f32_16x16x32_bf16 v[92:95], v[160:163], v[204:207], v[92:95]
	v_mfma_f32_16x16x32_bf16 v[84:87], v[146:149], v[212:215], v[84:87]
	v_mfma_f32_16x16x32_bf16 v[76:79], v[160:163], v[212:215], v[76:79]
	v_mfma_f32_16x16x32_bf16 v[124:127], v[156:159], v[192:195], v[124:127]
	v_mfma_f32_16x16x32_bf16 v[120:123], v[164:167], v[192:195], v[120:123]
	v_mfma_f32_16x16x32_bf16 v[116:119], v[156:159], v[200:203], v[116:119]
	v_mfma_f32_16x16x32_bf16 v[108:111], v[164:167], v[200:203], v[108:111]
	v_mfma_f32_16x16x32_bf16 v[100:103], v[156:159], v[208:211], v[100:103]
	v_mfma_f32_16x16x32_bf16 v[92:95], v[164:167], v[208:211], v[92:95]
	v_mfma_f32_16x16x32_bf16 v[84:87], v[156:159], v[216:219], v[84:87]
	v_mfma_f32_16x16x32_bf16 v[76:79], v[164:167], v[216:219], v[76:79]
	v_mfma_f32_16x16x32_bf16 v[112:115], v[168:171], v[184:187], v[112:115]
	v_mfma_f32_16x16x32_bf16 v[104:107], v[176:179], v[184:187], v[104:107]
	v_mfma_f32_16x16x32_bf16 v[96:99], v[168:171], v[196:199], v[96:99]
	v_mfma_f32_16x16x32_bf16 v[88:91], v[176:179], v[196:199], v[88:91]
	v_mfma_f32_16x16x32_bf16 v[80:83], v[168:171], v[204:207], v[80:83]
	v_mfma_f32_16x16x32_bf16 v[72:75], v[176:179], v[204:207], v[72:75]
	v_mfma_f32_16x16x32_bf16 v[68:71], v[168:171], v[212:215], v[68:71]
	v_mfma_f32_16x16x32_bf16 v[64:67], v[176:179], v[212:215], v[64:67]
	v_mfma_f32_16x16x32_bf16 v[112:115], v[172:175], v[192:195], v[112:115]
	v_mfma_f32_16x16x32_bf16 v[104:107], v[180:183], v[192:195], v[104:107]
	v_mfma_f32_16x16x32_bf16 v[96:99], v[172:175], v[200:203], v[96:99]
	v_mfma_f32_16x16x32_bf16 v[88:91], v[180:183], v[200:203], v[88:91]
	v_mfma_f32_16x16x32_bf16 v[80:83], v[172:175], v[208:211], v[80:83]
	v_mfma_f32_16x16x32_bf16 v[72:75], v[180:183], v[208:211], v[72:75]
	v_mfma_f32_16x16x32_bf16 v[68:71], v[172:175], v[216:219], v[68:71]
	v_mfma_f32_16x16x32_bf16 v[64:67], v[180:183], v[216:219], v[64:67]
	s_barrier
	s_add_i32 s64, s87, s68
	v_lshl_add_u64 v[188:189], v[188:189], 0, s[10:11]
	s_mov_b32 m0, s64
	ds_read_b128 v[184:187], v155 offset:49152
	ds_read_b128 v[192:195], v155 offset:50176
	ds_read_b128 v[196:199], v155 offset:51200
	ds_read_b128 v[200:203], v155 offset:52224
	ds_read_b128 v[204:207], v155 offset:53248
	ds_read_b128 v[208:211], v155 offset:54272
	ds_read_b128 v[212:215], v155 offset:55296
	ds_read_b128 v[216:219], v155 offset:56320
	global_load_lds_dwordx4 v[188:189], off
	s_add_i32 m0, s64, 0x2000
	s_add_u32 s62, s62, 0x40080
	v_lshl_add_u64 v[188:189], v[220:221], 0, s[10:11]
	s_addc_u32 s63, s63, 0
	s_add_i32 s64, s88, s68
	global_load_lds_dwordx4 v[188:189], off
	s_mov_b32 m0, s64
	s_nop 0
	global_load_lds_dwordx4 v132, s[62:63]
	s_add_i32 m0, s64, 0x2000
	s_nop 0
	global_load_lds_dwordx4 v128, s[62:63]
	v_lshl_add_u64 v[188:189], v[222:223], 0, s[10:11]
	s_mov_b32 m0, s33
	s_nop 0
	global_load_lds_dwordx4 v[188:189], off
	v_lshl_add_u64 v[188:189], v[224:225], 0, s[10:11]
	s_mov_b32 m0, s74
	s_nop 0
	global_load_lds_dwordx4 v[188:189], off
	s_waitcnt vmcnt(8) lgkmcnt(0)
	s_barrier
	v_mfma_f32_16x16x32_bf16 v[60:63], v[146:149], v[184:187], v[60:63]
	v_mfma_f32_16x16x32_bf16 v[56:59], v[160:163], v[184:187], v[56:59]
	v_mfma_f32_16x16x32_bf16 v[52:55], v[146:149], v[196:199], v[52:55]
	v_mfma_f32_16x16x32_bf16 v[44:47], v[160:163], v[196:199], v[44:47]
	v_mfma_f32_16x16x32_bf16 v[36:39], v[146:149], v[204:207], v[36:39]
	v_mfma_f32_16x16x32_bf16 v[28:31], v[160:163], v[204:207], v[28:31]
	v_mfma_f32_16x16x32_bf16 v[20:23], v[146:149], v[212:215], v[20:23]
	v_mfma_f32_16x16x32_bf16 v[12:15], v[160:163], v[212:215], v[12:15]
	v_mfma_f32_16x16x32_bf16 v[60:63], v[156:159], v[192:195], v[60:63]
	v_mfma_f32_16x16x32_bf16 v[56:59], v[164:167], v[192:195], v[56:59]
	v_mfma_f32_16x16x32_bf16 v[52:55], v[156:159], v[200:203], v[52:55]
	v_mfma_f32_16x16x32_bf16 v[44:47], v[164:167], v[200:203], v[44:47]
	v_mfma_f32_16x16x32_bf16 v[36:39], v[156:159], v[208:211], v[36:39]
	v_mfma_f32_16x16x32_bf16 v[28:31], v[164:167], v[208:211], v[28:31]
	v_mfma_f32_16x16x32_bf16 v[20:23], v[156:159], v[216:219], v[20:23]
	v_mfma_f32_16x16x32_bf16 v[12:15], v[164:167], v[216:219], v[12:15]
	v_mfma_f32_16x16x32_bf16 v[48:51], v[168:171], v[184:187], v[48:51]
	v_mfma_f32_16x16x32_bf16 v[40:43], v[176:179], v[184:187], v[40:43]
	v_mfma_f32_16x16x32_bf16 v[32:35], v[168:171], v[196:199], v[32:35]
	v_mfma_f32_16x16x32_bf16 v[24:27], v[176:179], v[196:199], v[24:27]
	v_mfma_f32_16x16x32_bf16 v[16:19], v[168:171], v[204:207], v[16:19]
	v_mfma_f32_16x16x32_bf16 v[8:11], v[176:179], v[204:207], v[8:11]
	v_mfma_f32_16x16x32_bf16 v[4:7], v[168:171], v[212:215], v[4:7]
	v_mfma_f32_16x16x32_bf16 v[0:3], v[176:179], v[212:215], v[0:3]
	v_mfma_f32_16x16x32_bf16 v[48:51], v[172:175], v[192:195], v[48:51]
	v_mfma_f32_16x16x32_bf16 v[40:43], v[180:183], v[192:195], v[40:43]
	v_mfma_f32_16x16x32_bf16 v[32:35], v[172:175], v[200:203], v[32:35]
	v_mfma_f32_16x16x32_bf16 v[24:27], v[180:183], v[200:203], v[24:27]
	v_mfma_f32_16x16x32_bf16 v[16:19], v[172:175], v[208:211], v[16:19]
	v_mfma_f32_16x16x32_bf16 v[8:11], v[180:183], v[208:211], v[8:11]
	v_mfma_f32_16x16x32_bf16 v[4:7], v[172:175], v[216:219], v[4:7]
	v_mfma_f32_16x16x32_bf16 v[0:3], v[180:183], v[216:219], v[0:3]
	s_barrier
	s_add_i32 s86, s86, 2
	s_add_u32 s60, s60, 0x100
	s_addc_u32 s61, s61, 0
	s_add_u32 s84, s84, 0x100
	s_addc_u32 s85, s85, 0
	s_cmp_gt_u32 s86, 13
	s_cbranch_scc0 .LBB0_272
	s_branch .Lpeel_exit0
.LBB0_272:
	ds_read_b128 v[146:149], v153
	ds_read_b128 v[156:159], v153 offset:1024
	ds_read_b128 v[160:163], v153 offset:2048
	ds_read_b128 v[164:167], v153 offset:3072
	ds_read_b128 v[168:171], v154
	ds_read_b128 v[172:175], v154 offset:1024
	ds_read_b128 v[176:179], v154 offset:2048
	ds_read_b128 v[180:183], v154 offset:3072
	s_add_u32 s62, s60, 0xfffc0080
	s_addc_u32 s63, s61, -1
	s_cmp_eq_u32 s86, 12
	s_cselect_b32 s65, s37, s63
	s_cselect_b32 s64, s43, s62
	s_cselect_b32 s63, s35, s85
	s_cselect_b32 s62, s55, s84
	s_add_i32 m0, s69, 0xc000
	ds_read_b128 v[184:187], v155
	ds_read_b128 v[192:195], v155 offset:1024
	ds_read_b128 v[196:199], v155 offset:2048
	ds_read_b128 v[200:203], v155 offset:3072
	ds_read_b128 v[204:207], v155 offset:4096
	ds_read_b128 v[208:211], v155 offset:5120
	ds_read_b128 v[212:215], v155 offset:6144
	ds_read_b128 v[216:219], v155 offset:7168
	global_load_lds_dwordx4 v138, s[60:61]
	v_lshl_add_u64 v[188:189], s[60:61], 0, v[140:141]
	s_add_i32 m0, s69, 0xe000
	s_nop 0
	global_load_lds_dwordx4 v[188:189], off
	s_waitcnt vmcnt(8) lgkmcnt(0)
	s_barrier
	v_mfma_f32_16x16x32_bf16 v[124:127], v[146:149], v[184:187], v[124:127]
	v_mfma_f32_16x16x32_bf16 v[120:123], v[160:163], v[184:187], v[120:123]
	v_mfma_f32_16x16x32_bf16 v[116:119], v[146:149], v[196:199], v[116:119]
	v_mfma_f32_16x16x32_bf16 v[108:111], v[160:163], v[196:199], v[108:111]
	v_mfma_f32_16x16x32_bf16 v[100:103], v[146:149], v[204:207], v[100:103]
	v_mfma_f32_16x16x32_bf16 v[92:95], v[160:163], v[204:207], v[92:95]
	v_mfma_f32_16x16x32_bf16 v[84:87], v[146:149], v[212:215], v[84:87]
	v_mfma_f32_16x16x32_bf16 v[76:79], v[160:163], v[212:215], v[76:79]
	v_mfma_f32_16x16x32_bf16 v[124:127], v[156:159], v[192:195], v[124:127]
	v_mfma_f32_16x16x32_bf16 v[120:123], v[164:167], v[192:195], v[120:123]
	v_mfma_f32_16x16x32_bf16 v[116:119], v[156:159], v[200:203], v[116:119]
	v_mfma_f32_16x16x32_bf16 v[108:111], v[164:167], v[200:203], v[108:111]
	v_mfma_f32_16x16x32_bf16 v[100:103], v[156:159], v[208:211], v[100:103]
	v_mfma_f32_16x16x32_bf16 v[92:95], v[164:167], v[208:211], v[92:95]
	v_mfma_f32_16x16x32_bf16 v[84:87], v[156:159], v[216:219], v[84:87]
	v_mfma_f32_16x16x32_bf16 v[76:79], v[164:167], v[216:219], v[76:79]
	v_mfma_f32_16x16x32_bf16 v[112:115], v[168:171], v[184:187], v[112:115]
	v_mfma_f32_16x16x32_bf16 v[104:107], v[176:179], v[184:187], v[104:107]
	v_mfma_f32_16x16x32_bf16 v[96:99], v[168:171], v[196:199], v[96:99]
	v_mfma_f32_16x16x32_bf16 v[88:91], v[176:179], v[196:199], v[88:91]
	v_mfma_f32_16x16x32_bf16 v[80:83], v[168:171], v[204:207], v[80:83]
	v_mfma_f32_16x16x32_bf16 v[72:75], v[176:179], v[204:207], v[72:75]
	v_mfma_f32_16x16x32_bf16 v[68:71], v[168:171], v[212:215], v[68:71]
	v_mfma_f32_16x16x32_bf16 v[64:67], v[176:179], v[212:215], v[64:67]
	v_mfma_f32_16x16x32_bf16 v[112:115], v[172:175], v[192:195], v[112:115]
	v_mfma_f32_16x16x32_bf16 v[104:107], v[180:183], v[192:195], v[104:107]
	v_mfma_f32_16x16x32_bf16 v[96:99], v[172:175], v[200:203], v[96:99]
	v_mfma_f32_16x16x32_bf16 v[88:91], v[180:183], v[200:203], v[88:91]
	v_mfma_f32_16x16x32_bf16 v[80:83], v[172:175], v[208:211], v[80:83]
	v_mfma_f32_16x16x32_bf16 v[72:75], v[180:183], v[208:211], v[72:75]
	v_mfma_f32_16x16x32_bf16 v[68:71], v[172:175], v[216:219], v[68:71]
	v_mfma_f32_16x16x32_bf16 v[64:67], v[180:183], v[216:219], v[64:67]
	s_barrier
	s_add_i32 s87, s76, s68
	v_lshl_add_u64 v[188:189], s[62:63], 0, v[132:133]
	s_mov_b32 m0, s87
	ds_read_b128 v[184:187], v155 offset:16384
	ds_read_b128 v[192:195], v155 offset:17408
	ds_read_b128 v[196:199], v155 offset:18432
	ds_read_b128 v[200:203], v155 offset:19456
	ds_read_b128 v[204:207], v155 offset:20480
	ds_read_b128 v[208:211], v155 offset:21504
	ds_read_b128 v[212:215], v155 offset:22528
	ds_read_b128 v[216:219], v155 offset:23552
	global_load_lds_dwordx4 v[188:189], off
	s_add_i32 m0, s87, 0x2000
	s_add_u32 s88, s62, 0x40000
	v_lshl_add_u64 v[220:221], s[62:63], 0, v[128:129]
	s_addc_u32 s89, s63, 0
	s_add_i32 s87, s77, s68
	global_load_lds_dwordx4 v[220:221], off
	s_mov_b32 m0, s87
	v_lshl_add_u64 v[224:225], s[64:65], 0, v[130:131]
	global_load_lds_dwordx4 v132, s[88:89]
	s_add_i32 m0, s87, 0x2000
	s_nop 0
	global_load_lds_dwordx4 v128, s[88:89]
	v_lshl_add_u64 v[222:223], s[64:65], 0, v[134:135]
	s_mov_b32 m0, s69
	s_nop 0
	global_load_lds_dwordx4 v[222:223], off
	s_mov_b32 m0, s70
	s_nop 0
	global_load_lds_dwordx4 v[224:225], off
	s_waitcnt vmcnt(8) lgkmcnt(0)
	s_barrier
	v_mfma_f32_16x16x32_bf16 v[60:63], v[146:149], v[184:187], v[60:63]
	v_mfma_f32_16x16x32_bf16 v[56:59], v[160:163], v[184:187], v[56:59]
	v_mfma_f32_16x16x32_bf16 v[52:55], v[146:149], v[196:199], v[52:55]
	v_mfma_f32_16x16x32_bf16 v[44:47], v[160:163], v[196:199], v[44:47]
	v_mfma_f32_16x16x32_bf16 v[36:39], v[146:149], v[204:207], v[36:39]
	v_mfma_f32_16x16x32_bf16 v[28:31], v[160:163], v[204:207], v[28:31]
	v_mfma_f32_16x16x32_bf16 v[20:23], v[146:149], v[212:215], v[20:23]
	v_mfma_f32_16x16x32_bf16 v[12:15], v[160:163], v[212:215], v[12:15]
	v_mfma_f32_16x16x32_bf16 v[60:63], v[156:159], v[192:195], v[60:63]
	v_mfma_f32_16x16x32_bf16 v[56:59], v[164:167], v[192:195], v[56:59]
	v_mfma_f32_16x16x32_bf16 v[52:55], v[156:159], v[200:203], v[52:55]
	v_mfma_f32_16x16x32_bf16 v[44:47], v[164:167], v[200:203], v[44:47]
	v_mfma_f32_16x16x32_bf16 v[36:39], v[156:159], v[208:211], v[36:39]
	v_mfma_f32_16x16x32_bf16 v[28:31], v[164:167], v[208:211], v[28:31]
	v_mfma_f32_16x16x32_bf16 v[20:23], v[156:159], v[216:219], v[20:23]
	v_mfma_f32_16x16x32_bf16 v[12:15], v[164:167], v[216:219], v[12:15]
	v_mfma_f32_16x16x32_bf16 v[48:51], v[168:171], v[184:187], v[48:51]
	v_mfma_f32_16x16x32_bf16 v[40:43], v[176:179], v[184:187], v[40:43]
	v_mfma_f32_16x16x32_bf16 v[32:35], v[168:171], v[196:199], v[32:35]
	v_mfma_f32_16x16x32_bf16 v[24:27], v[176:179], v[196:199], v[24:27]
	v_mfma_f32_16x16x32_bf16 v[16:19], v[168:171], v[204:207], v[16:19]
	v_mfma_f32_16x16x32_bf16 v[8:11], v[176:179], v[204:207], v[8:11]
	v_mfma_f32_16x16x32_bf16 v[4:7], v[168:171], v[212:215], v[4:7]
	v_mfma_f32_16x16x32_bf16 v[0:3], v[176:179], v[212:215], v[0:3]
	v_mfma_f32_16x16x32_bf16 v[48:51], v[172:175], v[192:195], v[48:51]
	v_mfma_f32_16x16x32_bf16 v[40:43], v[180:183], v[192:195], v[40:43]
	v_mfma_f32_16x16x32_bf16 v[32:35], v[172:175], v[200:203], v[32:35]
	v_mfma_f32_16x16x32_bf16 v[24:27], v[180:183], v[200:203], v[24:27]
	v_mfma_f32_16x16x32_bf16 v[16:19], v[172:175], v[208:211], v[16:19]
	v_mfma_f32_16x16x32_bf16 v[8:11], v[180:183], v[208:211], v[8:11]
	v_mfma_f32_16x16x32_bf16 v[4:7], v[172:175], v[216:219], v[4:7]
	v_mfma_f32_16x16x32_bf16 v[0:3], v[180:183], v[216:219], v[0:3]
	s_barrier
	s_add_i32 s87, 0, 0x18000
	s_add_i32 s88, 0, 0x1c000
	v_add_u32_e32 v164, s87, v151
	v_add_u32_e32 v180, s88, v151
	ds_read_b128 v[146:149], v164
	ds_read_b128 v[156:159], v164 offset:1024
	ds_read_b128 v[160:163], v164 offset:2048
	ds_read_b128 v[164:167], v164 offset:3072
	ds_read_b128 v[168:171], v180
	ds_read_b128 v[172:175], v180 offset:1024
	ds_read_b128 v[176:179], v180 offset:2048
	ds_read_b128 v[180:183], v180 offset:3072
	s_add_u32 s64, s64, 0x40000
	s_addc_u32 s65, s65, 0
	s_mov_b32 m0, s71
	ds_read_b128 v[184:187], v155 offset:32768
	ds_read_b128 v[192:195], v155 offset:33792
	ds_read_b128 v[196:199], v155 offset:34816
	ds_read_b128 v[200:203], v155 offset:35840
	ds_read_b128 v[204:207], v155 offset:36864
	ds_read_b128 v[208:211], v155 offset:37888
	ds_read_b128 v[212:215], v155 offset:38912
	ds_read_b128 v[216:219], v155 offset:39936
	global_load_lds_dwordx4 v134, s[64:65]
	s_mov_b32 m0, s72
	s_nop 0
	global_load_lds_dwordx4 v130, s[64:65]
	s_waitcnt vmcnt(8) lgkmcnt(0)
	s_barrier
	v_mfma_f32_16x16x32_bf16 v[124:127], v[146:149], v[184:187], v[124:127]
	v_mfma_f32_16x16x32_bf16 v[120:123], v[160:163], v[184:187], v[120:123]
	v_mfma_f32_16x16x32_bf16 v[116:119], v[146:149], v[196:199], v[116:119]
	v_mfma_f32_16x16x32_bf16 v[108:111], v[160:163], v[196:199], v[108:111]
	v_mfma_f32_16x16x32_bf16 v[100:103], v[146:149], v[204:207], v[100:103]
	v_mfma_f32_16x16x32_bf16 v[92:95], v[160:163], v[204:207], v[92:95]
	v_mfma_f32_16x16x32_bf16 v[84:87], v[146:149], v[212:215], v[84:87]
	v_mfma_f32_16x16x32_bf16 v[76:79], v[160:163], v[212:215], v[76:79]
	v_mfma_f32_16x16x32_bf16 v[124:127], v[156:159], v[192:195], v[124:127]
	v_mfma_f32_16x16x32_bf16 v[120:123], v[164:167], v[192:195], v[120:123]
	v_mfma_f32_16x16x32_bf16 v[116:119], v[156:159], v[200:203], v[116:119]
	v_mfma_f32_16x16x32_bf16 v[108:111], v[164:167], v[200:203], v[108:111]
	v_mfma_f32_16x16x32_bf16 v[100:103], v[156:159], v[208:211], v[100:103]
	v_mfma_f32_16x16x32_bf16 v[92:95], v[164:167], v[208:211], v[92:95]
	v_mfma_f32_16x16x32_bf16 v[84:87], v[156:159], v[216:219], v[84:87]
	v_mfma_f32_16x16x32_bf16 v[76:79], v[164:167], v[216:219], v[76:79]
	v_mfma_f32_16x16x32_bf16 v[112:115], v[168:171], v[184:187], v[112:115]
	v_mfma_f32_16x16x32_bf16 v[104:107], v[176:179], v[184:187], v[104:107]
	v_mfma_f32_16x16x32_bf16 v[96:99], v[168:171], v[196:199], v[96:99]
	v_mfma_f32_16x16x32_bf16 v[88:91], v[176:179], v[196:199], v[88:91]
	v_mfma_f32_16x16x32_bf16 v[80:83], v[168:171], v[204:207], v[80:83]
	v_mfma_f32_16x16x32_bf16 v[72:75], v[176:179], v[204:207], v[72:75]
	v_mfma_f32_16x16x32_bf16 v[68:71], v[168:171], v[212:215], v[68:71]
	v_mfma_f32_16x16x32_bf16 v[64:67], v[176:179], v[212:215], v[64:67]
	v_mfma_f32_16x16x32_bf16 v[112:115], v[172:175], v[192:195], v[112:115]
	v_mfma_f32_16x16x32_bf16 v[104:107], v[180:183], v[192:195], v[104:107]
	v_mfma_f32_16x16x32_bf16 v[96:99], v[172:175], v[200:203], v[96:99]
	v_mfma_f32_16x16x32_bf16 v[88:91], v[180:183], v[200:203], v[88:91]
	v_mfma_f32_16x16x32_bf16 v[80:83], v[172:175], v[208:211], v[80:83]
	v_mfma_f32_16x16x32_bf16 v[72:75], v[180:183], v[208:211], v[72:75]
	v_mfma_f32_16x16x32_bf16 v[68:71], v[172:175], v[216:219], v[68:71]
	v_mfma_f32_16x16x32_bf16 v[64:67], v[180:183], v[216:219], v[64:67]
	s_barrier
	s_add_i32 s64, s87, s68
	v_lshl_add_u64 v[188:189], v[188:189], 0, s[10:11]
	s_mov_b32 m0, s64
	ds_read_b128 v[184:187], v155 offset:49152
	ds_read_b128 v[192:195], v155 offset:50176
	ds_read_b128 v[196:199], v155 offset:51200
	ds_read_b128 v[200:203], v155 offset:52224
	ds_read_b128 v[204:207], v155 offset:53248
	ds_read_b128 v[208:211], v155 offset:54272
	ds_read_b128 v[212:215], v155 offset:55296
	ds_read_b128 v[216:219], v155 offset:56320
	global_load_lds_dwordx4 v[188:189], off
	s_add_i32 m0, s64, 0x2000
	s_add_u32 s62, s62, 0x40080
	v_lshl_add_u64 v[188:189], v[220:221], 0, s[10:11]
	s_addc_u32 s63, s63, 0
	s_add_i32 s64, s88, s68
	global_load_lds_dwordx4 v[188:189], off
	s_mov_b32 m0, s64
	s_nop 0
	global_load_lds_dwordx4 v132, s[62:63]
	s_add_i32 m0, s64, 0x2000
	s_nop 0
	global_load_lds_dwordx4 v128, s[62:63]
	v_lshl_add_u64 v[188:189], v[222:223], 0, s[10:11]
	s_mov_b32 m0, s33
	s_nop 0
	global_load_lds_dwordx4 v[188:189], off
	v_lshl_add_u64 v[188:189], v[224:225], 0, s[10:11]
	s_mov_b32 m0, s74
	s_nop 0
	global_load_lds_dwordx4 v[188:189], off
	s_waitcnt vmcnt(8) lgkmcnt(0)
	s_barrier
	v_mfma_f32_16x16x32_bf16 v[60:63], v[146:149], v[184:187], v[60:63]
	v_mfma_f32_16x16x32_bf16 v[56:59], v[160:163], v[184:187], v[56:59]
	v_mfma_f32_16x16x32_bf16 v[52:55], v[146:149], v[196:199], v[52:55]
	v_mfma_f32_16x16x32_bf16 v[44:47], v[160:163], v[196:199], v[44:47]
	v_mfma_f32_16x16x32_bf16 v[36:39], v[146:149], v[204:207], v[36:39]
	v_mfma_f32_16x16x32_bf16 v[28:31], v[160:163], v[204:207], v[28:31]
	v_mfma_f32_16x16x32_bf16 v[20:23], v[146:149], v[212:215], v[20:23]
	v_mfma_f32_16x16x32_bf16 v[12:15], v[160:163], v[212:215], v[12:15]
	v_mfma_f32_16x16x32_bf16 v[60:63], v[156:159], v[192:195], v[60:63]
	v_mfma_f32_16x16x32_bf16 v[56:59], v[164:167], v[192:195], v[56:59]
	v_mfma_f32_16x16x32_bf16 v[52:55], v[156:159], v[200:203], v[52:55]
	v_mfma_f32_16x16x32_bf16 v[44:47], v[164:167], v[200:203], v[44:47]
	v_mfma_f32_16x16x32_bf16 v[36:39], v[156:159], v[208:211], v[36:39]
	v_mfma_f32_16x16x32_bf16 v[28:31], v[164:167], v[208:211], v[28:31]
	v_mfma_f32_16x16x32_bf16 v[20:23], v[156:159], v[216:219], v[20:23]
	v_mfma_f32_16x16x32_bf16 v[12:15], v[164:167], v[216:219], v[12:15]
	v_mfma_f32_16x16x32_bf16 v[48:51], v[168:171], v[184:187], v[48:51]
	v_mfma_f32_16x16x32_bf16 v[40:43], v[176:179], v[184:187], v[40:43]
	v_mfma_f32_16x16x32_bf16 v[32:35], v[168:171], v[196:199], v[32:35]
	v_mfma_f32_16x16x32_bf16 v[24:27], v[176:179], v[196:199], v[24:27]
	v_mfma_f32_16x16x32_bf16 v[16:19], v[168:171], v[204:207], v[16:19]
	v_mfma_f32_16x16x32_bf16 v[8:11], v[176:179], v[204:207], v[8:11]
	v_mfma_f32_16x16x32_bf16 v[4:7], v[168:171], v[212:215], v[4:7]
	v_mfma_f32_16x16x32_bf16 v[0:3], v[176:179], v[212:215], v[0:3]
	v_mfma_f32_16x16x32_bf16 v[48:51], v[172:175], v[192:195], v[48:51]
	v_mfma_f32_16x16x32_bf16 v[40:43], v[180:183], v[192:195], v[40:43]
	v_mfma_f32_16x16x32_bf16 v[32:35], v[172:175], v[200:203], v[32:35]
	v_mfma_f32_16x16x32_bf16 v[24:27], v[180:183], v[200:203], v[24:27]
	v_mfma_f32_16x16x32_bf16 v[16:19], v[172:175], v[208:211], v[16:19]
	v_mfma_f32_16x16x32_bf16 v[8:11], v[180:183], v[208:211], v[8:11]
	v_mfma_f32_16x16x32_bf16 v[4:7], v[172:175], v[216:219], v[4:7]
	v_mfma_f32_16x16x32_bf16 v[0:3], v[180:183], v[216:219], v[0:3]
	s_barrier
	s_add_i32 s86, s86, 2
	s_add_u32 s60, s60, 0x100
	s_addc_u32 s61, s61, 0
	s_add_u32 s84, s84, 0x100
	s_addc_u32 s85, s85, 0
	s_cmp_gt_u32 s86, 13
	s_cbranch_scc0 .LBB0_272

.LBB0_301:
	s_ashr_i32 s27, s26, 31
	s_lshl_b64 s[28:29], s[26:27], 19
	s_add_u32 s28, s43, s28
	s_addc_u32 s29, s52, s29
	s_and_b64 s[30:31], s[4:5], exec
	s_cselect_b32 s27, s29, s37
	s_cselect_b32 s55, s28, s36
	s_ashr_i32 s25, s24, 31
	s_lshl_b64 s[30:31], s[24:25], 19
	s_add_u32 s30, s58, s30
	s_addc_u32 s31, s59, s31
	s_and_b64 s[40:41], s[4:5], exec
	s_cselect_b32 s25, s31, s39
	s_cselect_b32 s72, s30, s38
	s_add_u32 s36, s36, 0x40080
	s_addc_u32 s37, s37, 0
	s_add_u32 s73, s38, 0x100
	s_addc_u32 s74, s39, 0
	s_mov_b32 s75, -2
	ds_read_b128 v[152:155], v149
	ds_read_b128 v[156:159], v149 offset:1024
	ds_read_b128 v[160:163], v149 offset:2048
	ds_read_b128 v[164:167], v149 offset:3072
	ds_read_b128 v[168:171], v150
	ds_read_b128 v[172:175], v150 offset:1024
	ds_read_b128 v[176:179], v150 offset:2048
	ds_read_b128 v[180:183], v150 offset:3072
	s_add_u32 s38, s36, 0xfffc0080
	s_addc_u32 s39, s37, -1
	s_cmp_eq_u32 s75, 12
	s_cselect_b32 s41, s27, s39
	s_cselect_b32 s40, s55, s38
	s_cselect_b32 s39, s25, s74
	s_cselect_b32 s38, s72, s73
	v_lshl_add_u64 v[144:145], s[36:37], 0, v[136:137]
	s_add_i32 m0, s35, 0xc000
	ds_read_b128 v[184:187], v151
	ds_read_b128 v[192:195], v151 offset:1024
	ds_read_b128 v[196:199], v151 offset:2048
	ds_read_b128 v[200:203], v151 offset:3072
	ds_read_b128 v[204:207], v151 offset:4096
	ds_read_b128 v[208:211], v151 offset:5120
	ds_read_b128 v[212:215], v151 offset:6144
	ds_read_b128 v[216:219], v151 offset:7168
	global_load_lds_dwordx4 v[144:145], off
	s_add_i32 m0, s35, 0xe000
	s_nop 0
	global_load_lds_dwordx4 v138, s[36:37]
	s_waitcnt vmcnt(8) lgkmcnt(0)
	s_barrier
	v_mfma_f32_16x16x32_bf16 v[124:127], v[152:155], v[184:187], 0
	v_mfma_f32_16x16x32_bf16 v[120:123], v[160:163], v[184:187], 0
	v_mfma_f32_16x16x32_bf16 v[116:119], v[152:155], v[196:199], 0
	v_mfma_f32_16x16x32_bf16 v[108:111], v[160:163], v[196:199], 0
	v_mfma_f32_16x16x32_bf16 v[100:103], v[152:155], v[204:207], 0
	v_mfma_f32_16x16x32_bf16 v[92:95], v[160:163], v[204:207], 0
	v_mfma_f32_16x16x32_bf16 v[84:87], v[152:155], v[212:215], 0
	v_mfma_f32_16x16x32_bf16 v[76:79], v[160:163], v[212:215], 0
	v_mfma_f32_16x16x32_bf16 v[124:127], v[156:159], v[192:195], v[124:127]
	v_mfma_f32_16x16x32_bf16 v[120:123], v[164:167], v[192:195], v[120:123]
	v_mfma_f32_16x16x32_bf16 v[116:119], v[156:159], v[200:203], v[116:119]
	v_mfma_f32_16x16x32_bf16 v[108:111], v[164:167], v[200:203], v[108:111]
	v_mfma_f32_16x16x32_bf16 v[100:103], v[156:159], v[208:211], v[100:103]
	v_mfma_f32_16x16x32_bf16 v[92:95], v[164:167], v[208:211], v[92:95]
	v_mfma_f32_16x16x32_bf16 v[84:87], v[156:159], v[216:219], v[84:87]
	v_mfma_f32_16x16x32_bf16 v[76:79], v[164:167], v[216:219], v[76:79]
	v_mfma_f32_16x16x32_bf16 v[112:115], v[168:171], v[184:187], 0
	v_mfma_f32_16x16x32_bf16 v[104:107], v[176:179], v[184:187], 0
	v_mfma_f32_16x16x32_bf16 v[96:99], v[168:171], v[196:199], 0
	v_mfma_f32_16x16x32_bf16 v[88:91], v[176:179], v[196:199], 0
	v_mfma_f32_16x16x32_bf16 v[80:83], v[168:171], v[204:207], 0
	v_mfma_f32_16x16x32_bf16 v[72:75], v[176:179], v[204:207], 0
	v_mfma_f32_16x16x32_bf16 v[68:71], v[168:171], v[212:215], 0
	v_mfma_f32_16x16x32_bf16 v[64:67], v[176:179], v[212:215], 0
	v_mfma_f32_16x16x32_bf16 v[112:115], v[172:175], v[192:195], v[112:115]
	v_mfma_f32_16x16x32_bf16 v[104:107], v[180:183], v[192:195], v[104:107]
	v_mfma_f32_16x16x32_bf16 v[96:99], v[172:175], v[200:203], v[96:99]
	v_mfma_f32_16x16x32_bf16 v[88:91], v[180:183], v[200:203], v[88:91]
	v_mfma_f32_16x16x32_bf16 v[80:83], v[172:175], v[208:211], v[80:83]
	v_mfma_f32_16x16x32_bf16 v[72:75], v[180:183], v[208:211], v[72:75]
	v_mfma_f32_16x16x32_bf16 v[68:71], v[172:175], v[216:219], v[68:71]
	v_mfma_f32_16x16x32_bf16 v[64:67], v[180:183], v[216:219], v[64:67]
	s_barrier
	s_add_i32 s76, s66, s53
	v_lshl_add_u64 v[144:145], s[38:39], 0, v[130:131]
	s_mov_b32 m0, s76
	ds_read_b128 v[184:187], v151 offset:16384
	ds_read_b128 v[192:195], v151 offset:17408
	ds_read_b128 v[196:199], v151 offset:18432
	ds_read_b128 v[200:203], v151 offset:19456
	ds_read_b128 v[204:207], v151 offset:20480
	ds_read_b128 v[208:211], v151 offset:21504
	ds_read_b128 v[212:215], v151 offset:22528
	ds_read_b128 v[216:219], v151 offset:23552
	global_load_lds_dwordx4 v[144:145], off
	s_add_i32 m0, s76, 0x2000
	s_add_u32 s76, s38, 0x40000
	v_lshl_add_u64 v[188:189], s[38:39], 0, v[134:135]
	s_addc_u32 s77, s39, 0
	s_add_i32 s80, s67, s53
	global_load_lds_dwordx4 v[188:189], off
	s_mov_b32 m0, s80
	v_lshl_add_u64 v[222:223], s[40:41], 0, v[132:133]
	global_load_lds_dwordx4 v130, s[76:77]
	s_add_i32 m0, s80, 0x2000
	s_nop 0
	global_load_lds_dwordx4 v134, s[76:77]
	v_lshl_add_u64 v[220:221], s[40:41], 0, v[128:129]
	s_mov_b32 m0, s35
	s_nop 0
	global_load_lds_dwordx4 v[220:221], off
	s_mov_b32 m0, s33
	s_nop 0
	global_load_lds_dwordx4 v[222:223], off
	s_waitcnt vmcnt(8) lgkmcnt(0)
	s_barrier
	v_mfma_f32_16x16x32_bf16 v[60:63], v[152:155], v[184:187], 0
	v_mfma_f32_16x16x32_bf16 v[56:59], v[160:163], v[184:187], 0
	v_mfma_f32_16x16x32_bf16 v[52:55], v[152:155], v[196:199], 0
	v_mfma_f32_16x16x32_bf16 v[44:47], v[160:163], v[196:199], 0
	v_mfma_f32_16x16x32_bf16 v[36:39], v[152:155], v[204:207], 0
	v_mfma_f32_16x16x32_bf16 v[28:31], v[160:163], v[204:207], 0
	v_mfma_f32_16x16x32_bf16 v[20:23], v[152:155], v[212:215], 0
	v_mfma_f32_16x16x32_bf16 v[12:15], v[160:163], v[212:215], 0
	v_mfma_f32_16x16x32_bf16 v[60:63], v[156:159], v[192:195], v[60:63]
	v_mfma_f32_16x16x32_bf16 v[56:59], v[164:167], v[192:195], v[56:59]
	v_mfma_f32_16x16x32_bf16 v[52:55], v[156:159], v[200:203], v[52:55]
	v_mfma_f32_16x16x32_bf16 v[44:47], v[164:167], v[200:203], v[44:47]
	v_mfma_f32_16x16x32_bf16 v[36:39], v[156:159], v[208:211], v[36:39]
	v_mfma_f32_16x16x32_bf16 v[28:31], v[164:167], v[208:211], v[28:31]
	v_mfma_f32_16x16x32_bf16 v[20:23], v[156:159], v[216:219], v[20:23]
	v_mfma_f32_16x16x32_bf16 v[12:15], v[164:167], v[216:219], v[12:15]
	v_mfma_f32_16x16x32_bf16 v[48:51], v[168:171], v[184:187], 0
	v_mfma_f32_16x16x32_bf16 v[40:43], v[176:179], v[184:187], 0
	v_mfma_f32_16x16x32_bf16 v[32:35], v[168:171], v[196:199], 0
	v_mfma_f32_16x16x32_bf16 v[24:27], v[176:179], v[196:199], 0
	v_mfma_f32_16x16x32_bf16 v[16:19], v[168:171], v[204:207], 0
	v_mfma_f32_16x16x32_bf16 v[8:11], v[176:179], v[204:207], 0
	v_mfma_f32_16x16x32_bf16 v[4:7], v[168:171], v[212:215], 0
	v_mfma_f32_16x16x32_bf16 v[0:3], v[176:179], v[212:215], 0
	v_mfma_f32_16x16x32_bf16 v[48:51], v[172:175], v[192:195], v[48:51]
	v_mfma_f32_16x16x32_bf16 v[40:43], v[180:183], v[192:195], v[40:43]
	v_mfma_f32_16x16x32_bf16 v[32:35], v[172:175], v[200:203], v[32:35]
	v_mfma_f32_16x16x32_bf16 v[24:27], v[180:183], v[200:203], v[24:27]
	v_mfma_f32_16x16x32_bf16 v[16:19], v[172:175], v[208:211], v[16:19]
	v_mfma_f32_16x16x32_bf16 v[8:11], v[180:183], v[208:211], v[8:11]
	v_mfma_f32_16x16x32_bf16 v[4:7], v[172:175], v[216:219], v[4:7]
	v_mfma_f32_16x16x32_bf16 v[0:3], v[180:183], v[216:219], v[0:3]
	s_barrier
	s_add_i32 s76, 0, 0x18000
	s_add_i32 s77, 0, 0x1c000
	v_add_u32_e32 v164, s76, v147
	v_add_u32_e32 v180, s77, v147
	ds_read_b128 v[152:155], v164
	ds_read_b128 v[156:159], v164 offset:1024
	ds_read_b128 v[160:163], v164 offset:2048
	ds_read_b128 v[164:167], v164 offset:3072
	ds_read_b128 v[168:171], v180
	ds_read_b128 v[172:175], v180 offset:1024
	ds_read_b128 v[176:179], v180 offset:2048
	ds_read_b128 v[180:183], v180 offset:3072
	s_add_u32 s40, s40, 0x40000
	s_addc_u32 s41, s41, 0
	s_mov_b32 m0, s60
	ds_read_b128 v[184:187], v151 offset:32768
	ds_read_b128 v[192:195], v151 offset:33792
	ds_read_b128 v[196:199], v151 offset:34816
	ds_read_b128 v[200:203], v151 offset:35840
	ds_read_b128 v[204:207], v151 offset:36864
	ds_read_b128 v[208:211], v151 offset:37888
	ds_read_b128 v[212:215], v151 offset:38912
	ds_read_b128 v[216:219], v151 offset:39936
	global_load_lds_dwordx4 v128, s[40:41]
	s_mov_b32 m0, s61
	s_nop 0
	global_load_lds_dwordx4 v132, s[40:41]
	s_waitcnt vmcnt(8) lgkmcnt(0)
	s_barrier
	v_mfma_f32_16x16x32_bf16 v[124:127], v[152:155], v[184:187], v[124:127]
	v_mfma_f32_16x16x32_bf16 v[120:123], v[160:163], v[184:187], v[120:123]
	v_mfma_f32_16x16x32_bf16 v[116:119], v[152:155], v[196:199], v[116:119]
	v_mfma_f32_16x16x32_bf16 v[108:111], v[160:163], v[196:199], v[108:111]
	v_mfma_f32_16x16x32_bf16 v[100:103], v[152:155], v[204:207], v[100:103]
	v_mfma_f32_16x16x32_bf16 v[92:95], v[160:163], v[204:207], v[92:95]
	v_mfma_f32_16x16x32_bf16 v[84:87], v[152:155], v[212:215], v[84:87]
	v_mfma_f32_16x16x32_bf16 v[76:79], v[160:163], v[212:215], v[76:79]
	v_mfma_f32_16x16x32_bf16 v[124:127], v[156:159], v[192:195], v[124:127]
	v_mfma_f32_16x16x32_bf16 v[120:123], v[164:167], v[192:195], v[120:123]
	v_mfma_f32_16x16x32_bf16 v[116:119], v[156:159], v[200:203], v[116:119]
	v_mfma_f32_16x16x32_bf16 v[108:111], v[164:167], v[200:203], v[108:111]
	v_mfma_f32_16x16x32_bf16 v[100:103], v[156:159], v[208:211], v[100:103]
	v_mfma_f32_16x16x32_bf16 v[92:95], v[164:167], v[208:211], v[92:95]
	v_mfma_f32_16x16x32_bf16 v[84:87], v[156:159], v[216:219], v[84:87]
	v_mfma_f32_16x16x32_bf16 v[76:79], v[164:167], v[216:219], v[76:79]
	v_mfma_f32_16x16x32_bf16 v[112:115], v[168:171], v[184:187], v[112:115]
	v_mfma_f32_16x16x32_bf16 v[104:107], v[176:179], v[184:187], v[104:107]
	v_mfma_f32_16x16x32_bf16 v[96:99], v[168:171], v[196:199], v[96:99]
	v_mfma_f32_16x16x32_bf16 v[88:91], v[176:179], v[196:199], v[88:91]
	v_mfma_f32_16x16x32_bf16 v[80:83], v[168:171], v[204:207], v[80:83]
	v_mfma_f32_16x16x32_bf16 v[72:75], v[176:179], v[204:207], v[72:75]
	v_mfma_f32_16x16x32_bf16 v[68:71], v[168:171], v[212:215], v[68:71]
	v_mfma_f32_16x16x32_bf16 v[64:67], v[176:179], v[212:215], v[64:67]
	v_mfma_f32_16x16x32_bf16 v[112:115], v[172:175], v[192:195], v[112:115]
	v_mfma_f32_16x16x32_bf16 v[104:107], v[180:183], v[192:195], v[104:107]
	v_mfma_f32_16x16x32_bf16 v[96:99], v[172:175], v[200:203], v[96:99]
	v_mfma_f32_16x16x32_bf16 v[88:91], v[180:183], v[200:203], v[88:91]
	v_mfma_f32_16x16x32_bf16 v[80:83], v[172:175], v[208:211], v[80:83]
	v_mfma_f32_16x16x32_bf16 v[72:75], v[180:183], v[208:211], v[72:75]
	v_mfma_f32_16x16x32_bf16 v[68:71], v[172:175], v[216:219], v[68:71]
	v_mfma_f32_16x16x32_bf16 v[64:67], v[180:183], v[216:219], v[64:67]
	s_barrier
	s_add_i32 s40, s76, s53
	v_lshl_add_u64 v[144:145], v[144:145], 0, s[12:13]
	s_mov_b32 m0, s40
	ds_read_b128 v[184:187], v151 offset:49152
	ds_read_b128 v[192:195], v151 offset:50176
	ds_read_b128 v[196:199], v151 offset:51200
	ds_read_b128 v[200:203], v151 offset:52224
	ds_read_b128 v[204:207], v151 offset:53248
	ds_read_b128 v[208:211], v151 offset:54272
	ds_read_b128 v[212:215], v151 offset:55296
	ds_read_b128 v[216:219], v151 offset:56320
	global_load_lds_dwordx4 v[144:145], off
	s_add_i32 m0, s40, 0x2000
	s_add_u32 s38, s38, 0x40080
	v_lshl_add_u64 v[144:145], v[188:189], 0, s[12:13]
	s_addc_u32 s39, s39, 0
	s_add_i32 s40, s77, s53
	global_load_lds_dwordx4 v[144:145], off
	s_mov_b32 m0, s40
	s_nop 0
	global_load_lds_dwordx4 v130, s[38:39]
	s_add_i32 m0, s40, 0x2000
	s_nop 0
	global_load_lds_dwordx4 v134, s[38:39]
	v_lshl_add_u64 v[144:145], v[220:221], 0, s[12:13]
	s_mov_b32 m0, s63
	s_nop 0
	global_load_lds_dwordx4 v[144:145], off
	v_lshl_add_u64 v[144:145], v[222:223], 0, s[12:13]
	s_mov_b32 m0, s64
	s_nop 0
	global_load_lds_dwordx4 v[144:145], off
	s_waitcnt vmcnt(8) lgkmcnt(0)
	s_barrier
	v_mfma_f32_16x16x32_bf16 v[60:63], v[152:155], v[184:187], v[60:63]
	v_mfma_f32_16x16x32_bf16 v[56:59], v[160:163], v[184:187], v[56:59]
	v_mfma_f32_16x16x32_bf16 v[52:55], v[152:155], v[196:199], v[52:55]
	v_mfma_f32_16x16x32_bf16 v[44:47], v[160:163], v[196:199], v[44:47]
	v_mfma_f32_16x16x32_bf16 v[36:39], v[152:155], v[204:207], v[36:39]
	v_mfma_f32_16x16x32_bf16 v[28:31], v[160:163], v[204:207], v[28:31]
	v_mfma_f32_16x16x32_bf16 v[20:23], v[152:155], v[212:215], v[20:23]
	v_mfma_f32_16x16x32_bf16 v[12:15], v[160:163], v[212:215], v[12:15]
	v_mfma_f32_16x16x32_bf16 v[60:63], v[156:159], v[192:195], v[60:63]
	v_mfma_f32_16x16x32_bf16 v[56:59], v[164:167], v[192:195], v[56:59]
	v_mfma_f32_16x16x32_bf16 v[52:55], v[156:159], v[200:203], v[52:55]
	v_mfma_f32_16x16x32_bf16 v[44:47], v[164:167], v[200:203], v[44:47]
	v_mfma_f32_16x16x32_bf16 v[36:39], v[156:159], v[208:211], v[36:39]
	v_mfma_f32_16x16x32_bf16 v[28:31], v[164:167], v[208:211], v[28:31]
	v_mfma_f32_16x16x32_bf16 v[20:23], v[156:159], v[216:219], v[20:23]
	v_mfma_f32_16x16x32_bf16 v[12:15], v[164:167], v[216:219], v[12:15]
	v_mfma_f32_16x16x32_bf16 v[48:51], v[168:171], v[184:187], v[48:51]
	v_mfma_f32_16x16x32_bf16 v[40:43], v[176:179], v[184:187], v[40:43]
	v_mfma_f32_16x16x32_bf16 v[32:35], v[168:171], v[196:199], v[32:35]
	v_mfma_f32_16x16x32_bf16 v[24:27], v[176:179], v[196:199], v[24:27]
	v_mfma_f32_16x16x32_bf16 v[16:19], v[168:171], v[204:207], v[16:19]
	v_mfma_f32_16x16x32_bf16 v[8:11], v[176:179], v[204:207], v[8:11]
	v_mfma_f32_16x16x32_bf16 v[4:7], v[168:171], v[212:215], v[4:7]
	v_mfma_f32_16x16x32_bf16 v[0:3], v[176:179], v[212:215], v[0:3]
	v_mfma_f32_16x16x32_bf16 v[48:51], v[172:175], v[192:195], v[48:51]
	v_mfma_f32_16x16x32_bf16 v[40:43], v[180:183], v[192:195], v[40:43]
	v_mfma_f32_16x16x32_bf16 v[32:35], v[172:175], v[200:203], v[32:35]
	v_mfma_f32_16x16x32_bf16 v[24:27], v[180:183], v[200:203], v[24:27]
	v_mfma_f32_16x16x32_bf16 v[16:19], v[172:175], v[208:211], v[16:19]
	v_mfma_f32_16x16x32_bf16 v[8:11], v[180:183], v[208:211], v[8:11]
	v_mfma_f32_16x16x32_bf16 v[4:7], v[172:175], v[216:219], v[4:7]
	v_mfma_f32_16x16x32_bf16 v[0:3], v[180:183], v[216:219], v[0:3]
	s_barrier
	s_add_i32 s75, s75, 2
	s_add_u32 s36, s36, 0x100
	s_addc_u32 s37, s37, 0
	s_add_u32 s73, s73, 0x100
	s_addc_u32 s74, s74, 0
	s_cmp_gt_u32 s75, 13
	s_cbranch_scc0 .LBB0_302
	s_branch .Lpeel_exit1
.LBB0_302:
	ds_read_b128 v[152:155], v149
	ds_read_b128 v[156:159], v149 offset:1024
	ds_read_b128 v[160:163], v149 offset:2048
	ds_read_b128 v[164:167], v149 offset:3072
	ds_read_b128 v[168:171], v150
	ds_read_b128 v[172:175], v150 offset:1024
	ds_read_b128 v[176:179], v150 offset:2048
	ds_read_b128 v[180:183], v150 offset:3072
	s_add_u32 s38, s36, 0xfffc0080
	s_addc_u32 s39, s37, -1
	s_cmp_eq_u32 s75, 12
	s_cselect_b32 s41, s27, s39
	s_cselect_b32 s40, s55, s38
	s_cselect_b32 s39, s25, s74
	s_cselect_b32 s38, s72, s73
	v_lshl_add_u64 v[144:145], s[36:37], 0, v[136:137]
	s_add_i32 m0, s35, 0xc000
	ds_read_b128 v[184:187], v151
	ds_read_b128 v[192:195], v151 offset:1024
	ds_read_b128 v[196:199], v151 offset:2048
	ds_read_b128 v[200:203], v151 offset:3072
	ds_read_b128 v[204:207], v151 offset:4096
	ds_read_b128 v[208:211], v151 offset:5120
	ds_read_b128 v[212:215], v151 offset:6144
	ds_read_b128 v[216:219], v151 offset:7168
	global_load_lds_dwordx4 v[144:145], off
	s_add_i32 m0, s35, 0xe000
	s_nop 0
	global_load_lds_dwordx4 v138, s[36:37]
	s_waitcnt vmcnt(8) lgkmcnt(0)
	s_barrier
	v_mfma_f32_16x16x32_bf16 v[124:127], v[152:155], v[184:187], v[124:127]
	v_mfma_f32_16x16x32_bf16 v[120:123], v[160:163], v[184:187], v[120:123]
	v_mfma_f32_16x16x32_bf16 v[116:119], v[152:155], v[196:199], v[116:119]
	v_mfma_f32_16x16x32_bf16 v[108:111], v[160:163], v[196:199], v[108:111]
	v_mfma_f32_16x16x32_bf16 v[100:103], v[152:155], v[204:207], v[100:103]
	v_mfma_f32_16x16x32_bf16 v[92:95], v[160:163], v[204:207], v[92:95]
	v_mfma_f32_16x16x32_bf16 v[84:87], v[152:155], v[212:215], v[84:87]
	v_mfma_f32_16x16x32_bf16 v[76:79], v[160:163], v[212:215], v[76:79]
	v_mfma_f32_16x16x32_bf16 v[124:127], v[156:159], v[192:195], v[124:127]
	v_mfma_f32_16x16x32_bf16 v[120:123], v[164:167], v[192:195], v[120:123]
	v_mfma_f32_16x16x32_bf16 v[116:119], v[156:159], v[200:203], v[116:119]
	v_mfma_f32_16x16x32_bf16 v[108:111], v[164:167], v[200:203], v[108:111]
	v_mfma_f32_16x16x32_bf16 v[100:103], v[156:159], v[208:211], v[100:103]
	v_mfma_f32_16x16x32_bf16 v[92:95], v[164:167], v[208:211], v[92:95]
	v_mfma_f32_16x16x32_bf16 v[84:87], v[156:159], v[216:219], v[84:87]
	v_mfma_f32_16x16x32_bf16 v[76:79], v[164:167], v[216:219], v[76:79]
	v_mfma_f32_16x16x32_bf16 v[112:115], v[168:171], v[184:187], v[112:115]
	v_mfma_f32_16x16x32_bf16 v[104:107], v[176:179], v[184:187], v[104:107]
	v_mfma_f32_16x16x32_bf16 v[96:99], v[168:171], v[196:199], v[96:99]
	v_mfma_f32_16x16x32_bf16 v[88:91], v[176:179], v[196:199], v[88:91]
	v_mfma_f32_16x16x32_bf16 v[80:83], v[168:171], v[204:207], v[80:83]
	v_mfma_f32_16x16x32_bf16 v[72:75], v[176:179], v[204:207], v[72:75]
	v_mfma_f32_16x16x32_bf16 v[68:71], v[168:171], v[212:215], v[68:71]
	v_mfma_f32_16x16x32_bf16 v[64:67], v[176:179], v[212:215], v[64:67]
	v_mfma_f32_16x16x32_bf16 v[112:115], v[172:175], v[192:195], v[112:115]
	v_mfma_f32_16x16x32_bf16 v[104:107], v[180:183], v[192:195], v[104:107]
	v_mfma_f32_16x16x32_bf16 v[96:99], v[172:175], v[200:203], v[96:99]
	v_mfma_f32_16x16x32_bf16 v[88:91], v[180:183], v[200:203], v[88:91]
	v_mfma_f32_16x16x32_bf16 v[80:83], v[172:175], v[208:211], v[80:83]
	v_mfma_f32_16x16x32_bf16 v[72:75], v[180:183], v[208:211], v[72:75]
	v_mfma_f32_16x16x32_bf16 v[68:71], v[172:175], v[216:219], v[68:71]
	v_mfma_f32_16x16x32_bf16 v[64:67], v[180:183], v[216:219], v[64:67]
	s_barrier
	s_add_i32 s76, s66, s53
	v_lshl_add_u64 v[144:145], s[38:39], 0, v[130:131]
	s_mov_b32 m0, s76
	ds_read_b128 v[184:187], v151 offset:16384
	ds_read_b128 v[192:195], v151 offset:17408
	ds_read_b128 v[196:199], v151 offset:18432
	ds_read_b128 v[200:203], v151 offset:19456
	ds_read_b128 v[204:207], v151 offset:20480
	ds_read_b128 v[208:211], v151 offset:21504
	ds_read_b128 v[212:215], v151 offset:22528
	ds_read_b128 v[216:219], v151 offset:23552
	global_load_lds_dwordx4 v[144:145], off
	s_add_i32 m0, s76, 0x2000
	s_add_u32 s76, s38, 0x40000
	v_lshl_add_u64 v[188:189], s[38:39], 0, v[134:135]
	s_addc_u32 s77, s39, 0
	s_add_i32 s80, s67, s53
	global_load_lds_dwordx4 v[188:189], off
	s_mov_b32 m0, s80
	v_lshl_add_u64 v[222:223], s[40:41], 0, v[132:133]
	global_load_lds_dwordx4 v130, s[76:77]
	s_add_i32 m0, s80, 0x2000
	s_nop 0
	global_load_lds_dwordx4 v134, s[76:77]
	v_lshl_add_u64 v[220:221], s[40:41], 0, v[128:129]
	s_mov_b32 m0, s35
	s_nop 0
	global_load_lds_dwordx4 v[220:221], off
	s_mov_b32 m0, s33
	s_nop 0
	global_load_lds_dwordx4 v[222:223], off
	s_waitcnt vmcnt(8) lgkmcnt(0)
	s_barrier
	v_mfma_f32_16x16x32_bf16 v[60:63], v[152:155], v[184:187], v[60:63]
	v_mfma_f32_16x16x32_bf16 v[56:59], v[160:163], v[184:187], v[56:59]
	v_mfma_f32_16x16x32_bf16 v[52:55], v[152:155], v[196:199], v[52:55]
	v_mfma_f32_16x16x32_bf16 v[44:47], v[160:163], v[196:199], v[44:47]
	v_mfma_f32_16x16x32_bf16 v[36:39], v[152:155], v[204:207], v[36:39]
	v_mfma_f32_16x16x32_bf16 v[28:31], v[160:163], v[204:207], v[28:31]
	v_mfma_f32_16x16x32_bf16 v[20:23], v[152:155], v[212:215], v[20:23]
	v_mfma_f32_16x16x32_bf16 v[12:15], v[160:163], v[212:215], v[12:15]
	v_mfma_f32_16x16x32_bf16 v[60:63], v[156:159], v[192:195], v[60:63]
	v_mfma_f32_16x16x32_bf16 v[56:59], v[164:167], v[192:195], v[56:59]
	v_mfma_f32_16x16x32_bf16 v[52:55], v[156:159], v[200:203], v[52:55]
	v_mfma_f32_16x16x32_bf16 v[44:47], v[164:167], v[200:203], v[44:47]
	v_mfma_f32_16x16x32_bf16 v[36:39], v[156:159], v[208:211], v[36:39]
	v_mfma_f32_16x16x32_bf16 v[28:31], v[164:167], v[208:211], v[28:31]
	v_mfma_f32_16x16x32_bf16 v[20:23], v[156:159], v[216:219], v[20:23]
	v_mfma_f32_16x16x32_bf16 v[12:15], v[164:167], v[216:219], v[12:15]
	v_mfma_f32_16x16x32_bf16 v[48:51], v[168:171], v[184:187], v[48:51]
	v_mfma_f32_16x16x32_bf16 v[40:43], v[176:179], v[184:187], v[40:43]
	v_mfma_f32_16x16x32_bf16 v[32:35], v[168:171], v[196:199], v[32:35]
	v_mfma_f32_16x16x32_bf16 v[24:27], v[176:179], v[196:199], v[24:27]
	v_mfma_f32_16x16x32_bf16 v[16:19], v[168:171], v[204:207], v[16:19]
	v_mfma_f32_16x16x32_bf16 v[8:11], v[176:179], v[204:207], v[8:11]
	v_mfma_f32_16x16x32_bf16 v[4:7], v[168:171], v[212:215], v[4:7]
	v_mfma_f32_16x16x32_bf16 v[0:3], v[176:179], v[212:215], v[0:3]
	v_mfma_f32_16x16x32_bf16 v[48:51], v[172:175], v[192:195], v[48:51]
	v_mfma_f32_16x16x32_bf16 v[40:43], v[180:183], v[192:195], v[40:43]
	v_mfma_f32_16x16x32_bf16 v[32:35], v[172:175], v[200:203], v[32:35]
	v_mfma_f32_16x16x32_bf16 v[24:27], v[180:183], v[200:203], v[24:27]
	v_mfma_f32_16x16x32_bf16 v[16:19], v[172:175], v[208:211], v[16:19]
	v_mfma_f32_16x16x32_bf16 v[8:11], v[180:183], v[208:211], v[8:11]
	v_mfma_f32_16x16x32_bf16 v[4:7], v[172:175], v[216:219], v[4:7]
	v_mfma_f32_16x16x32_bf16 v[0:3], v[180:183], v[216:219], v[0:3]
	s_barrier
	s_add_i32 s76, 0, 0x18000
	s_add_i32 s77, 0, 0x1c000
	v_add_u32_e32 v164, s76, v147
	v_add_u32_e32 v180, s77, v147
	ds_read_b128 v[152:155], v164
	ds_read_b128 v[156:159], v164 offset:1024
	ds_read_b128 v[160:163], v164 offset:2048
	ds_read_b128 v[164:167], v164 offset:3072
	ds_read_b128 v[168:171], v180
	ds_read_b128 v[172:175], v180 offset:1024
	ds_read_b128 v[176:179], v180 offset:2048
	ds_read_b128 v[180:183], v180 offset:3072
	s_add_u32 s40, s40, 0x40000
	s_addc_u32 s41, s41, 0
	s_mov_b32 m0, s60
	ds_read_b128 v[184:187], v151 offset:32768
	ds_read_b128 v[192:195], v151 offset:33792
	ds_read_b128 v[196:199], v151 offset:34816
	ds_read_b128 v[200:203], v151 offset:35840
	ds_read_b128 v[204:207], v151 offset:36864
	ds_read_b128 v[208:211], v151 offset:37888
	ds_read_b128 v[212:215], v151 offset:38912
	ds_read_b128 v[216:219], v151 offset:39936
	global_load_lds_dwordx4 v128, s[40:41]
	s_mov_b32 m0, s61
	s_nop 0
	global_load_lds_dwordx4 v132, s[40:41]
	s_waitcnt vmcnt(8) lgkmcnt(0)
	s_barrier
	v_mfma_f32_16x16x32_bf16 v[124:127], v[152:155], v[184:187], v[124:127]
	v_mfma_f32_16x16x32_bf16 v[120:123], v[160:163], v[184:187], v[120:123]
	v_mfma_f32_16x16x32_bf16 v[116:119], v[152:155], v[196:199], v[116:119]
	v_mfma_f32_16x16x32_bf16 v[108:111], v[160:163], v[196:199], v[108:111]
	v_mfma_f32_16x16x32_bf16 v[100:103], v[152:155], v[204:207], v[100:103]
	v_mfma_f32_16x16x32_bf16 v[92:95], v[160:163], v[204:207], v[92:95]
	v_mfma_f32_16x16x32_bf16 v[84:87], v[152:155], v[212:215], v[84:87]
	v_mfma_f32_16x16x32_bf16 v[76:79], v[160:163], v[212:215], v[76:79]
	v_mfma_f32_16x16x32_bf16 v[124:127], v[156:159], v[192:195], v[124:127]
	v_mfma_f32_16x16x32_bf16 v[120:123], v[164:167], v[192:195], v[120:123]
	v_mfma_f32_16x16x32_bf16 v[116:119], v[156:159], v[200:203], v[116:119]
	v_mfma_f32_16x16x32_bf16 v[108:111], v[164:167], v[200:203], v[108:111]
	v_mfma_f32_16x16x32_bf16 v[100:103], v[156:159], v[208:211], v[100:103]
	v_mfma_f32_16x16x32_bf16 v[92:95], v[164:167], v[208:211], v[92:95]
	v_mfma_f32_16x16x32_bf16 v[84:87], v[156:159], v[216:219], v[84:87]
	v_mfma_f32_16x16x32_bf16 v[76:79], v[164:167], v[216:219], v[76:79]
	v_mfma_f32_16x16x32_bf16 v[112:115], v[168:171], v[184:187], v[112:115]
	v_mfma_f32_16x16x32_bf16 v[104:107], v[176:179], v[184:187], v[104:107]
	v_mfma_f32_16x16x32_bf16 v[96:99], v[168:171], v[196:199], v[96:99]
	v_mfma_f32_16x16x32_bf16 v[88:91], v[176:179], v[196:199], v[88:91]
	v_mfma_f32_16x16x32_bf16 v[80:83], v[168:171], v[204:207], v[80:83]
	v_mfma_f32_16x16x32_bf16 v[72:75], v[176:179], v[204:207], v[72:75]
	v_mfma_f32_16x16x32_bf16 v[68:71], v[168:171], v[212:215], v[68:71]
	v_mfma_f32_16x16x32_bf16 v[64:67], v[176:179], v[212:215], v[64:67]
	v_mfma_f32_16x16x32_bf16 v[112:115], v[172:175], v[192:195], v[112:115]
	v_mfma_f32_16x16x32_bf16 v[104:107], v[180:183], v[192:195], v[104:107]
	v_mfma_f32_16x16x32_bf16 v[96:99], v[172:175], v[200:203], v[96:99]
	v_mfma_f32_16x16x32_bf16 v[88:91], v[180:183], v[200:203], v[88:91]
	v_mfma_f32_16x16x32_bf16 v[80:83], v[172:175], v[208:211], v[80:83]
	v_mfma_f32_16x16x32_bf16 v[72:75], v[180:183], v[208:211], v[72:75]
	v_mfma_f32_16x16x32_bf16 v[68:71], v[172:175], v[216:219], v[68:71]
	v_mfma_f32_16x16x32_bf16 v[64:67], v[180:183], v[216:219], v[64:67]
	s_barrier
	s_add_i32 s40, s76, s53
	v_lshl_add_u64 v[144:145], v[144:145], 0, s[12:13]
	s_mov_b32 m0, s40
	ds_read_b128 v[184:187], v151 offset:49152
	ds_read_b128 v[192:195], v151 offset:50176
	ds_read_b128 v[196:199], v151 offset:51200
	ds_read_b128 v[200:203], v151 offset:52224
	ds_read_b128 v[204:207], v151 offset:53248
	ds_read_b128 v[208:211], v151 offset:54272
	ds_read_b128 v[212:215], v151 offset:55296
	ds_read_b128 v[216:219], v151 offset:56320
	global_load_lds_dwordx4 v[144:145], off
	s_add_i32 m0, s40, 0x2000
	s_add_u32 s38, s38, 0x40080
	v_lshl_add_u64 v[144:145], v[188:189], 0, s[12:13]
	s_addc_u32 s39, s39, 0
	s_add_i32 s40, s77, s53
	global_load_lds_dwordx4 v[144:145], off
	s_mov_b32 m0, s40
	s_nop 0
	global_load_lds_dwordx4 v130, s[38:39]
	s_add_i32 m0, s40, 0x2000
	s_nop 0
	global_load_lds_dwordx4 v134, s[38:39]
	v_lshl_add_u64 v[144:145], v[220:221], 0, s[12:13]
	s_mov_b32 m0, s63
	s_nop 0
	global_load_lds_dwordx4 v[144:145], off
	v_lshl_add_u64 v[144:145], v[222:223], 0, s[12:13]
	s_mov_b32 m0, s64
	s_nop 0
	global_load_lds_dwordx4 v[144:145], off
	s_waitcnt vmcnt(8) lgkmcnt(0)
	s_barrier
	v_mfma_f32_16x16x32_bf16 v[60:63], v[152:155], v[184:187], v[60:63]
	v_mfma_f32_16x16x32_bf16 v[56:59], v[160:163], v[184:187], v[56:59]
	v_mfma_f32_16x16x32_bf16 v[52:55], v[152:155], v[196:199], v[52:55]
	v_mfma_f32_16x16x32_bf16 v[44:47], v[160:163], v[196:199], v[44:47]
	v_mfma_f32_16x16x32_bf16 v[36:39], v[152:155], v[204:207], v[36:39]
	v_mfma_f32_16x16x32_bf16 v[28:31], v[160:163], v[204:207], v[28:31]
	v_mfma_f32_16x16x32_bf16 v[20:23], v[152:155], v[212:215], v[20:23]
	v_mfma_f32_16x16x32_bf16 v[12:15], v[160:163], v[212:215], v[12:15]
	v_mfma_f32_16x16x32_bf16 v[60:63], v[156:159], v[192:195], v[60:63]
	v_mfma_f32_16x16x32_bf16 v[56:59], v[164:167], v[192:195], v[56:59]
	v_mfma_f32_16x16x32_bf16 v[52:55], v[156:159], v[200:203], v[52:55]
	v_mfma_f32_16x16x32_bf16 v[44:47], v[164:167], v[200:203], v[44:47]
	v_mfma_f32_16x16x32_bf16 v[36:39], v[156:159], v[208:211], v[36:39]
	v_mfma_f32_16x16x32_bf16 v[28:31], v[164:167], v[208:211], v[28:31]
	v_mfma_f32_16x16x32_bf16 v[20:23], v[156:159], v[216:219], v[20:23]
	v_mfma_f32_16x16x32_bf16 v[12:15], v[164:167], v[216:219], v[12:15]
	v_mfma_f32_16x16x32_bf16 v[48:51], v[168:171], v[184:187], v[48:51]
	v_mfma_f32_16x16x32_bf16 v[40:43], v[176:179], v[184:187], v[40:43]
	v_mfma_f32_16x16x32_bf16 v[32:35], v[168:171], v[196:199], v[32:35]
	v_mfma_f32_16x16x32_bf16 v[24:27], v[176:179], v[196:199], v[24:27]
	v_mfma_f32_16x16x32_bf16 v[16:19], v[168:171], v[204:207], v[16:19]
	v_mfma_f32_16x16x32_bf16 v[8:11], v[176:179], v[204:207], v[8:11]
	v_mfma_f32_16x16x32_bf16 v[4:7], v[168:171], v[212:215], v[4:7]
	v_mfma_f32_16x16x32_bf16 v[0:3], v[176:179], v[212:215], v[0:3]
	v_mfma_f32_16x16x32_bf16 v[48:51], v[172:175], v[192:195], v[48:51]
	v_mfma_f32_16x16x32_bf16 v[40:43], v[180:183], v[192:195], v[40:43]
	v_mfma_f32_16x16x32_bf16 v[32:35], v[172:175], v[200:203], v[32:35]
	v_mfma_f32_16x16x32_bf16 v[24:27], v[180:183], v[200:203], v[24:27]
	v_mfma_f32_16x16x32_bf16 v[16:19], v[172:175], v[208:211], v[16:19]
	v_mfma_f32_16x16x32_bf16 v[8:11], v[180:183], v[208:211], v[8:11]
	v_mfma_f32_16x16x32_bf16 v[4:7], v[172:175], v[216:219], v[4:7]
	v_mfma_f32_16x16x32_bf16 v[0:3], v[180:183], v[216:219], v[0:3]
	s_barrier
	s_add_i32 s75, s75, 2
	s_add_u32 s36, s36, 0x100
	s_addc_u32 s37, s37, 0
	s_add_u32 s73, s73, 0x100
	s_addc_u32 s74, s74, 0
	s_cmp_gt_u32 s75, 13
	s_cbranch_scc0 .LBB0_302

.LBB0_699:
	s_ashr_i32 s25, s24, 31
	s_lshl_b64 s[26:27], s[24:25], 19
	s_add_u32 s26, s58, s26
	s_addc_u32 s27, s59, s27
	s_and_b64 s[28:29], s[4:5], exec
	s_cselect_b32 s25, s27, s35
	s_cselect_b32 s55, s26, s34
	s_ashr_i32 s23, s22, 31
	s_lshl_b64 s[28:29], s[22:23], 19
	s_add_u32 s28, s43, s28
	s_addc_u32 s29, s52, s29
	s_and_b64 s[40:41], s[4:5], exec
	s_cselect_b32 s23, s29, s39
	s_cselect_b32 s72, s28, s38
	s_add_u32 s34, s34, 0x40080
	s_addc_u32 s35, s35, 0
	s_add_u32 s73, s38, 0x100
	s_addc_u32 s74, s39, 0
	s_mov_b32 s75, -2
	ds_read_b128 v[152:155], v149
	ds_read_b128 v[156:159], v149 offset:1024
	ds_read_b128 v[160:163], v149 offset:2048
	ds_read_b128 v[164:167], v149 offset:3072
	ds_read_b128 v[168:171], v150
	ds_read_b128 v[172:175], v150 offset:1024
	ds_read_b128 v[176:179], v150 offset:2048
	ds_read_b128 v[180:183], v150 offset:3072
	s_add_u32 s38, s34, 0xfffc0080
	s_addc_u32 s39, s35, -1
	s_cmp_eq_u32 s75, 12
	s_cselect_b32 s41, s25, s39
	s_cselect_b32 s40, s55, s38
	s_cselect_b32 s39, s23, s74
	s_cselect_b32 s38, s72, s73
	s_add_i32 m0, s31, 0xc000
	ds_read_b128 v[184:187], v151
	ds_read_b128 v[192:195], v151 offset:1024
	ds_read_b128 v[196:199], v151 offset:2048
	ds_read_b128 v[200:203], v151 offset:3072
	ds_read_b128 v[204:207], v151 offset:4096
	ds_read_b128 v[208:211], v151 offset:5120
	ds_read_b128 v[212:215], v151 offset:6144
	ds_read_b128 v[216:219], v151 offset:7168
	global_load_lds_dwordx4 v136, s[34:35]
	s_add_i32 m0, s31, 0xe000
	s_nop 0
	global_load_lds_dwordx4 v138, s[34:35]
	s_waitcnt vmcnt(8) lgkmcnt(0)
	s_barrier
	v_mfma_f32_16x16x32_bf16 v[124:127], v[152:155], v[184:187], 0
	v_mfma_f32_16x16x32_bf16 v[120:123], v[160:163], v[184:187], 0
	v_mfma_f32_16x16x32_bf16 v[116:119], v[152:155], v[196:199], 0
	v_mfma_f32_16x16x32_bf16 v[108:111], v[160:163], v[196:199], 0
	v_mfma_f32_16x16x32_bf16 v[100:103], v[152:155], v[204:207], 0
	v_mfma_f32_16x16x32_bf16 v[92:95], v[160:163], v[204:207], 0
	v_mfma_f32_16x16x32_bf16 v[84:87], v[152:155], v[212:215], 0
	v_mfma_f32_16x16x32_bf16 v[76:79], v[160:163], v[212:215], 0
	v_mfma_f32_16x16x32_bf16 v[124:127], v[156:159], v[192:195], v[124:127]
	v_mfma_f32_16x16x32_bf16 v[120:123], v[164:167], v[192:195], v[120:123]
	v_mfma_f32_16x16x32_bf16 v[116:119], v[156:159], v[200:203], v[116:119]
	v_mfma_f32_16x16x32_bf16 v[108:111], v[164:167], v[200:203], v[108:111]
	v_mfma_f32_16x16x32_bf16 v[100:103], v[156:159], v[208:211], v[100:103]
	v_mfma_f32_16x16x32_bf16 v[92:95], v[164:167], v[208:211], v[92:95]
	v_mfma_f32_16x16x32_bf16 v[84:87], v[156:159], v[216:219], v[84:87]
	v_mfma_f32_16x16x32_bf16 v[76:79], v[164:167], v[216:219], v[76:79]
	v_mfma_f32_16x16x32_bf16 v[112:115], v[168:171], v[184:187], 0
	v_mfma_f32_16x16x32_bf16 v[104:107], v[176:179], v[184:187], 0
	v_mfma_f32_16x16x32_bf16 v[96:99], v[168:171], v[196:199], 0
	v_mfma_f32_16x16x32_bf16 v[88:91], v[176:179], v[196:199], 0
	v_mfma_f32_16x16x32_bf16 v[80:83], v[168:171], v[204:207], 0
	v_mfma_f32_16x16x32_bf16 v[72:75], v[176:179], v[204:207], 0
	v_mfma_f32_16x16x32_bf16 v[68:71], v[168:171], v[212:215], 0
	v_mfma_f32_16x16x32_bf16 v[64:67], v[176:179], v[212:215], 0
	v_mfma_f32_16x16x32_bf16 v[112:115], v[172:175], v[192:195], v[112:115]
	v_mfma_f32_16x16x32_bf16 v[104:107], v[180:183], v[192:195], v[104:107]
	v_mfma_f32_16x16x32_bf16 v[96:99], v[172:175], v[200:203], v[96:99]
	v_mfma_f32_16x16x32_bf16 v[88:91], v[180:183], v[200:203], v[88:91]
	v_mfma_f32_16x16x32_bf16 v[80:83], v[172:175], v[208:211], v[80:83]
	v_mfma_f32_16x16x32_bf16 v[72:75], v[180:183], v[208:211], v[72:75]
	v_mfma_f32_16x16x32_bf16 v[68:71], v[172:175], v[216:219], v[68:71]
	v_mfma_f32_16x16x32_bf16 v[64:67], v[180:183], v[216:219], v[64:67]
	s_barrier
	s_add_i32 s76, s66, s53
	v_lshl_add_u64 v[144:145], s[38:39], 0, v[130:131]
	s_mov_b32 m0, s76
	ds_read_b128 v[184:187], v151 offset:16384
	ds_read_b128 v[192:195], v151 offset:17408
	ds_read_b128 v[196:199], v151 offset:18432
	ds_read_b128 v[200:203], v151 offset:19456
	ds_read_b128 v[204:207], v151 offset:20480
	ds_read_b128 v[208:211], v151 offset:21504
	ds_read_b128 v[212:215], v151 offset:22528
	ds_read_b128 v[216:219], v151 offset:23552
	global_load_lds_dwordx4 v[144:145], off
	s_add_i32 m0, s76, 0x2000
	s_add_u32 s76, s38, 0x40000
	v_lshl_add_u64 v[188:189], s[38:39], 0, v[134:135]
	s_addc_u32 s77, s39, 0
	s_add_i32 s79, s67, s53
	global_load_lds_dwordx4 v[188:189], off
	s_mov_b32 m0, s79
	v_lshl_add_u64 v[222:223], s[40:41], 0, v[132:133]
	global_load_lds_dwordx4 v130, s[76:77]
	s_add_i32 m0, s79, 0x2000
	s_nop 0
	global_load_lds_dwordx4 v134, s[76:77]
	v_lshl_add_u64 v[220:221], s[40:41], 0, v[128:129]
	s_mov_b32 m0, s31
	s_nop 0
	global_load_lds_dwordx4 v[220:221], off
	s_mov_b32 m0, s33
	s_nop 0
	global_load_lds_dwordx4 v[222:223], off
	s_waitcnt vmcnt(8) lgkmcnt(0)
	s_barrier
	v_mfma_f32_16x16x32_bf16 v[60:63], v[152:155], v[184:187], 0
	v_mfma_f32_16x16x32_bf16 v[56:59], v[160:163], v[184:187], 0
	v_mfma_f32_16x16x32_bf16 v[52:55], v[152:155], v[196:199], 0
	v_mfma_f32_16x16x32_bf16 v[44:47], v[160:163], v[196:199], 0
	v_mfma_f32_16x16x32_bf16 v[36:39], v[152:155], v[204:207], 0
	v_mfma_f32_16x16x32_bf16 v[28:31], v[160:163], v[204:207], 0
	v_mfma_f32_16x16x32_bf16 v[20:23], v[152:155], v[212:215], 0
	v_mfma_f32_16x16x32_bf16 v[12:15], v[160:163], v[212:215], 0
	v_mfma_f32_16x16x32_bf16 v[60:63], v[156:159], v[192:195], v[60:63]
	v_mfma_f32_16x16x32_bf16 v[56:59], v[164:167], v[192:195], v[56:59]
	v_mfma_f32_16x16x32_bf16 v[52:55], v[156:159], v[200:203], v[52:55]
	v_mfma_f32_16x16x32_bf16 v[44:47], v[164:167], v[200:203], v[44:47]
	v_mfma_f32_16x16x32_bf16 v[36:39], v[156:159], v[208:211], v[36:39]
	v_mfma_f32_16x16x32_bf16 v[28:31], v[164:167], v[208:211], v[28:31]
	v_mfma_f32_16x16x32_bf16 v[20:23], v[156:159], v[216:219], v[20:23]
	v_mfma_f32_16x16x32_bf16 v[12:15], v[164:167], v[216:219], v[12:15]
	v_mfma_f32_16x16x32_bf16 v[48:51], v[168:171], v[184:187], 0
	v_mfma_f32_16x16x32_bf16 v[40:43], v[176:179], v[184:187], 0
	v_mfma_f32_16x16x32_bf16 v[32:35], v[168:171], v[196:199], 0
	v_mfma_f32_16x16x32_bf16 v[24:27], v[176:179], v[196:199], 0
	v_mfma_f32_16x16x32_bf16 v[16:19], v[168:171], v[204:207], 0
	v_mfma_f32_16x16x32_bf16 v[8:11], v[176:179], v[204:207], 0
	v_mfma_f32_16x16x32_bf16 v[4:7], v[168:171], v[212:215], 0
	v_mfma_f32_16x16x32_bf16 v[0:3], v[176:179], v[212:215], 0
	v_mfma_f32_16x16x32_bf16 v[48:51], v[172:175], v[192:195], v[48:51]
	v_mfma_f32_16x16x32_bf16 v[40:43], v[180:183], v[192:195], v[40:43]
	v_mfma_f32_16x16x32_bf16 v[32:35], v[172:175], v[200:203], v[32:35]
	v_mfma_f32_16x16x32_bf16 v[24:27], v[180:183], v[200:203], v[24:27]
	v_mfma_f32_16x16x32_bf16 v[16:19], v[172:175], v[208:211], v[16:19]
	v_mfma_f32_16x16x32_bf16 v[8:11], v[180:183], v[208:211], v[8:11]
	v_mfma_f32_16x16x32_bf16 v[4:7], v[172:175], v[216:219], v[4:7]
	v_mfma_f32_16x16x32_bf16 v[0:3], v[180:183], v[216:219], v[0:3]
	s_barrier
	s_add_i32 s76, 0, 0x18000
	s_add_i32 s77, 0, 0x1c000
	v_add_u32_e32 v164, s76, v147
	v_add_u32_e32 v180, s77, v147
	ds_read_b128 v[152:155], v164
	ds_read_b128 v[156:159], v164 offset:1024
	ds_read_b128 v[160:163], v164 offset:2048
	ds_read_b128 v[164:167], v164 offset:3072
	ds_read_b128 v[168:171], v180
	ds_read_b128 v[172:175], v180 offset:1024
	ds_read_b128 v[176:179], v180 offset:2048
	ds_read_b128 v[180:183], v180 offset:3072
	s_add_u32 s40, s40, 0x40000
	s_addc_u32 s41, s41, 0
	s_mov_b32 m0, s60
	ds_read_b128 v[184:187], v151 offset:32768
	ds_read_b128 v[192:195], v151 offset:33792
	ds_read_b128 v[196:199], v151 offset:34816
	ds_read_b128 v[200:203], v151 offset:35840
	ds_read_b128 v[204:207], v151 offset:36864
	ds_read_b128 v[208:211], v151 offset:37888
	ds_read_b128 v[212:215], v151 offset:38912
	ds_read_b128 v[216:219], v151 offset:39936
	global_load_lds_dwordx4 v128, s[40:41]
	s_mov_b32 m0, s61
	s_nop 0
	global_load_lds_dwordx4 v132, s[40:41]
	s_waitcnt vmcnt(8) lgkmcnt(0)
	s_barrier
	v_mfma_f32_16x16x32_bf16 v[124:127], v[152:155], v[184:187], v[124:127]
	v_mfma_f32_16x16x32_bf16 v[120:123], v[160:163], v[184:187], v[120:123]
	v_mfma_f32_16x16x32_bf16 v[116:119], v[152:155], v[196:199], v[116:119]
	v_mfma_f32_16x16x32_bf16 v[108:111], v[160:163], v[196:199], v[108:111]
	v_mfma_f32_16x16x32_bf16 v[100:103], v[152:155], v[204:207], v[100:103]
	v_mfma_f32_16x16x32_bf16 v[92:95], v[160:163], v[204:207], v[92:95]
	v_mfma_f32_16x16x32_bf16 v[84:87], v[152:155], v[212:215], v[84:87]
	v_mfma_f32_16x16x32_bf16 v[76:79], v[160:163], v[212:215], v[76:79]
	v_mfma_f32_16x16x32_bf16 v[124:127], v[156:159], v[192:195], v[124:127]
	v_mfma_f32_16x16x32_bf16 v[120:123], v[164:167], v[192:195], v[120:123]
	v_mfma_f32_16x16x32_bf16 v[116:119], v[156:159], v[200:203], v[116:119]
	v_mfma_f32_16x16x32_bf16 v[108:111], v[164:167], v[200:203], v[108:111]
	v_mfma_f32_16x16x32_bf16 v[100:103], v[156:159], v[208:211], v[100:103]
	v_mfma_f32_16x16x32_bf16 v[92:95], v[164:167], v[208:211], v[92:95]
	v_mfma_f32_16x16x32_bf16 v[84:87], v[156:159], v[216:219], v[84:87]
	v_mfma_f32_16x16x32_bf16 v[76:79], v[164:167], v[216:219], v[76:79]
	v_mfma_f32_16x16x32_bf16 v[112:115], v[168:171], v[184:187], v[112:115]
	v_mfma_f32_16x16x32_bf16 v[104:107], v[176:179], v[184:187], v[104:107]
	v_mfma_f32_16x16x32_bf16 v[96:99], v[168:171], v[196:199], v[96:99]
	v_mfma_f32_16x16x32_bf16 v[88:91], v[176:179], v[196:199], v[88:91]
	v_mfma_f32_16x16x32_bf16 v[80:83], v[168:171], v[204:207], v[80:83]
	v_mfma_f32_16x16x32_bf16 v[72:75], v[176:179], v[204:207], v[72:75]
	v_mfma_f32_16x16x32_bf16 v[68:71], v[168:171], v[212:215], v[68:71]
	v_mfma_f32_16x16x32_bf16 v[64:67], v[176:179], v[212:215], v[64:67]
	v_mfma_f32_16x16x32_bf16 v[112:115], v[172:175], v[192:195], v[112:115]
	v_mfma_f32_16x16x32_bf16 v[104:107], v[180:183], v[192:195], v[104:107]
	v_mfma_f32_16x16x32_bf16 v[96:99], v[172:175], v[200:203], v[96:99]
	v_mfma_f32_16x16x32_bf16 v[88:91], v[180:183], v[200:203], v[88:91]
	v_mfma_f32_16x16x32_bf16 v[80:83], v[172:175], v[208:211], v[80:83]
	v_mfma_f32_16x16x32_bf16 v[72:75], v[180:183], v[208:211], v[72:75]
	v_mfma_f32_16x16x32_bf16 v[68:71], v[172:175], v[216:219], v[68:71]
	v_mfma_f32_16x16x32_bf16 v[64:67], v[180:183], v[216:219], v[64:67]
	s_barrier
	s_add_i32 s40, s76, s53
	v_lshl_add_u64 v[144:145], v[144:145], 0, s[12:13]
	s_mov_b32 m0, s40
	ds_read_b128 v[184:187], v151 offset:49152
	ds_read_b128 v[192:195], v151 offset:50176
	ds_read_b128 v[196:199], v151 offset:51200
	ds_read_b128 v[200:203], v151 offset:52224
	ds_read_b128 v[204:207], v151 offset:53248
	ds_read_b128 v[208:211], v151 offset:54272
	ds_read_b128 v[212:215], v151 offset:55296
	ds_read_b128 v[216:219], v151 offset:56320
	global_load_lds_dwordx4 v[144:145], off
	s_add_i32 m0, s40, 0x2000
	s_add_u32 s38, s38, 0x40080
	v_lshl_add_u64 v[144:145], v[188:189], 0, s[12:13]
	s_addc_u32 s39, s39, 0
	s_add_i32 s40, s77, s53
	global_load_lds_dwordx4 v[144:145], off
	s_mov_b32 m0, s40
	s_nop 0
	global_load_lds_dwordx4 v130, s[38:39]
	s_add_i32 m0, s40, 0x2000
	s_nop 0
	global_load_lds_dwordx4 v134, s[38:39]
	v_lshl_add_u64 v[144:145], v[220:221], 0, s[12:13]
	s_mov_b32 m0, s63
	s_nop 0
	global_load_lds_dwordx4 v[144:145], off
	v_lshl_add_u64 v[144:145], v[222:223], 0, s[12:13]
	s_mov_b32 m0, s64
	s_nop 0
	global_load_lds_dwordx4 v[144:145], off
	s_waitcnt vmcnt(8) lgkmcnt(0)
	s_barrier
	v_mfma_f32_16x16x32_bf16 v[60:63], v[152:155], v[184:187], v[60:63]
	v_mfma_f32_16x16x32_bf16 v[56:59], v[160:163], v[184:187], v[56:59]
	v_mfma_f32_16x16x32_bf16 v[52:55], v[152:155], v[196:199], v[52:55]
	v_mfma_f32_16x16x32_bf16 v[44:47], v[160:163], v[196:199], v[44:47]
	v_mfma_f32_16x16x32_bf16 v[36:39], v[152:155], v[204:207], v[36:39]
	v_mfma_f32_16x16x32_bf16 v[28:31], v[160:163], v[204:207], v[28:31]
	v_mfma_f32_16x16x32_bf16 v[20:23], v[152:155], v[212:215], v[20:23]
	v_mfma_f32_16x16x32_bf16 v[12:15], v[160:163], v[212:215], v[12:15]
	v_mfma_f32_16x16x32_bf16 v[60:63], v[156:159], v[192:195], v[60:63]
	v_mfma_f32_16x16x32_bf16 v[56:59], v[164:167], v[192:195], v[56:59]
	v_mfma_f32_16x16x32_bf16 v[52:55], v[156:159], v[200:203], v[52:55]
	v_mfma_f32_16x16x32_bf16 v[44:47], v[164:167], v[200:203], v[44:47]
	v_mfma_f32_16x16x32_bf16 v[36:39], v[156:159], v[208:211], v[36:39]
	v_mfma_f32_16x16x32_bf16 v[28:31], v[164:167], v[208:211], v[28:31]
	v_mfma_f32_16x16x32_bf16 v[20:23], v[156:159], v[216:219], v[20:23]
	v_mfma_f32_16x16x32_bf16 v[12:15], v[164:167], v[216:219], v[12:15]
	v_mfma_f32_16x16x32_bf16 v[48:51], v[168:171], v[184:187], v[48:51]
	v_mfma_f32_16x16x32_bf16 v[40:43], v[176:179], v[184:187], v[40:43]
	v_mfma_f32_16x16x32_bf16 v[32:35], v[168:171], v[196:199], v[32:35]
	v_mfma_f32_16x16x32_bf16 v[24:27], v[176:179], v[196:199], v[24:27]
	v_mfma_f32_16x16x32_bf16 v[16:19], v[168:171], v[204:207], v[16:19]
	v_mfma_f32_16x16x32_bf16 v[8:11], v[176:179], v[204:207], v[8:11]
	v_mfma_f32_16x16x32_bf16 v[4:7], v[168:171], v[212:215], v[4:7]
	v_mfma_f32_16x16x32_bf16 v[0:3], v[176:179], v[212:215], v[0:3]
	v_mfma_f32_16x16x32_bf16 v[48:51], v[172:175], v[192:195], v[48:51]
	v_mfma_f32_16x16x32_bf16 v[40:43], v[180:183], v[192:195], v[40:43]
	v_mfma_f32_16x16x32_bf16 v[32:35], v[172:175], v[200:203], v[32:35]
	v_mfma_f32_16x16x32_bf16 v[24:27], v[180:183], v[200:203], v[24:27]
	v_mfma_f32_16x16x32_bf16 v[16:19], v[172:175], v[208:211], v[16:19]
	v_mfma_f32_16x16x32_bf16 v[8:11], v[180:183], v[208:211], v[8:11]
	v_mfma_f32_16x16x32_bf16 v[4:7], v[172:175], v[216:219], v[4:7]
	v_mfma_f32_16x16x32_bf16 v[0:3], v[180:183], v[216:219], v[0:3]
	s_barrier
	s_add_i32 s75, s75, 2
	s_add_u32 s34, s34, 0x100
	s_addc_u32 s35, s35, 0
	s_add_u32 s73, s73, 0x100
	s_addc_u32 s74, s74, 0
	s_cmp_gt_u32 s75, 13
	s_cbranch_scc0 .LBB0_700
	s_branch .Lpeel_exit2
.LBB0_700:
	ds_read_b128 v[152:155], v149
	ds_read_b128 v[156:159], v149 offset:1024
	ds_read_b128 v[160:163], v149 offset:2048
	ds_read_b128 v[164:167], v149 offset:3072
	ds_read_b128 v[168:171], v150
	ds_read_b128 v[172:175], v150 offset:1024
	ds_read_b128 v[176:179], v150 offset:2048
	ds_read_b128 v[180:183], v150 offset:3072
	s_add_u32 s38, s34, 0xfffc0080
	s_addc_u32 s39, s35, -1
	s_cmp_eq_u32 s75, 12
	s_cselect_b32 s41, s25, s39
	s_cselect_b32 s40, s55, s38
	s_cselect_b32 s39, s23, s74
	s_cselect_b32 s38, s72, s73
	s_add_i32 m0, s31, 0xc000
	ds_read_b128 v[184:187], v151
	ds_read_b128 v[192:195], v151 offset:1024
	ds_read_b128 v[196:199], v151 offset:2048
	ds_read_b128 v[200:203], v151 offset:3072
	ds_read_b128 v[204:207], v151 offset:4096
	ds_read_b128 v[208:211], v151 offset:5120
	ds_read_b128 v[212:215], v151 offset:6144
	ds_read_b128 v[216:219], v151 offset:7168
	global_load_lds_dwordx4 v136, s[34:35]
	s_add_i32 m0, s31, 0xe000
	s_nop 0
	global_load_lds_dwordx4 v138, s[34:35]
	s_waitcnt vmcnt(8) lgkmcnt(0)
	s_barrier
	v_mfma_f32_16x16x32_bf16 v[124:127], v[152:155], v[184:187], v[124:127]
	v_mfma_f32_16x16x32_bf16 v[120:123], v[160:163], v[184:187], v[120:123]
	v_mfma_f32_16x16x32_bf16 v[116:119], v[152:155], v[196:199], v[116:119]
	v_mfma_f32_16x16x32_bf16 v[108:111], v[160:163], v[196:199], v[108:111]
	v_mfma_f32_16x16x32_bf16 v[100:103], v[152:155], v[204:207], v[100:103]
	v_mfma_f32_16x16x32_bf16 v[92:95], v[160:163], v[204:207], v[92:95]
	v_mfma_f32_16x16x32_bf16 v[84:87], v[152:155], v[212:215], v[84:87]
	v_mfma_f32_16x16x32_bf16 v[76:79], v[160:163], v[212:215], v[76:79]
	v_mfma_f32_16x16x32_bf16 v[124:127], v[156:159], v[192:195], v[124:127]
	v_mfma_f32_16x16x32_bf16 v[120:123], v[164:167], v[192:195], v[120:123]
	v_mfma_f32_16x16x32_bf16 v[116:119], v[156:159], v[200:203], v[116:119]
	v_mfma_f32_16x16x32_bf16 v[108:111], v[164:167], v[200:203], v[108:111]
	v_mfma_f32_16x16x32_bf16 v[100:103], v[156:159], v[208:211], v[100:103]
	v_mfma_f32_16x16x32_bf16 v[92:95], v[164:167], v[208:211], v[92:95]
	v_mfma_f32_16x16x32_bf16 v[84:87], v[156:159], v[216:219], v[84:87]
	v_mfma_f32_16x16x32_bf16 v[76:79], v[164:167], v[216:219], v[76:79]
	v_mfma_f32_16x16x32_bf16 v[112:115], v[168:171], v[184:187], v[112:115]
	v_mfma_f32_16x16x32_bf16 v[104:107], v[176:179], v[184:187], v[104:107]
	v_mfma_f32_16x16x32_bf16 v[96:99], v[168:171], v[196:199], v[96:99]
	v_mfma_f32_16x16x32_bf16 v[88:91], v[176:179], v[196:199], v[88:91]
	v_mfma_f32_16x16x32_bf16 v[80:83], v[168:171], v[204:207], v[80:83]
	v_mfma_f32_16x16x32_bf16 v[72:75], v[176:179], v[204:207], v[72:75]
	v_mfma_f32_16x16x32_bf16 v[68:71], v[168:171], v[212:215], v[68:71]
	v_mfma_f32_16x16x32_bf16 v[64:67], v[176:179], v[212:215], v[64:67]
	v_mfma_f32_16x16x32_bf16 v[112:115], v[172:175], v[192:195], v[112:115]
	v_mfma_f32_16x16x32_bf16 v[104:107], v[180:183], v[192:195], v[104:107]
	v_mfma_f32_16x16x32_bf16 v[96:99], v[172:175], v[200:203], v[96:99]
	v_mfma_f32_16x16x32_bf16 v[88:91], v[180:183], v[200:203], v[88:91]
	v_mfma_f32_16x16x32_bf16 v[80:83], v[172:175], v[208:211], v[80:83]
	v_mfma_f32_16x16x32_bf16 v[72:75], v[180:183], v[208:211], v[72:75]
	v_mfma_f32_16x16x32_bf16 v[68:71], v[172:175], v[216:219], v[68:71]
	v_mfma_f32_16x16x32_bf16 v[64:67], v[180:183], v[216:219], v[64:67]
	s_barrier
	s_add_i32 s76, s66, s53
	v_lshl_add_u64 v[144:145], s[38:39], 0, v[130:131]
	s_mov_b32 m0, s76
	ds_read_b128 v[184:187], v151 offset:16384
	ds_read_b128 v[192:195], v151 offset:17408
	ds_read_b128 v[196:199], v151 offset:18432
	ds_read_b128 v[200:203], v151 offset:19456
	ds_read_b128 v[204:207], v151 offset:20480
	ds_read_b128 v[208:211], v151 offset:21504
	ds_read_b128 v[212:215], v151 offset:22528
	ds_read_b128 v[216:219], v151 offset:23552
	global_load_lds_dwordx4 v[144:145], off
	s_add_i32 m0, s76, 0x2000
	s_add_u32 s76, s38, 0x40000
	v_lshl_add_u64 v[188:189], s[38:39], 0, v[134:135]
	s_addc_u32 s77, s39, 0
	s_add_i32 s79, s67, s53
	global_load_lds_dwordx4 v[188:189], off
	s_mov_b32 m0, s79
	v_lshl_add_u64 v[222:223], s[40:41], 0, v[132:133]
	global_load_lds_dwordx4 v130, s[76:77]
	s_add_i32 m0, s79, 0x2000
	s_nop 0
	global_load_lds_dwordx4 v134, s[76:77]
	v_lshl_add_u64 v[220:221], s[40:41], 0, v[128:129]
	s_mov_b32 m0, s31
	s_nop 0
	global_load_lds_dwordx4 v[220:221], off
	s_mov_b32 m0, s33
	s_nop 0
	global_load_lds_dwordx4 v[222:223], off
	s_waitcnt vmcnt(8) lgkmcnt(0)
	s_barrier
	v_mfma_f32_16x16x32_bf16 v[60:63], v[152:155], v[184:187], v[60:63]
	v_mfma_f32_16x16x32_bf16 v[56:59], v[160:163], v[184:187], v[56:59]
	v_mfma_f32_16x16x32_bf16 v[52:55], v[152:155], v[196:199], v[52:55]
	v_mfma_f32_16x16x32_bf16 v[44:47], v[160:163], v[196:199], v[44:47]
	v_mfma_f32_16x16x32_bf16 v[36:39], v[152:155], v[204:207], v[36:39]
	v_mfma_f32_16x16x32_bf16 v[28:31], v[160:163], v[204:207], v[28:31]
	v_mfma_f32_16x16x32_bf16 v[20:23], v[152:155], v[212:215], v[20:23]
	v_mfma_f32_16x16x32_bf16 v[12:15], v[160:163], v[212:215], v[12:15]
	v_mfma_f32_16x16x32_bf16 v[60:63], v[156:159], v[192:195], v[60:63]
	v_mfma_f32_16x16x32_bf16 v[56:59], v[164:167], v[192:195], v[56:59]
	v_mfma_f32_16x16x32_bf16 v[52:55], v[156:159], v[200:203], v[52:55]
	v_mfma_f32_16x16x32_bf16 v[44:47], v[164:167], v[200:203], v[44:47]
	v_mfma_f32_16x16x32_bf16 v[36:39], v[156:159], v[208:211], v[36:39]
	v_mfma_f32_16x16x32_bf16 v[28:31], v[164:167], v[208:211], v[28:31]
	v_mfma_f32_16x16x32_bf16 v[20:23], v[156:159], v[216:219], v[20:23]
	v_mfma_f32_16x16x32_bf16 v[12:15], v[164:167], v[216:219], v[12:15]
	v_mfma_f32_16x16x32_bf16 v[48:51], v[168:171], v[184:187], v[48:51]
	v_mfma_f32_16x16x32_bf16 v[40:43], v[176:179], v[184:187], v[40:43]
	v_mfma_f32_16x16x32_bf16 v[32:35], v[168:171], v[196:199], v[32:35]
	v_mfma_f32_16x16x32_bf16 v[24:27], v[176:179], v[196:199], v[24:27]
	v_mfma_f32_16x16x32_bf16 v[16:19], v[168:171], v[204:207], v[16:19]
	v_mfma_f32_16x16x32_bf16 v[8:11], v[176:179], v[204:207], v[8:11]
	v_mfma_f32_16x16x32_bf16 v[4:7], v[168:171], v[212:215], v[4:7]
	v_mfma_f32_16x16x32_bf16 v[0:3], v[176:179], v[212:215], v[0:3]
	v_mfma_f32_16x16x32_bf16 v[48:51], v[172:175], v[192:195], v[48:51]
	v_mfma_f32_16x16x32_bf16 v[40:43], v[180:183], v[192:195], v[40:43]
	v_mfma_f32_16x16x32_bf16 v[32:35], v[172:175], v[200:203], v[32:35]
	v_mfma_f32_16x16x32_bf16 v[24:27], v[180:183], v[200:203], v[24:27]
	v_mfma_f32_16x16x32_bf16 v[16:19], v[172:175], v[208:211], v[16:19]
	v_mfma_f32_16x16x32_bf16 v[8:11], v[180:183], v[208:211], v[8:11]
	v_mfma_f32_16x16x32_bf16 v[4:7], v[172:175], v[216:219], v[4:7]
	v_mfma_f32_16x16x32_bf16 v[0:3], v[180:183], v[216:219], v[0:3]
	s_barrier
	s_add_i32 s76, 0, 0x18000
	s_add_i32 s77, 0, 0x1c000
	v_add_u32_e32 v164, s76, v147
	v_add_u32_e32 v180, s77, v147
	ds_read_b128 v[152:155], v164
	ds_read_b128 v[156:159], v164 offset:1024
	ds_read_b128 v[160:163], v164 offset:2048
	ds_read_b128 v[164:167], v164 offset:3072
	ds_read_b128 v[168:171], v180
	ds_read_b128 v[172:175], v180 offset:1024
	ds_read_b128 v[176:179], v180 offset:2048
	ds_read_b128 v[180:183], v180 offset:3072
	s_add_u32 s40, s40, 0x40000
	s_addc_u32 s41, s41, 0
	s_mov_b32 m0, s60
	ds_read_b128 v[184:187], v151 offset:32768
	ds_read_b128 v[192:195], v151 offset:33792
	ds_read_b128 v[196:199], v151 offset:34816
	ds_read_b128 v[200:203], v151 offset:35840
	ds_read_b128 v[204:207], v151 offset:36864
	ds_read_b128 v[208:211], v151 offset:37888
	ds_read_b128 v[212:215], v151 offset:38912
	ds_read_b128 v[216:219], v151 offset:39936
	global_load_lds_dwordx4 v128, s[40:41]
	s_mov_b32 m0, s61
	s_nop 0
	global_load_lds_dwordx4 v132, s[40:41]
	s_waitcnt vmcnt(8) lgkmcnt(0)
	s_barrier
	v_mfma_f32_16x16x32_bf16 v[124:127], v[152:155], v[184:187], v[124:127]
	v_mfma_f32_16x16x32_bf16 v[120:123], v[160:163], v[184:187], v[120:123]
	v_mfma_f32_16x16x32_bf16 v[116:119], v[152:155], v[196:199], v[116:119]
	v_mfma_f32_16x16x32_bf16 v[108:111], v[160:163], v[196:199], v[108:111]
	v_mfma_f32_16x16x32_bf16 v[100:103], v[152:155], v[204:207], v[100:103]
	v_mfma_f32_16x16x32_bf16 v[92:95], v[160:163], v[204:207], v[92:95]
	v_mfma_f32_16x16x32_bf16 v[84:87], v[152:155], v[212:215], v[84:87]
	v_mfma_f32_16x16x32_bf16 v[76:79], v[160:163], v[212:215], v[76:79]
	v_mfma_f32_16x16x32_bf16 v[124:127], v[156:159], v[192:195], v[124:127]
	v_mfma_f32_16x16x32_bf16 v[120:123], v[164:167], v[192:195], v[120:123]
	v_mfma_f32_16x16x32_bf16 v[116:119], v[156:159], v[200:203], v[116:119]
	v_mfma_f32_16x16x32_bf16 v[108:111], v[164:167], v[200:203], v[108:111]
	v_mfma_f32_16x16x32_bf16 v[100:103], v[156:159], v[208:211], v[100:103]
	v_mfma_f32_16x16x32_bf16 v[92:95], v[164:167], v[208:211], v[92:95]
	v_mfma_f32_16x16x32_bf16 v[84:87], v[156:159], v[216:219], v[84:87]
	v_mfma_f32_16x16x32_bf16 v[76:79], v[164:167], v[216:219], v[76:79]
	v_mfma_f32_16x16x32_bf16 v[112:115], v[168:171], v[184:187], v[112:115]
	v_mfma_f32_16x16x32_bf16 v[104:107], v[176:179], v[184:187], v[104:107]
	v_mfma_f32_16x16x32_bf16 v[96:99], v[168:171], v[196:199], v[96:99]
	v_mfma_f32_16x16x32_bf16 v[88:91], v[176:179], v[196:199], v[88:91]
	v_mfma_f32_16x16x32_bf16 v[80:83], v[168:171], v[204:207], v[80:83]
	v_mfma_f32_16x16x32_bf16 v[72:75], v[176:179], v[204:207], v[72:75]
	v_mfma_f32_16x16x32_bf16 v[68:71], v[168:171], v[212:215], v[68:71]
	v_mfma_f32_16x16x32_bf16 v[64:67], v[176:179], v[212:215], v[64:67]
	v_mfma_f32_16x16x32_bf16 v[112:115], v[172:175], v[192:195], v[112:115]
	v_mfma_f32_16x16x32_bf16 v[104:107], v[180:183], v[192:195], v[104:107]
	v_mfma_f32_16x16x32_bf16 v[96:99], v[172:175], v[200:203], v[96:99]
	v_mfma_f32_16x16x32_bf16 v[88:91], v[180:183], v[200:203], v[88:91]
	v_mfma_f32_16x16x32_bf16 v[80:83], v[172:175], v[208:211], v[80:83]
	v_mfma_f32_16x16x32_bf16 v[72:75], v[180:183], v[208:211], v[72:75]
	v_mfma_f32_16x16x32_bf16 v[68:71], v[172:175], v[216:219], v[68:71]
	v_mfma_f32_16x16x32_bf16 v[64:67], v[180:183], v[216:219], v[64:67]
	s_barrier
	s_add_i32 s40, s76, s53
	v_lshl_add_u64 v[144:145], v[144:145], 0, s[12:13]
	s_mov_b32 m0, s40
	ds_read_b128 v[184:187], v151 offset:49152
	ds_read_b128 v[192:195], v151 offset:50176
	ds_read_b128 v[196:199], v151 offset:51200
	ds_read_b128 v[200:203], v151 offset:52224
	ds_read_b128 v[204:207], v151 offset:53248
	ds_read_b128 v[208:211], v151 offset:54272
	ds_read_b128 v[212:215], v151 offset:55296
	ds_read_b128 v[216:219], v151 offset:56320
	global_load_lds_dwordx4 v[144:145], off
	s_add_i32 m0, s40, 0x2000
	s_add_u32 s38, s38, 0x40080
	v_lshl_add_u64 v[144:145], v[188:189], 0, s[12:13]
	s_addc_u32 s39, s39, 0
	s_add_i32 s40, s77, s53
	global_load_lds_dwordx4 v[144:145], off
	s_mov_b32 m0, s40
	s_nop 0
	global_load_lds_dwordx4 v130, s[38:39]
	s_add_i32 m0, s40, 0x2000
	s_nop 0
	global_load_lds_dwordx4 v134, s[38:39]
	v_lshl_add_u64 v[144:145], v[220:221], 0, s[12:13]
	s_mov_b32 m0, s63
	s_nop 0
	global_load_lds_dwordx4 v[144:145], off
	v_lshl_add_u64 v[144:145], v[222:223], 0, s[12:13]
	s_mov_b32 m0, s64
	s_nop 0
	global_load_lds_dwordx4 v[144:145], off
	s_waitcnt vmcnt(8) lgkmcnt(0)
	s_barrier
	v_mfma_f32_16x16x32_bf16 v[60:63], v[152:155], v[184:187], v[60:63]
	v_mfma_f32_16x16x32_bf16 v[56:59], v[160:163], v[184:187], v[56:59]
	v_mfma_f32_16x16x32_bf16 v[52:55], v[152:155], v[196:199], v[52:55]
	v_mfma_f32_16x16x32_bf16 v[44:47], v[160:163], v[196:199], v[44:47]
	v_mfma_f32_16x16x32_bf16 v[36:39], v[152:155], v[204:207], v[36:39]
	v_mfma_f32_16x16x32_bf16 v[28:31], v[160:163], v[204:207], v[28:31]
	v_mfma_f32_16x16x32_bf16 v[20:23], v[152:155], v[212:215], v[20:23]
	v_mfma_f32_16x16x32_bf16 v[12:15], v[160:163], v[212:215], v[12:15]
	v_mfma_f32_16x16x32_bf16 v[60:63], v[156:159], v[192:195], v[60:63]
	v_mfma_f32_16x16x32_bf16 v[56:59], v[164:167], v[192:195], v[56:59]
	v_mfma_f32_16x16x32_bf16 v[52:55], v[156:159], v[200:203], v[52:55]
	v_mfma_f32_16x16x32_bf16 v[44:47], v[164:167], v[200:203], v[44:47]
	v_mfma_f32_16x16x32_bf16 v[36:39], v[156:159], v[208:211], v[36:39]
	v_mfma_f32_16x16x32_bf16 v[28:31], v[164:167], v[208:211], v[28:31]
	v_mfma_f32_16x16x32_bf16 v[20:23], v[156:159], v[216:219], v[20:23]
	v_mfma_f32_16x16x32_bf16 v[12:15], v[164:167], v[216:219], v[12:15]
	v_mfma_f32_16x16x32_bf16 v[48:51], v[168:171], v[184:187], v[48:51]
	v_mfma_f32_16x16x32_bf16 v[40:43], v[176:179], v[184:187], v[40:43]
	v_mfma_f32_16x16x32_bf16 v[32:35], v[168:171], v[196:199], v[32:35]
	v_mfma_f32_16x16x32_bf16 v[24:27], v[176:179], v[196:199], v[24:27]
	v_mfma_f32_16x16x32_bf16 v[16:19], v[168:171], v[204:207], v[16:19]
	v_mfma_f32_16x16x32_bf16 v[8:11], v[176:179], v[204:207], v[8:11]
	v_mfma_f32_16x16x32_bf16 v[4:7], v[168:171], v[212:215], v[4:7]
	v_mfma_f32_16x16x32_bf16 v[0:3], v[176:179], v[212:215], v[0:3]
	v_mfma_f32_16x16x32_bf16 v[48:51], v[172:175], v[192:195], v[48:51]
	v_mfma_f32_16x16x32_bf16 v[40:43], v[180:183], v[192:195], v[40:43]
	v_mfma_f32_16x16x32_bf16 v[32:35], v[172:175], v[200:203], v[32:35]
	v_mfma_f32_16x16x32_bf16 v[24:27], v[180:183], v[200:203], v[24:27]
	v_mfma_f32_16x16x32_bf16 v[16:19], v[172:175], v[208:211], v[16:19]
	v_mfma_f32_16x16x32_bf16 v[8:11], v[180:183], v[208:211], v[8:11]
	v_mfma_f32_16x16x32_bf16 v[4:7], v[172:175], v[216:219], v[4:7]
	v_mfma_f32_16x16x32_bf16 v[0:3], v[180:183], v[216:219], v[0:3]
	s_barrier
	s_add_i32 s75, s75, 2
	s_add_u32 s34, s34, 0x100
	s_addc_u32 s35, s35, 0
	s_add_u32 s73, s73, 0x100
	s_addc_u32 s74, s74, 0
	s_cmp_gt_u32 s75, 13
	s_cbranch_scc0 .LBB0_700

.LBB0_836:
	s_ashr_i32 s25, s24, 31
	s_lshl_b64 s[26:27], s[24:25], 19
	s_add_u32 s26, s58, s26
	s_addc_u32 s27, s59, s27
	s_and_b64 s[28:29], s[4:5], exec
	s_cselect_b32 s25, s27, s35
	s_cselect_b32 s54, s26, s34
	s_ashr_i32 s23, s22, 31
	s_lshl_b64 s[28:29], s[22:23], 19
	s_add_u32 s28, s61, s28
	s_addc_u32 s29, s62, s29
	s_and_b64 s[42:43], s[4:5], exec
	s_cselect_b32 s23, s29, s41
	s_cselect_b32 s55, s28, s40
	s_add_u32 s34, s34, 0x40080
	s_addc_u32 s35, s35, 0
	s_add_u32 s75, s40, 0x100
	s_addc_u32 s76, s41, 0
	s_mov_b32 s77, -2
	ds_read_b128 v[152:155], v149
	ds_read_b128 v[156:159], v149 offset:1024
	ds_read_b128 v[160:163], v149 offset:2048
	ds_read_b128 v[164:167], v149 offset:3072
	ds_read_b128 v[168:171], v150
	ds_read_b128 v[172:175], v150 offset:1024
	ds_read_b128 v[176:179], v150 offset:2048
	ds_read_b128 v[180:183], v150 offset:3072
	s_add_u32 s40, s34, 0xfffc0080
	s_addc_u32 s41, s35, -1
	s_cmp_eq_u32 s77, 12
	s_cselect_b32 s43, s25, s41
	s_cselect_b32 s42, s54, s40
	s_cselect_b32 s41, s23, s76
	s_cselect_b32 s40, s55, s75
	s_add_i32 m0, s31, 0xc000
	ds_read_b128 v[184:187], v151
	ds_read_b128 v[192:195], v151 offset:1024
	ds_read_b128 v[196:199], v151 offset:2048
	ds_read_b128 v[200:203], v151 offset:3072
	ds_read_b128 v[204:207], v151 offset:4096
	ds_read_b128 v[208:211], v151 offset:5120
	ds_read_b128 v[212:215], v151 offset:6144
	ds_read_b128 v[216:219], v151 offset:7168
	global_load_lds_dwordx4 v136, s[34:35]
	s_add_i32 m0, s31, 0xe000
	s_nop 0
	global_load_lds_dwordx4 v138, s[34:35]
	s_waitcnt vmcnt(8) lgkmcnt(0)
	s_barrier
	v_mfma_f32_16x16x32_bf16 v[124:127], v[152:155], v[184:187], 0
	v_mfma_f32_16x16x32_bf16 v[120:123], v[160:163], v[184:187], 0
	v_mfma_f32_16x16x32_bf16 v[108:111], v[152:155], v[196:199], 0
	v_mfma_f32_16x16x32_bf16 v[104:107], v[160:163], v[196:199], 0
	v_mfma_f32_16x16x32_bf16 v[92:95], v[152:155], v[204:207], 0
	v_mfma_f32_16x16x32_bf16 v[88:91], v[160:163], v[204:207], 0
	v_mfma_f32_16x16x32_bf16 v[76:79], v[152:155], v[212:215], 0
	v_mfma_f32_16x16x32_bf16 v[72:75], v[160:163], v[212:215], 0
	v_mfma_f32_16x16x32_bf16 v[124:127], v[156:159], v[192:195], v[124:127]
	v_mfma_f32_16x16x32_bf16 v[120:123], v[164:167], v[192:195], v[120:123]
	v_mfma_f32_16x16x32_bf16 v[108:111], v[156:159], v[200:203], v[108:111]
	v_mfma_f32_16x16x32_bf16 v[104:107], v[164:167], v[200:203], v[104:107]
	v_mfma_f32_16x16x32_bf16 v[92:95], v[156:159], v[208:211], v[92:95]
	v_mfma_f32_16x16x32_bf16 v[88:91], v[164:167], v[208:211], v[88:91]
	v_mfma_f32_16x16x32_bf16 v[76:79], v[156:159], v[216:219], v[76:79]
	v_mfma_f32_16x16x32_bf16 v[72:75], v[164:167], v[216:219], v[72:75]
	v_mfma_f32_16x16x32_bf16 v[116:119], v[168:171], v[184:187], 0
	v_mfma_f32_16x16x32_bf16 v[112:115], v[176:179], v[184:187], 0
	v_mfma_f32_16x16x32_bf16 v[100:103], v[168:171], v[196:199], 0
	v_mfma_f32_16x16x32_bf16 v[96:99], v[176:179], v[196:199], 0
	v_mfma_f32_16x16x32_bf16 v[84:87], v[168:171], v[204:207], 0
	v_mfma_f32_16x16x32_bf16 v[80:83], v[176:179], v[204:207], 0
	v_mfma_f32_16x16x32_bf16 v[68:71], v[168:171], v[212:215], 0
	v_mfma_f32_16x16x32_bf16 v[64:67], v[176:179], v[212:215], 0
	v_mfma_f32_16x16x32_bf16 v[116:119], v[172:175], v[192:195], v[116:119]
	v_mfma_f32_16x16x32_bf16 v[112:115], v[180:183], v[192:195], v[112:115]
	v_mfma_f32_16x16x32_bf16 v[100:103], v[172:175], v[200:203], v[100:103]
	v_mfma_f32_16x16x32_bf16 v[96:99], v[180:183], v[200:203], v[96:99]
	v_mfma_f32_16x16x32_bf16 v[84:87], v[172:175], v[208:211], v[84:87]
	v_mfma_f32_16x16x32_bf16 v[80:83], v[180:183], v[208:211], v[80:83]
	v_mfma_f32_16x16x32_bf16 v[68:71], v[172:175], v[216:219], v[68:71]
	v_mfma_f32_16x16x32_bf16 v[64:67], v[180:183], v[216:219], v[64:67]
	s_barrier
	s_add_i32 s79, s69, s63
	v_lshl_add_u64 v[144:145], s[40:41], 0, v[130:131]
	s_mov_b32 m0, s79
	ds_read_b128 v[184:187], v151 offset:16384
	ds_read_b128 v[192:195], v151 offset:17408
	ds_read_b128 v[196:199], v151 offset:18432
	ds_read_b128 v[200:203], v151 offset:19456
	ds_read_b128 v[204:207], v151 offset:20480
	ds_read_b128 v[208:211], v151 offset:21504
	ds_read_b128 v[212:215], v151 offset:22528
	ds_read_b128 v[216:219], v151 offset:23552
	global_load_lds_dwordx4 v[144:145], off
	s_add_i32 m0, s79, 0x2000
	s_add_u32 s80, s40, 0x40000
	v_lshl_add_u64 v[188:189], s[40:41], 0, v[134:135]
	s_addc_u32 s81, s41, 0
	s_add_i32 s79, s70, s63
	global_load_lds_dwordx4 v[188:189], off
	s_mov_b32 m0, s79
	v_lshl_add_u64 v[222:223], s[42:43], 0, v[132:133]
	global_load_lds_dwordx4 v130, s[80:81]
	s_add_i32 m0, s79, 0x2000
	s_nop 0
	global_load_lds_dwordx4 v134, s[80:81]
	v_lshl_add_u64 v[220:221], s[42:43], 0, v[128:129]
	s_mov_b32 m0, s31
	s_nop 0
	global_load_lds_dwordx4 v[220:221], off
	s_mov_b32 m0, s64
	s_nop 0
	global_load_lds_dwordx4 v[222:223], off
	s_waitcnt vmcnt(8) lgkmcnt(0)
	s_barrier
	v_mfma_f32_16x16x32_bf16 v[60:63], v[152:155], v[184:187], 0
	v_mfma_f32_16x16x32_bf16 v[56:59], v[160:163], v[184:187], 0
	v_mfma_f32_16x16x32_bf16 v[44:47], v[152:155], v[196:199], 0
	v_mfma_f32_16x16x32_bf16 v[40:43], v[160:163], v[196:199], 0
	v_mfma_f32_16x16x32_bf16 v[28:31], v[152:155], v[204:207], 0
	v_mfma_f32_16x16x32_bf16 v[24:27], v[160:163], v[204:207], 0
	v_mfma_f32_16x16x32_bf16 v[12:15], v[152:155], v[212:215], 0
	v_mfma_f32_16x16x32_bf16 v[8:11], v[160:163], v[212:215], 0
	v_mfma_f32_16x16x32_bf16 v[60:63], v[156:159], v[192:195], v[60:63]
	v_mfma_f32_16x16x32_bf16 v[56:59], v[164:167], v[192:195], v[56:59]
	v_mfma_f32_16x16x32_bf16 v[44:47], v[156:159], v[200:203], v[44:47]
	v_mfma_f32_16x16x32_bf16 v[40:43], v[164:167], v[200:203], v[40:43]
	v_mfma_f32_16x16x32_bf16 v[28:31], v[156:159], v[208:211], v[28:31]
	v_mfma_f32_16x16x32_bf16 v[24:27], v[164:167], v[208:211], v[24:27]
	v_mfma_f32_16x16x32_bf16 v[12:15], v[156:159], v[216:219], v[12:15]
	v_mfma_f32_16x16x32_bf16 v[8:11], v[164:167], v[216:219], v[8:11]
	v_mfma_f32_16x16x32_bf16 v[52:55], v[168:171], v[184:187], 0
	v_mfma_f32_16x16x32_bf16 v[48:51], v[176:179], v[184:187], 0
	v_mfma_f32_16x16x32_bf16 v[36:39], v[168:171], v[196:199], 0
	v_mfma_f32_16x16x32_bf16 v[32:35], v[176:179], v[196:199], 0
	v_mfma_f32_16x16x32_bf16 v[20:23], v[168:171], v[204:207], 0
	v_mfma_f32_16x16x32_bf16 v[16:19], v[176:179], v[204:207], 0
	v_mfma_f32_16x16x32_bf16 v[4:7], v[168:171], v[212:215], 0
	v_mfma_f32_16x16x32_bf16 v[0:3], v[176:179], v[212:215], 0
	v_mfma_f32_16x16x32_bf16 v[52:55], v[172:175], v[192:195], v[52:55]
	v_mfma_f32_16x16x32_bf16 v[48:51], v[180:183], v[192:195], v[48:51]
	v_mfma_f32_16x16x32_bf16 v[36:39], v[172:175], v[200:203], v[36:39]
	v_mfma_f32_16x16x32_bf16 v[32:35], v[180:183], v[200:203], v[32:35]
	v_mfma_f32_16x16x32_bf16 v[20:23], v[172:175], v[208:211], v[20:23]
	v_mfma_f32_16x16x32_bf16 v[16:19], v[180:183], v[208:211], v[16:19]
	v_mfma_f32_16x16x32_bf16 v[4:7], v[172:175], v[216:219], v[4:7]
	v_mfma_f32_16x16x32_bf16 v[0:3], v[180:183], v[216:219], v[0:3]
	s_barrier
	s_add_i32 s79, 0, 0x18000
	s_add_i32 s80, 0, 0x1c000
	v_add_u32_e32 v164, s79, v147
	v_add_u32_e32 v180, s80, v147
	ds_read_b128 v[152:155], v164
	ds_read_b128 v[156:159], v164 offset:1024
	ds_read_b128 v[160:163], v164 offset:2048
	ds_read_b128 v[164:167], v164 offset:3072
	ds_read_b128 v[168:171], v180
	ds_read_b128 v[172:175], v180 offset:1024
	ds_read_b128 v[176:179], v180 offset:2048
	ds_read_b128 v[180:183], v180 offset:3072
	s_add_u32 s42, s42, 0x40000
	s_addc_u32 s43, s43, 0
	s_mov_b32 m0, s65
	ds_read_b128 v[184:187], v151 offset:32768
	ds_read_b128 v[192:195], v151 offset:33792
	ds_read_b128 v[196:199], v151 offset:34816
	ds_read_b128 v[200:203], v151 offset:35840
	ds_read_b128 v[204:207], v151 offset:36864
	ds_read_b128 v[208:211], v151 offset:37888
	ds_read_b128 v[212:215], v151 offset:38912
	ds_read_b128 v[216:219], v151 offset:39936
	global_load_lds_dwordx4 v128, s[42:43]
	s_mov_b32 m0, s66
	s_nop 0
	global_load_lds_dwordx4 v132, s[42:43]
	s_waitcnt vmcnt(8) lgkmcnt(0)
	s_barrier
	v_mfma_f32_16x16x32_bf16 v[124:127], v[152:155], v[184:187], v[124:127]
	v_mfma_f32_16x16x32_bf16 v[120:123], v[160:163], v[184:187], v[120:123]
	v_mfma_f32_16x16x32_bf16 v[108:111], v[152:155], v[196:199], v[108:111]
	v_mfma_f32_16x16x32_bf16 v[104:107], v[160:163], v[196:199], v[104:107]
	v_mfma_f32_16x16x32_bf16 v[92:95], v[152:155], v[204:207], v[92:95]
	v_mfma_f32_16x16x32_bf16 v[88:91], v[160:163], v[204:207], v[88:91]
	v_mfma_f32_16x16x32_bf16 v[76:79], v[152:155], v[212:215], v[76:79]
	v_mfma_f32_16x16x32_bf16 v[72:75], v[160:163], v[212:215], v[72:75]
	v_mfma_f32_16x16x32_bf16 v[124:127], v[156:159], v[192:195], v[124:127]
	v_mfma_f32_16x16x32_bf16 v[120:123], v[164:167], v[192:195], v[120:123]
	v_mfma_f32_16x16x32_bf16 v[108:111], v[156:159], v[200:203], v[108:111]
	v_mfma_f32_16x16x32_bf16 v[104:107], v[164:167], v[200:203], v[104:107]
	v_mfma_f32_16x16x32_bf16 v[92:95], v[156:159], v[208:211], v[92:95]
	v_mfma_f32_16x16x32_bf16 v[88:91], v[164:167], v[208:211], v[88:91]
	v_mfma_f32_16x16x32_bf16 v[76:79], v[156:159], v[216:219], v[76:79]
	v_mfma_f32_16x16x32_bf16 v[72:75], v[164:167], v[216:219], v[72:75]
	v_mfma_f32_16x16x32_bf16 v[116:119], v[168:171], v[184:187], v[116:119]
	v_mfma_f32_16x16x32_bf16 v[112:115], v[176:179], v[184:187], v[112:115]
	v_mfma_f32_16x16x32_bf16 v[100:103], v[168:171], v[196:199], v[100:103]
	v_mfma_f32_16x16x32_bf16 v[96:99], v[176:179], v[196:199], v[96:99]
	v_mfma_f32_16x16x32_bf16 v[84:87], v[168:171], v[204:207], v[84:87]
	v_mfma_f32_16x16x32_bf16 v[80:83], v[176:179], v[204:207], v[80:83]
	v_mfma_f32_16x16x32_bf16 v[68:71], v[168:171], v[212:215], v[68:71]
	v_mfma_f32_16x16x32_bf16 v[64:67], v[176:179], v[212:215], v[64:67]
	v_mfma_f32_16x16x32_bf16 v[116:119], v[172:175], v[192:195], v[116:119]
	v_mfma_f32_16x16x32_bf16 v[112:115], v[180:183], v[192:195], v[112:115]
	v_mfma_f32_16x16x32_bf16 v[100:103], v[172:175], v[200:203], v[100:103]
	v_mfma_f32_16x16x32_bf16 v[96:99], v[180:183], v[200:203], v[96:99]
	v_mfma_f32_16x16x32_bf16 v[84:87], v[172:175], v[208:211], v[84:87]
	v_mfma_f32_16x16x32_bf16 v[80:83], v[180:183], v[208:211], v[80:83]
	v_mfma_f32_16x16x32_bf16 v[68:71], v[172:175], v[216:219], v[68:71]
	v_mfma_f32_16x16x32_bf16 v[64:67], v[180:183], v[216:219], v[64:67]
	s_barrier
	s_add_i32 s42, s79, s63
	v_lshl_add_u64 v[144:145], v[144:145], 0, s[10:11]
	s_mov_b32 m0, s42
	ds_read_b128 v[184:187], v151 offset:49152
	ds_read_b128 v[192:195], v151 offset:50176
	ds_read_b128 v[196:199], v151 offset:51200
	ds_read_b128 v[200:203], v151 offset:52224
	ds_read_b128 v[204:207], v151 offset:53248
	ds_read_b128 v[208:211], v151 offset:54272
	ds_read_b128 v[212:215], v151 offset:55296
	ds_read_b128 v[216:219], v151 offset:56320
	global_load_lds_dwordx4 v[144:145], off
	s_add_i32 m0, s42, 0x2000
	s_add_u32 s40, s40, 0x40080
	v_lshl_add_u64 v[144:145], v[188:189], 0, s[10:11]
	s_addc_u32 s41, s41, 0
	s_add_i32 s42, s80, s63
	global_load_lds_dwordx4 v[144:145], off
	s_mov_b32 m0, s42
	s_nop 0
	global_load_lds_dwordx4 v130, s[40:41]
	s_add_i32 m0, s42, 0x2000
	s_nop 0
	global_load_lds_dwordx4 v134, s[40:41]
	v_lshl_add_u64 v[144:145], v[220:221], 0, s[10:11]
	s_mov_b32 m0, s52
	s_nop 0
	global_load_lds_dwordx4 v[144:145], off
	v_lshl_add_u64 v[144:145], v[222:223], 0, s[10:11]
	s_mov_b32 m0, s53
	s_nop 0
	global_load_lds_dwordx4 v[144:145], off
	s_waitcnt vmcnt(8) lgkmcnt(0)
	s_barrier
	v_mfma_f32_16x16x32_bf16 v[60:63], v[152:155], v[184:187], v[60:63]
	v_mfma_f32_16x16x32_bf16 v[56:59], v[160:163], v[184:187], v[56:59]
	v_mfma_f32_16x16x32_bf16 v[44:47], v[152:155], v[196:199], v[44:47]
	v_mfma_f32_16x16x32_bf16 v[40:43], v[160:163], v[196:199], v[40:43]
	v_mfma_f32_16x16x32_bf16 v[28:31], v[152:155], v[204:207], v[28:31]
	v_mfma_f32_16x16x32_bf16 v[24:27], v[160:163], v[204:207], v[24:27]
	v_mfma_f32_16x16x32_bf16 v[12:15], v[152:155], v[212:215], v[12:15]
	v_mfma_f32_16x16x32_bf16 v[8:11], v[160:163], v[212:215], v[8:11]
	v_mfma_f32_16x16x32_bf16 v[60:63], v[156:159], v[192:195], v[60:63]
	v_mfma_f32_16x16x32_bf16 v[56:59], v[164:167], v[192:195], v[56:59]
	v_mfma_f32_16x16x32_bf16 v[44:47], v[156:159], v[200:203], v[44:47]
	v_mfma_f32_16x16x32_bf16 v[40:43], v[164:167], v[200:203], v[40:43]
	v_mfma_f32_16x16x32_bf16 v[28:31], v[156:159], v[208:211], v[28:31]
	v_mfma_f32_16x16x32_bf16 v[24:27], v[164:167], v[208:211], v[24:27]
	v_mfma_f32_16x16x32_bf16 v[12:15], v[156:159], v[216:219], v[12:15]
	v_mfma_f32_16x16x32_bf16 v[8:11], v[164:167], v[216:219], v[8:11]
	v_mfma_f32_16x16x32_bf16 v[52:55], v[168:171], v[184:187], v[52:55]
	v_mfma_f32_16x16x32_bf16 v[48:51], v[176:179], v[184:187], v[48:51]
	v_mfma_f32_16x16x32_bf16 v[36:39], v[168:171], v[196:199], v[36:39]
	v_mfma_f32_16x16x32_bf16 v[32:35], v[176:179], v[196:199], v[32:35]
	v_mfma_f32_16x16x32_bf16 v[20:23], v[168:171], v[204:207], v[20:23]
	v_mfma_f32_16x16x32_bf16 v[16:19], v[176:179], v[204:207], v[16:19]
	v_mfma_f32_16x16x32_bf16 v[4:7], v[168:171], v[212:215], v[4:7]
	v_mfma_f32_16x16x32_bf16 v[0:3], v[176:179], v[212:215], v[0:3]
	v_mfma_f32_16x16x32_bf16 v[52:55], v[172:175], v[192:195], v[52:55]
	v_mfma_f32_16x16x32_bf16 v[48:51], v[180:183], v[192:195], v[48:51]
	v_mfma_f32_16x16x32_bf16 v[36:39], v[172:175], v[200:203], v[36:39]
	v_mfma_f32_16x16x32_bf16 v[32:35], v[180:183], v[200:203], v[32:35]
	v_mfma_f32_16x16x32_bf16 v[20:23], v[172:175], v[208:211], v[20:23]
	v_mfma_f32_16x16x32_bf16 v[16:19], v[180:183], v[208:211], v[16:19]
	v_mfma_f32_16x16x32_bf16 v[4:7], v[172:175], v[216:219], v[4:7]
	v_mfma_f32_16x16x32_bf16 v[0:3], v[180:183], v[216:219], v[0:3]
	s_barrier
	s_add_i32 s77, s77, 2
	s_add_u32 s34, s34, 0x100
	s_addc_u32 s35, s35, 0
	s_add_u32 s75, s75, 0x100
	s_addc_u32 s76, s76, 0
	s_cmp_gt_u32 s77, 13
	s_cbranch_scc0 .LBB0_837
	s_branch .Lpeel_exit3
.LBB0_837:
	ds_read_b128 v[152:155], v149
	ds_read_b128 v[156:159], v149 offset:1024
	ds_read_b128 v[160:163], v149 offset:2048
	ds_read_b128 v[164:167], v149 offset:3072
	ds_read_b128 v[168:171], v150
	ds_read_b128 v[172:175], v150 offset:1024
	ds_read_b128 v[176:179], v150 offset:2048
	ds_read_b128 v[180:183], v150 offset:3072
	s_add_u32 s40, s34, 0xfffc0080
	s_addc_u32 s41, s35, -1
	s_cmp_eq_u32 s77, 12
	s_cselect_b32 s43, s25, s41
	s_cselect_b32 s42, s54, s40
	s_cselect_b32 s41, s23, s76
	s_cselect_b32 s40, s55, s75
	s_add_i32 m0, s31, 0xc000
	ds_read_b128 v[184:187], v151
	ds_read_b128 v[192:195], v151 offset:1024
	ds_read_b128 v[196:199], v151 offset:2048
	ds_read_b128 v[200:203], v151 offset:3072
	ds_read_b128 v[204:207], v151 offset:4096
	ds_read_b128 v[208:211], v151 offset:5120
	ds_read_b128 v[212:215], v151 offset:6144
	ds_read_b128 v[216:219], v151 offset:7168
	global_load_lds_dwordx4 v136, s[34:35]
	s_add_i32 m0, s31, 0xe000
	s_nop 0
	global_load_lds_dwordx4 v138, s[34:35]
	s_waitcnt vmcnt(8) lgkmcnt(0)
	s_barrier
	v_mfma_f32_16x16x32_bf16 v[124:127], v[152:155], v[184:187], v[124:127]
	v_mfma_f32_16x16x32_bf16 v[120:123], v[160:163], v[184:187], v[120:123]
	v_mfma_f32_16x16x32_bf16 v[108:111], v[152:155], v[196:199], v[108:111]
	v_mfma_f32_16x16x32_bf16 v[104:107], v[160:163], v[196:199], v[104:107]
	v_mfma_f32_16x16x32_bf16 v[92:95], v[152:155], v[204:207], v[92:95]
	v_mfma_f32_16x16x32_bf16 v[88:91], v[160:163], v[204:207], v[88:91]
	v_mfma_f32_16x16x32_bf16 v[76:79], v[152:155], v[212:215], v[76:79]
	v_mfma_f32_16x16x32_bf16 v[72:75], v[160:163], v[212:215], v[72:75]
	v_mfma_f32_16x16x32_bf16 v[124:127], v[156:159], v[192:195], v[124:127]
	v_mfma_f32_16x16x32_bf16 v[120:123], v[164:167], v[192:195], v[120:123]
	v_mfma_f32_16x16x32_bf16 v[108:111], v[156:159], v[200:203], v[108:111]
	v_mfma_f32_16x16x32_bf16 v[104:107], v[164:167], v[200:203], v[104:107]
	v_mfma_f32_16x16x32_bf16 v[92:95], v[156:159], v[208:211], v[92:95]
	v_mfma_f32_16x16x32_bf16 v[88:91], v[164:167], v[208:211], v[88:91]
	v_mfma_f32_16x16x32_bf16 v[76:79], v[156:159], v[216:219], v[76:79]
	v_mfma_f32_16x16x32_bf16 v[72:75], v[164:167], v[216:219], v[72:75]
	v_mfma_f32_16x16x32_bf16 v[116:119], v[168:171], v[184:187], v[116:119]
	v_mfma_f32_16x16x32_bf16 v[112:115], v[176:179], v[184:187], v[112:115]
	v_mfma_f32_16x16x32_bf16 v[100:103], v[168:171], v[196:199], v[100:103]
	v_mfma_f32_16x16x32_bf16 v[96:99], v[176:179], v[196:199], v[96:99]
	v_mfma_f32_16x16x32_bf16 v[84:87], v[168:171], v[204:207], v[84:87]
	v_mfma_f32_16x16x32_bf16 v[80:83], v[176:179], v[204:207], v[80:83]
	v_mfma_f32_16x16x32_bf16 v[68:71], v[168:171], v[212:215], v[68:71]
	v_mfma_f32_16x16x32_bf16 v[64:67], v[176:179], v[212:215], v[64:67]
	v_mfma_f32_16x16x32_bf16 v[116:119], v[172:175], v[192:195], v[116:119]
	v_mfma_f32_16x16x32_bf16 v[112:115], v[180:183], v[192:195], v[112:115]
	v_mfma_f32_16x16x32_bf16 v[100:103], v[172:175], v[200:203], v[100:103]
	v_mfma_f32_16x16x32_bf16 v[96:99], v[180:183], v[200:203], v[96:99]
	v_mfma_f32_16x16x32_bf16 v[84:87], v[172:175], v[208:211], v[84:87]
	v_mfma_f32_16x16x32_bf16 v[80:83], v[180:183], v[208:211], v[80:83]
	v_mfma_f32_16x16x32_bf16 v[68:71], v[172:175], v[216:219], v[68:71]
	v_mfma_f32_16x16x32_bf16 v[64:67], v[180:183], v[216:219], v[64:67]
	s_barrier
	s_add_i32 s79, s69, s63
	v_lshl_add_u64 v[144:145], s[40:41], 0, v[130:131]
	s_mov_b32 m0, s79
	ds_read_b128 v[184:187], v151 offset:16384
	ds_read_b128 v[192:195], v151 offset:17408
	ds_read_b128 v[196:199], v151 offset:18432
	ds_read_b128 v[200:203], v151 offset:19456
	ds_read_b128 v[204:207], v151 offset:20480
	ds_read_b128 v[208:211], v151 offset:21504
	ds_read_b128 v[212:215], v151 offset:22528
	ds_read_b128 v[216:219], v151 offset:23552
	global_load_lds_dwordx4 v[144:145], off
	s_add_i32 m0, s79, 0x2000
	s_add_u32 s80, s40, 0x40000
	v_lshl_add_u64 v[188:189], s[40:41], 0, v[134:135]
	s_addc_u32 s81, s41, 0
	s_add_i32 s79, s70, s63
	global_load_lds_dwordx4 v[188:189], off
	s_mov_b32 m0, s79
	v_lshl_add_u64 v[222:223], s[42:43], 0, v[132:133]
	global_load_lds_dwordx4 v130, s[80:81]
	s_add_i32 m0, s79, 0x2000
	s_nop 0
	global_load_lds_dwordx4 v134, s[80:81]
	v_lshl_add_u64 v[220:221], s[42:43], 0, v[128:129]
	s_mov_b32 m0, s31
	s_nop 0
	global_load_lds_dwordx4 v[220:221], off
	s_mov_b32 m0, s64
	s_nop 0
	global_load_lds_dwordx4 v[222:223], off
	s_waitcnt vmcnt(8) lgkmcnt(0)
	s_barrier
	v_mfma_f32_16x16x32_bf16 v[60:63], v[152:155], v[184:187], v[60:63]
	v_mfma_f32_16x16x32_bf16 v[56:59], v[160:163], v[184:187], v[56:59]
	v_mfma_f32_16x16x32_bf16 v[44:47], v[152:155], v[196:199], v[44:47]
	v_mfma_f32_16x16x32_bf16 v[40:43], v[160:163], v[196:199], v[40:43]
	v_mfma_f32_16x16x32_bf16 v[28:31], v[152:155], v[204:207], v[28:31]
	v_mfma_f32_16x16x32_bf16 v[24:27], v[160:163], v[204:207], v[24:27]
	v_mfma_f32_16x16x32_bf16 v[12:15], v[152:155], v[212:215], v[12:15]
	v_mfma_f32_16x16x32_bf16 v[8:11], v[160:163], v[212:215], v[8:11]
	v_mfma_f32_16x16x32_bf16 v[60:63], v[156:159], v[192:195], v[60:63]
	v_mfma_f32_16x16x32_bf16 v[56:59], v[164:167], v[192:195], v[56:59]
	v_mfma_f32_16x16x32_bf16 v[44:47], v[156:159], v[200:203], v[44:47]
	v_mfma_f32_16x16x32_bf16 v[40:43], v[164:167], v[200:203], v[40:43]
	v_mfma_f32_16x16x32_bf16 v[28:31], v[156:159], v[208:211], v[28:31]
	v_mfma_f32_16x16x32_bf16 v[24:27], v[164:167], v[208:211], v[24:27]
	v_mfma_f32_16x16x32_bf16 v[12:15], v[156:159], v[216:219], v[12:15]
	v_mfma_f32_16x16x32_bf16 v[8:11], v[164:167], v[216:219], v[8:11]
	v_mfma_f32_16x16x32_bf16 v[52:55], v[168:171], v[184:187], v[52:55]
	v_mfma_f32_16x16x32_bf16 v[48:51], v[176:179], v[184:187], v[48:51]
	v_mfma_f32_16x16x32_bf16 v[36:39], v[168:171], v[196:199], v[36:39]
	v_mfma_f32_16x16x32_bf16 v[32:35], v[176:179], v[196:199], v[32:35]
	v_mfma_f32_16x16x32_bf16 v[20:23], v[168:171], v[204:207], v[20:23]
	v_mfma_f32_16x16x32_bf16 v[16:19], v[176:179], v[204:207], v[16:19]
	v_mfma_f32_16x16x32_bf16 v[4:7], v[168:171], v[212:215], v[4:7]
	v_mfma_f32_16x16x32_bf16 v[0:3], v[176:179], v[212:215], v[0:3]
	v_mfma_f32_16x16x32_bf16 v[52:55], v[172:175], v[192:195], v[52:55]
	v_mfma_f32_16x16x32_bf16 v[48:51], v[180:183], v[192:195], v[48:51]
	v_mfma_f32_16x16x32_bf16 v[36:39], v[172:175], v[200:203], v[36:39]
	v_mfma_f32_16x16x32_bf16 v[32:35], v[180:183], v[200:203], v[32:35]
	v_mfma_f32_16x16x32_bf16 v[20:23], v[172:175], v[208:211], v[20:23]
	v_mfma_f32_16x16x32_bf16 v[16:19], v[180:183], v[208:211], v[16:19]
	v_mfma_f32_16x16x32_bf16 v[4:7], v[172:175], v[216:219], v[4:7]
	v_mfma_f32_16x16x32_bf16 v[0:3], v[180:183], v[216:219], v[0:3]
	s_barrier
	s_add_i32 s79, 0, 0x18000
	s_add_i32 s80, 0, 0x1c000
	v_add_u32_e32 v164, s79, v147
	v_add_u32_e32 v180, s80, v147
	ds_read_b128 v[152:155], v164
	ds_read_b128 v[156:159], v164 offset:1024
	ds_read_b128 v[160:163], v164 offset:2048
	ds_read_b128 v[164:167], v164 offset:3072
	ds_read_b128 v[168:171], v180
	ds_read_b128 v[172:175], v180 offset:1024
	ds_read_b128 v[176:179], v180 offset:2048
	ds_read_b128 v[180:183], v180 offset:3072
	s_add_u32 s42, s42, 0x40000
	s_addc_u32 s43, s43, 0
	s_mov_b32 m0, s65
	ds_read_b128 v[184:187], v151 offset:32768
	ds_read_b128 v[192:195], v151 offset:33792
	ds_read_b128 v[196:199], v151 offset:34816
	ds_read_b128 v[200:203], v151 offset:35840
	ds_read_b128 v[204:207], v151 offset:36864
	ds_read_b128 v[208:211], v151 offset:37888
	ds_read_b128 v[212:215], v151 offset:38912
	ds_read_b128 v[216:219], v151 offset:39936
	global_load_lds_dwordx4 v128, s[42:43]
	s_mov_b32 m0, s66
	s_nop 0
	global_load_lds_dwordx4 v132, s[42:43]
	s_waitcnt vmcnt(8) lgkmcnt(0)
	s_barrier
	v_mfma_f32_16x16x32_bf16 v[124:127], v[152:155], v[184:187], v[124:127]
	v_mfma_f32_16x16x32_bf16 v[120:123], v[160:163], v[184:187], v[120:123]
	v_mfma_f32_16x16x32_bf16 v[108:111], v[152:155], v[196:199], v[108:111]
	v_mfma_f32_16x16x32_bf16 v[104:107], v[160:163], v[196:199], v[104:107]
	v_mfma_f32_16x16x32_bf16 v[92:95], v[152:155], v[204:207], v[92:95]
	v_mfma_f32_16x16x32_bf16 v[88:91], v[160:163], v[204:207], v[88:91]
	v_mfma_f32_16x16x32_bf16 v[76:79], v[152:155], v[212:215], v[76:79]
	v_mfma_f32_16x16x32_bf16 v[72:75], v[160:163], v[212:215], v[72:75]
	v_mfma_f32_16x16x32_bf16 v[124:127], v[156:159], v[192:195], v[124:127]
	v_mfma_f32_16x16x32_bf16 v[120:123], v[164:167], v[192:195], v[120:123]
	v_mfma_f32_16x16x32_bf16 v[108:111], v[156:159], v[200:203], v[108:111]
	v_mfma_f32_16x16x32_bf16 v[104:107], v[164:167], v[200:203], v[104:107]
	v_mfma_f32_16x16x32_bf16 v[92:95], v[156:159], v[208:211], v[92:95]
	v_mfma_f32_16x16x32_bf16 v[88:91], v[164:167], v[208:211], v[88:91]
	v_mfma_f32_16x16x32_bf16 v[76:79], v[156:159], v[216:219], v[76:79]
	v_mfma_f32_16x16x32_bf16 v[72:75], v[164:167], v[216:219], v[72:75]
	v_mfma_f32_16x16x32_bf16 v[116:119], v[168:171], v[184:187], v[116:119]
	v_mfma_f32_16x16x32_bf16 v[112:115], v[176:179], v[184:187], v[112:115]
	v_mfma_f32_16x16x32_bf16 v[100:103], v[168:171], v[196:199], v[100:103]
	v_mfma_f32_16x16x32_bf16 v[96:99], v[176:179], v[196:199], v[96:99]
	v_mfma_f32_16x16x32_bf16 v[84:87], v[168:171], v[204:207], v[84:87]
	v_mfma_f32_16x16x32_bf16 v[80:83], v[176:179], v[204:207], v[80:83]
	v_mfma_f32_16x16x32_bf16 v[68:71], v[168:171], v[212:215], v[68:71]
	v_mfma_f32_16x16x32_bf16 v[64:67], v[176:179], v[212:215], v[64:67]
	v_mfma_f32_16x16x32_bf16 v[116:119], v[172:175], v[192:195], v[116:119]
	v_mfma_f32_16x16x32_bf16 v[112:115], v[180:183], v[192:195], v[112:115]
	v_mfma_f32_16x16x32_bf16 v[100:103], v[172:175], v[200:203], v[100:103]
	v_mfma_f32_16x16x32_bf16 v[96:99], v[180:183], v[200:203], v[96:99]
	v_mfma_f32_16x16x32_bf16 v[84:87], v[172:175], v[208:211], v[84:87]
	v_mfma_f32_16x16x32_bf16 v[80:83], v[180:183], v[208:211], v[80:83]
	v_mfma_f32_16x16x32_bf16 v[68:71], v[172:175], v[216:219], v[68:71]
	v_mfma_f32_16x16x32_bf16 v[64:67], v[180:183], v[216:219], v[64:67]
	s_barrier
	s_add_i32 s42, s79, s63
	v_lshl_add_u64 v[144:145], v[144:145], 0, s[10:11]
	s_mov_b32 m0, s42
	ds_read_b128 v[184:187], v151 offset:49152
	ds_read_b128 v[192:195], v151 offset:50176
	ds_read_b128 v[196:199], v151 offset:51200
	ds_read_b128 v[200:203], v151 offset:52224
	ds_read_b128 v[204:207], v151 offset:53248
	ds_read_b128 v[208:211], v151 offset:54272
	ds_read_b128 v[212:215], v151 offset:55296
	ds_read_b128 v[216:219], v151 offset:56320
	global_load_lds_dwordx4 v[144:145], off
	s_add_i32 m0, s42, 0x2000
	s_add_u32 s40, s40, 0x40080
	v_lshl_add_u64 v[144:145], v[188:189], 0, s[10:11]
	s_addc_u32 s41, s41, 0
	s_add_i32 s42, s80, s63
	global_load_lds_dwordx4 v[144:145], off
	s_mov_b32 m0, s42
	s_nop 0
	global_load_lds_dwordx4 v130, s[40:41]
	s_add_i32 m0, s42, 0x2000
	s_nop 0
	global_load_lds_dwordx4 v134, s[40:41]
	v_lshl_add_u64 v[144:145], v[220:221], 0, s[10:11]
	s_mov_b32 m0, s52
	s_nop 0
	global_load_lds_dwordx4 v[144:145], off
	v_lshl_add_u64 v[144:145], v[222:223], 0, s[10:11]
	s_mov_b32 m0, s53
	s_nop 0
	global_load_lds_dwordx4 v[144:145], off
	s_waitcnt vmcnt(8) lgkmcnt(0)
	s_barrier
	v_mfma_f32_16x16x32_bf16 v[60:63], v[152:155], v[184:187], v[60:63]
	v_mfma_f32_16x16x32_bf16 v[56:59], v[160:163], v[184:187], v[56:59]
	v_mfma_f32_16x16x32_bf16 v[44:47], v[152:155], v[196:199], v[44:47]
	v_mfma_f32_16x16x32_bf16 v[40:43], v[160:163], v[196:199], v[40:43]
	v_mfma_f32_16x16x32_bf16 v[28:31], v[152:155], v[204:207], v[28:31]
	v_mfma_f32_16x16x32_bf16 v[24:27], v[160:163], v[204:207], v[24:27]
	v_mfma_f32_16x16x32_bf16 v[12:15], v[152:155], v[212:215], v[12:15]
	v_mfma_f32_16x16x32_bf16 v[8:11], v[160:163], v[212:215], v[8:11]
	v_mfma_f32_16x16x32_bf16 v[60:63], v[156:159], v[192:195], v[60:63]
	v_mfma_f32_16x16x32_bf16 v[56:59], v[164:167], v[192:195], v[56:59]
	v_mfma_f32_16x16x32_bf16 v[44:47], v[156:159], v[200:203], v[44:47]
	v_mfma_f32_16x16x32_bf16 v[40:43], v[164:167], v[200:203], v[40:43]
	v_mfma_f32_16x16x32_bf16 v[28:31], v[156:159], v[208:211], v[28:31]
	v_mfma_f32_16x16x32_bf16 v[24:27], v[164:167], v[208:211], v[24:27]
	v_mfma_f32_16x16x32_bf16 v[12:15], v[156:159], v[216:219], v[12:15]
	v_mfma_f32_16x16x32_bf16 v[8:11], v[164:167], v[216:219], v[8:11]
	v_mfma_f32_16x16x32_bf16 v[52:55], v[168:171], v[184:187], v[52:55]
	v_mfma_f32_16x16x32_bf16 v[48:51], v[176:179], v[184:187], v[48:51]
	v_mfma_f32_16x16x32_bf16 v[36:39], v[168:171], v[196:199], v[36:39]
	v_mfma_f32_16x16x32_bf16 v[32:35], v[176:179], v[196:199], v[32:35]
	v_mfma_f32_16x16x32_bf16 v[20:23], v[168:171], v[204:207], v[20:23]
	v_mfma_f32_16x16x32_bf16 v[16:19], v[176:179], v[204:207], v[16:19]
	v_mfma_f32_16x16x32_bf16 v[4:7], v[168:171], v[212:215], v[4:7]
	v_mfma_f32_16x16x32_bf16 v[0:3], v[176:179], v[212:215], v[0:3]
	v_mfma_f32_16x16x32_bf16 v[52:55], v[172:175], v[192:195], v[52:55]
	v_mfma_f32_16x16x32_bf16 v[48:51], v[180:183], v[192:195], v[48:51]
	v_mfma_f32_16x16x32_bf16 v[36:39], v[172:175], v[200:203], v[36:39]
	v_mfma_f32_16x16x32_bf16 v[32:35], v[180:183], v[200:203], v[32:35]
	v_mfma_f32_16x16x32_bf16 v[20:23], v[172:175], v[208:211], v[20:23]
	v_mfma_f32_16x16x32_bf16 v[16:19], v[180:183], v[208:211], v[16:19]
	v_mfma_f32_16x16x32_bf16 v[4:7], v[172:175], v[216:219], v[4:7]
	v_mfma_f32_16x16x32_bf16 v[0:3], v[180:183], v[216:219], v[0:3]
	s_barrier
	s_add_i32 s77, s77, 2
	s_add_u32 s34, s34, 0x100
	s_addc_u32 s35, s35, 0
	s_add_u32 s75, s75, 0x100
	s_addc_u32 s76, s76, 0
	s_cmp_gt_u32 s77, 13
	s_cbranch_scc0 .LBB0_837

.LBB0_915:
	s_ashr_i32 s25, s24, 31
	s_lshl_b64 s[26:27], s[24:25], 21
	s_add_u32 s26, s56, s26
	s_addc_u32 s27, s57, s27
	s_and_b64 s[28:29], s[4:5], exec
	s_cselect_b32 s25, s27, s35
	s_cselect_b32 s55, s26, s34
	s_ashr_i32 s23, s22, 31
	s_lshl_b64 s[28:29], s[22:23], 21
	s_add_u32 s28, s53, s28
	s_addc_u32 s29, s60, s29
	s_and_b64 s[42:43], s[4:5], exec
	s_cselect_b32 s23, s29, s41
	s_cselect_b32 s74, s28, s40
	s_add_u32 s34, s34, 0x100080
	s_addc_u32 s35, s35, 0
	s_add_u32 s75, s40, 0x100
	s_addc_u32 s76, s41, 0
	s_mov_b32 s77, -2
	ds_read_b128 v[152:155], v149
	ds_read_b128 v[156:159], v149 offset:1024
	ds_read_b128 v[160:163], v149 offset:2048
	ds_read_b128 v[164:167], v149 offset:3072
	ds_read_b128 v[168:171], v150
	ds_read_b128 v[172:175], v150 offset:1024
	ds_read_b128 v[176:179], v150 offset:2048
	ds_read_b128 v[180:183], v150 offset:3072
	s_add_u32 s40, s34, 0xfff00080
	s_addc_u32 s41, s35, -1
	s_cmp_eq_u32 s77, 60
	s_cselect_b32 s43, s25, s41
	s_cselect_b32 s42, s55, s40
	s_cselect_b32 s41, s23, s76
	s_cselect_b32 s40, s74, s75
	s_add_i32 m0, s31, 0xc000
	ds_read_b128 v[184:187], v151
	ds_read_b128 v[192:195], v151 offset:1024
	ds_read_b128 v[196:199], v151 offset:2048
	ds_read_b128 v[200:203], v151 offset:3072
	ds_read_b128 v[204:207], v151 offset:4096
	ds_read_b128 v[208:211], v151 offset:5120
	ds_read_b128 v[212:215], v151 offset:6144
	ds_read_b128 v[216:219], v151 offset:7168
	global_load_lds_dwordx4 v136, s[34:35]
	s_add_i32 m0, s31, 0xe000
	s_nop 0
	global_load_lds_dwordx4 v138, s[34:35]
	s_waitcnt vmcnt(8) lgkmcnt(0)
	s_barrier
	v_mfma_f32_16x16x32_bf16 v[124:127], v[152:155], v[184:187], 0
	v_mfma_f32_16x16x32_bf16 v[120:123], v[160:163], v[184:187], 0
	v_mfma_f32_16x16x32_bf16 v[116:119], v[152:155], v[196:199], 0
	v_mfma_f32_16x16x32_bf16 v[108:111], v[160:163], v[196:199], 0
	v_mfma_f32_16x16x32_bf16 v[100:103], v[152:155], v[204:207], 0
	v_mfma_f32_16x16x32_bf16 v[92:95], v[160:163], v[204:207], 0
	v_mfma_f32_16x16x32_bf16 v[84:87], v[152:155], v[212:215], 0
	v_mfma_f32_16x16x32_bf16 v[76:79], v[160:163], v[212:215], 0
	v_mfma_f32_16x16x32_bf16 v[124:127], v[156:159], v[192:195], v[124:127]
	v_mfma_f32_16x16x32_bf16 v[120:123], v[164:167], v[192:195], v[120:123]
	v_mfma_f32_16x16x32_bf16 v[116:119], v[156:159], v[200:203], v[116:119]
	v_mfma_f32_16x16x32_bf16 v[108:111], v[164:167], v[200:203], v[108:111]
	v_mfma_f32_16x16x32_bf16 v[100:103], v[156:159], v[208:211], v[100:103]
	v_mfma_f32_16x16x32_bf16 v[92:95], v[164:167], v[208:211], v[92:95]
	v_mfma_f32_16x16x32_bf16 v[84:87], v[156:159], v[216:219], v[84:87]
	v_mfma_f32_16x16x32_bf16 v[76:79], v[164:167], v[216:219], v[76:79]
	v_mfma_f32_16x16x32_bf16 v[112:115], v[168:171], v[184:187], 0
	v_mfma_f32_16x16x32_bf16 v[104:107], v[176:179], v[184:187], 0
	v_mfma_f32_16x16x32_bf16 v[96:99], v[168:171], v[196:199], 0
	v_mfma_f32_16x16x32_bf16 v[88:91], v[176:179], v[196:199], 0
	v_mfma_f32_16x16x32_bf16 v[80:83], v[168:171], v[204:207], 0
	v_mfma_f32_16x16x32_bf16 v[72:75], v[176:179], v[204:207], 0
	v_mfma_f32_16x16x32_bf16 v[68:71], v[168:171], v[212:215], 0
	v_mfma_f32_16x16x32_bf16 v[64:67], v[176:179], v[212:215], 0
	v_mfma_f32_16x16x32_bf16 v[112:115], v[172:175], v[192:195], v[112:115]
	v_mfma_f32_16x16x32_bf16 v[104:107], v[180:183], v[192:195], v[104:107]
	v_mfma_f32_16x16x32_bf16 v[96:99], v[172:175], v[200:203], v[96:99]
	v_mfma_f32_16x16x32_bf16 v[88:91], v[180:183], v[200:203], v[88:91]
	v_mfma_f32_16x16x32_bf16 v[80:83], v[172:175], v[208:211], v[80:83]
	v_mfma_f32_16x16x32_bf16 v[72:75], v[180:183], v[208:211], v[72:75]
	v_mfma_f32_16x16x32_bf16 v[68:71], v[172:175], v[216:219], v[68:71]
	v_mfma_f32_16x16x32_bf16 v[64:67], v[180:183], v[216:219], v[64:67]
	s_barrier
	s_add_i32 s79, s68, s61
	v_lshl_add_u64 v[144:145], s[40:41], 0, v[130:131]
	s_mov_b32 m0, s79
	ds_read_b128 v[184:187], v151 offset:16384
	ds_read_b128 v[192:195], v151 offset:17408
	ds_read_b128 v[196:199], v151 offset:18432
	ds_read_b128 v[200:203], v151 offset:19456
	ds_read_b128 v[204:207], v151 offset:20480
	ds_read_b128 v[208:211], v151 offset:21504
	ds_read_b128 v[212:215], v151 offset:22528
	ds_read_b128 v[216:219], v151 offset:23552
	global_load_lds_dwordx4 v[144:145], off
	s_add_i32 m0, s79, 0x2000
	s_add_u32 s80, s40, 0x100000
	v_lshl_add_u64 v[188:189], s[40:41], 0, v[134:135]
	s_addc_u32 s81, s41, 0
	s_add_i32 s79, s69, s61
	global_load_lds_dwordx4 v[188:189], off
	s_mov_b32 m0, s79
	v_lshl_add_u64 v[222:223], s[42:43], 0, v[132:133]
	global_load_lds_dwordx4 v130, s[80:81]
	s_add_i32 m0, s79, 0x2000
	s_nop 0
	global_load_lds_dwordx4 v134, s[80:81]
	v_lshl_add_u64 v[220:221], s[42:43], 0, v[128:129]
	s_mov_b32 m0, s31
	s_nop 0
	global_load_lds_dwordx4 v[220:221], off
	s_mov_b32 m0, s33
	s_nop 0
	global_load_lds_dwordx4 v[222:223], off
	s_waitcnt vmcnt(8) lgkmcnt(0)
	s_barrier
	v_mfma_f32_16x16x32_bf16 v[60:63], v[152:155], v[184:187], 0
	v_mfma_f32_16x16x32_bf16 v[56:59], v[160:163], v[184:187], 0
	v_mfma_f32_16x16x32_bf16 v[52:55], v[152:155], v[196:199], 0
	v_mfma_f32_16x16x32_bf16 v[44:47], v[160:163], v[196:199], 0
	v_mfma_f32_16x16x32_bf16 v[36:39], v[152:155], v[204:207], 0
	v_mfma_f32_16x16x32_bf16 v[28:31], v[160:163], v[204:207], 0
	v_mfma_f32_16x16x32_bf16 v[20:23], v[152:155], v[212:215], 0
	v_mfma_f32_16x16x32_bf16 v[12:15], v[160:163], v[212:215], 0
	v_mfma_f32_16x16x32_bf16 v[60:63], v[156:159], v[192:195], v[60:63]
	v_mfma_f32_16x16x32_bf16 v[56:59], v[164:167], v[192:195], v[56:59]
	v_mfma_f32_16x16x32_bf16 v[52:55], v[156:159], v[200:203], v[52:55]
	v_mfma_f32_16x16x32_bf16 v[44:47], v[164:167], v[200:203], v[44:47]
	v_mfma_f32_16x16x32_bf16 v[36:39], v[156:159], v[208:211], v[36:39]
	v_mfma_f32_16x16x32_bf16 v[28:31], v[164:167], v[208:211], v[28:31]
	v_mfma_f32_16x16x32_bf16 v[20:23], v[156:159], v[216:219], v[20:23]
	v_mfma_f32_16x16x32_bf16 v[12:15], v[164:167], v[216:219], v[12:15]
	v_mfma_f32_16x16x32_bf16 v[48:51], v[168:171], v[184:187], 0
	v_mfma_f32_16x16x32_bf16 v[40:43], v[176:179], v[184:187], 0
	v_mfma_f32_16x16x32_bf16 v[32:35], v[168:171], v[196:199], 0
	v_mfma_f32_16x16x32_bf16 v[24:27], v[176:179], v[196:199], 0
	v_mfma_f32_16x16x32_bf16 v[16:19], v[168:171], v[204:207], 0
	v_mfma_f32_16x16x32_bf16 v[8:11], v[176:179], v[204:207], 0
	v_mfma_f32_16x16x32_bf16 v[4:7], v[168:171], v[212:215], 0
	v_mfma_f32_16x16x32_bf16 v[0:3], v[176:179], v[212:215], 0
	v_mfma_f32_16x16x32_bf16 v[48:51], v[172:175], v[192:195], v[48:51]
	v_mfma_f32_16x16x32_bf16 v[40:43], v[180:183], v[192:195], v[40:43]
	v_mfma_f32_16x16x32_bf16 v[32:35], v[172:175], v[200:203], v[32:35]
	v_mfma_f32_16x16x32_bf16 v[24:27], v[180:183], v[200:203], v[24:27]
	v_mfma_f32_16x16x32_bf16 v[16:19], v[172:175], v[208:211], v[16:19]
	v_mfma_f32_16x16x32_bf16 v[8:11], v[180:183], v[208:211], v[8:11]
	v_mfma_f32_16x16x32_bf16 v[4:7], v[172:175], v[216:219], v[4:7]
	v_mfma_f32_16x16x32_bf16 v[0:3], v[180:183], v[216:219], v[0:3]
	s_barrier
	s_add_i32 s79, 0, 0x18000
	s_add_i32 s80, 0, 0x1c000
	v_add_u32_e32 v164, s79, v147
	v_add_u32_e32 v180, s80, v147
	ds_read_b128 v[152:155], v164
	ds_read_b128 v[156:159], v164 offset:1024
	ds_read_b128 v[160:163], v164 offset:2048
	ds_read_b128 v[164:167], v164 offset:3072
	ds_read_b128 v[168:171], v180
	ds_read_b128 v[172:175], v180 offset:1024
	ds_read_b128 v[176:179], v180 offset:2048
	ds_read_b128 v[180:183], v180 offset:3072
	s_add_u32 s42, s42, 0x100000
	s_addc_u32 s43, s43, 0
	s_mov_b32 m0, s62
	ds_read_b128 v[184:187], v151 offset:32768
	ds_read_b128 v[192:195], v151 offset:33792
	ds_read_b128 v[196:199], v151 offset:34816
	ds_read_b128 v[200:203], v151 offset:35840
	ds_read_b128 v[204:207], v151 offset:36864
	ds_read_b128 v[208:211], v151 offset:37888
	ds_read_b128 v[212:215], v151 offset:38912
	ds_read_b128 v[216:219], v151 offset:39936
	global_load_lds_dwordx4 v128, s[42:43]
	s_mov_b32 m0, s63
	s_nop 0
	global_load_lds_dwordx4 v132, s[42:43]
	s_waitcnt vmcnt(8) lgkmcnt(0)
	s_barrier
	v_mfma_f32_16x16x32_bf16 v[124:127], v[152:155], v[184:187], v[124:127]
	v_mfma_f32_16x16x32_bf16 v[120:123], v[160:163], v[184:187], v[120:123]
	v_mfma_f32_16x16x32_bf16 v[116:119], v[152:155], v[196:199], v[116:119]
	v_mfma_f32_16x16x32_bf16 v[108:111], v[160:163], v[196:199], v[108:111]
	v_mfma_f32_16x16x32_bf16 v[100:103], v[152:155], v[204:207], v[100:103]
	v_mfma_f32_16x16x32_bf16 v[92:95], v[160:163], v[204:207], v[92:95]
	v_mfma_f32_16x16x32_bf16 v[84:87], v[152:155], v[212:215], v[84:87]
	v_mfma_f32_16x16x32_bf16 v[76:79], v[160:163], v[212:215], v[76:79]
	v_mfma_f32_16x16x32_bf16 v[124:127], v[156:159], v[192:195], v[124:127]
	v_mfma_f32_16x16x32_bf16 v[120:123], v[164:167], v[192:195], v[120:123]
	v_mfma_f32_16x16x32_bf16 v[116:119], v[156:159], v[200:203], v[116:119]
	v_mfma_f32_16x16x32_bf16 v[108:111], v[164:167], v[200:203], v[108:111]
	v_mfma_f32_16x16x32_bf16 v[100:103], v[156:159], v[208:211], v[100:103]
	v_mfma_f32_16x16x32_bf16 v[92:95], v[164:167], v[208:211], v[92:95]
	v_mfma_f32_16x16x32_bf16 v[84:87], v[156:159], v[216:219], v[84:87]
	v_mfma_f32_16x16x32_bf16 v[76:79], v[164:167], v[216:219], v[76:79]
	v_mfma_f32_16x16x32_bf16 v[112:115], v[168:171], v[184:187], v[112:115]
	v_mfma_f32_16x16x32_bf16 v[104:107], v[176:179], v[184:187], v[104:107]
	v_mfma_f32_16x16x32_bf16 v[96:99], v[168:171], v[196:199], v[96:99]
	v_mfma_f32_16x16x32_bf16 v[88:91], v[176:179], v[196:199], v[88:91]
	v_mfma_f32_16x16x32_bf16 v[80:83], v[168:171], v[204:207], v[80:83]
	v_mfma_f32_16x16x32_bf16 v[72:75], v[176:179], v[204:207], v[72:75]
	v_mfma_f32_16x16x32_bf16 v[68:71], v[168:171], v[212:215], v[68:71]
	v_mfma_f32_16x16x32_bf16 v[64:67], v[176:179], v[212:215], v[64:67]
	v_mfma_f32_16x16x32_bf16 v[112:115], v[172:175], v[192:195], v[112:115]
	v_mfma_f32_16x16x32_bf16 v[104:107], v[180:183], v[192:195], v[104:107]
	v_mfma_f32_16x16x32_bf16 v[96:99], v[172:175], v[200:203], v[96:99]
	v_mfma_f32_16x16x32_bf16 v[88:91], v[180:183], v[200:203], v[88:91]
	v_mfma_f32_16x16x32_bf16 v[80:83], v[172:175], v[208:211], v[80:83]
	v_mfma_f32_16x16x32_bf16 v[72:75], v[180:183], v[208:211], v[72:75]
	v_mfma_f32_16x16x32_bf16 v[68:71], v[172:175], v[216:219], v[68:71]
	v_mfma_f32_16x16x32_bf16 v[64:67], v[180:183], v[216:219], v[64:67]
	s_barrier
	s_add_i32 s42, s79, s61
	v_lshl_add_u64 v[144:145], v[144:145], 0, s[10:11]
	s_mov_b32 m0, s42
	ds_read_b128 v[184:187], v151 offset:49152
	ds_read_b128 v[192:195], v151 offset:50176
	ds_read_b128 v[196:199], v151 offset:51200
	ds_read_b128 v[200:203], v151 offset:52224
	ds_read_b128 v[204:207], v151 offset:53248
	ds_read_b128 v[208:211], v151 offset:54272
	ds_read_b128 v[212:215], v151 offset:55296
	ds_read_b128 v[216:219], v151 offset:56320
	global_load_lds_dwordx4 v[144:145], off
	s_add_i32 m0, s42, 0x2000
	s_add_u32 s40, s40, 0x100080
	v_lshl_add_u64 v[144:145], v[188:189], 0, s[10:11]
	s_addc_u32 s41, s41, 0
	s_add_i32 s42, s80, s61
	global_load_lds_dwordx4 v[144:145], off
	s_mov_b32 m0, s42
	s_nop 0
	global_load_lds_dwordx4 v130, s[40:41]
	s_add_i32 m0, s42, 0x2000
	s_nop 0
	global_load_lds_dwordx4 v134, s[40:41]
	v_lshl_add_u64 v[144:145], v[220:221], 0, s[10:11]
	s_mov_b32 m0, s65
	s_nop 0
	global_load_lds_dwordx4 v[144:145], off
	v_lshl_add_u64 v[144:145], v[222:223], 0, s[10:11]
	s_mov_b32 m0, s66
	s_nop 0
	global_load_lds_dwordx4 v[144:145], off
	s_waitcnt vmcnt(8) lgkmcnt(0)
	s_barrier
	v_mfma_f32_16x16x32_bf16 v[60:63], v[152:155], v[184:187], v[60:63]
	v_mfma_f32_16x16x32_bf16 v[56:59], v[160:163], v[184:187], v[56:59]
	v_mfma_f32_16x16x32_bf16 v[52:55], v[152:155], v[196:199], v[52:55]
	v_mfma_f32_16x16x32_bf16 v[44:47], v[160:163], v[196:199], v[44:47]
	v_mfma_f32_16x16x32_bf16 v[36:39], v[152:155], v[204:207], v[36:39]
	v_mfma_f32_16x16x32_bf16 v[28:31], v[160:163], v[204:207], v[28:31]
	v_mfma_f32_16x16x32_bf16 v[20:23], v[152:155], v[212:215], v[20:23]
	v_mfma_f32_16x16x32_bf16 v[12:15], v[160:163], v[212:215], v[12:15]
	v_mfma_f32_16x16x32_bf16 v[60:63], v[156:159], v[192:195], v[60:63]
	v_mfma_f32_16x16x32_bf16 v[56:59], v[164:167], v[192:195], v[56:59]
	v_mfma_f32_16x16x32_bf16 v[52:55], v[156:159], v[200:203], v[52:55]
	v_mfma_f32_16x16x32_bf16 v[44:47], v[164:167], v[200:203], v[44:47]
	v_mfma_f32_16x16x32_bf16 v[36:39], v[156:159], v[208:211], v[36:39]
	v_mfma_f32_16x16x32_bf16 v[28:31], v[164:167], v[208:211], v[28:31]
	v_mfma_f32_16x16x32_bf16 v[20:23], v[156:159], v[216:219], v[20:23]
	v_mfma_f32_16x16x32_bf16 v[12:15], v[164:167], v[216:219], v[12:15]
	v_mfma_f32_16x16x32_bf16 v[48:51], v[168:171], v[184:187], v[48:51]
	v_mfma_f32_16x16x32_bf16 v[40:43], v[176:179], v[184:187], v[40:43]
	v_mfma_f32_16x16x32_bf16 v[32:35], v[168:171], v[196:199], v[32:35]
	v_mfma_f32_16x16x32_bf16 v[24:27], v[176:179], v[196:199], v[24:27]
	v_mfma_f32_16x16x32_bf16 v[16:19], v[168:171], v[204:207], v[16:19]
	v_mfma_f32_16x16x32_bf16 v[8:11], v[176:179], v[204:207], v[8:11]
	v_mfma_f32_16x16x32_bf16 v[4:7], v[168:171], v[212:215], v[4:7]
	v_mfma_f32_16x16x32_bf16 v[0:3], v[176:179], v[212:215], v[0:3]
	v_mfma_f32_16x16x32_bf16 v[48:51], v[172:175], v[192:195], v[48:51]
	v_mfma_f32_16x16x32_bf16 v[40:43], v[180:183], v[192:195], v[40:43]
	v_mfma_f32_16x16x32_bf16 v[32:35], v[172:175], v[200:203], v[32:35]
	v_mfma_f32_16x16x32_bf16 v[24:27], v[180:183], v[200:203], v[24:27]
	v_mfma_f32_16x16x32_bf16 v[16:19], v[172:175], v[208:211], v[16:19]
	v_mfma_f32_16x16x32_bf16 v[8:11], v[180:183], v[208:211], v[8:11]
	v_mfma_f32_16x16x32_bf16 v[4:7], v[172:175], v[216:219], v[4:7]
	v_mfma_f32_16x16x32_bf16 v[0:3], v[180:183], v[216:219], v[0:3]
	s_barrier
	s_add_i32 s77, s77, 2
	s_add_u32 s34, s34, 0x100
	s_addc_u32 s35, s35, 0
	s_add_u32 s75, s75, 0x100
	s_addc_u32 s76, s76, 0
	s_cmp_gt_u32 s77, 61
	s_cbranch_scc0 .LBB0_916
	s_branch .Lpeel_exit4
.LBB0_916:
	ds_read_b128 v[152:155], v149
	ds_read_b128 v[156:159], v149 offset:1024
	ds_read_b128 v[160:163], v149 offset:2048
	ds_read_b128 v[164:167], v149 offset:3072
	ds_read_b128 v[168:171], v150
	ds_read_b128 v[172:175], v150 offset:1024
	ds_read_b128 v[176:179], v150 offset:2048
	ds_read_b128 v[180:183], v150 offset:3072
	s_add_u32 s40, s34, 0xfff00080
	s_addc_u32 s41, s35, -1
	s_cmp_eq_u32 s77, 60
	s_cselect_b32 s43, s25, s41
	s_cselect_b32 s42, s55, s40
	s_cselect_b32 s41, s23, s76
	s_cselect_b32 s40, s74, s75
	s_add_i32 m0, s31, 0xc000
	ds_read_b128 v[184:187], v151
	ds_read_b128 v[192:195], v151 offset:1024
	ds_read_b128 v[196:199], v151 offset:2048
	ds_read_b128 v[200:203], v151 offset:3072
	ds_read_b128 v[204:207], v151 offset:4096
	ds_read_b128 v[208:211], v151 offset:5120
	ds_read_b128 v[212:215], v151 offset:6144
	ds_read_b128 v[216:219], v151 offset:7168
	global_load_lds_dwordx4 v136, s[34:35]
	s_add_i32 m0, s31, 0xe000
	s_nop 0
	global_load_lds_dwordx4 v138, s[34:35]
	s_waitcnt vmcnt(8) lgkmcnt(0)
	s_barrier
	v_mfma_f32_16x16x32_bf16 v[124:127], v[152:155], v[184:187], v[124:127]
	v_mfma_f32_16x16x32_bf16 v[120:123], v[160:163], v[184:187], v[120:123]
	v_mfma_f32_16x16x32_bf16 v[116:119], v[152:155], v[196:199], v[116:119]
	v_mfma_f32_16x16x32_bf16 v[108:111], v[160:163], v[196:199], v[108:111]
	v_mfma_f32_16x16x32_bf16 v[100:103], v[152:155], v[204:207], v[100:103]
	v_mfma_f32_16x16x32_bf16 v[92:95], v[160:163], v[204:207], v[92:95]
	v_mfma_f32_16x16x32_bf16 v[84:87], v[152:155], v[212:215], v[84:87]
	v_mfma_f32_16x16x32_bf16 v[76:79], v[160:163], v[212:215], v[76:79]
	v_mfma_f32_16x16x32_bf16 v[124:127], v[156:159], v[192:195], v[124:127]
	v_mfma_f32_16x16x32_bf16 v[120:123], v[164:167], v[192:195], v[120:123]
	v_mfma_f32_16x16x32_bf16 v[116:119], v[156:159], v[200:203], v[116:119]
	v_mfma_f32_16x16x32_bf16 v[108:111], v[164:167], v[200:203], v[108:111]
	v_mfma_f32_16x16x32_bf16 v[100:103], v[156:159], v[208:211], v[100:103]
	v_mfma_f32_16x16x32_bf16 v[92:95], v[164:167], v[208:211], v[92:95]
	v_mfma_f32_16x16x32_bf16 v[84:87], v[156:159], v[216:219], v[84:87]
	v_mfma_f32_16x16x32_bf16 v[76:79], v[164:167], v[216:219], v[76:79]
	v_mfma_f32_16x16x32_bf16 v[112:115], v[168:171], v[184:187], v[112:115]
	v_mfma_f32_16x16x32_bf16 v[104:107], v[176:179], v[184:187], v[104:107]
	v_mfma_f32_16x16x32_bf16 v[96:99], v[168:171], v[196:199], v[96:99]
	v_mfma_f32_16x16x32_bf16 v[88:91], v[176:179], v[196:199], v[88:91]
	v_mfma_f32_16x16x32_bf16 v[80:83], v[168:171], v[204:207], v[80:83]
	v_mfma_f32_16x16x32_bf16 v[72:75], v[176:179], v[204:207], v[72:75]
	v_mfma_f32_16x16x32_bf16 v[68:71], v[168:171], v[212:215], v[68:71]
	v_mfma_f32_16x16x32_bf16 v[64:67], v[176:179], v[212:215], v[64:67]
	v_mfma_f32_16x16x32_bf16 v[112:115], v[172:175], v[192:195], v[112:115]
	v_mfma_f32_16x16x32_bf16 v[104:107], v[180:183], v[192:195], v[104:107]
	v_mfma_f32_16x16x32_bf16 v[96:99], v[172:175], v[200:203], v[96:99]
	v_mfma_f32_16x16x32_bf16 v[88:91], v[180:183], v[200:203], v[88:91]
	v_mfma_f32_16x16x32_bf16 v[80:83], v[172:175], v[208:211], v[80:83]
	v_mfma_f32_16x16x32_bf16 v[72:75], v[180:183], v[208:211], v[72:75]
	v_mfma_f32_16x16x32_bf16 v[68:71], v[172:175], v[216:219], v[68:71]
	v_mfma_f32_16x16x32_bf16 v[64:67], v[180:183], v[216:219], v[64:67]
	s_barrier
	s_add_i32 s79, s68, s61
	v_lshl_add_u64 v[144:145], s[40:41], 0, v[130:131]
	s_mov_b32 m0, s79
	ds_read_b128 v[184:187], v151 offset:16384
	ds_read_b128 v[192:195], v151 offset:17408
	ds_read_b128 v[196:199], v151 offset:18432
	ds_read_b128 v[200:203], v151 offset:19456
	ds_read_b128 v[204:207], v151 offset:20480
	ds_read_b128 v[208:211], v151 offset:21504
	ds_read_b128 v[212:215], v151 offset:22528
	ds_read_b128 v[216:219], v151 offset:23552
	global_load_lds_dwordx4 v[144:145], off
	s_add_i32 m0, s79, 0x2000
	s_add_u32 s80, s40, 0x100000
	v_lshl_add_u64 v[188:189], s[40:41], 0, v[134:135]
	s_addc_u32 s81, s41, 0
	s_add_i32 s79, s69, s61
	global_load_lds_dwordx4 v[188:189], off
	s_mov_b32 m0, s79
	v_lshl_add_u64 v[222:223], s[42:43], 0, v[132:133]
	global_load_lds_dwordx4 v130, s[80:81]
	s_add_i32 m0, s79, 0x2000
	s_nop 0
	global_load_lds_dwordx4 v134, s[80:81]
	v_lshl_add_u64 v[220:221], s[42:43], 0, v[128:129]
	s_mov_b32 m0, s31
	s_nop 0
	global_load_lds_dwordx4 v[220:221], off
	s_mov_b32 m0, s33
	s_nop 0
	global_load_lds_dwordx4 v[222:223], off
	s_waitcnt vmcnt(8) lgkmcnt(0)
	s_barrier
	v_mfma_f32_16x16x32_bf16 v[60:63], v[152:155], v[184:187], v[60:63]
	v_mfma_f32_16x16x32_bf16 v[56:59], v[160:163], v[184:187], v[56:59]
	v_mfma_f32_16x16x32_bf16 v[52:55], v[152:155], v[196:199], v[52:55]
	v_mfma_f32_16x16x32_bf16 v[44:47], v[160:163], v[196:199], v[44:47]
	v_mfma_f32_16x16x32_bf16 v[36:39], v[152:155], v[204:207], v[36:39]
	v_mfma_f32_16x16x32_bf16 v[28:31], v[160:163], v[204:207], v[28:31]
	v_mfma_f32_16x16x32_bf16 v[20:23], v[152:155], v[212:215], v[20:23]
	v_mfma_f32_16x16x32_bf16 v[12:15], v[160:163], v[212:215], v[12:15]
	v_mfma_f32_16x16x32_bf16 v[60:63], v[156:159], v[192:195], v[60:63]
	v_mfma_f32_16x16x32_bf16 v[56:59], v[164:167], v[192:195], v[56:59]
	v_mfma_f32_16x16x32_bf16 v[52:55], v[156:159], v[200:203], v[52:55]
	v_mfma_f32_16x16x32_bf16 v[44:47], v[164:167], v[200:203], v[44:47]
	v_mfma_f32_16x16x32_bf16 v[36:39], v[156:159], v[208:211], v[36:39]
	v_mfma_f32_16x16x32_bf16 v[28:31], v[164:167], v[208:211], v[28:31]
	v_mfma_f32_16x16x32_bf16 v[20:23], v[156:159], v[216:219], v[20:23]
	v_mfma_f32_16x16x32_bf16 v[12:15], v[164:167], v[216:219], v[12:15]
	v_mfma_f32_16x16x32_bf16 v[48:51], v[168:171], v[184:187], v[48:51]
	v_mfma_f32_16x16x32_bf16 v[40:43], v[176:179], v[184:187], v[40:43]
	v_mfma_f32_16x16x32_bf16 v[32:35], v[168:171], v[196:199], v[32:35]
	v_mfma_f32_16x16x32_bf16 v[24:27], v[176:179], v[196:199], v[24:27]
	v_mfma_f32_16x16x32_bf16 v[16:19], v[168:171], v[204:207], v[16:19]
	v_mfma_f32_16x16x32_bf16 v[8:11], v[176:179], v[204:207], v[8:11]
	v_mfma_f32_16x16x32_bf16 v[4:7], v[168:171], v[212:215], v[4:7]
	v_mfma_f32_16x16x32_bf16 v[0:3], v[176:179], v[212:215], v[0:3]
	v_mfma_f32_16x16x32_bf16 v[48:51], v[172:175], v[192:195], v[48:51]
	v_mfma_f32_16x16x32_bf16 v[40:43], v[180:183], v[192:195], v[40:43]
	v_mfma_f32_16x16x32_bf16 v[32:35], v[172:175], v[200:203], v[32:35]
	v_mfma_f32_16x16x32_bf16 v[24:27], v[180:183], v[200:203], v[24:27]
	v_mfma_f32_16x16x32_bf16 v[16:19], v[172:175], v[208:211], v[16:19]
	v_mfma_f32_16x16x32_bf16 v[8:11], v[180:183], v[208:211], v[8:11]
	v_mfma_f32_16x16x32_bf16 v[4:7], v[172:175], v[216:219], v[4:7]
	v_mfma_f32_16x16x32_bf16 v[0:3], v[180:183], v[216:219], v[0:3]
	s_barrier
	s_add_i32 s79, 0, 0x18000
	s_add_i32 s80, 0, 0x1c000
	v_add_u32_e32 v164, s79, v147
	v_add_u32_e32 v180, s80, v147
	ds_read_b128 v[152:155], v164
	ds_read_b128 v[156:159], v164 offset:1024
	ds_read_b128 v[160:163], v164 offset:2048
	ds_read_b128 v[164:167], v164 offset:3072
	ds_read_b128 v[168:171], v180
	ds_read_b128 v[172:175], v180 offset:1024
	ds_read_b128 v[176:179], v180 offset:2048
	ds_read_b128 v[180:183], v180 offset:3072
	s_add_u32 s42, s42, 0x100000
	s_addc_u32 s43, s43, 0
	s_mov_b32 m0, s62
	ds_read_b128 v[184:187], v151 offset:32768
	ds_read_b128 v[192:195], v151 offset:33792
	ds_read_b128 v[196:199], v151 offset:34816
	ds_read_b128 v[200:203], v151 offset:35840
	ds_read_b128 v[204:207], v151 offset:36864
	ds_read_b128 v[208:211], v151 offset:37888
	ds_read_b128 v[212:215], v151 offset:38912
	ds_read_b128 v[216:219], v151 offset:39936
	global_load_lds_dwordx4 v128, s[42:43]
	s_mov_b32 m0, s63
	s_nop 0
	global_load_lds_dwordx4 v132, s[42:43]
	s_waitcnt vmcnt(8) lgkmcnt(0)
	s_barrier
	v_mfma_f32_16x16x32_bf16 v[124:127], v[152:155], v[184:187], v[124:127]
	v_mfma_f32_16x16x32_bf16 v[120:123], v[160:163], v[184:187], v[120:123]
	v_mfma_f32_16x16x32_bf16 v[116:119], v[152:155], v[196:199], v[116:119]
	v_mfma_f32_16x16x32_bf16 v[108:111], v[160:163], v[196:199], v[108:111]
	v_mfma_f32_16x16x32_bf16 v[100:103], v[152:155], v[204:207], v[100:103]
	v_mfma_f32_16x16x32_bf16 v[92:95], v[160:163], v[204:207], v[92:95]
	v_mfma_f32_16x16x32_bf16 v[84:87], v[152:155], v[212:215], v[84:87]
	v_mfma_f32_16x16x32_bf16 v[76:79], v[160:163], v[212:215], v[76:79]
	v_mfma_f32_16x16x32_bf16 v[124:127], v[156:159], v[192:195], v[124:127]
	v_mfma_f32_16x16x32_bf16 v[120:123], v[164:167], v[192:195], v[120:123]
	v_mfma_f32_16x16x32_bf16 v[116:119], v[156:159], v[200:203], v[116:119]
	v_mfma_f32_16x16x32_bf16 v[108:111], v[164:167], v[200:203], v[108:111]
	v_mfma_f32_16x16x32_bf16 v[100:103], v[156:159], v[208:211], v[100:103]
	v_mfma_f32_16x16x32_bf16 v[92:95], v[164:167], v[208:211], v[92:95]
	v_mfma_f32_16x16x32_bf16 v[84:87], v[156:159], v[216:219], v[84:87]
	v_mfma_f32_16x16x32_bf16 v[76:79], v[164:167], v[216:219], v[76:79]
	v_mfma_f32_16x16x32_bf16 v[112:115], v[168:171], v[184:187], v[112:115]
	v_mfma_f32_16x16x32_bf16 v[104:107], v[176:179], v[184:187], v[104:107]
	v_mfma_f32_16x16x32_bf16 v[96:99], v[168:171], v[196:199], v[96:99]
	v_mfma_f32_16x16x32_bf16 v[88:91], v[176:179], v[196:199], v[88:91]
	v_mfma_f32_16x16x32_bf16 v[80:83], v[168:171], v[204:207], v[80:83]
	v_mfma_f32_16x16x32_bf16 v[72:75], v[176:179], v[204:207], v[72:75]
	v_mfma_f32_16x16x32_bf16 v[68:71], v[168:171], v[212:215], v[68:71]
	v_mfma_f32_16x16x32_bf16 v[64:67], v[176:179], v[212:215], v[64:67]
	v_mfma_f32_16x16x32_bf16 v[112:115], v[172:175], v[192:195], v[112:115]
	v_mfma_f32_16x16x32_bf16 v[104:107], v[180:183], v[192:195], v[104:107]
	v_mfma_f32_16x16x32_bf16 v[96:99], v[172:175], v[200:203], v[96:99]
	v_mfma_f32_16x16x32_bf16 v[88:91], v[180:183], v[200:203], v[88:91]
	v_mfma_f32_16x16x32_bf16 v[80:83], v[172:175], v[208:211], v[80:83]
	v_mfma_f32_16x16x32_bf16 v[72:75], v[180:183], v[208:211], v[72:75]
	v_mfma_f32_16x16x32_bf16 v[68:71], v[172:175], v[216:219], v[68:71]
	v_mfma_f32_16x16x32_bf16 v[64:67], v[180:183], v[216:219], v[64:67]
	s_barrier
	s_add_i32 s42, s79, s61
	v_lshl_add_u64 v[144:145], v[144:145], 0, s[10:11]
	s_mov_b32 m0, s42
	ds_read_b128 v[184:187], v151 offset:49152
	ds_read_b128 v[192:195], v151 offset:50176
	ds_read_b128 v[196:199], v151 offset:51200
	ds_read_b128 v[200:203], v151 offset:52224
	ds_read_b128 v[204:207], v151 offset:53248
	ds_read_b128 v[208:211], v151 offset:54272
	ds_read_b128 v[212:215], v151 offset:55296
	ds_read_b128 v[216:219], v151 offset:56320
	global_load_lds_dwordx4 v[144:145], off
	s_add_i32 m0, s42, 0x2000
	s_add_u32 s40, s40, 0x100080
	v_lshl_add_u64 v[144:145], v[188:189], 0, s[10:11]
	s_addc_u32 s41, s41, 0
	s_add_i32 s42, s80, s61
	global_load_lds_dwordx4 v[144:145], off
	s_mov_b32 m0, s42
	s_nop 0
	global_load_lds_dwordx4 v130, s[40:41]
	s_add_i32 m0, s42, 0x2000
	s_nop 0
	global_load_lds_dwordx4 v134, s[40:41]
	v_lshl_add_u64 v[144:145], v[220:221], 0, s[10:11]
	s_mov_b32 m0, s65
	s_nop 0
	global_load_lds_dwordx4 v[144:145], off
	v_lshl_add_u64 v[144:145], v[222:223], 0, s[10:11]
	s_mov_b32 m0, s66
	s_nop 0
	global_load_lds_dwordx4 v[144:145], off
	s_waitcnt vmcnt(8) lgkmcnt(0)
	s_barrier
	v_mfma_f32_16x16x32_bf16 v[60:63], v[152:155], v[184:187], v[60:63]
	v_mfma_f32_16x16x32_bf16 v[56:59], v[160:163], v[184:187], v[56:59]
	v_mfma_f32_16x16x32_bf16 v[52:55], v[152:155], v[196:199], v[52:55]
	v_mfma_f32_16x16x32_bf16 v[44:47], v[160:163], v[196:199], v[44:47]
	v_mfma_f32_16x16x32_bf16 v[36:39], v[152:155], v[204:207], v[36:39]
	v_mfma_f32_16x16x32_bf16 v[28:31], v[160:163], v[204:207], v[28:31]
	v_mfma_f32_16x16x32_bf16 v[20:23], v[152:155], v[212:215], v[20:23]
	v_mfma_f32_16x16x32_bf16 v[12:15], v[160:163], v[212:215], v[12:15]
	v_mfma_f32_16x16x32_bf16 v[60:63], v[156:159], v[192:195], v[60:63]
	v_mfma_f32_16x16x32_bf16 v[56:59], v[164:167], v[192:195], v[56:59]
	v_mfma_f32_16x16x32_bf16 v[52:55], v[156:159], v[200:203], v[52:55]
	v_mfma_f32_16x16x32_bf16 v[44:47], v[164:167], v[200:203], v[44:47]
	v_mfma_f32_16x16x32_bf16 v[36:39], v[156:159], v[208:211], v[36:39]
	v_mfma_f32_16x16x32_bf16 v[28:31], v[164:167], v[208:211], v[28:31]
	v_mfma_f32_16x16x32_bf16 v[20:23], v[156:159], v[216:219], v[20:23]
	v_mfma_f32_16x16x32_bf16 v[12:15], v[164:167], v[216:219], v[12:15]
	v_mfma_f32_16x16x32_bf16 v[48:51], v[168:171], v[184:187], v[48:51]
	v_mfma_f32_16x16x32_bf16 v[40:43], v[176:179], v[184:187], v[40:43]
	v_mfma_f32_16x16x32_bf16 v[32:35], v[168:171], v[196:199], v[32:35]
	v_mfma_f32_16x16x32_bf16 v[24:27], v[176:179], v[196:199], v[24:27]
	v_mfma_f32_16x16x32_bf16 v[16:19], v[168:171], v[204:207], v[16:19]
	v_mfma_f32_16x16x32_bf16 v[8:11], v[176:179], v[204:207], v[8:11]
	v_mfma_f32_16x16x32_bf16 v[4:7], v[168:171], v[212:215], v[4:7]
	v_mfma_f32_16x16x32_bf16 v[0:3], v[176:179], v[212:215], v[0:3]
	v_mfma_f32_16x16x32_bf16 v[48:51], v[172:175], v[192:195], v[48:51]
	v_mfma_f32_16x16x32_bf16 v[40:43], v[180:183], v[192:195], v[40:43]
	v_mfma_f32_16x16x32_bf16 v[32:35], v[172:175], v[200:203], v[32:35]
	v_mfma_f32_16x16x32_bf16 v[24:27], v[180:183], v[200:203], v[24:27]
	v_mfma_f32_16x16x32_bf16 v[16:19], v[172:175], v[208:211], v[16:19]
	v_mfma_f32_16x16x32_bf16 v[8:11], v[180:183], v[208:211], v[8:11]
	v_mfma_f32_16x16x32_bf16 v[4:7], v[172:175], v[216:219], v[4:7]
	v_mfma_f32_16x16x32_bf16 v[0:3], v[180:183], v[216:219], v[0:3]
	s_barrier
	s_add_i32 s77, s77, 2
	s_add_u32 s34, s34, 0x100
	s_addc_u32 s35, s35, 0
	s_add_u32 s75, s75, 0x100
	s_addc_u32 s76, s76, 0
	s_cmp_gt_u32 s77, 61
	s_cbranch_scc0 .LBB0_916

.LBB0_1052:
	s_ashr_i32 s27, s26, 31
	s_lshl_b64 s[28:29], s[26:27], 19
	s_add_u32 s28, s58, s28
	s_addc_u32 s29, s59, s29
	s_and_b64 s[30:31], s[4:5], exec
	s_cselect_b32 s27, s29, s43
	s_cselect_b32 s55, s28, s42
	s_ashr_i32 s25, s24, 31
	s_lshl_b64 s[30:31], s[24:25], 19
	s_add_u32 s30, s53, s30
	s_addc_u32 s31, s64, s31
	s_and_b64 s[62:63], s[4:5], exec
	s_cselect_b32 s25, s31, s61
	s_cselect_b32 s79, s30, s60
	s_add_u32 s42, s42, 0x40080
	s_addc_u32 s43, s43, 0
	s_add_u32 s80, s60, 0x100
	s_addc_u32 s81, s61, 0
	s_mov_b32 s82, -2
	ds_read_b128 v[152:155], v149
	ds_read_b128 v[156:159], v149 offset:1024
	ds_read_b128 v[160:163], v149 offset:2048
	ds_read_b128 v[164:167], v149 offset:3072
	ds_read_b128 v[168:171], v150
	ds_read_b128 v[172:175], v150 offset:1024
	ds_read_b128 v[176:179], v150 offset:2048
	ds_read_b128 v[180:183], v150 offset:3072
	s_add_u32 s60, s42, 0xfffc0080
	s_addc_u32 s61, s43, -1
	s_cmp_eq_u32 s82, 12
	s_cselect_b32 s63, s27, s61
	s_cselect_b32 s62, s55, s60
	s_cselect_b32 s61, s25, s81
	s_cselect_b32 s60, s79, s80
	s_add_i32 m0, s35, 0xc000
	ds_read_b128 v[184:187], v151
	ds_read_b128 v[192:195], v151 offset:1024
	ds_read_b128 v[196:199], v151 offset:2048
	ds_read_b128 v[200:203], v151 offset:3072
	ds_read_b128 v[204:207], v151 offset:4096
	ds_read_b128 v[208:211], v151 offset:5120
	ds_read_b128 v[212:215], v151 offset:6144
	ds_read_b128 v[216:219], v151 offset:7168
	global_load_lds_dwordx4 v136, s[42:43]
	s_add_i32 m0, s35, 0xe000
	s_nop 0
	global_load_lds_dwordx4 v138, s[42:43]
	s_waitcnt vmcnt(8) lgkmcnt(0)
	s_barrier
	v_mfma_f32_16x16x32_bf16 v[124:127], v[152:155], v[184:187], 0
	v_mfma_f32_16x16x32_bf16 v[120:123], v[160:163], v[184:187], 0
	v_mfma_f32_16x16x32_bf16 v[116:119], v[152:155], v[196:199], 0
	v_mfma_f32_16x16x32_bf16 v[108:111], v[160:163], v[196:199], 0
	v_mfma_f32_16x16x32_bf16 v[100:103], v[152:155], v[204:207], 0
	v_mfma_f32_16x16x32_bf16 v[92:95], v[160:163], v[204:207], 0
	v_mfma_f32_16x16x32_bf16 v[84:87], v[152:155], v[212:215], 0
	v_mfma_f32_16x16x32_bf16 v[76:79], v[160:163], v[212:215], 0
	v_mfma_f32_16x16x32_bf16 v[124:127], v[156:159], v[192:195], v[124:127]
	v_mfma_f32_16x16x32_bf16 v[120:123], v[164:167], v[192:195], v[120:123]
	v_mfma_f32_16x16x32_bf16 v[116:119], v[156:159], v[200:203], v[116:119]
	v_mfma_f32_16x16x32_bf16 v[108:111], v[164:167], v[200:203], v[108:111]
	v_mfma_f32_16x16x32_bf16 v[100:103], v[156:159], v[208:211], v[100:103]
	v_mfma_f32_16x16x32_bf16 v[92:95], v[164:167], v[208:211], v[92:95]
	v_mfma_f32_16x16x32_bf16 v[84:87], v[156:159], v[216:219], v[84:87]
	v_mfma_f32_16x16x32_bf16 v[76:79], v[164:167], v[216:219], v[76:79]
	v_mfma_f32_16x16x32_bf16 v[112:115], v[168:171], v[184:187], 0
	v_mfma_f32_16x16x32_bf16 v[104:107], v[176:179], v[184:187], 0
	v_mfma_f32_16x16x32_bf16 v[96:99], v[168:171], v[196:199], 0
	v_mfma_f32_16x16x32_bf16 v[88:91], v[176:179], v[196:199], 0
	v_mfma_f32_16x16x32_bf16 v[80:83], v[168:171], v[204:207], 0
	v_mfma_f32_16x16x32_bf16 v[72:75], v[176:179], v[204:207], 0
	v_mfma_f32_16x16x32_bf16 v[68:71], v[168:171], v[212:215], 0
	v_mfma_f32_16x16x32_bf16 v[64:67], v[176:179], v[212:215], 0
	v_mfma_f32_16x16x32_bf16 v[112:115], v[172:175], v[192:195], v[112:115]
	v_mfma_f32_16x16x32_bf16 v[104:107], v[180:183], v[192:195], v[104:107]
	v_mfma_f32_16x16x32_bf16 v[96:99], v[172:175], v[200:203], v[96:99]
	v_mfma_f32_16x16x32_bf16 v[88:91], v[180:183], v[200:203], v[88:91]
	v_mfma_f32_16x16x32_bf16 v[80:83], v[172:175], v[208:211], v[80:83]
	v_mfma_f32_16x16x32_bf16 v[72:75], v[180:183], v[208:211], v[72:75]
	v_mfma_f32_16x16x32_bf16 v[68:71], v[172:175], v[216:219], v[68:71]
	v_mfma_f32_16x16x32_bf16 v[64:67], v[180:183], v[216:219], v[64:67]
	s_barrier
	s_add_i32 s83, s72, s65
	v_lshl_add_u64 v[144:145], s[60:61], 0, v[130:131]
	s_mov_b32 m0, s83
	ds_read_b128 v[184:187], v151 offset:16384
	ds_read_b128 v[192:195], v151 offset:17408
	ds_read_b128 v[196:199], v151 offset:18432
	ds_read_b128 v[200:203], v151 offset:19456
	ds_read_b128 v[204:207], v151 offset:20480
	ds_read_b128 v[208:211], v151 offset:21504
	ds_read_b128 v[212:215], v151 offset:22528
	ds_read_b128 v[216:219], v151 offset:23552
	global_load_lds_dwordx4 v[144:145], off
	s_add_i32 m0, s83, 0x2000
	s_add_u32 s84, s60, 0x40000
	v_lshl_add_u64 v[188:189], s[60:61], 0, v[134:135]
	s_addc_u32 s85, s61, 0
	s_add_i32 s83, s73, s65
	global_load_lds_dwordx4 v[188:189], off
	s_mov_b32 m0, s83
	v_lshl_add_u64 v[222:223], s[62:63], 0, v[132:133]
	global_load_lds_dwordx4 v130, s[84:85]
	s_add_i32 m0, s83, 0x2000
	s_nop 0
	global_load_lds_dwordx4 v134, s[84:85]
	v_lshl_add_u64 v[220:221], s[62:63], 0, v[128:129]
	s_mov_b32 m0, s35
	s_nop 0
	global_load_lds_dwordx4 v[220:221], off
	s_mov_b32 m0, s33
	s_nop 0
	global_load_lds_dwordx4 v[222:223], off
	s_waitcnt vmcnt(8) lgkmcnt(0)
	s_barrier
	v_mfma_f32_16x16x32_bf16 v[60:63], v[152:155], v[184:187], 0
	v_mfma_f32_16x16x32_bf16 v[56:59], v[160:163], v[184:187], 0
	v_mfma_f32_16x16x32_bf16 v[52:55], v[152:155], v[196:199], 0
	v_mfma_f32_16x16x32_bf16 v[44:47], v[160:163], v[196:199], 0
	v_mfma_f32_16x16x32_bf16 v[36:39], v[152:155], v[204:207], 0
	v_mfma_f32_16x16x32_bf16 v[28:31], v[160:163], v[204:207], 0
	v_mfma_f32_16x16x32_bf16 v[20:23], v[152:155], v[212:215], 0
	v_mfma_f32_16x16x32_bf16 v[12:15], v[160:163], v[212:215], 0
	v_mfma_f32_16x16x32_bf16 v[60:63], v[156:159], v[192:195], v[60:63]
	v_mfma_f32_16x16x32_bf16 v[56:59], v[164:167], v[192:195], v[56:59]
	v_mfma_f32_16x16x32_bf16 v[52:55], v[156:159], v[200:203], v[52:55]
	v_mfma_f32_16x16x32_bf16 v[44:47], v[164:167], v[200:203], v[44:47]
	v_mfma_f32_16x16x32_bf16 v[36:39], v[156:159], v[208:211], v[36:39]
	v_mfma_f32_16x16x32_bf16 v[28:31], v[164:167], v[208:211], v[28:31]
	v_mfma_f32_16x16x32_bf16 v[20:23], v[156:159], v[216:219], v[20:23]
	v_mfma_f32_16x16x32_bf16 v[12:15], v[164:167], v[216:219], v[12:15]
	v_mfma_f32_16x16x32_bf16 v[48:51], v[168:171], v[184:187], 0
	v_mfma_f32_16x16x32_bf16 v[40:43], v[176:179], v[184:187], 0
	v_mfma_f32_16x16x32_bf16 v[32:35], v[168:171], v[196:199], 0
	v_mfma_f32_16x16x32_bf16 v[24:27], v[176:179], v[196:199], 0
	v_mfma_f32_16x16x32_bf16 v[16:19], v[168:171], v[204:207], 0
	v_mfma_f32_16x16x32_bf16 v[8:11], v[176:179], v[204:207], 0
	v_mfma_f32_16x16x32_bf16 v[4:7], v[168:171], v[212:215], 0
	v_mfma_f32_16x16x32_bf16 v[0:3], v[176:179], v[212:215], 0
	v_mfma_f32_16x16x32_bf16 v[48:51], v[172:175], v[192:195], v[48:51]
	v_mfma_f32_16x16x32_bf16 v[40:43], v[180:183], v[192:195], v[40:43]
	v_mfma_f32_16x16x32_bf16 v[32:35], v[172:175], v[200:203], v[32:35]
	v_mfma_f32_16x16x32_bf16 v[24:27], v[180:183], v[200:203], v[24:27]
	v_mfma_f32_16x16x32_bf16 v[16:19], v[172:175], v[208:211], v[16:19]
	v_mfma_f32_16x16x32_bf16 v[8:11], v[180:183], v[208:211], v[8:11]
	v_mfma_f32_16x16x32_bf16 v[4:7], v[172:175], v[216:219], v[4:7]
	v_mfma_f32_16x16x32_bf16 v[0:3], v[180:183], v[216:219], v[0:3]
	s_barrier
	s_add_i32 s83, 0, 0x18000
	s_add_i32 s84, 0, 0x1c000
	v_add_u32_e32 v164, s83, v147
	v_add_u32_e32 v180, s84, v147
	ds_read_b128 v[152:155], v164
	ds_read_b128 v[156:159], v164 offset:1024
	ds_read_b128 v[160:163], v164 offset:2048
	ds_read_b128 v[164:167], v164 offset:3072
	ds_read_b128 v[168:171], v180
	ds_read_b128 v[172:175], v180 offset:1024
	ds_read_b128 v[176:179], v180 offset:2048
	ds_read_b128 v[180:183], v180 offset:3072
	s_add_u32 s62, s62, 0x40000
	s_addc_u32 s63, s63, 0
	s_mov_b32 m0, s66
	ds_read_b128 v[184:187], v151 offset:32768
	ds_read_b128 v[192:195], v151 offset:33792
	ds_read_b128 v[196:199], v151 offset:34816
	ds_read_b128 v[200:203], v151 offset:35840
	ds_read_b128 v[204:207], v151 offset:36864
	ds_read_b128 v[208:211], v151 offset:37888
	ds_read_b128 v[212:215], v151 offset:38912
	ds_read_b128 v[216:219], v151 offset:39936
	global_load_lds_dwordx4 v128, s[62:63]
	s_mov_b32 m0, s67
	s_nop 0
	global_load_lds_dwordx4 v132, s[62:63]
	s_waitcnt vmcnt(8) lgkmcnt(0)
	s_barrier
	v_mfma_f32_16x16x32_bf16 v[124:127], v[152:155], v[184:187], v[124:127]
	v_mfma_f32_16x16x32_bf16 v[120:123], v[160:163], v[184:187], v[120:123]
	v_mfma_f32_16x16x32_bf16 v[116:119], v[152:155], v[196:199], v[116:119]
	v_mfma_f32_16x16x32_bf16 v[108:111], v[160:163], v[196:199], v[108:111]
	v_mfma_f32_16x16x32_bf16 v[100:103], v[152:155], v[204:207], v[100:103]
	v_mfma_f32_16x16x32_bf16 v[92:95], v[160:163], v[204:207], v[92:95]
	v_mfma_f32_16x16x32_bf16 v[84:87], v[152:155], v[212:215], v[84:87]
	v_mfma_f32_16x16x32_bf16 v[76:79], v[160:163], v[212:215], v[76:79]
	v_mfma_f32_16x16x32_bf16 v[124:127], v[156:159], v[192:195], v[124:127]
	v_mfma_f32_16x16x32_bf16 v[120:123], v[164:167], v[192:195], v[120:123]
	v_mfma_f32_16x16x32_bf16 v[116:119], v[156:159], v[200:203], v[116:119]
	v_mfma_f32_16x16x32_bf16 v[108:111], v[164:167], v[200:203], v[108:111]
	v_mfma_f32_16x16x32_bf16 v[100:103], v[156:159], v[208:211], v[100:103]
	v_mfma_f32_16x16x32_bf16 v[92:95], v[164:167], v[208:211], v[92:95]
	v_mfma_f32_16x16x32_bf16 v[84:87], v[156:159], v[216:219], v[84:87]
	v_mfma_f32_16x16x32_bf16 v[76:79], v[164:167], v[216:219], v[76:79]
	v_mfma_f32_16x16x32_bf16 v[112:115], v[168:171], v[184:187], v[112:115]
	v_mfma_f32_16x16x32_bf16 v[104:107], v[176:179], v[184:187], v[104:107]
	v_mfma_f32_16x16x32_bf16 v[96:99], v[168:171], v[196:199], v[96:99]
	v_mfma_f32_16x16x32_bf16 v[88:91], v[176:179], v[196:199], v[88:91]
	v_mfma_f32_16x16x32_bf16 v[80:83], v[168:171], v[204:207], v[80:83]
	v_mfma_f32_16x16x32_bf16 v[72:75], v[176:179], v[204:207], v[72:75]
	v_mfma_f32_16x16x32_bf16 v[68:71], v[168:171], v[212:215], v[68:71]
	v_mfma_f32_16x16x32_bf16 v[64:67], v[176:179], v[212:215], v[64:67]
	v_mfma_f32_16x16x32_bf16 v[112:115], v[172:175], v[192:195], v[112:115]
	v_mfma_f32_16x16x32_bf16 v[104:107], v[180:183], v[192:195], v[104:107]
	v_mfma_f32_16x16x32_bf16 v[96:99], v[172:175], v[200:203], v[96:99]
	v_mfma_f32_16x16x32_bf16 v[88:91], v[180:183], v[200:203], v[88:91]
	v_mfma_f32_16x16x32_bf16 v[80:83], v[172:175], v[208:211], v[80:83]
	v_mfma_f32_16x16x32_bf16 v[72:75], v[180:183], v[208:211], v[72:75]
	v_mfma_f32_16x16x32_bf16 v[68:71], v[172:175], v[216:219], v[68:71]
	v_mfma_f32_16x16x32_bf16 v[64:67], v[180:183], v[216:219], v[64:67]
	s_barrier
	s_add_i32 s62, s83, s65
	v_lshl_add_u64 v[144:145], v[144:145], 0, s[12:13]
	s_mov_b32 m0, s62
	ds_read_b128 v[184:187], v151 offset:49152
	ds_read_b128 v[192:195], v151 offset:50176
	ds_read_b128 v[196:199], v151 offset:51200
	ds_read_b128 v[200:203], v151 offset:52224
	ds_read_b128 v[204:207], v151 offset:53248
	ds_read_b128 v[208:211], v151 offset:54272
	ds_read_b128 v[212:215], v151 offset:55296
	ds_read_b128 v[216:219], v151 offset:56320
	global_load_lds_dwordx4 v[144:145], off
	s_add_i32 m0, s62, 0x2000
	s_add_u32 s60, s60, 0x40080
	v_lshl_add_u64 v[144:145], v[188:189], 0, s[12:13]
	s_addc_u32 s61, s61, 0
	s_add_i32 s62, s84, s65
	global_load_lds_dwordx4 v[144:145], off
	s_mov_b32 m0, s62
	s_nop 0
	global_load_lds_dwordx4 v130, s[60:61]
	s_add_i32 m0, s62, 0x2000
	s_nop 0
	global_load_lds_dwordx4 v134, s[60:61]
	v_lshl_add_u64 v[144:145], v[220:221], 0, s[12:13]
	s_mov_b32 m0, s69
	s_nop 0
	global_load_lds_dwordx4 v[144:145], off
	v_lshl_add_u64 v[144:145], v[222:223], 0, s[12:13]
	s_mov_b32 m0, s70
	s_nop 0
	global_load_lds_dwordx4 v[144:145], off
	s_waitcnt vmcnt(8) lgkmcnt(0)
	s_barrier
	v_mfma_f32_16x16x32_bf16 v[60:63], v[152:155], v[184:187], v[60:63]
	v_mfma_f32_16x16x32_bf16 v[56:59], v[160:163], v[184:187], v[56:59]
	v_mfma_f32_16x16x32_bf16 v[52:55], v[152:155], v[196:199], v[52:55]
	v_mfma_f32_16x16x32_bf16 v[44:47], v[160:163], v[196:199], v[44:47]
	v_mfma_f32_16x16x32_bf16 v[36:39], v[152:155], v[204:207], v[36:39]
	v_mfma_f32_16x16x32_bf16 v[28:31], v[160:163], v[204:207], v[28:31]
	v_mfma_f32_16x16x32_bf16 v[20:23], v[152:155], v[212:215], v[20:23]
	v_mfma_f32_16x16x32_bf16 v[12:15], v[160:163], v[212:215], v[12:15]
	v_mfma_f32_16x16x32_bf16 v[60:63], v[156:159], v[192:195], v[60:63]
	v_mfma_f32_16x16x32_bf16 v[56:59], v[164:167], v[192:195], v[56:59]
	v_mfma_f32_16x16x32_bf16 v[52:55], v[156:159], v[200:203], v[52:55]
	v_mfma_f32_16x16x32_bf16 v[44:47], v[164:167], v[200:203], v[44:47]
	v_mfma_f32_16x16x32_bf16 v[36:39], v[156:159], v[208:211], v[36:39]
	v_mfma_f32_16x16x32_bf16 v[28:31], v[164:167], v[208:211], v[28:31]
	v_mfma_f32_16x16x32_bf16 v[20:23], v[156:159], v[216:219], v[20:23]
	v_mfma_f32_16x16x32_bf16 v[12:15], v[164:167], v[216:219], v[12:15]
	v_mfma_f32_16x16x32_bf16 v[48:51], v[168:171], v[184:187], v[48:51]
	v_mfma_f32_16x16x32_bf16 v[40:43], v[176:179], v[184:187], v[40:43]
	v_mfma_f32_16x16x32_bf16 v[32:35], v[168:171], v[196:199], v[32:35]
	v_mfma_f32_16x16x32_bf16 v[24:27], v[176:179], v[196:199], v[24:27]
	v_mfma_f32_16x16x32_bf16 v[16:19], v[168:171], v[204:207], v[16:19]
	v_mfma_f32_16x16x32_bf16 v[8:11], v[176:179], v[204:207], v[8:11]
	v_mfma_f32_16x16x32_bf16 v[4:7], v[168:171], v[212:215], v[4:7]
	v_mfma_f32_16x16x32_bf16 v[0:3], v[176:179], v[212:215], v[0:3]
	v_mfma_f32_16x16x32_bf16 v[48:51], v[172:175], v[192:195], v[48:51]
	v_mfma_f32_16x16x32_bf16 v[40:43], v[180:183], v[192:195], v[40:43]
	v_mfma_f32_16x16x32_bf16 v[32:35], v[172:175], v[200:203], v[32:35]
	v_mfma_f32_16x16x32_bf16 v[24:27], v[180:183], v[200:203], v[24:27]
	v_mfma_f32_16x16x32_bf16 v[16:19], v[172:175], v[208:211], v[16:19]
	v_mfma_f32_16x16x32_bf16 v[8:11], v[180:183], v[208:211], v[8:11]
	v_mfma_f32_16x16x32_bf16 v[4:7], v[172:175], v[216:219], v[4:7]
	v_mfma_f32_16x16x32_bf16 v[0:3], v[180:183], v[216:219], v[0:3]
	s_barrier
	s_add_i32 s82, s82, 2
	s_add_u32 s42, s42, 0x100
	s_addc_u32 s43, s43, 0
	s_add_u32 s80, s80, 0x100
	s_addc_u32 s81, s81, 0
	s_cmp_gt_u32 s82, 13
	s_cbranch_scc0 .LBB0_1053
	s_branch .Lpeel_exit5
.LBB0_1053:
	ds_read_b128 v[152:155], v149
	ds_read_b128 v[156:159], v149 offset:1024
	ds_read_b128 v[160:163], v149 offset:2048
	ds_read_b128 v[164:167], v149 offset:3072
	ds_read_b128 v[168:171], v150
	ds_read_b128 v[172:175], v150 offset:1024
	ds_read_b128 v[176:179], v150 offset:2048
	ds_read_b128 v[180:183], v150 offset:3072
	s_add_u32 s60, s42, 0xfffc0080
	s_addc_u32 s61, s43, -1
	s_cmp_eq_u32 s82, 12
	s_cselect_b32 s63, s27, s61
	s_cselect_b32 s62, s55, s60
	s_cselect_b32 s61, s25, s81
	s_cselect_b32 s60, s79, s80
	s_add_i32 m0, s35, 0xc000
	ds_read_b128 v[184:187], v151
	ds_read_b128 v[192:195], v151 offset:1024
	ds_read_b128 v[196:199], v151 offset:2048
	ds_read_b128 v[200:203], v151 offset:3072
	ds_read_b128 v[204:207], v151 offset:4096
	ds_read_b128 v[208:211], v151 offset:5120
	ds_read_b128 v[212:215], v151 offset:6144
	ds_read_b128 v[216:219], v151 offset:7168
	global_load_lds_dwordx4 v136, s[42:43]
	s_add_i32 m0, s35, 0xe000
	s_nop 0
	global_load_lds_dwordx4 v138, s[42:43]
	s_waitcnt vmcnt(8) lgkmcnt(0)
	s_barrier
	v_mfma_f32_16x16x32_bf16 v[124:127], v[152:155], v[184:187], v[124:127]
	v_mfma_f32_16x16x32_bf16 v[120:123], v[160:163], v[184:187], v[120:123]
	v_mfma_f32_16x16x32_bf16 v[116:119], v[152:155], v[196:199], v[116:119]
	v_mfma_f32_16x16x32_bf16 v[108:111], v[160:163], v[196:199], v[108:111]
	v_mfma_f32_16x16x32_bf16 v[100:103], v[152:155], v[204:207], v[100:103]
	v_mfma_f32_16x16x32_bf16 v[92:95], v[160:163], v[204:207], v[92:95]
	v_mfma_f32_16x16x32_bf16 v[84:87], v[152:155], v[212:215], v[84:87]
	v_mfma_f32_16x16x32_bf16 v[76:79], v[160:163], v[212:215], v[76:79]
	v_mfma_f32_16x16x32_bf16 v[124:127], v[156:159], v[192:195], v[124:127]
	v_mfma_f32_16x16x32_bf16 v[120:123], v[164:167], v[192:195], v[120:123]
	v_mfma_f32_16x16x32_bf16 v[116:119], v[156:159], v[200:203], v[116:119]
	v_mfma_f32_16x16x32_bf16 v[108:111], v[164:167], v[200:203], v[108:111]
	v_mfma_f32_16x16x32_bf16 v[100:103], v[156:159], v[208:211], v[100:103]
	v_mfma_f32_16x16x32_bf16 v[92:95], v[164:167], v[208:211], v[92:95]
	v_mfma_f32_16x16x32_bf16 v[84:87], v[156:159], v[216:219], v[84:87]
	v_mfma_f32_16x16x32_bf16 v[76:79], v[164:167], v[216:219], v[76:79]
	v_mfma_f32_16x16x32_bf16 v[112:115], v[168:171], v[184:187], v[112:115]
	v_mfma_f32_16x16x32_bf16 v[104:107], v[176:179], v[184:187], v[104:107]
	v_mfma_f32_16x16x32_bf16 v[96:99], v[168:171], v[196:199], v[96:99]
	v_mfma_f32_16x16x32_bf16 v[88:91], v[176:179], v[196:199], v[88:91]
	v_mfma_f32_16x16x32_bf16 v[80:83], v[168:171], v[204:207], v[80:83]
	v_mfma_f32_16x16x32_bf16 v[72:75], v[176:179], v[204:207], v[72:75]
	v_mfma_f32_16x16x32_bf16 v[68:71], v[168:171], v[212:215], v[68:71]
	v_mfma_f32_16x16x32_bf16 v[64:67], v[176:179], v[212:215], v[64:67]
	v_mfma_f32_16x16x32_bf16 v[112:115], v[172:175], v[192:195], v[112:115]
	v_mfma_f32_16x16x32_bf16 v[104:107], v[180:183], v[192:195], v[104:107]
	v_mfma_f32_16x16x32_bf16 v[96:99], v[172:175], v[200:203], v[96:99]
	v_mfma_f32_16x16x32_bf16 v[88:91], v[180:183], v[200:203], v[88:91]
	v_mfma_f32_16x16x32_bf16 v[80:83], v[172:175], v[208:211], v[80:83]
	v_mfma_f32_16x16x32_bf16 v[72:75], v[180:183], v[208:211], v[72:75]
	v_mfma_f32_16x16x32_bf16 v[68:71], v[172:175], v[216:219], v[68:71]
	v_mfma_f32_16x16x32_bf16 v[64:67], v[180:183], v[216:219], v[64:67]
	s_barrier
	s_add_i32 s83, s72, s65
	v_lshl_add_u64 v[144:145], s[60:61], 0, v[130:131]
	s_mov_b32 m0, s83
	ds_read_b128 v[184:187], v151 offset:16384
	ds_read_b128 v[192:195], v151 offset:17408
	ds_read_b128 v[196:199], v151 offset:18432
	ds_read_b128 v[200:203], v151 offset:19456
	ds_read_b128 v[204:207], v151 offset:20480
	ds_read_b128 v[208:211], v151 offset:21504
	ds_read_b128 v[212:215], v151 offset:22528
	ds_read_b128 v[216:219], v151 offset:23552
	global_load_lds_dwordx4 v[144:145], off
	s_add_i32 m0, s83, 0x2000
	s_add_u32 s84, s60, 0x40000
	v_lshl_add_u64 v[188:189], s[60:61], 0, v[134:135]
	s_addc_u32 s85, s61, 0
	s_add_i32 s83, s73, s65
	global_load_lds_dwordx4 v[188:189], off
	s_mov_b32 m0, s83
	v_lshl_add_u64 v[222:223], s[62:63], 0, v[132:133]
	global_load_lds_dwordx4 v130, s[84:85]
	s_add_i32 m0, s83, 0x2000
	s_nop 0
	global_load_lds_dwordx4 v134, s[84:85]
	v_lshl_add_u64 v[220:221], s[62:63], 0, v[128:129]
	s_mov_b32 m0, s35
	s_nop 0
	global_load_lds_dwordx4 v[220:221], off
	s_mov_b32 m0, s33
	s_nop 0
	global_load_lds_dwordx4 v[222:223], off
	s_waitcnt vmcnt(8) lgkmcnt(0)
	s_barrier
	v_mfma_f32_16x16x32_bf16 v[60:63], v[152:155], v[184:187], v[60:63]
	v_mfma_f32_16x16x32_bf16 v[56:59], v[160:163], v[184:187], v[56:59]
	v_mfma_f32_16x16x32_bf16 v[52:55], v[152:155], v[196:199], v[52:55]
	v_mfma_f32_16x16x32_bf16 v[44:47], v[160:163], v[196:199], v[44:47]
	v_mfma_f32_16x16x32_bf16 v[36:39], v[152:155], v[204:207], v[36:39]
	v_mfma_f32_16x16x32_bf16 v[28:31], v[160:163], v[204:207], v[28:31]
	v_mfma_f32_16x16x32_bf16 v[20:23], v[152:155], v[212:215], v[20:23]
	v_mfma_f32_16x16x32_bf16 v[12:15], v[160:163], v[212:215], v[12:15]
	v_mfma_f32_16x16x32_bf16 v[60:63], v[156:159], v[192:195], v[60:63]
	v_mfma_f32_16x16x32_bf16 v[56:59], v[164:167], v[192:195], v[56:59]
	v_mfma_f32_16x16x32_bf16 v[52:55], v[156:159], v[200:203], v[52:55]
	v_mfma_f32_16x16x32_bf16 v[44:47], v[164:167], v[200:203], v[44:47]
	v_mfma_f32_16x16x32_bf16 v[36:39], v[156:159], v[208:211], v[36:39]
	v_mfma_f32_16x16x32_bf16 v[28:31], v[164:167], v[208:211], v[28:31]
	v_mfma_f32_16x16x32_bf16 v[20:23], v[156:159], v[216:219], v[20:23]
	v_mfma_f32_16x16x32_bf16 v[12:15], v[164:167], v[216:219], v[12:15]
	v_mfma_f32_16x16x32_bf16 v[48:51], v[168:171], v[184:187], v[48:51]
	v_mfma_f32_16x16x32_bf16 v[40:43], v[176:179], v[184:187], v[40:43]
	v_mfma_f32_16x16x32_bf16 v[32:35], v[168:171], v[196:199], v[32:35]
	v_mfma_f32_16x16x32_bf16 v[24:27], v[176:179], v[196:199], v[24:27]
	v_mfma_f32_16x16x32_bf16 v[16:19], v[168:171], v[204:207], v[16:19]
	v_mfma_f32_16x16x32_bf16 v[8:11], v[176:179], v[204:207], v[8:11]
	v_mfma_f32_16x16x32_bf16 v[4:7], v[168:171], v[212:215], v[4:7]
	v_mfma_f32_16x16x32_bf16 v[0:3], v[176:179], v[212:215], v[0:3]
	v_mfma_f32_16x16x32_bf16 v[48:51], v[172:175], v[192:195], v[48:51]
	v_mfma_f32_16x16x32_bf16 v[40:43], v[180:183], v[192:195], v[40:43]
	v_mfma_f32_16x16x32_bf16 v[32:35], v[172:175], v[200:203], v[32:35]
	v_mfma_f32_16x16x32_bf16 v[24:27], v[180:183], v[200:203], v[24:27]
	v_mfma_f32_16x16x32_bf16 v[16:19], v[172:175], v[208:211], v[16:19]
	v_mfma_f32_16x16x32_bf16 v[8:11], v[180:183], v[208:211], v[8:11]
	v_mfma_f32_16x16x32_bf16 v[4:7], v[172:175], v[216:219], v[4:7]
	v_mfma_f32_16x16x32_bf16 v[0:3], v[180:183], v[216:219], v[0:3]
	s_barrier
	s_add_i32 s83, 0, 0x18000
	s_add_i32 s84, 0, 0x1c000
	v_add_u32_e32 v164, s83, v147
	v_add_u32_e32 v180, s84, v147
	ds_read_b128 v[152:155], v164
	ds_read_b128 v[156:159], v164 offset:1024
	ds_read_b128 v[160:163], v164 offset:2048
	ds_read_b128 v[164:167], v164 offset:3072
	ds_read_b128 v[168:171], v180
	ds_read_b128 v[172:175], v180 offset:1024
	ds_read_b128 v[176:179], v180 offset:2048
	ds_read_b128 v[180:183], v180 offset:3072
	s_add_u32 s62, s62, 0x40000
	s_addc_u32 s63, s63, 0
	s_mov_b32 m0, s66
	ds_read_b128 v[184:187], v151 offset:32768
	ds_read_b128 v[192:195], v151 offset:33792
	ds_read_b128 v[196:199], v151 offset:34816
	ds_read_b128 v[200:203], v151 offset:35840
	ds_read_b128 v[204:207], v151 offset:36864
	ds_read_b128 v[208:211], v151 offset:37888
	ds_read_b128 v[212:215], v151 offset:38912
	ds_read_b128 v[216:219], v151 offset:39936
	global_load_lds_dwordx4 v128, s[62:63]
	s_mov_b32 m0, s67
	s_nop 0
	global_load_lds_dwordx4 v132, s[62:63]
	s_waitcnt vmcnt(8) lgkmcnt(0)
	s_barrier
	v_mfma_f32_16x16x32_bf16 v[124:127], v[152:155], v[184:187], v[124:127]
	v_mfma_f32_16x16x32_bf16 v[120:123], v[160:163], v[184:187], v[120:123]
	v_mfma_f32_16x16x32_bf16 v[116:119], v[152:155], v[196:199], v[116:119]
	v_mfma_f32_16x16x32_bf16 v[108:111], v[160:163], v[196:199], v[108:111]
	v_mfma_f32_16x16x32_bf16 v[100:103], v[152:155], v[204:207], v[100:103]
	v_mfma_f32_16x16x32_bf16 v[92:95], v[160:163], v[204:207], v[92:95]
	v_mfma_f32_16x16x32_bf16 v[84:87], v[152:155], v[212:215], v[84:87]
	v_mfma_f32_16x16x32_bf16 v[76:79], v[160:163], v[212:215], v[76:79]
	v_mfma_f32_16x16x32_bf16 v[124:127], v[156:159], v[192:195], v[124:127]
	v_mfma_f32_16x16x32_bf16 v[120:123], v[164:167], v[192:195], v[120:123]
	v_mfma_f32_16x16x32_bf16 v[116:119], v[156:159], v[200:203], v[116:119]
	v_mfma_f32_16x16x32_bf16 v[108:111], v[164:167], v[200:203], v[108:111]
	v_mfma_f32_16x16x32_bf16 v[100:103], v[156:159], v[208:211], v[100:103]
	v_mfma_f32_16x16x32_bf16 v[92:95], v[164:167], v[208:211], v[92:95]
	v_mfma_f32_16x16x32_bf16 v[84:87], v[156:159], v[216:219], v[84:87]
	v_mfma_f32_16x16x32_bf16 v[76:79], v[164:167], v[216:219], v[76:79]
	v_mfma_f32_16x16x32_bf16 v[112:115], v[168:171], v[184:187], v[112:115]
	v_mfma_f32_16x16x32_bf16 v[104:107], v[176:179], v[184:187], v[104:107]
	v_mfma_f32_16x16x32_bf16 v[96:99], v[168:171], v[196:199], v[96:99]
	v_mfma_f32_16x16x32_bf16 v[88:91], v[176:179], v[196:199], v[88:91]
	v_mfma_f32_16x16x32_bf16 v[80:83], v[168:171], v[204:207], v[80:83]
	v_mfma_f32_16x16x32_bf16 v[72:75], v[176:179], v[204:207], v[72:75]
	v_mfma_f32_16x16x32_bf16 v[68:71], v[168:171], v[212:215], v[68:71]
	v_mfma_f32_16x16x32_bf16 v[64:67], v[176:179], v[212:215], v[64:67]
	v_mfma_f32_16x16x32_bf16 v[112:115], v[172:175], v[192:195], v[112:115]
	v_mfma_f32_16x16x32_bf16 v[104:107], v[180:183], v[192:195], v[104:107]
	v_mfma_f32_16x16x32_bf16 v[96:99], v[172:175], v[200:203], v[96:99]
	v_mfma_f32_16x16x32_bf16 v[88:91], v[180:183], v[200:203], v[88:91]
	v_mfma_f32_16x16x32_bf16 v[80:83], v[172:175], v[208:211], v[80:83]
	v_mfma_f32_16x16x32_bf16 v[72:75], v[180:183], v[208:211], v[72:75]
	v_mfma_f32_16x16x32_bf16 v[68:71], v[172:175], v[216:219], v[68:71]
	v_mfma_f32_16x16x32_bf16 v[64:67], v[180:183], v[216:219], v[64:67]
	s_barrier
	s_add_i32 s62, s83, s65
	v_lshl_add_u64 v[144:145], v[144:145], 0, s[12:13]
	s_mov_b32 m0, s62
	ds_read_b128 v[184:187], v151 offset:49152
	ds_read_b128 v[192:195], v151 offset:50176
	ds_read_b128 v[196:199], v151 offset:51200
	ds_read_b128 v[200:203], v151 offset:52224
	ds_read_b128 v[204:207], v151 offset:53248
	ds_read_b128 v[208:211], v151 offset:54272
	ds_read_b128 v[212:215], v151 offset:55296
	ds_read_b128 v[216:219], v151 offset:56320
	global_load_lds_dwordx4 v[144:145], off
	s_add_i32 m0, s62, 0x2000
	s_add_u32 s60, s60, 0x40080
	v_lshl_add_u64 v[144:145], v[188:189], 0, s[12:13]
	s_addc_u32 s61, s61, 0
	s_add_i32 s62, s84, s65
	global_load_lds_dwordx4 v[144:145], off
	s_mov_b32 m0, s62
	s_nop 0
	global_load_lds_dwordx4 v130, s[60:61]
	s_add_i32 m0, s62, 0x2000
	s_nop 0
	global_load_lds_dwordx4 v134, s[60:61]
	v_lshl_add_u64 v[144:145], v[220:221], 0, s[12:13]
	s_mov_b32 m0, s69
	s_nop 0
	global_load_lds_dwordx4 v[144:145], off
	v_lshl_add_u64 v[144:145], v[222:223], 0, s[12:13]
	s_mov_b32 m0, s70
	s_nop 0
	global_load_lds_dwordx4 v[144:145], off
	s_waitcnt vmcnt(8) lgkmcnt(0)
	s_barrier
	v_mfma_f32_16x16x32_bf16 v[60:63], v[152:155], v[184:187], v[60:63]
	v_mfma_f32_16x16x32_bf16 v[56:59], v[160:163], v[184:187], v[56:59]
	v_mfma_f32_16x16x32_bf16 v[52:55], v[152:155], v[196:199], v[52:55]
	v_mfma_f32_16x16x32_bf16 v[44:47], v[160:163], v[196:199], v[44:47]
	v_mfma_f32_16x16x32_bf16 v[36:39], v[152:155], v[204:207], v[36:39]
	v_mfma_f32_16x16x32_bf16 v[28:31], v[160:163], v[204:207], v[28:31]
	v_mfma_f32_16x16x32_bf16 v[20:23], v[152:155], v[212:215], v[20:23]
	v_mfma_f32_16x16x32_bf16 v[12:15], v[160:163], v[212:215], v[12:15]
	v_mfma_f32_16x16x32_bf16 v[60:63], v[156:159], v[192:195], v[60:63]
	v_mfma_f32_16x16x32_bf16 v[56:59], v[164:167], v[192:195], v[56:59]
	v_mfma_f32_16x16x32_bf16 v[52:55], v[156:159], v[200:203], v[52:55]
	v_mfma_f32_16x16x32_bf16 v[44:47], v[164:167], v[200:203], v[44:47]
	v_mfma_f32_16x16x32_bf16 v[36:39], v[156:159], v[208:211], v[36:39]
	v_mfma_f32_16x16x32_bf16 v[28:31], v[164:167], v[208:211], v[28:31]
	v_mfma_f32_16x16x32_bf16 v[20:23], v[156:159], v[216:219], v[20:23]
	v_mfma_f32_16x16x32_bf16 v[12:15], v[164:167], v[216:219], v[12:15]
	v_mfma_f32_16x16x32_bf16 v[48:51], v[168:171], v[184:187], v[48:51]
	v_mfma_f32_16x16x32_bf16 v[40:43], v[176:179], v[184:187], v[40:43]
	v_mfma_f32_16x16x32_bf16 v[32:35], v[168:171], v[196:199], v[32:35]
	v_mfma_f32_16x16x32_bf16 v[24:27], v[176:179], v[196:199], v[24:27]
	v_mfma_f32_16x16x32_bf16 v[16:19], v[168:171], v[204:207], v[16:19]
	v_mfma_f32_16x16x32_bf16 v[8:11], v[176:179], v[204:207], v[8:11]
	v_mfma_f32_16x16x32_bf16 v[4:7], v[168:171], v[212:215], v[4:7]
	v_mfma_f32_16x16x32_bf16 v[0:3], v[176:179], v[212:215], v[0:3]
	v_mfma_f32_16x16x32_bf16 v[48:51], v[172:175], v[192:195], v[48:51]
	v_mfma_f32_16x16x32_bf16 v[40:43], v[180:183], v[192:195], v[40:43]
	v_mfma_f32_16x16x32_bf16 v[32:35], v[172:175], v[200:203], v[32:35]
	v_mfma_f32_16x16x32_bf16 v[24:27], v[180:183], v[200:203], v[24:27]
	v_mfma_f32_16x16x32_bf16 v[16:19], v[172:175], v[208:211], v[16:19]
	v_mfma_f32_16x16x32_bf16 v[8:11], v[180:183], v[208:211], v[8:11]
	v_mfma_f32_16x16x32_bf16 v[4:7], v[172:175], v[216:219], v[4:7]
	v_mfma_f32_16x16x32_bf16 v[0:3], v[180:183], v[216:219], v[0:3]
	s_barrier
	s_add_i32 s82, s82, 2
	s_add_u32 s42, s42, 0x100
	s_addc_u32 s43, s43, 0
	s_add_u32 s80, s80, 0x100
	s_addc_u32 s81, s81, 0
	s_cmp_gt_u32 s82, 13
	s_cbranch_scc0 .LBB0_1053

.LBB0_1076:
	s_ashr_i32 s27, s26, 31
	s_lshl_b64 s[28:29], s[26:27], 19
	s_add_u32 s28, s40, s28
	s_addc_u32 s29, s41, s29
	s_and_b64 s[30:31], s[4:5], exec
	s_cselect_b32 s27, s29, s43
	s_cselect_b32 s55, s28, s42
	s_ashr_i32 s25, s24, 31
	s_lshl_b64 s[30:31], s[24:25], 19
	s_add_u32 s30, s53, s30
	s_addc_u32 s31, s64, s31
	s_and_b64 s[62:63], s[4:5], exec
	s_cselect_b32 s25, s31, s61
	s_cselect_b32 s79, s30, s60
	s_add_u32 s42, s42, 0x40080
	s_addc_u32 s43, s43, 0
	s_add_u32 s80, s60, 0x100
	s_addc_u32 s81, s61, 0
	s_mov_b32 s82, -2
	ds_read_b128 v[152:155], v149
	ds_read_b128 v[156:159], v149 offset:1024
	ds_read_b128 v[160:163], v149 offset:2048
	ds_read_b128 v[164:167], v149 offset:3072
	ds_read_b128 v[168:171], v150
	ds_read_b128 v[172:175], v150 offset:1024
	ds_read_b128 v[176:179], v150 offset:2048
	ds_read_b128 v[180:183], v150 offset:3072
	s_add_u32 s60, s42, 0xfffc0080
	s_addc_u32 s61, s43, -1
	s_cmp_eq_u32 s82, 12
	s_cselect_b32 s63, s27, s61
	s_cselect_b32 s62, s55, s60
	s_cselect_b32 s61, s25, s81
	s_cselect_b32 s60, s79, s80
	s_add_i32 m0, s35, 0xc000
	ds_read_b128 v[184:187], v151
	ds_read_b128 v[192:195], v151 offset:1024
	ds_read_b128 v[196:199], v151 offset:2048
	ds_read_b128 v[200:203], v151 offset:3072
	ds_read_b128 v[204:207], v151 offset:4096
	ds_read_b128 v[208:211], v151 offset:5120
	ds_read_b128 v[212:215], v151 offset:6144
	ds_read_b128 v[216:219], v151 offset:7168
	global_load_lds_dwordx4 v136, s[42:43]
	s_add_i32 m0, s35, 0xe000
	s_nop 0
	global_load_lds_dwordx4 v138, s[42:43]
	s_waitcnt vmcnt(8) lgkmcnt(0)
	s_barrier
	v_mfma_f32_16x16x32_bf16 v[124:127], v[152:155], v[184:187], 0
	v_mfma_f32_16x16x32_bf16 v[120:123], v[160:163], v[184:187], 0
	v_mfma_f32_16x16x32_bf16 v[116:119], v[152:155], v[196:199], 0
	v_mfma_f32_16x16x32_bf16 v[108:111], v[160:163], v[196:199], 0
	v_mfma_f32_16x16x32_bf16 v[100:103], v[152:155], v[204:207], 0
	v_mfma_f32_16x16x32_bf16 v[92:95], v[160:163], v[204:207], 0
	v_mfma_f32_16x16x32_bf16 v[84:87], v[152:155], v[212:215], 0
	v_mfma_f32_16x16x32_bf16 v[76:79], v[160:163], v[212:215], 0
	v_mfma_f32_16x16x32_bf16 v[124:127], v[156:159], v[192:195], v[124:127]
	v_mfma_f32_16x16x32_bf16 v[120:123], v[164:167], v[192:195], v[120:123]
	v_mfma_f32_16x16x32_bf16 v[116:119], v[156:159], v[200:203], v[116:119]
	v_mfma_f32_16x16x32_bf16 v[108:111], v[164:167], v[200:203], v[108:111]
	v_mfma_f32_16x16x32_bf16 v[100:103], v[156:159], v[208:211], v[100:103]
	v_mfma_f32_16x16x32_bf16 v[92:95], v[164:167], v[208:211], v[92:95]
	v_mfma_f32_16x16x32_bf16 v[84:87], v[156:159], v[216:219], v[84:87]
	v_mfma_f32_16x16x32_bf16 v[76:79], v[164:167], v[216:219], v[76:79]
	v_mfma_f32_16x16x32_bf16 v[112:115], v[168:171], v[184:187], 0
	v_mfma_f32_16x16x32_bf16 v[104:107], v[176:179], v[184:187], 0
	v_mfma_f32_16x16x32_bf16 v[96:99], v[168:171], v[196:199], 0
	v_mfma_f32_16x16x32_bf16 v[88:91], v[176:179], v[196:199], 0
	v_mfma_f32_16x16x32_bf16 v[80:83], v[168:171], v[204:207], 0
	v_mfma_f32_16x16x32_bf16 v[72:75], v[176:179], v[204:207], 0
	v_mfma_f32_16x16x32_bf16 v[68:71], v[168:171], v[212:215], 0
	v_mfma_f32_16x16x32_bf16 v[64:67], v[176:179], v[212:215], 0
	v_mfma_f32_16x16x32_bf16 v[112:115], v[172:175], v[192:195], v[112:115]
	v_mfma_f32_16x16x32_bf16 v[104:107], v[180:183], v[192:195], v[104:107]
	v_mfma_f32_16x16x32_bf16 v[96:99], v[172:175], v[200:203], v[96:99]
	v_mfma_f32_16x16x32_bf16 v[88:91], v[180:183], v[200:203], v[88:91]
	v_mfma_f32_16x16x32_bf16 v[80:83], v[172:175], v[208:211], v[80:83]
	v_mfma_f32_16x16x32_bf16 v[72:75], v[180:183], v[208:211], v[72:75]
	v_mfma_f32_16x16x32_bf16 v[68:71], v[172:175], v[216:219], v[68:71]
	v_mfma_f32_16x16x32_bf16 v[64:67], v[180:183], v[216:219], v[64:67]
	s_barrier
	s_add_i32 s83, s72, s65
	v_lshl_add_u64 v[144:145], s[60:61], 0, v[130:131]
	s_mov_b32 m0, s83
	ds_read_b128 v[184:187], v151 offset:16384
	ds_read_b128 v[192:195], v151 offset:17408
	ds_read_b128 v[196:199], v151 offset:18432
	ds_read_b128 v[200:203], v151 offset:19456
	ds_read_b128 v[204:207], v151 offset:20480
	ds_read_b128 v[208:211], v151 offset:21504
	ds_read_b128 v[212:215], v151 offset:22528
	ds_read_b128 v[216:219], v151 offset:23552
	global_load_lds_dwordx4 v[144:145], off
	s_add_i32 m0, s83, 0x2000
	s_add_u32 s84, s60, 0x40000
	v_lshl_add_u64 v[188:189], s[60:61], 0, v[134:135]
	s_addc_u32 s85, s61, 0
	s_add_i32 s83, s73, s65
	global_load_lds_dwordx4 v[188:189], off
	s_mov_b32 m0, s83
	v_lshl_add_u64 v[222:223], s[62:63], 0, v[132:133]
	global_load_lds_dwordx4 v130, s[84:85]
	s_add_i32 m0, s83, 0x2000
	s_nop 0
	global_load_lds_dwordx4 v134, s[84:85]
	v_lshl_add_u64 v[220:221], s[62:63], 0, v[128:129]
	s_mov_b32 m0, s35
	s_nop 0
	global_load_lds_dwordx4 v[220:221], off
	s_mov_b32 m0, s33
	s_nop 0
	global_load_lds_dwordx4 v[222:223], off
	s_waitcnt vmcnt(8) lgkmcnt(0)
	s_barrier
	v_mfma_f32_16x16x32_bf16 v[60:63], v[152:155], v[184:187], 0
	v_mfma_f32_16x16x32_bf16 v[56:59], v[160:163], v[184:187], 0
	v_mfma_f32_16x16x32_bf16 v[52:55], v[152:155], v[196:199], 0
	v_mfma_f32_16x16x32_bf16 v[44:47], v[160:163], v[196:199], 0
	v_mfma_f32_16x16x32_bf16 v[36:39], v[152:155], v[204:207], 0
	v_mfma_f32_16x16x32_bf16 v[28:31], v[160:163], v[204:207], 0
	v_mfma_f32_16x16x32_bf16 v[20:23], v[152:155], v[212:215], 0
	v_mfma_f32_16x16x32_bf16 v[12:15], v[160:163], v[212:215], 0
	v_mfma_f32_16x16x32_bf16 v[60:63], v[156:159], v[192:195], v[60:63]
	v_mfma_f32_16x16x32_bf16 v[56:59], v[164:167], v[192:195], v[56:59]
	v_mfma_f32_16x16x32_bf16 v[52:55], v[156:159], v[200:203], v[52:55]
	v_mfma_f32_16x16x32_bf16 v[44:47], v[164:167], v[200:203], v[44:47]
	v_mfma_f32_16x16x32_bf16 v[36:39], v[156:159], v[208:211], v[36:39]
	v_mfma_f32_16x16x32_bf16 v[28:31], v[164:167], v[208:211], v[28:31]
	v_mfma_f32_16x16x32_bf16 v[20:23], v[156:159], v[216:219], v[20:23]
	v_mfma_f32_16x16x32_bf16 v[12:15], v[164:167], v[216:219], v[12:15]
	v_mfma_f32_16x16x32_bf16 v[48:51], v[168:171], v[184:187], 0
	v_mfma_f32_16x16x32_bf16 v[40:43], v[176:179], v[184:187], 0
	v_mfma_f32_16x16x32_bf16 v[32:35], v[168:171], v[196:199], 0
	v_mfma_f32_16x16x32_bf16 v[24:27], v[176:179], v[196:199], 0
	v_mfma_f32_16x16x32_bf16 v[16:19], v[168:171], v[204:207], 0
	v_mfma_f32_16x16x32_bf16 v[8:11], v[176:179], v[204:207], 0
	v_mfma_f32_16x16x32_bf16 v[4:7], v[168:171], v[212:215], 0
	v_mfma_f32_16x16x32_bf16 v[0:3], v[176:179], v[212:215], 0
	v_mfma_f32_16x16x32_bf16 v[48:51], v[172:175], v[192:195], v[48:51]
	v_mfma_f32_16x16x32_bf16 v[40:43], v[180:183], v[192:195], v[40:43]
	v_mfma_f32_16x16x32_bf16 v[32:35], v[172:175], v[200:203], v[32:35]
	v_mfma_f32_16x16x32_bf16 v[24:27], v[180:183], v[200:203], v[24:27]
	v_mfma_f32_16x16x32_bf16 v[16:19], v[172:175], v[208:211], v[16:19]
	v_mfma_f32_16x16x32_bf16 v[8:11], v[180:183], v[208:211], v[8:11]
	v_mfma_f32_16x16x32_bf16 v[4:7], v[172:175], v[216:219], v[4:7]
	v_mfma_f32_16x16x32_bf16 v[0:3], v[180:183], v[216:219], v[0:3]
	s_barrier
	s_add_i32 s83, 0, 0x18000
	s_add_i32 s84, 0, 0x1c000
	v_add_u32_e32 v164, s83, v147
	v_add_u32_e32 v180, s84, v147
	ds_read_b128 v[152:155], v164
	ds_read_b128 v[156:159], v164 offset:1024
	ds_read_b128 v[160:163], v164 offset:2048
	ds_read_b128 v[164:167], v164 offset:3072
	ds_read_b128 v[168:171], v180
	ds_read_b128 v[172:175], v180 offset:1024
	ds_read_b128 v[176:179], v180 offset:2048
	ds_read_b128 v[180:183], v180 offset:3072
	s_add_u32 s62, s62, 0x40000
	s_addc_u32 s63, s63, 0
	s_mov_b32 m0, s66
	ds_read_b128 v[184:187], v151 offset:32768
	ds_read_b128 v[192:195], v151 offset:33792
	ds_read_b128 v[196:199], v151 offset:34816
	ds_read_b128 v[200:203], v151 offset:35840
	ds_read_b128 v[204:207], v151 offset:36864
	ds_read_b128 v[208:211], v151 offset:37888
	ds_read_b128 v[212:215], v151 offset:38912
	ds_read_b128 v[216:219], v151 offset:39936
	global_load_lds_dwordx4 v128, s[62:63]
	s_mov_b32 m0, s67
	s_nop 0
	global_load_lds_dwordx4 v132, s[62:63]
	s_waitcnt vmcnt(8) lgkmcnt(0)
	s_barrier
	v_mfma_f32_16x16x32_bf16 v[124:127], v[152:155], v[184:187], v[124:127]
	v_mfma_f32_16x16x32_bf16 v[120:123], v[160:163], v[184:187], v[120:123]
	v_mfma_f32_16x16x32_bf16 v[116:119], v[152:155], v[196:199], v[116:119]
	v_mfma_f32_16x16x32_bf16 v[108:111], v[160:163], v[196:199], v[108:111]
	v_mfma_f32_16x16x32_bf16 v[100:103], v[152:155], v[204:207], v[100:103]
	v_mfma_f32_16x16x32_bf16 v[92:95], v[160:163], v[204:207], v[92:95]
	v_mfma_f32_16x16x32_bf16 v[84:87], v[152:155], v[212:215], v[84:87]
	v_mfma_f32_16x16x32_bf16 v[76:79], v[160:163], v[212:215], v[76:79]
	v_mfma_f32_16x16x32_bf16 v[124:127], v[156:159], v[192:195], v[124:127]
	v_mfma_f32_16x16x32_bf16 v[120:123], v[164:167], v[192:195], v[120:123]
	v_mfma_f32_16x16x32_bf16 v[116:119], v[156:159], v[200:203], v[116:119]
	v_mfma_f32_16x16x32_bf16 v[108:111], v[164:167], v[200:203], v[108:111]
	v_mfma_f32_16x16x32_bf16 v[100:103], v[156:159], v[208:211], v[100:103]
	v_mfma_f32_16x16x32_bf16 v[92:95], v[164:167], v[208:211], v[92:95]
	v_mfma_f32_16x16x32_bf16 v[84:87], v[156:159], v[216:219], v[84:87]
	v_mfma_f32_16x16x32_bf16 v[76:79], v[164:167], v[216:219], v[76:79]
	v_mfma_f32_16x16x32_bf16 v[112:115], v[168:171], v[184:187], v[112:115]
	v_mfma_f32_16x16x32_bf16 v[104:107], v[176:179], v[184:187], v[104:107]
	v_mfma_f32_16x16x32_bf16 v[96:99], v[168:171], v[196:199], v[96:99]
	v_mfma_f32_16x16x32_bf16 v[88:91], v[176:179], v[196:199], v[88:91]
	v_mfma_f32_16x16x32_bf16 v[80:83], v[168:171], v[204:207], v[80:83]
	v_mfma_f32_16x16x32_bf16 v[72:75], v[176:179], v[204:207], v[72:75]
	v_mfma_f32_16x16x32_bf16 v[68:71], v[168:171], v[212:215], v[68:71]
	v_mfma_f32_16x16x32_bf16 v[64:67], v[176:179], v[212:215], v[64:67]
	v_mfma_f32_16x16x32_bf16 v[112:115], v[172:175], v[192:195], v[112:115]
	v_mfma_f32_16x16x32_bf16 v[104:107], v[180:183], v[192:195], v[104:107]
	v_mfma_f32_16x16x32_bf16 v[96:99], v[172:175], v[200:203], v[96:99]
	v_mfma_f32_16x16x32_bf16 v[88:91], v[180:183], v[200:203], v[88:91]
	v_mfma_f32_16x16x32_bf16 v[80:83], v[172:175], v[208:211], v[80:83]
	v_mfma_f32_16x16x32_bf16 v[72:75], v[180:183], v[208:211], v[72:75]
	v_mfma_f32_16x16x32_bf16 v[68:71], v[172:175], v[216:219], v[68:71]
	v_mfma_f32_16x16x32_bf16 v[64:67], v[180:183], v[216:219], v[64:67]
	s_barrier
	s_add_i32 s62, s83, s65
	v_lshl_add_u64 v[144:145], v[144:145], 0, s[12:13]
	s_mov_b32 m0, s62
	ds_read_b128 v[184:187], v151 offset:49152
	ds_read_b128 v[192:195], v151 offset:50176
	ds_read_b128 v[196:199], v151 offset:51200
	ds_read_b128 v[200:203], v151 offset:52224
	ds_read_b128 v[204:207], v151 offset:53248
	ds_read_b128 v[208:211], v151 offset:54272
	ds_read_b128 v[212:215], v151 offset:55296
	ds_read_b128 v[216:219], v151 offset:56320
	global_load_lds_dwordx4 v[144:145], off
	s_add_i32 m0, s62, 0x2000
	s_add_u32 s60, s60, 0x40080
	v_lshl_add_u64 v[144:145], v[188:189], 0, s[12:13]
	s_addc_u32 s61, s61, 0
	s_add_i32 s62, s84, s65
	global_load_lds_dwordx4 v[144:145], off
	s_mov_b32 m0, s62
	s_nop 0
	global_load_lds_dwordx4 v130, s[60:61]
	s_add_i32 m0, s62, 0x2000
	s_nop 0
	global_load_lds_dwordx4 v134, s[60:61]
	v_lshl_add_u64 v[144:145], v[220:221], 0, s[12:13]
	s_mov_b32 m0, s69
	s_nop 0
	global_load_lds_dwordx4 v[144:145], off
	v_lshl_add_u64 v[144:145], v[222:223], 0, s[12:13]
	s_mov_b32 m0, s70
	s_nop 0
	global_load_lds_dwordx4 v[144:145], off
	s_waitcnt vmcnt(8) lgkmcnt(0)
	s_barrier
	v_mfma_f32_16x16x32_bf16 v[60:63], v[152:155], v[184:187], v[60:63]
	v_mfma_f32_16x16x32_bf16 v[56:59], v[160:163], v[184:187], v[56:59]
	v_mfma_f32_16x16x32_bf16 v[52:55], v[152:155], v[196:199], v[52:55]
	v_mfma_f32_16x16x32_bf16 v[44:47], v[160:163], v[196:199], v[44:47]
	v_mfma_f32_16x16x32_bf16 v[36:39], v[152:155], v[204:207], v[36:39]
	v_mfma_f32_16x16x32_bf16 v[28:31], v[160:163], v[204:207], v[28:31]
	v_mfma_f32_16x16x32_bf16 v[20:23], v[152:155], v[212:215], v[20:23]
	v_mfma_f32_16x16x32_bf16 v[12:15], v[160:163], v[212:215], v[12:15]
	v_mfma_f32_16x16x32_bf16 v[60:63], v[156:159], v[192:195], v[60:63]
	v_mfma_f32_16x16x32_bf16 v[56:59], v[164:167], v[192:195], v[56:59]
	v_mfma_f32_16x16x32_bf16 v[52:55], v[156:159], v[200:203], v[52:55]
	v_mfma_f32_16x16x32_bf16 v[44:47], v[164:167], v[200:203], v[44:47]
	v_mfma_f32_16x16x32_bf16 v[36:39], v[156:159], v[208:211], v[36:39]
	v_mfma_f32_16x16x32_bf16 v[28:31], v[164:167], v[208:211], v[28:31]
	v_mfma_f32_16x16x32_bf16 v[20:23], v[156:159], v[216:219], v[20:23]
	v_mfma_f32_16x16x32_bf16 v[12:15], v[164:167], v[216:219], v[12:15]
	v_mfma_f32_16x16x32_bf16 v[48:51], v[168:171], v[184:187], v[48:51]
	v_mfma_f32_16x16x32_bf16 v[40:43], v[176:179], v[184:187], v[40:43]
	v_mfma_f32_16x16x32_bf16 v[32:35], v[168:171], v[196:199], v[32:35]
	v_mfma_f32_16x16x32_bf16 v[24:27], v[176:179], v[196:199], v[24:27]
	v_mfma_f32_16x16x32_bf16 v[16:19], v[168:171], v[204:207], v[16:19]
	v_mfma_f32_16x16x32_bf16 v[8:11], v[176:179], v[204:207], v[8:11]
	v_mfma_f32_16x16x32_bf16 v[4:7], v[168:171], v[212:215], v[4:7]
	v_mfma_f32_16x16x32_bf16 v[0:3], v[176:179], v[212:215], v[0:3]
	v_mfma_f32_16x16x32_bf16 v[48:51], v[172:175], v[192:195], v[48:51]
	v_mfma_f32_16x16x32_bf16 v[40:43], v[180:183], v[192:195], v[40:43]
	v_mfma_f32_16x16x32_bf16 v[32:35], v[172:175], v[200:203], v[32:35]
	v_mfma_f32_16x16x32_bf16 v[24:27], v[180:183], v[200:203], v[24:27]
	v_mfma_f32_16x16x32_bf16 v[16:19], v[172:175], v[208:211], v[16:19]
	v_mfma_f32_16x16x32_bf16 v[8:11], v[180:183], v[208:211], v[8:11]
	v_mfma_f32_16x16x32_bf16 v[4:7], v[172:175], v[216:219], v[4:7]
	v_mfma_f32_16x16x32_bf16 v[0:3], v[180:183], v[216:219], v[0:3]
	s_barrier
	s_add_i32 s82, s82, 2
	s_add_u32 s42, s42, 0x100
	s_addc_u32 s43, s43, 0
	s_add_u32 s80, s80, 0x100
	s_addc_u32 s81, s81, 0
	s_cmp_gt_u32 s82, 13
	s_cbranch_scc0 .LBB0_1077
	s_branch .Lpeel_exit6

.LBB0_1221:
	s_ashr_i32 s21, s20, 31
	s_lshl_b64 s[22:23], s[20:21], 17
	s_add_u32 s22, s70, s22
	s_addc_u32 s23, s71, s23
	s_and_b64 s[24:25], s[0:1], exec
	s_cselect_b32 s21, s23, s31
	s_cselect_b32 s55, s22, s30
	s_ashr_i32 s19, s18, 31
	s_lshl_b64 s[24:25], s[18:19], 17
	s_add_u32 s24, s53, s24
	s_addc_u32 s25, s72, s25
	s_and_b64 s[34:35], s[0:1], exec
	s_cselect_b32 s19, s25, s29
	s_cselect_b32 s85, s24, s28
	s_mov_b32 s60, 0
	s_mov_b64 s[34:35], -1
	s_mov_b64 s[42:43], 0
	s_add_u32 s61, s30, s60
	s_addc_u32 s66, s31, 0
	s_add_u32 s64, s61, 0x100
	s_addc_u32 s65, s66, 0
	s_and_b64 s[62:63], s[42:43], exec
	s_cselect_b32 s63, s21, s65
	s_cselect_b32 s62, s55, s64
	s_add_u32 s60, s28, s60
	s_addc_u32 s64, s29, 0
	s_add_u32 s60, s60, 0x100
	s_addc_u32 s64, s64, 0
	s_and_b64 s[42:43], s[42:43], exec
	s_cselect_b32 s65, s19, s64
	s_cselect_b32 s64, s85, s60
	s_add_u32 s68, s61, 0x10080
	ds_read_b128 v[148:151], v145
	ds_read_b128 v[152:155], v145 offset:1024
	ds_read_b128 v[156:159], v145 offset:2048
	ds_read_b128 v[160:163], v145 offset:3072
	ds_read_b128 v[164:167], v146
	ds_read_b128 v[168:171], v146 offset:1024
	ds_read_b128 v[172:175], v146 offset:2048
	ds_read_b128 v[176:179], v146 offset:3072
	s_addc_u32 s69, s66, 0
	s_add_i32 s95, s81, s73
	s_add_i32 m0, s27, 0xc000
	s_add_i32 s96, s27, 0xe000
	s_add_i32 s92, s95, 0x2000
	s_add_u32 s66, s64, 0x10000
	s_addc_u32 s67, s65, 0
	s_add_i32 s94, s82, s73
	s_add_i32 s93, s94, 0x2000
	s_add_i32 s91, 0, 0x18000
	s_add_i32 s90, 0, 0x1c000
	s_add_u32 s60, s62, 0x10000
	s_addc_u32 s61, s63, 0
	s_add_i32 s89, s91, s73
	s_add_i32 s87, s89, 0x2000
	s_add_u32 s42, s64, 0x10080
	s_addc_u32 s43, s65, 0
	s_add_i32 s88, s90, s73
	s_add_i32 s86, s88, 0x2000
	ds_read_b128 v[180:183], v147
	ds_read_b128 v[184:187], v147 offset:1024
	ds_read_b128 v[192:195], v147 offset:2048
	ds_read_b128 v[196:199], v147 offset:3072
	ds_read_b128 v[200:203], v147 offset:4096
	ds_read_b128 v[204:207], v147 offset:5120
	ds_read_b128 v[208:211], v147 offset:6144
	ds_read_b128 v[212:215], v147 offset:7168
	global_load_lds_dwordx4 v128, s[68:69]
	s_mov_b32 m0, s96
	s_nop 0
	global_load_lds_dwordx4 v132, s[68:69]
	s_waitcnt vmcnt(8) lgkmcnt(0)
	s_barrier
	v_mfma_f32_16x16x32_bf16 v[124:127], v[148:151], v[180:183], 0
	v_mfma_f32_16x16x32_bf16 v[120:123], v[156:159], v[180:183], 0
	v_mfma_f32_16x16x32_bf16 v[116:119], v[148:151], v[192:195], 0
	v_mfma_f32_16x16x32_bf16 v[108:111], v[156:159], v[192:195], 0
	v_mfma_f32_16x16x32_bf16 v[100:103], v[148:151], v[200:203], 0
	v_mfma_f32_16x16x32_bf16 v[92:95], v[156:159], v[200:203], 0
	v_mfma_f32_16x16x32_bf16 v[84:87], v[148:151], v[208:211], 0
	v_mfma_f32_16x16x32_bf16 v[76:79], v[156:159], v[208:211], 0
	v_mfma_f32_16x16x32_bf16 v[124:127], v[152:155], v[184:187], v[124:127]
	v_mfma_f32_16x16x32_bf16 v[120:123], v[160:163], v[184:187], v[120:123]
	v_mfma_f32_16x16x32_bf16 v[116:119], v[152:155], v[196:199], v[116:119]
	v_mfma_f32_16x16x32_bf16 v[108:111], v[160:163], v[196:199], v[108:111]
	v_mfma_f32_16x16x32_bf16 v[100:103], v[152:155], v[204:207], v[100:103]
	v_mfma_f32_16x16x32_bf16 v[92:95], v[160:163], v[204:207], v[92:95]
	v_mfma_f32_16x16x32_bf16 v[84:87], v[152:155], v[212:215], v[84:87]
	v_mfma_f32_16x16x32_bf16 v[76:79], v[160:163], v[212:215], v[76:79]
	v_mfma_f32_16x16x32_bf16 v[112:115], v[164:167], v[180:183], 0
	v_mfma_f32_16x16x32_bf16 v[104:107], v[172:175], v[180:183], 0
	v_mfma_f32_16x16x32_bf16 v[96:99], v[164:167], v[192:195], 0
	v_mfma_f32_16x16x32_bf16 v[88:91], v[172:175], v[192:195], 0
	v_mfma_f32_16x16x32_bf16 v[80:83], v[164:167], v[200:203], 0
	v_mfma_f32_16x16x32_bf16 v[72:75], v[172:175], v[200:203], 0
	v_mfma_f32_16x16x32_bf16 v[68:71], v[164:167], v[208:211], 0
	v_mfma_f32_16x16x32_bf16 v[64:67], v[172:175], v[208:211], 0
	v_mfma_f32_16x16x32_bf16 v[112:115], v[168:171], v[184:187], v[112:115]
	v_mfma_f32_16x16x32_bf16 v[104:107], v[176:179], v[184:187], v[104:107]
	v_mfma_f32_16x16x32_bf16 v[96:99], v[168:171], v[196:199], v[96:99]
	v_mfma_f32_16x16x32_bf16 v[88:91], v[176:179], v[196:199], v[88:91]
	v_mfma_f32_16x16x32_bf16 v[80:83], v[168:171], v[204:207], v[80:83]
	v_mfma_f32_16x16x32_bf16 v[72:75], v[176:179], v[204:207], v[72:75]
	v_mfma_f32_16x16x32_bf16 v[68:71], v[168:171], v[212:215], v[68:71]
	v_mfma_f32_16x16x32_bf16 v[64:67], v[176:179], v[212:215], v[64:67]
	s_barrier
	s_mov_b32 m0, s95
	v_lshl_add_u64 v[140:141], s[64:65], 0, v[130:131]
	ds_read_b128 v[180:183], v147 offset:16384
	ds_read_b128 v[184:187], v147 offset:17408
	ds_read_b128 v[192:195], v147 offset:18432
	ds_read_b128 v[196:199], v147 offset:19456
	ds_read_b128 v[200:203], v147 offset:20480
	ds_read_b128 v[204:207], v147 offset:21504
	ds_read_b128 v[208:211], v147 offset:22528
	ds_read_b128 v[212:215], v147 offset:23552
	global_load_lds_dwordx4 v[140:141], off
	v_lshl_add_u64 v[188:189], s[64:65], 0, v[134:135]
	s_mov_b32 m0, s92
	s_nop 0
	global_load_lds_dwordx4 v[188:189], off
	s_mov_b32 m0, s94
	v_lshl_add_u64 v[218:219], s[62:63], 0, v[132:133]
	global_load_lds_dwordx4 v130, s[66:67]
	s_mov_b32 m0, s93
	s_nop 0
	global_load_lds_dwordx4 v134, s[66:67]
	v_lshl_add_u64 v[216:217], s[62:63], 0, v[128:129]
	s_mov_b32 m0, s27
	s_nop 0
	global_load_lds_dwordx4 v[216:217], off
	s_mov_b32 m0, s33
	s_nop 0
	global_load_lds_dwordx4 v[218:219], off
	s_waitcnt vmcnt(8) lgkmcnt(0)
	s_barrier
	v_mfma_f32_16x16x32_bf16 v[60:63], v[148:151], v[180:183], 0
	v_mfma_f32_16x16x32_bf16 v[56:59], v[156:159], v[180:183], 0
	v_mfma_f32_16x16x32_bf16 v[52:55], v[148:151], v[192:195], 0
	v_mfma_f32_16x16x32_bf16 v[44:47], v[156:159], v[192:195], 0
	v_mfma_f32_16x16x32_bf16 v[36:39], v[148:151], v[200:203], 0
	v_mfma_f32_16x16x32_bf16 v[28:31], v[156:159], v[200:203], 0
	v_mfma_f32_16x16x32_bf16 v[20:23], v[148:151], v[208:211], 0
	v_mfma_f32_16x16x32_bf16 v[12:15], v[156:159], v[208:211], 0
	v_mfma_f32_16x16x32_bf16 v[60:63], v[152:155], v[184:187], v[60:63]
	v_mfma_f32_16x16x32_bf16 v[56:59], v[160:163], v[184:187], v[56:59]
	v_mfma_f32_16x16x32_bf16 v[52:55], v[152:155], v[196:199], v[52:55]
	v_mfma_f32_16x16x32_bf16 v[44:47], v[160:163], v[196:199], v[44:47]
	v_mfma_f32_16x16x32_bf16 v[36:39], v[152:155], v[204:207], v[36:39]
	v_mfma_f32_16x16x32_bf16 v[28:31], v[160:163], v[204:207], v[28:31]
	v_mfma_f32_16x16x32_bf16 v[20:23], v[152:155], v[212:215], v[20:23]
	v_mfma_f32_16x16x32_bf16 v[12:15], v[160:163], v[212:215], v[12:15]
	v_mfma_f32_16x16x32_bf16 v[48:51], v[164:167], v[180:183], 0
	v_mfma_f32_16x16x32_bf16 v[40:43], v[172:175], v[180:183], 0
	v_mfma_f32_16x16x32_bf16 v[32:35], v[164:167], v[192:195], 0
	v_mfma_f32_16x16x32_bf16 v[24:27], v[172:175], v[192:195], 0
	v_mfma_f32_16x16x32_bf16 v[16:19], v[164:167], v[200:203], 0
	v_mfma_f32_16x16x32_bf16 v[8:11], v[172:175], v[200:203], 0
	v_mfma_f32_16x16x32_bf16 v[4:7], v[164:167], v[208:211], 0
	v_mfma_f32_16x16x32_bf16 v[0:3], v[172:175], v[208:211], 0
	v_mfma_f32_16x16x32_bf16 v[48:51], v[168:171], v[184:187], v[48:51]
	v_mfma_f32_16x16x32_bf16 v[40:43], v[176:179], v[184:187], v[40:43]
	v_mfma_f32_16x16x32_bf16 v[32:35], v[168:171], v[196:199], v[32:35]
	v_mfma_f32_16x16x32_bf16 v[24:27], v[176:179], v[196:199], v[24:27]
	v_mfma_f32_16x16x32_bf16 v[16:19], v[168:171], v[204:207], v[16:19]
	v_mfma_f32_16x16x32_bf16 v[8:11], v[176:179], v[204:207], v[8:11]
	v_mfma_f32_16x16x32_bf16 v[4:7], v[168:171], v[212:215], v[4:7]
	v_mfma_f32_16x16x32_bf16 v[0:3], v[176:179], v[212:215], v[0:3]
	s_barrier
	v_add_u32_e32 v160, s91, v143
	v_add_u32_e32 v176, s90, v143
	ds_read_b128 v[148:151], v160
	ds_read_b128 v[152:155], v160 offset:1024
	ds_read_b128 v[156:159], v160 offset:2048
	ds_read_b128 v[160:163], v160 offset:3072
	ds_read_b128 v[164:167], v176
	ds_read_b128 v[168:171], v176 offset:1024
	ds_read_b128 v[172:175], v176 offset:2048
	ds_read_b128 v[176:179], v176 offset:3072
	s_mov_b32 m0, s74
	ds_read_b128 v[180:183], v147 offset:32768
	ds_read_b128 v[184:187], v147 offset:33792
	ds_read_b128 v[192:195], v147 offset:34816
	ds_read_b128 v[196:199], v147 offset:35840
	ds_read_b128 v[200:203], v147 offset:36864
	ds_read_b128 v[204:207], v147 offset:37888
	ds_read_b128 v[208:211], v147 offset:38912
	ds_read_b128 v[212:215], v147 offset:39936
	global_load_lds_dwordx4 v128, s[60:61]
	s_mov_b32 m0, s75
	s_nop 0
	global_load_lds_dwordx4 v132, s[60:61]
	s_waitcnt vmcnt(8) lgkmcnt(0)
	s_barrier
	v_mfma_f32_16x16x32_bf16 v[124:127], v[148:151], v[180:183], v[124:127]
	v_mfma_f32_16x16x32_bf16 v[120:123], v[156:159], v[180:183], v[120:123]
	v_mfma_f32_16x16x32_bf16 v[116:119], v[148:151], v[192:195], v[116:119]
	v_mfma_f32_16x16x32_bf16 v[108:111], v[156:159], v[192:195], v[108:111]
	v_mfma_f32_16x16x32_bf16 v[100:103], v[148:151], v[200:203], v[100:103]
	v_mfma_f32_16x16x32_bf16 v[92:95], v[156:159], v[200:203], v[92:95]
	v_mfma_f32_16x16x32_bf16 v[84:87], v[148:151], v[208:211], v[84:87]
	v_mfma_f32_16x16x32_bf16 v[76:79], v[156:159], v[208:211], v[76:79]
	v_mfma_f32_16x16x32_bf16 v[124:127], v[152:155], v[184:187], v[124:127]
	v_mfma_f32_16x16x32_bf16 v[120:123], v[160:163], v[184:187], v[120:123]
	v_mfma_f32_16x16x32_bf16 v[116:119], v[152:155], v[196:199], v[116:119]
	v_mfma_f32_16x16x32_bf16 v[108:111], v[160:163], v[196:199], v[108:111]
	v_mfma_f32_16x16x32_bf16 v[100:103], v[152:155], v[204:207], v[100:103]
	v_mfma_f32_16x16x32_bf16 v[92:95], v[160:163], v[204:207], v[92:95]
	v_mfma_f32_16x16x32_bf16 v[84:87], v[152:155], v[212:215], v[84:87]
	v_mfma_f32_16x16x32_bf16 v[76:79], v[160:163], v[212:215], v[76:79]
	v_mfma_f32_16x16x32_bf16 v[112:115], v[164:167], v[180:183], v[112:115]
	v_mfma_f32_16x16x32_bf16 v[104:107], v[172:175], v[180:183], v[104:107]
	v_mfma_f32_16x16x32_bf16 v[96:99], v[164:167], v[192:195], v[96:99]
	v_mfma_f32_16x16x32_bf16 v[88:91], v[172:175], v[192:195], v[88:91]
	v_mfma_f32_16x16x32_bf16 v[80:83], v[164:167], v[200:203], v[80:83]
	v_mfma_f32_16x16x32_bf16 v[72:75], v[172:175], v[200:203], v[72:75]
	v_mfma_f32_16x16x32_bf16 v[68:71], v[164:167], v[208:211], v[68:71]
	v_mfma_f32_16x16x32_bf16 v[64:67], v[172:175], v[208:211], v[64:67]
	v_mfma_f32_16x16x32_bf16 v[112:115], v[168:171], v[184:187], v[112:115]
	v_mfma_f32_16x16x32_bf16 v[104:107], v[176:179], v[184:187], v[104:107]
	v_mfma_f32_16x16x32_bf16 v[96:99], v[168:171], v[196:199], v[96:99]
	v_mfma_f32_16x16x32_bf16 v[88:91], v[176:179], v[196:199], v[88:91]
	v_mfma_f32_16x16x32_bf16 v[80:83], v[168:171], v[204:207], v[80:83]
	v_mfma_f32_16x16x32_bf16 v[72:75], v[176:179], v[204:207], v[72:75]
	v_mfma_f32_16x16x32_bf16 v[68:71], v[168:171], v[212:215], v[68:71]
	v_mfma_f32_16x16x32_bf16 v[64:67], v[176:179], v[212:215], v[64:67]
	s_barrier
	s_mov_b32 m0, s89
	v_lshl_add_u64 v[140:141], v[140:141], 0, s[12:13]
	ds_read_b128 v[180:183], v147 offset:49152
	ds_read_b128 v[184:187], v147 offset:50176
	ds_read_b128 v[192:195], v147 offset:51200
	ds_read_b128 v[196:199], v147 offset:52224
	ds_read_b128 v[200:203], v147 offset:53248
	ds_read_b128 v[204:207], v147 offset:54272
	ds_read_b128 v[208:211], v147 offset:55296
	ds_read_b128 v[212:215], v147 offset:56320
	global_load_lds_dwordx4 v[140:141], off
	v_lshl_add_u64 v[140:141], v[188:189], 0, s[12:13]
	s_mov_b32 m0, s87
	s_nop 0
	global_load_lds_dwordx4 v[140:141], off
	s_mov_b32 m0, s88
	s_nop 0
	global_load_lds_dwordx4 v130, s[42:43]
	s_mov_b32 m0, s86
	s_nop 0
	global_load_lds_dwordx4 v134, s[42:43]
	v_lshl_add_u64 v[140:141], v[216:217], 0, s[12:13]
	s_mov_b32 m0, s77
	s_nop 0
	global_load_lds_dwordx4 v[140:141], off
	v_lshl_add_u64 v[140:141], v[218:219], 0, s[12:13]
	s_mov_b32 m0, s79
	s_nop 0
	global_load_lds_dwordx4 v[140:141], off
	s_waitcnt vmcnt(8) lgkmcnt(0)
	s_barrier
	v_mfma_f32_16x16x32_bf16 v[60:63], v[148:151], v[180:183], v[60:63]
	v_mfma_f32_16x16x32_bf16 v[56:59], v[156:159], v[180:183], v[56:59]
	v_mfma_f32_16x16x32_bf16 v[52:55], v[148:151], v[192:195], v[52:55]
	v_mfma_f32_16x16x32_bf16 v[44:47], v[156:159], v[192:195], v[44:47]
	v_mfma_f32_16x16x32_bf16 v[36:39], v[148:151], v[200:203], v[36:39]
	v_mfma_f32_16x16x32_bf16 v[28:31], v[156:159], v[200:203], v[28:31]
	v_mfma_f32_16x16x32_bf16 v[20:23], v[148:151], v[208:211], v[20:23]
	v_mfma_f32_16x16x32_bf16 v[12:15], v[156:159], v[208:211], v[12:15]
	v_mfma_f32_16x16x32_bf16 v[60:63], v[152:155], v[184:187], v[60:63]
	v_mfma_f32_16x16x32_bf16 v[56:59], v[160:163], v[184:187], v[56:59]
	v_mfma_f32_16x16x32_bf16 v[52:55], v[152:155], v[196:199], v[52:55]
	v_mfma_f32_16x16x32_bf16 v[44:47], v[160:163], v[196:199], v[44:47]
	v_mfma_f32_16x16x32_bf16 v[36:39], v[152:155], v[204:207], v[36:39]
	v_mfma_f32_16x16x32_bf16 v[28:31], v[160:163], v[204:207], v[28:31]
	v_mfma_f32_16x16x32_bf16 v[20:23], v[152:155], v[212:215], v[20:23]
	v_mfma_f32_16x16x32_bf16 v[12:15], v[160:163], v[212:215], v[12:15]
	v_mfma_f32_16x16x32_bf16 v[48:51], v[164:167], v[180:183], v[48:51]
	v_mfma_f32_16x16x32_bf16 v[40:43], v[172:175], v[180:183], v[40:43]
	v_mfma_f32_16x16x32_bf16 v[32:35], v[164:167], v[192:195], v[32:35]
	v_mfma_f32_16x16x32_bf16 v[24:27], v[172:175], v[192:195], v[24:27]
	v_mfma_f32_16x16x32_bf16 v[16:19], v[164:167], v[200:203], v[16:19]
	v_mfma_f32_16x16x32_bf16 v[8:11], v[172:175], v[200:203], v[8:11]
	v_mfma_f32_16x16x32_bf16 v[4:7], v[164:167], v[208:211], v[4:7]
	v_mfma_f32_16x16x32_bf16 v[0:3], v[172:175], v[208:211], v[0:3]
	v_mfma_f32_16x16x32_bf16 v[48:51], v[168:171], v[184:187], v[48:51]
	v_mfma_f32_16x16x32_bf16 v[40:43], v[176:179], v[184:187], v[40:43]
	v_mfma_f32_16x16x32_bf16 v[32:35], v[168:171], v[196:199], v[32:35]
	v_mfma_f32_16x16x32_bf16 v[24:27], v[176:179], v[196:199], v[24:27]
	v_mfma_f32_16x16x32_bf16 v[16:19], v[168:171], v[204:207], v[16:19]
	v_mfma_f32_16x16x32_bf16 v[8:11], v[176:179], v[204:207], v[8:11]
	v_mfma_f32_16x16x32_bf16 v[4:7], v[168:171], v[212:215], v[4:7]
	v_mfma_f32_16x16x32_bf16 v[0:3], v[176:179], v[212:215], v[0:3]
	s_barrier
	s_movk_i32 s60, 0x100
	s_andn2_b64 vcc, exec, s[34:35]
	s_mov_b64 s[42:43], -1
	s_mov_b64 s[34:35], 0
	s_cbranch_vccz .LBB0_1222
	s_branch .Lpeel_exit7
.LBB0_1222:
	s_add_u32 s61, s30, s60
	s_addc_u32 s66, s31, 0
	s_add_u32 s64, s61, 0x100
	s_addc_u32 s65, s66, 0
	s_and_b64 s[62:63], s[42:43], exec
	s_cselect_b32 s63, s21, s65
	s_cselect_b32 s62, s55, s64
	s_add_u32 s60, s28, s60
	s_addc_u32 s64, s29, 0
	s_add_u32 s60, s60, 0x100
	s_addc_u32 s64, s64, 0
	s_and_b64 s[42:43], s[42:43], exec
	s_cselect_b32 s65, s19, s64
	s_cselect_b32 s64, s85, s60
	s_add_u32 s68, s61, 0x10080
	ds_read_b128 v[148:151], v145
	ds_read_b128 v[152:155], v145 offset:1024
	ds_read_b128 v[156:159], v145 offset:2048
	ds_read_b128 v[160:163], v145 offset:3072
	ds_read_b128 v[164:167], v146
	ds_read_b128 v[168:171], v146 offset:1024
	ds_read_b128 v[172:175], v146 offset:2048
	ds_read_b128 v[176:179], v146 offset:3072
	s_addc_u32 s69, s66, 0
	s_add_i32 s95, s81, s73
	s_add_i32 m0, s27, 0xc000
	s_add_i32 s96, s27, 0xe000
	s_add_i32 s92, s95, 0x2000
	s_add_u32 s66, s64, 0x10000
	s_addc_u32 s67, s65, 0
	s_add_i32 s94, s82, s73
	s_add_i32 s93, s94, 0x2000
	s_add_i32 s91, 0, 0x18000
	s_add_i32 s90, 0, 0x1c000
	s_add_u32 s60, s62, 0x10000
	s_addc_u32 s61, s63, 0
	s_add_i32 s89, s91, s73
	s_add_i32 s87, s89, 0x2000
	s_add_u32 s42, s64, 0x10080
	s_addc_u32 s43, s65, 0
	s_add_i32 s88, s90, s73
	s_add_i32 s86, s88, 0x2000
	ds_read_b128 v[180:183], v147
	ds_read_b128 v[184:187], v147 offset:1024
	ds_read_b128 v[192:195], v147 offset:2048
	ds_read_b128 v[196:199], v147 offset:3072
	ds_read_b128 v[200:203], v147 offset:4096
	ds_read_b128 v[204:207], v147 offset:5120
	ds_read_b128 v[208:211], v147 offset:6144
	ds_read_b128 v[212:215], v147 offset:7168
	global_load_lds_dwordx4 v128, s[68:69]
	s_mov_b32 m0, s96
	s_nop 0
	global_load_lds_dwordx4 v132, s[68:69]
	s_waitcnt vmcnt(8) lgkmcnt(0)
	s_barrier
	v_mfma_f32_16x16x32_bf16 v[124:127], v[148:151], v[180:183], v[124:127]
	v_mfma_f32_16x16x32_bf16 v[120:123], v[156:159], v[180:183], v[120:123]
	v_mfma_f32_16x16x32_bf16 v[116:119], v[148:151], v[192:195], v[116:119]
	v_mfma_f32_16x16x32_bf16 v[108:111], v[156:159], v[192:195], v[108:111]
	v_mfma_f32_16x16x32_bf16 v[100:103], v[148:151], v[200:203], v[100:103]
	v_mfma_f32_16x16x32_bf16 v[92:95], v[156:159], v[200:203], v[92:95]
	v_mfma_f32_16x16x32_bf16 v[84:87], v[148:151], v[208:211], v[84:87]
	v_mfma_f32_16x16x32_bf16 v[76:79], v[156:159], v[208:211], v[76:79]
	v_mfma_f32_16x16x32_bf16 v[124:127], v[152:155], v[184:187], v[124:127]
	v_mfma_f32_16x16x32_bf16 v[120:123], v[160:163], v[184:187], v[120:123]
	v_mfma_f32_16x16x32_bf16 v[116:119], v[152:155], v[196:199], v[116:119]
	v_mfma_f32_16x16x32_bf16 v[108:111], v[160:163], v[196:199], v[108:111]
	v_mfma_f32_16x16x32_bf16 v[100:103], v[152:155], v[204:207], v[100:103]
	v_mfma_f32_16x16x32_bf16 v[92:95], v[160:163], v[204:207], v[92:95]
	v_mfma_f32_16x16x32_bf16 v[84:87], v[152:155], v[212:215], v[84:87]
	v_mfma_f32_16x16x32_bf16 v[76:79], v[160:163], v[212:215], v[76:79]
	v_mfma_f32_16x16x32_bf16 v[112:115], v[164:167], v[180:183], v[112:115]
	v_mfma_f32_16x16x32_bf16 v[104:107], v[172:175], v[180:183], v[104:107]
	v_mfma_f32_16x16x32_bf16 v[96:99], v[164:167], v[192:195], v[96:99]
	v_mfma_f32_16x16x32_bf16 v[88:91], v[172:175], v[192:195], v[88:91]
	v_mfma_f32_16x16x32_bf16 v[80:83], v[164:167], v[200:203], v[80:83]
	v_mfma_f32_16x16x32_bf16 v[72:75], v[172:175], v[200:203], v[72:75]
	v_mfma_f32_16x16x32_bf16 v[68:71], v[164:167], v[208:211], v[68:71]
	v_mfma_f32_16x16x32_bf16 v[64:67], v[172:175], v[208:211], v[64:67]
	v_mfma_f32_16x16x32_bf16 v[112:115], v[168:171], v[184:187], v[112:115]
	v_mfma_f32_16x16x32_bf16 v[104:107], v[176:179], v[184:187], v[104:107]
	v_mfma_f32_16x16x32_bf16 v[96:99], v[168:171], v[196:199], v[96:99]
	v_mfma_f32_16x16x32_bf16 v[88:91], v[176:179], v[196:199], v[88:91]
	v_mfma_f32_16x16x32_bf16 v[80:83], v[168:171], v[204:207], v[80:83]
	v_mfma_f32_16x16x32_bf16 v[72:75], v[176:179], v[204:207], v[72:75]
	v_mfma_f32_16x16x32_bf16 v[68:71], v[168:171], v[212:215], v[68:71]
	v_mfma_f32_16x16x32_bf16 v[64:67], v[176:179], v[212:215], v[64:67]
	s_barrier
	s_mov_b32 m0, s95
	v_lshl_add_u64 v[140:141], s[64:65], 0, v[130:131]
	ds_read_b128 v[180:183], v147 offset:16384
	ds_read_b128 v[184:187], v147 offset:17408
	ds_read_b128 v[192:195], v147 offset:18432
	ds_read_b128 v[196:199], v147 offset:19456
	ds_read_b128 v[200:203], v147 offset:20480
	ds_read_b128 v[204:207], v147 offset:21504
	ds_read_b128 v[208:211], v147 offset:22528
	ds_read_b128 v[212:215], v147 offset:23552
	global_load_lds_dwordx4 v[140:141], off
	v_lshl_add_u64 v[188:189], s[64:65], 0, v[134:135]
	s_mov_b32 m0, s92
	s_nop 0
	global_load_lds_dwordx4 v[188:189], off
	s_mov_b32 m0, s94
	v_lshl_add_u64 v[218:219], s[62:63], 0, v[132:133]
	global_load_lds_dwordx4 v130, s[66:67]
	s_mov_b32 m0, s93
	s_nop 0
	global_load_lds_dwordx4 v134, s[66:67]
	v_lshl_add_u64 v[216:217], s[62:63], 0, v[128:129]
	s_mov_b32 m0, s27
	s_nop 0
	global_load_lds_dwordx4 v[216:217], off
	s_mov_b32 m0, s33
	s_nop 0
	global_load_lds_dwordx4 v[218:219], off
	s_waitcnt vmcnt(8) lgkmcnt(0)
	s_barrier
	v_mfma_f32_16x16x32_bf16 v[60:63], v[148:151], v[180:183], v[60:63]
	v_mfma_f32_16x16x32_bf16 v[56:59], v[156:159], v[180:183], v[56:59]
	v_mfma_f32_16x16x32_bf16 v[52:55], v[148:151], v[192:195], v[52:55]
	v_mfma_f32_16x16x32_bf16 v[44:47], v[156:159], v[192:195], v[44:47]
	v_mfma_f32_16x16x32_bf16 v[36:39], v[148:151], v[200:203], v[36:39]
	v_mfma_f32_16x16x32_bf16 v[28:31], v[156:159], v[200:203], v[28:31]
	v_mfma_f32_16x16x32_bf16 v[20:23], v[148:151], v[208:211], v[20:23]
	v_mfma_f32_16x16x32_bf16 v[12:15], v[156:159], v[208:211], v[12:15]
	v_mfma_f32_16x16x32_bf16 v[60:63], v[152:155], v[184:187], v[60:63]
	v_mfma_f32_16x16x32_bf16 v[56:59], v[160:163], v[184:187], v[56:59]
	v_mfma_f32_16x16x32_bf16 v[52:55], v[152:155], v[196:199], v[52:55]
	v_mfma_f32_16x16x32_bf16 v[44:47], v[160:163], v[196:199], v[44:47]
	v_mfma_f32_16x16x32_bf16 v[36:39], v[152:155], v[204:207], v[36:39]
	v_mfma_f32_16x16x32_bf16 v[28:31], v[160:163], v[204:207], v[28:31]
	v_mfma_f32_16x16x32_bf16 v[20:23], v[152:155], v[212:215], v[20:23]
	v_mfma_f32_16x16x32_bf16 v[12:15], v[160:163], v[212:215], v[12:15]
	v_mfma_f32_16x16x32_bf16 v[48:51], v[164:167], v[180:183], v[48:51]
	v_mfma_f32_16x16x32_bf16 v[40:43], v[172:175], v[180:183], v[40:43]
	v_mfma_f32_16x16x32_bf16 v[32:35], v[164:167], v[192:195], v[32:35]
	v_mfma_f32_16x16x32_bf16 v[24:27], v[172:175], v[192:195], v[24:27]
	v_mfma_f32_16x16x32_bf16 v[16:19], v[164:167], v[200:203], v[16:19]
	v_mfma_f32_16x16x32_bf16 v[8:11], v[172:175], v[200:203], v[8:11]
	v_mfma_f32_16x16x32_bf16 v[4:7], v[164:167], v[208:211], v[4:7]
	v_mfma_f32_16x16x32_bf16 v[0:3], v[172:175], v[208:211], v[0:3]
	v_mfma_f32_16x16x32_bf16 v[48:51], v[168:171], v[184:187], v[48:51]
	v_mfma_f32_16x16x32_bf16 v[40:43], v[176:179], v[184:187], v[40:43]
	v_mfma_f32_16x16x32_bf16 v[32:35], v[168:171], v[196:199], v[32:35]
	v_mfma_f32_16x16x32_bf16 v[24:27], v[176:179], v[196:199], v[24:27]
	v_mfma_f32_16x16x32_bf16 v[16:19], v[168:171], v[204:207], v[16:19]
	v_mfma_f32_16x16x32_bf16 v[8:11], v[176:179], v[204:207], v[8:11]
	v_mfma_f32_16x16x32_bf16 v[4:7], v[168:171], v[212:215], v[4:7]
	v_mfma_f32_16x16x32_bf16 v[0:3], v[176:179], v[212:215], v[0:3]
	s_barrier
	v_add_u32_e32 v160, s91, v143
	v_add_u32_e32 v176, s90, v143
	ds_read_b128 v[148:151], v160
	ds_read_b128 v[152:155], v160 offset:1024
	ds_read_b128 v[156:159], v160 offset:2048
	ds_read_b128 v[160:163], v160 offset:3072
	ds_read_b128 v[164:167], v176
	ds_read_b128 v[168:171], v176 offset:1024
	ds_read_b128 v[172:175], v176 offset:2048
	ds_read_b128 v[176:179], v176 offset:3072
	s_mov_b32 m0, s74
	ds_read_b128 v[180:183], v147 offset:32768
	ds_read_b128 v[184:187], v147 offset:33792
	ds_read_b128 v[192:195], v147 offset:34816
	ds_read_b128 v[196:199], v147 offset:35840
	ds_read_b128 v[200:203], v147 offset:36864
	ds_read_b128 v[204:207], v147 offset:37888
	ds_read_b128 v[208:211], v147 offset:38912
	ds_read_b128 v[212:215], v147 offset:39936
	global_load_lds_dwordx4 v128, s[60:61]
	s_mov_b32 m0, s75
	s_nop 0
	global_load_lds_dwordx4 v132, s[60:61]
	s_waitcnt vmcnt(8) lgkmcnt(0)
	s_barrier
	v_mfma_f32_16x16x32_bf16 v[124:127], v[148:151], v[180:183], v[124:127]
	v_mfma_f32_16x16x32_bf16 v[120:123], v[156:159], v[180:183], v[120:123]
	v_mfma_f32_16x16x32_bf16 v[116:119], v[148:151], v[192:195], v[116:119]
	v_mfma_f32_16x16x32_bf16 v[108:111], v[156:159], v[192:195], v[108:111]
	v_mfma_f32_16x16x32_bf16 v[100:103], v[148:151], v[200:203], v[100:103]
	v_mfma_f32_16x16x32_bf16 v[92:95], v[156:159], v[200:203], v[92:95]
	v_mfma_f32_16x16x32_bf16 v[84:87], v[148:151], v[208:211], v[84:87]
	v_mfma_f32_16x16x32_bf16 v[76:79], v[156:159], v[208:211], v[76:79]
	v_mfma_f32_16x16x32_bf16 v[124:127], v[152:155], v[184:187], v[124:127]
	v_mfma_f32_16x16x32_bf16 v[120:123], v[160:163], v[184:187], v[120:123]
	v_mfma_f32_16x16x32_bf16 v[116:119], v[152:155], v[196:199], v[116:119]
	v_mfma_f32_16x16x32_bf16 v[108:111], v[160:163], v[196:199], v[108:111]
	v_mfma_f32_16x16x32_bf16 v[100:103], v[152:155], v[204:207], v[100:103]
	v_mfma_f32_16x16x32_bf16 v[92:95], v[160:163], v[204:207], v[92:95]
	v_mfma_f32_16x16x32_bf16 v[84:87], v[152:155], v[212:215], v[84:87]
	v_mfma_f32_16x16x32_bf16 v[76:79], v[160:163], v[212:215], v[76:79]
	v_mfma_f32_16x16x32_bf16 v[112:115], v[164:167], v[180:183], v[112:115]
	v_mfma_f32_16x16x32_bf16 v[104:107], v[172:175], v[180:183], v[104:107]
	v_mfma_f32_16x16x32_bf16 v[96:99], v[164:167], v[192:195], v[96:99]
	v_mfma_f32_16x16x32_bf16 v[88:91], v[172:175], v[192:195], v[88:91]
	v_mfma_f32_16x16x32_bf16 v[80:83], v[164:167], v[200:203], v[80:83]
	v_mfma_f32_16x16x32_bf16 v[72:75], v[172:175], v[200:203], v[72:75]
	v_mfma_f32_16x16x32_bf16 v[68:71], v[164:167], v[208:211], v[68:71]
	v_mfma_f32_16x16x32_bf16 v[64:67], v[172:175], v[208:211], v[64:67]
	v_mfma_f32_16x16x32_bf16 v[112:115], v[168:171], v[184:187], v[112:115]
	v_mfma_f32_16x16x32_bf16 v[104:107], v[176:179], v[184:187], v[104:107]
	v_mfma_f32_16x16x32_bf16 v[96:99], v[168:171], v[196:199], v[96:99]
	v_mfma_f32_16x16x32_bf16 v[88:91], v[176:179], v[196:199], v[88:91]
	v_mfma_f32_16x16x32_bf16 v[80:83], v[168:171], v[204:207], v[80:83]
	v_mfma_f32_16x16x32_bf16 v[72:75], v[176:179], v[204:207], v[72:75]
	v_mfma_f32_16x16x32_bf16 v[68:71], v[168:171], v[212:215], v[68:71]
	v_mfma_f32_16x16x32_bf16 v[64:67], v[176:179], v[212:215], v[64:67]
	s_barrier
	s_mov_b32 m0, s89
	v_lshl_add_u64 v[140:141], v[140:141], 0, s[12:13]
	ds_read_b128 v[180:183], v147 offset:49152
	ds_read_b128 v[184:187], v147 offset:50176
	ds_read_b128 v[192:195], v147 offset:51200
	ds_read_b128 v[196:199], v147 offset:52224
	ds_read_b128 v[200:203], v147 offset:53248
	ds_read_b128 v[204:207], v147 offset:54272
	ds_read_b128 v[208:211], v147 offset:55296
	ds_read_b128 v[212:215], v147 offset:56320
	global_load_lds_dwordx4 v[140:141], off
	v_lshl_add_u64 v[140:141], v[188:189], 0, s[12:13]
	s_mov_b32 m0, s87
	s_nop 0
	global_load_lds_dwordx4 v[140:141], off
	s_mov_b32 m0, s88
	s_nop 0
	global_load_lds_dwordx4 v130, s[42:43]
	s_mov_b32 m0, s86
	s_nop 0
	global_load_lds_dwordx4 v134, s[42:43]
	v_lshl_add_u64 v[140:141], v[216:217], 0, s[12:13]
	s_mov_b32 m0, s77
	s_nop 0
	global_load_lds_dwordx4 v[140:141], off
	v_lshl_add_u64 v[140:141], v[218:219], 0, s[12:13]
	s_mov_b32 m0, s79
	s_nop 0
	global_load_lds_dwordx4 v[140:141], off
	s_waitcnt vmcnt(8) lgkmcnt(0)
	s_barrier
	v_mfma_f32_16x16x32_bf16 v[60:63], v[148:151], v[180:183], v[60:63]
	v_mfma_f32_16x16x32_bf16 v[56:59], v[156:159], v[180:183], v[56:59]
	v_mfma_f32_16x16x32_bf16 v[52:55], v[148:151], v[192:195], v[52:55]
	v_mfma_f32_16x16x32_bf16 v[44:47], v[156:159], v[192:195], v[44:47]
	v_mfma_f32_16x16x32_bf16 v[36:39], v[148:151], v[200:203], v[36:39]
	v_mfma_f32_16x16x32_bf16 v[28:31], v[156:159], v[200:203], v[28:31]
	v_mfma_f32_16x16x32_bf16 v[20:23], v[148:151], v[208:211], v[20:23]
	v_mfma_f32_16x16x32_bf16 v[12:15], v[156:159], v[208:211], v[12:15]
	v_mfma_f32_16x16x32_bf16 v[60:63], v[152:155], v[184:187], v[60:63]
	v_mfma_f32_16x16x32_bf16 v[56:59], v[160:163], v[184:187], v[56:59]
	v_mfma_f32_16x16x32_bf16 v[52:55], v[152:155], v[196:199], v[52:55]
	v_mfma_f32_16x16x32_bf16 v[44:47], v[160:163], v[196:199], v[44:47]
	v_mfma_f32_16x16x32_bf16 v[36:39], v[152:155], v[204:207], v[36:39]
	v_mfma_f32_16x16x32_bf16 v[28:31], v[160:163], v[204:207], v[28:31]
	v_mfma_f32_16x16x32_bf16 v[20:23], v[152:155], v[212:215], v[20:23]
	v_mfma_f32_16x16x32_bf16 v[12:15], v[160:163], v[212:215], v[12:15]
	v_mfma_f32_16x16x32_bf16 v[48:51], v[164:167], v[180:183], v[48:51]
	v_mfma_f32_16x16x32_bf16 v[40:43], v[172:175], v[180:183], v[40:43]
	v_mfma_f32_16x16x32_bf16 v[32:35], v[164:167], v[192:195], v[32:35]
	v_mfma_f32_16x16x32_bf16 v[24:27], v[172:175], v[192:195], v[24:27]
	v_mfma_f32_16x16x32_bf16 v[16:19], v[164:167], v[200:203], v[16:19]
	v_mfma_f32_16x16x32_bf16 v[8:11], v[172:175], v[200:203], v[8:11]
	v_mfma_f32_16x16x32_bf16 v[4:7], v[164:167], v[208:211], v[4:7]
	v_mfma_f32_16x16x32_bf16 v[0:3], v[172:175], v[208:211], v[0:3]
	v_mfma_f32_16x16x32_bf16 v[48:51], v[168:171], v[184:187], v[48:51]
	v_mfma_f32_16x16x32_bf16 v[40:43], v[176:179], v[184:187], v[40:43]
	v_mfma_f32_16x16x32_bf16 v[32:35], v[168:171], v[196:199], v[32:35]
	v_mfma_f32_16x16x32_bf16 v[24:27], v[176:179], v[196:199], v[24:27]
	v_mfma_f32_16x16x32_bf16 v[16:19], v[168:171], v[204:207], v[16:19]
	v_mfma_f32_16x16x32_bf16 v[8:11], v[176:179], v[204:207], v[8:11]
	v_mfma_f32_16x16x32_bf16 v[4:7], v[168:171], v[212:215], v[4:7]
	v_mfma_f32_16x16x32_bf16 v[0:3], v[176:179], v[212:215], v[0:3]
	s_barrier
	s_movk_i32 s60, 0x100
	s_andn2_b64 vcc, exec, s[34:35]
	s_mov_b64 s[42:43], -1
	s_mov_b64 s[34:35], 0
	s_cbranch_vccz .LBB0_1222

.LBB0_1245:
	s_ashr_i32 s21, s20, 31
	s_lshl_b64 s[22:23], s[20:21], 17
	s_add_u32 s22, s52, s22
	s_addc_u32 s23, s53, s23
	s_and_b64 s[24:25], s[0:1], exec
	s_cselect_b32 s21, s23, s31
	s_cselect_b32 s55, s22, s30
	s_ashr_i32 s19, s18, 31
	s_lshl_b64 s[24:25], s[18:19], 17
	s_add_u32 s24, s70, s24
	s_addc_u32 s25, s71, s25
	s_and_b64 s[34:35], s[0:1], exec
	s_cselect_b32 s19, s25, s29
	s_cselect_b32 s86, s24, s28
	s_mov_b32 s60, 0
	s_mov_b64 s[34:35], -1
	s_mov_b64 s[42:43], 0
	s_add_u32 s61, s30, s60
	s_addc_u32 s66, s31, 0
	s_add_u32 s64, s61, 0x100
	s_addc_u32 s65, s66, 0
	s_and_b64 s[62:63], s[42:43], exec
	s_cselect_b32 s63, s21, s65
	s_cselect_b32 s62, s55, s64
	s_add_u32 s60, s28, s60
	s_addc_u32 s64, s29, 0
	s_add_u32 s60, s60, 0x100
	s_addc_u32 s64, s64, 0
	s_and_b64 s[42:43], s[42:43], exec
	s_cselect_b32 s65, s19, s64
	s_cselect_b32 s64, s86, s60
	s_add_u32 s68, s61, 0x10080
	ds_read_b128 v[148:151], v145
	ds_read_b128 v[152:155], v145 offset:1024
	ds_read_b128 v[156:159], v145 offset:2048
	ds_read_b128 v[160:163], v145 offset:3072
	ds_read_b128 v[164:167], v146
	ds_read_b128 v[168:171], v146 offset:1024
	ds_read_b128 v[172:175], v146 offset:2048
	ds_read_b128 v[176:179], v146 offset:3072
	s_addc_u32 s69, s66, 0
	s_add_i32 s96, s81, s73
	s_add_i32 m0, s27, 0xc000
	s_add_i32 s97, s27, 0xe000
	s_add_i32 s93, s96, 0x2000
	s_add_u32 s66, s64, 0x10000
	s_addc_u32 s67, s65, 0
	s_add_i32 s95, s82, s73
	s_add_i32 s94, s95, 0x2000
	s_add_i32 s92, 0, 0x18000
	s_add_i32 s91, 0, 0x1c000
	s_add_u32 s60, s62, 0x10000
	s_addc_u32 s61, s63, 0
	s_add_i32 s90, s92, s73
	s_add_i32 s88, s90, 0x2000
	s_add_u32 s42, s64, 0x10080
	s_addc_u32 s43, s65, 0
	s_add_i32 s89, s91, s73
	s_add_i32 s87, s89, 0x2000
	ds_read_b128 v[180:183], v147
	ds_read_b128 v[184:187], v147 offset:1024
	ds_read_b128 v[192:195], v147 offset:2048
	ds_read_b128 v[196:199], v147 offset:3072
	ds_read_b128 v[200:203], v147 offset:4096
	ds_read_b128 v[204:207], v147 offset:5120
	ds_read_b128 v[208:211], v147 offset:6144
	ds_read_b128 v[212:215], v147 offset:7168
	global_load_lds_dwordx4 v128, s[68:69]
	s_mov_b32 m0, s97
	s_nop 0
	global_load_lds_dwordx4 v132, s[68:69]
	s_waitcnt vmcnt(8) lgkmcnt(0)
	s_barrier
	v_mfma_f32_16x16x32_bf16 v[124:127], v[148:151], v[180:183], 0
	v_mfma_f32_16x16x32_bf16 v[120:123], v[156:159], v[180:183], 0
	v_mfma_f32_16x16x32_bf16 v[116:119], v[148:151], v[192:195], 0
	v_mfma_f32_16x16x32_bf16 v[108:111], v[156:159], v[192:195], 0
	v_mfma_f32_16x16x32_bf16 v[100:103], v[148:151], v[200:203], 0
	v_mfma_f32_16x16x32_bf16 v[92:95], v[156:159], v[200:203], 0
	v_mfma_f32_16x16x32_bf16 v[84:87], v[148:151], v[208:211], 0
	v_mfma_f32_16x16x32_bf16 v[76:79], v[156:159], v[208:211], 0
	v_mfma_f32_16x16x32_bf16 v[124:127], v[152:155], v[184:187], v[124:127]
	v_mfma_f32_16x16x32_bf16 v[120:123], v[160:163], v[184:187], v[120:123]
	v_mfma_f32_16x16x32_bf16 v[116:119], v[152:155], v[196:199], v[116:119]
	v_mfma_f32_16x16x32_bf16 v[108:111], v[160:163], v[196:199], v[108:111]
	v_mfma_f32_16x16x32_bf16 v[100:103], v[152:155], v[204:207], v[100:103]
	v_mfma_f32_16x16x32_bf16 v[92:95], v[160:163], v[204:207], v[92:95]
	v_mfma_f32_16x16x32_bf16 v[84:87], v[152:155], v[212:215], v[84:87]
	v_mfma_f32_16x16x32_bf16 v[76:79], v[160:163], v[212:215], v[76:79]
	v_mfma_f32_16x16x32_bf16 v[112:115], v[164:167], v[180:183], 0
	v_mfma_f32_16x16x32_bf16 v[104:107], v[172:175], v[180:183], 0
	v_mfma_f32_16x16x32_bf16 v[96:99], v[164:167], v[192:195], 0
	v_mfma_f32_16x16x32_bf16 v[88:91], v[172:175], v[192:195], 0
	v_mfma_f32_16x16x32_bf16 v[80:83], v[164:167], v[200:203], 0
	v_mfma_f32_16x16x32_bf16 v[72:75], v[172:175], v[200:203], 0
	v_mfma_f32_16x16x32_bf16 v[68:71], v[164:167], v[208:211], 0
	v_mfma_f32_16x16x32_bf16 v[64:67], v[172:175], v[208:211], 0
	v_mfma_f32_16x16x32_bf16 v[112:115], v[168:171], v[184:187], v[112:115]
	v_mfma_f32_16x16x32_bf16 v[104:107], v[176:179], v[184:187], v[104:107]
	v_mfma_f32_16x16x32_bf16 v[96:99], v[168:171], v[196:199], v[96:99]
	v_mfma_f32_16x16x32_bf16 v[88:91], v[176:179], v[196:199], v[88:91]
	v_mfma_f32_16x16x32_bf16 v[80:83], v[168:171], v[204:207], v[80:83]
	v_mfma_f32_16x16x32_bf16 v[72:75], v[176:179], v[204:207], v[72:75]
	v_mfma_f32_16x16x32_bf16 v[68:71], v[168:171], v[212:215], v[68:71]
	v_mfma_f32_16x16x32_bf16 v[64:67], v[176:179], v[212:215], v[64:67]
	s_barrier
	s_mov_b32 m0, s96
	v_lshl_add_u64 v[140:141], s[64:65], 0, v[130:131]
	ds_read_b128 v[180:183], v147 offset:16384
	ds_read_b128 v[184:187], v147 offset:17408
	ds_read_b128 v[192:195], v147 offset:18432
	ds_read_b128 v[196:199], v147 offset:19456
	ds_read_b128 v[200:203], v147 offset:20480
	ds_read_b128 v[204:207], v147 offset:21504
	ds_read_b128 v[208:211], v147 offset:22528
	ds_read_b128 v[212:215], v147 offset:23552
	global_load_lds_dwordx4 v[140:141], off
	v_lshl_add_u64 v[188:189], s[64:65], 0, v[134:135]
	s_mov_b32 m0, s93
	s_nop 0
	global_load_lds_dwordx4 v[188:189], off
	s_mov_b32 m0, s95
	v_lshl_add_u64 v[218:219], s[62:63], 0, v[132:133]
	global_load_lds_dwordx4 v130, s[66:67]
	s_mov_b32 m0, s94
	s_nop 0
	global_load_lds_dwordx4 v134, s[66:67]
	v_lshl_add_u64 v[216:217], s[62:63], 0, v[128:129]
	s_mov_b32 m0, s27
	s_nop 0
	global_load_lds_dwordx4 v[216:217], off
	s_mov_b32 m0, s33
	s_nop 0
	global_load_lds_dwordx4 v[218:219], off
	s_waitcnt vmcnt(8) lgkmcnt(0)
	s_barrier
	v_mfma_f32_16x16x32_bf16 v[60:63], v[148:151], v[180:183], 0
	v_mfma_f32_16x16x32_bf16 v[56:59], v[156:159], v[180:183], 0
	v_mfma_f32_16x16x32_bf16 v[52:55], v[148:151], v[192:195], 0
	v_mfma_f32_16x16x32_bf16 v[44:47], v[156:159], v[192:195], 0
	v_mfma_f32_16x16x32_bf16 v[36:39], v[148:151], v[200:203], 0
	v_mfma_f32_16x16x32_bf16 v[28:31], v[156:159], v[200:203], 0
	v_mfma_f32_16x16x32_bf16 v[20:23], v[148:151], v[208:211], 0
	v_mfma_f32_16x16x32_bf16 v[12:15], v[156:159], v[208:211], 0
	v_mfma_f32_16x16x32_bf16 v[60:63], v[152:155], v[184:187], v[60:63]
	v_mfma_f32_16x16x32_bf16 v[56:59], v[160:163], v[184:187], v[56:59]
	v_mfma_f32_16x16x32_bf16 v[52:55], v[152:155], v[196:199], v[52:55]
	v_mfma_f32_16x16x32_bf16 v[44:47], v[160:163], v[196:199], v[44:47]
	v_mfma_f32_16x16x32_bf16 v[36:39], v[152:155], v[204:207], v[36:39]
	v_mfma_f32_16x16x32_bf16 v[28:31], v[160:163], v[204:207], v[28:31]
	v_mfma_f32_16x16x32_bf16 v[20:23], v[152:155], v[212:215], v[20:23]
	v_mfma_f32_16x16x32_bf16 v[12:15], v[160:163], v[212:215], v[12:15]
	v_mfma_f32_16x16x32_bf16 v[48:51], v[164:167], v[180:183], 0
	v_mfma_f32_16x16x32_bf16 v[40:43], v[172:175], v[180:183], 0
	v_mfma_f32_16x16x32_bf16 v[32:35], v[164:167], v[192:195], 0
	v_mfma_f32_16x16x32_bf16 v[24:27], v[172:175], v[192:195], 0
	v_mfma_f32_16x16x32_bf16 v[16:19], v[164:167], v[200:203], 0
	v_mfma_f32_16x16x32_bf16 v[8:11], v[172:175], v[200:203], 0
	v_mfma_f32_16x16x32_bf16 v[4:7], v[164:167], v[208:211], 0
	v_mfma_f32_16x16x32_bf16 v[0:3], v[172:175], v[208:211], 0
	v_mfma_f32_16x16x32_bf16 v[48:51], v[168:171], v[184:187], v[48:51]
	v_mfma_f32_16x16x32_bf16 v[40:43], v[176:179], v[184:187], v[40:43]
	v_mfma_f32_16x16x32_bf16 v[32:35], v[168:171], v[196:199], v[32:35]
	v_mfma_f32_16x16x32_bf16 v[24:27], v[176:179], v[196:199], v[24:27]
	v_mfma_f32_16x16x32_bf16 v[16:19], v[168:171], v[204:207], v[16:19]
	v_mfma_f32_16x16x32_bf16 v[8:11], v[176:179], v[204:207], v[8:11]
	v_mfma_f32_16x16x32_bf16 v[4:7], v[168:171], v[212:215], v[4:7]
	v_mfma_f32_16x16x32_bf16 v[0:3], v[176:179], v[212:215], v[0:3]
	s_barrier
	v_add_u32_e32 v160, s92, v143
	v_add_u32_e32 v176, s91, v143
	ds_read_b128 v[148:151], v160
	ds_read_b128 v[152:155], v160 offset:1024
	ds_read_b128 v[156:159], v160 offset:2048
	ds_read_b128 v[160:163], v160 offset:3072
	ds_read_b128 v[164:167], v176
	ds_read_b128 v[168:171], v176 offset:1024
	ds_read_b128 v[172:175], v176 offset:2048
	ds_read_b128 v[176:179], v176 offset:3072
	s_mov_b32 m0, s74
	ds_read_b128 v[180:183], v147 offset:32768
	ds_read_b128 v[184:187], v147 offset:33792
	ds_read_b128 v[192:195], v147 offset:34816
	ds_read_b128 v[196:199], v147 offset:35840
	ds_read_b128 v[200:203], v147 offset:36864
	ds_read_b128 v[204:207], v147 offset:37888
	ds_read_b128 v[208:211], v147 offset:38912
	ds_read_b128 v[212:215], v147 offset:39936
	global_load_lds_dwordx4 v128, s[60:61]
	s_mov_b32 m0, s75
	s_nop 0
	global_load_lds_dwordx4 v132, s[60:61]
	s_waitcnt vmcnt(8) lgkmcnt(0)
	s_barrier
	v_mfma_f32_16x16x32_bf16 v[124:127], v[148:151], v[180:183], v[124:127]
	v_mfma_f32_16x16x32_bf16 v[120:123], v[156:159], v[180:183], v[120:123]
	v_mfma_f32_16x16x32_bf16 v[116:119], v[148:151], v[192:195], v[116:119]
	v_mfma_f32_16x16x32_bf16 v[108:111], v[156:159], v[192:195], v[108:111]
	v_mfma_f32_16x16x32_bf16 v[100:103], v[148:151], v[200:203], v[100:103]
	v_mfma_f32_16x16x32_bf16 v[92:95], v[156:159], v[200:203], v[92:95]
	v_mfma_f32_16x16x32_bf16 v[84:87], v[148:151], v[208:211], v[84:87]
	v_mfma_f32_16x16x32_bf16 v[76:79], v[156:159], v[208:211], v[76:79]
	v_mfma_f32_16x16x32_bf16 v[124:127], v[152:155], v[184:187], v[124:127]
	v_mfma_f32_16x16x32_bf16 v[120:123], v[160:163], v[184:187], v[120:123]
	v_mfma_f32_16x16x32_bf16 v[116:119], v[152:155], v[196:199], v[116:119]
	v_mfma_f32_16x16x32_bf16 v[108:111], v[160:163], v[196:199], v[108:111]
	v_mfma_f32_16x16x32_bf16 v[100:103], v[152:155], v[204:207], v[100:103]
	v_mfma_f32_16x16x32_bf16 v[92:95], v[160:163], v[204:207], v[92:95]
	v_mfma_f32_16x16x32_bf16 v[84:87], v[152:155], v[212:215], v[84:87]
	v_mfma_f32_16x16x32_bf16 v[76:79], v[160:163], v[212:215], v[76:79]
	v_mfma_f32_16x16x32_bf16 v[112:115], v[164:167], v[180:183], v[112:115]
	v_mfma_f32_16x16x32_bf16 v[104:107], v[172:175], v[180:183], v[104:107]
	v_mfma_f32_16x16x32_bf16 v[96:99], v[164:167], v[192:195], v[96:99]
	v_mfma_f32_16x16x32_bf16 v[88:91], v[172:175], v[192:195], v[88:91]
	v_mfma_f32_16x16x32_bf16 v[80:83], v[164:167], v[200:203], v[80:83]
	v_mfma_f32_16x16x32_bf16 v[72:75], v[172:175], v[200:203], v[72:75]
	v_mfma_f32_16x16x32_bf16 v[68:71], v[164:167], v[208:211], v[68:71]
	v_mfma_f32_16x16x32_bf16 v[64:67], v[172:175], v[208:211], v[64:67]
	v_mfma_f32_16x16x32_bf16 v[112:115], v[168:171], v[184:187], v[112:115]
	v_mfma_f32_16x16x32_bf16 v[104:107], v[176:179], v[184:187], v[104:107]
	v_mfma_f32_16x16x32_bf16 v[96:99], v[168:171], v[196:199], v[96:99]
	v_mfma_f32_16x16x32_bf16 v[88:91], v[176:179], v[196:199], v[88:91]
	v_mfma_f32_16x16x32_bf16 v[80:83], v[168:171], v[204:207], v[80:83]
	v_mfma_f32_16x16x32_bf16 v[72:75], v[176:179], v[204:207], v[72:75]
	v_mfma_f32_16x16x32_bf16 v[68:71], v[168:171], v[212:215], v[68:71]
	v_mfma_f32_16x16x32_bf16 v[64:67], v[176:179], v[212:215], v[64:67]
	s_barrier
	s_mov_b32 m0, s90
	v_lshl_add_u64 v[140:141], v[140:141], 0, s[10:11]
	ds_read_b128 v[180:183], v147 offset:49152
	ds_read_b128 v[184:187], v147 offset:50176
	ds_read_b128 v[192:195], v147 offset:51200
	ds_read_b128 v[196:199], v147 offset:52224
	ds_read_b128 v[200:203], v147 offset:53248
	ds_read_b128 v[204:207], v147 offset:54272
	ds_read_b128 v[208:211], v147 offset:55296
	ds_read_b128 v[212:215], v147 offset:56320
	global_load_lds_dwordx4 v[140:141], off
	v_lshl_add_u64 v[140:141], v[188:189], 0, s[10:11]
	s_mov_b32 m0, s88
	s_nop 0
	global_load_lds_dwordx4 v[140:141], off
	s_mov_b32 m0, s89
	s_nop 0
	global_load_lds_dwordx4 v130, s[42:43]
	s_mov_b32 m0, s87
	s_nop 0
	global_load_lds_dwordx4 v134, s[42:43]
	v_lshl_add_u64 v[140:141], v[216:217], 0, s[10:11]
	s_mov_b32 m0, s77
	s_nop 0
	global_load_lds_dwordx4 v[140:141], off
	v_lshl_add_u64 v[140:141], v[218:219], 0, s[10:11]
	s_mov_b32 m0, s79
	s_nop 0
	global_load_lds_dwordx4 v[140:141], off
	s_waitcnt vmcnt(8) lgkmcnt(0)
	s_barrier
	v_mfma_f32_16x16x32_bf16 v[60:63], v[148:151], v[180:183], v[60:63]
	v_mfma_f32_16x16x32_bf16 v[56:59], v[156:159], v[180:183], v[56:59]
	v_mfma_f32_16x16x32_bf16 v[52:55], v[148:151], v[192:195], v[52:55]
	v_mfma_f32_16x16x32_bf16 v[44:47], v[156:159], v[192:195], v[44:47]
	v_mfma_f32_16x16x32_bf16 v[36:39], v[148:151], v[200:203], v[36:39]
	v_mfma_f32_16x16x32_bf16 v[28:31], v[156:159], v[200:203], v[28:31]
	v_mfma_f32_16x16x32_bf16 v[20:23], v[148:151], v[208:211], v[20:23]
	v_mfma_f32_16x16x32_bf16 v[12:15], v[156:159], v[208:211], v[12:15]
	v_mfma_f32_16x16x32_bf16 v[60:63], v[152:155], v[184:187], v[60:63]
	v_mfma_f32_16x16x32_bf16 v[56:59], v[160:163], v[184:187], v[56:59]
	v_mfma_f32_16x16x32_bf16 v[52:55], v[152:155], v[196:199], v[52:55]
	v_mfma_f32_16x16x32_bf16 v[44:47], v[160:163], v[196:199], v[44:47]
	v_mfma_f32_16x16x32_bf16 v[36:39], v[152:155], v[204:207], v[36:39]
	v_mfma_f32_16x16x32_bf16 v[28:31], v[160:163], v[204:207], v[28:31]
	v_mfma_f32_16x16x32_bf16 v[20:23], v[152:155], v[212:215], v[20:23]
	v_mfma_f32_16x16x32_bf16 v[12:15], v[160:163], v[212:215], v[12:15]
	v_mfma_f32_16x16x32_bf16 v[48:51], v[164:167], v[180:183], v[48:51]
	v_mfma_f32_16x16x32_bf16 v[40:43], v[172:175], v[180:183], v[40:43]
	v_mfma_f32_16x16x32_bf16 v[32:35], v[164:167], v[192:195], v[32:35]
	v_mfma_f32_16x16x32_bf16 v[24:27], v[172:175], v[192:195], v[24:27]
	v_mfma_f32_16x16x32_bf16 v[16:19], v[164:167], v[200:203], v[16:19]
	v_mfma_f32_16x16x32_bf16 v[8:11], v[172:175], v[200:203], v[8:11]
	v_mfma_f32_16x16x32_bf16 v[4:7], v[164:167], v[208:211], v[4:7]
	v_mfma_f32_16x16x32_bf16 v[0:3], v[172:175], v[208:211], v[0:3]
	v_mfma_f32_16x16x32_bf16 v[48:51], v[168:171], v[184:187], v[48:51]
	v_mfma_f32_16x16x32_bf16 v[40:43], v[176:179], v[184:187], v[40:43]
	v_mfma_f32_16x16x32_bf16 v[32:35], v[168:171], v[196:199], v[32:35]
	v_mfma_f32_16x16x32_bf16 v[24:27], v[176:179], v[196:199], v[24:27]
	v_mfma_f32_16x16x32_bf16 v[16:19], v[168:171], v[204:207], v[16:19]
	v_mfma_f32_16x16x32_bf16 v[8:11], v[176:179], v[204:207], v[8:11]
	v_mfma_f32_16x16x32_bf16 v[4:7], v[168:171], v[212:215], v[4:7]
	v_mfma_f32_16x16x32_bf16 v[0:3], v[176:179], v[212:215], v[0:3]
	s_barrier
	s_movk_i32 s60, 0x100
	s_andn2_b64 vcc, exec, s[34:35]
	s_mov_b64 s[42:43], -1
	s_mov_b64 s[34:35], 0
	s_cbranch_vccz .LBB0_1246
	s_branch .Lpeel_exit8
.LBB0_1246:
	s_add_u32 s61, s30, s60
	s_addc_u32 s66, s31, 0
	s_add_u32 s64, s61, 0x100
	s_addc_u32 s65, s66, 0
	s_and_b64 s[62:63], s[42:43], exec
	s_cselect_b32 s63, s21, s65
	s_cselect_b32 s62, s55, s64
	s_add_u32 s60, s28, s60
	s_addc_u32 s64, s29, 0
	s_add_u32 s60, s60, 0x100
	s_addc_u32 s64, s64, 0
	s_and_b64 s[42:43], s[42:43], exec
	s_cselect_b32 s65, s19, s64
	s_cselect_b32 s64, s86, s60
	s_add_u32 s68, s61, 0x10080
	ds_read_b128 v[148:151], v145
	ds_read_b128 v[152:155], v145 offset:1024
	ds_read_b128 v[156:159], v145 offset:2048
	ds_read_b128 v[160:163], v145 offset:3072
	ds_read_b128 v[164:167], v146
	ds_read_b128 v[168:171], v146 offset:1024
	ds_read_b128 v[172:175], v146 offset:2048
	ds_read_b128 v[176:179], v146 offset:3072
	s_addc_u32 s69, s66, 0
	s_add_i32 s96, s81, s73
	s_add_i32 m0, s27, 0xc000
	s_add_i32 s97, s27, 0xe000
	s_add_i32 s93, s96, 0x2000
	s_add_u32 s66, s64, 0x10000
	s_addc_u32 s67, s65, 0
	s_add_i32 s95, s82, s73
	s_add_i32 s94, s95, 0x2000
	s_add_i32 s92, 0, 0x18000
	s_add_i32 s91, 0, 0x1c000
	s_add_u32 s60, s62, 0x10000
	s_addc_u32 s61, s63, 0
	s_add_i32 s90, s92, s73
	s_add_i32 s88, s90, 0x2000
	s_add_u32 s42, s64, 0x10080
	s_addc_u32 s43, s65, 0
	s_add_i32 s89, s91, s73
	s_add_i32 s87, s89, 0x2000
	ds_read_b128 v[180:183], v147
	ds_read_b128 v[184:187], v147 offset:1024
	ds_read_b128 v[192:195], v147 offset:2048
	ds_read_b128 v[196:199], v147 offset:3072
	ds_read_b128 v[200:203], v147 offset:4096
	ds_read_b128 v[204:207], v147 offset:5120
	ds_read_b128 v[208:211], v147 offset:6144
	ds_read_b128 v[212:215], v147 offset:7168
	global_load_lds_dwordx4 v128, s[68:69]
	s_mov_b32 m0, s97
	s_nop 0
	global_load_lds_dwordx4 v132, s[68:69]
	s_waitcnt vmcnt(8) lgkmcnt(0)
	s_barrier
	v_mfma_f32_16x16x32_bf16 v[124:127], v[148:151], v[180:183], v[124:127]
	v_mfma_f32_16x16x32_bf16 v[120:123], v[156:159], v[180:183], v[120:123]
	v_mfma_f32_16x16x32_bf16 v[116:119], v[148:151], v[192:195], v[116:119]
	v_mfma_f32_16x16x32_bf16 v[108:111], v[156:159], v[192:195], v[108:111]
	v_mfma_f32_16x16x32_bf16 v[100:103], v[148:151], v[200:203], v[100:103]
	v_mfma_f32_16x16x32_bf16 v[92:95], v[156:159], v[200:203], v[92:95]
	v_mfma_f32_16x16x32_bf16 v[84:87], v[148:151], v[208:211], v[84:87]
	v_mfma_f32_16x16x32_bf16 v[76:79], v[156:159], v[208:211], v[76:79]
	v_mfma_f32_16x16x32_bf16 v[124:127], v[152:155], v[184:187], v[124:127]
	v_mfma_f32_16x16x32_bf16 v[120:123], v[160:163], v[184:187], v[120:123]
	v_mfma_f32_16x16x32_bf16 v[116:119], v[152:155], v[196:199], v[116:119]
	v_mfma_f32_16x16x32_bf16 v[108:111], v[160:163], v[196:199], v[108:111]
	v_mfma_f32_16x16x32_bf16 v[100:103], v[152:155], v[204:207], v[100:103]
	v_mfma_f32_16x16x32_bf16 v[92:95], v[160:163], v[204:207], v[92:95]
	v_mfma_f32_16x16x32_bf16 v[84:87], v[152:155], v[212:215], v[84:87]
	v_mfma_f32_16x16x32_bf16 v[76:79], v[160:163], v[212:215], v[76:79]
	v_mfma_f32_16x16x32_bf16 v[112:115], v[164:167], v[180:183], v[112:115]
	v_mfma_f32_16x16x32_bf16 v[104:107], v[172:175], v[180:183], v[104:107]
	v_mfma_f32_16x16x32_bf16 v[96:99], v[164:167], v[192:195], v[96:99]
	v_mfma_f32_16x16x32_bf16 v[88:91], v[172:175], v[192:195], v[88:91]
	v_mfma_f32_16x16x32_bf16 v[80:83], v[164:167], v[200:203], v[80:83]
	v_mfma_f32_16x16x32_bf16 v[72:75], v[172:175], v[200:203], v[72:75]
	v_mfma_f32_16x16x32_bf16 v[68:71], v[164:167], v[208:211], v[68:71]
	v_mfma_f32_16x16x32_bf16 v[64:67], v[172:175], v[208:211], v[64:67]
	v_mfma_f32_16x16x32_bf16 v[112:115], v[168:171], v[184:187], v[112:115]
	v_mfma_f32_16x16x32_bf16 v[104:107], v[176:179], v[184:187], v[104:107]
	v_mfma_f32_16x16x32_bf16 v[96:99], v[168:171], v[196:199], v[96:99]
	v_mfma_f32_16x16x32_bf16 v[88:91], v[176:179], v[196:199], v[88:91]
	v_mfma_f32_16x16x32_bf16 v[80:83], v[168:171], v[204:207], v[80:83]
	v_mfma_f32_16x16x32_bf16 v[72:75], v[176:179], v[204:207], v[72:75]
	v_mfma_f32_16x16x32_bf16 v[68:71], v[168:171], v[212:215], v[68:71]
	v_mfma_f32_16x16x32_bf16 v[64:67], v[176:179], v[212:215], v[64:67]
	s_barrier
	s_mov_b32 m0, s96
	v_lshl_add_u64 v[140:141], s[64:65], 0, v[130:131]
	ds_read_b128 v[180:183], v147 offset:16384
	ds_read_b128 v[184:187], v147 offset:17408
	ds_read_b128 v[192:195], v147 offset:18432
	ds_read_b128 v[196:199], v147 offset:19456
	ds_read_b128 v[200:203], v147 offset:20480
	ds_read_b128 v[204:207], v147 offset:21504
	ds_read_b128 v[208:211], v147 offset:22528
	ds_read_b128 v[212:215], v147 offset:23552
	global_load_lds_dwordx4 v[140:141], off
	v_lshl_add_u64 v[188:189], s[64:65], 0, v[134:135]
	s_mov_b32 m0, s93
	s_nop 0
	global_load_lds_dwordx4 v[188:189], off
	s_mov_b32 m0, s95
	v_lshl_add_u64 v[218:219], s[62:63], 0, v[132:133]
	global_load_lds_dwordx4 v130, s[66:67]
	s_mov_b32 m0, s94
	s_nop 0
	global_load_lds_dwordx4 v134, s[66:67]
	v_lshl_add_u64 v[216:217], s[62:63], 0, v[128:129]
	s_mov_b32 m0, s27
	s_nop 0
	global_load_lds_dwordx4 v[216:217], off
	s_mov_b32 m0, s33
	s_nop 0
	global_load_lds_dwordx4 v[218:219], off
	s_waitcnt vmcnt(8) lgkmcnt(0)
	s_barrier
	v_mfma_f32_16x16x32_bf16 v[60:63], v[148:151], v[180:183], v[60:63]
	v_mfma_f32_16x16x32_bf16 v[56:59], v[156:159], v[180:183], v[56:59]
	v_mfma_f32_16x16x32_bf16 v[52:55], v[148:151], v[192:195], v[52:55]
	v_mfma_f32_16x16x32_bf16 v[44:47], v[156:159], v[192:195], v[44:47]
	v_mfma_f32_16x16x32_bf16 v[36:39], v[148:151], v[200:203], v[36:39]
	v_mfma_f32_16x16x32_bf16 v[28:31], v[156:159], v[200:203], v[28:31]
	v_mfma_f32_16x16x32_bf16 v[20:23], v[148:151], v[208:211], v[20:23]
	v_mfma_f32_16x16x32_bf16 v[12:15], v[156:159], v[208:211], v[12:15]
	v_mfma_f32_16x16x32_bf16 v[60:63], v[152:155], v[184:187], v[60:63]
	v_mfma_f32_16x16x32_bf16 v[56:59], v[160:163], v[184:187], v[56:59]
	v_mfma_f32_16x16x32_bf16 v[52:55], v[152:155], v[196:199], v[52:55]
	v_mfma_f32_16x16x32_bf16 v[44:47], v[160:163], v[196:199], v[44:47]
	v_mfma_f32_16x16x32_bf16 v[36:39], v[152:155], v[204:207], v[36:39]
	v_mfma_f32_16x16x32_bf16 v[28:31], v[160:163], v[204:207], v[28:31]
	v_mfma_f32_16x16x32_bf16 v[20:23], v[152:155], v[212:215], v[20:23]
	v_mfma_f32_16x16x32_bf16 v[12:15], v[160:163], v[212:215], v[12:15]
	v_mfma_f32_16x16x32_bf16 v[48:51], v[164:167], v[180:183], v[48:51]
	v_mfma_f32_16x16x32_bf16 v[40:43], v[172:175], v[180:183], v[40:43]
	v_mfma_f32_16x16x32_bf16 v[32:35], v[164:167], v[192:195], v[32:35]
	v_mfma_f32_16x16x32_bf16 v[24:27], v[172:175], v[192:195], v[24:27]
	v_mfma_f32_16x16x32_bf16 v[16:19], v[164:167], v[200:203], v[16:19]
	v_mfma_f32_16x16x32_bf16 v[8:11], v[172:175], v[200:203], v[8:11]
	v_mfma_f32_16x16x32_bf16 v[4:7], v[164:167], v[208:211], v[4:7]
	v_mfma_f32_16x16x32_bf16 v[0:3], v[172:175], v[208:211], v[0:3]
	v_mfma_f32_16x16x32_bf16 v[48:51], v[168:171], v[184:187], v[48:51]
	v_mfma_f32_16x16x32_bf16 v[40:43], v[176:179], v[184:187], v[40:43]
	v_mfma_f32_16x16x32_bf16 v[32:35], v[168:171], v[196:199], v[32:35]
	v_mfma_f32_16x16x32_bf16 v[24:27], v[176:179], v[196:199], v[24:27]
	v_mfma_f32_16x16x32_bf16 v[16:19], v[168:171], v[204:207], v[16:19]
	v_mfma_f32_16x16x32_bf16 v[8:11], v[176:179], v[204:207], v[8:11]
	v_mfma_f32_16x16x32_bf16 v[4:7], v[168:171], v[212:215], v[4:7]
	v_mfma_f32_16x16x32_bf16 v[0:3], v[176:179], v[212:215], v[0:3]
	s_barrier
	v_add_u32_e32 v160, s92, v143
	v_add_u32_e32 v176, s91, v143
	ds_read_b128 v[148:151], v160
	ds_read_b128 v[152:155], v160 offset:1024
	ds_read_b128 v[156:159], v160 offset:2048
	ds_read_b128 v[160:163], v160 offset:3072
	ds_read_b128 v[164:167], v176
	ds_read_b128 v[168:171], v176 offset:1024
	ds_read_b128 v[172:175], v176 offset:2048
	ds_read_b128 v[176:179], v176 offset:3072
	s_mov_b32 m0, s74
	ds_read_b128 v[180:183], v147 offset:32768
	ds_read_b128 v[184:187], v147 offset:33792
	ds_read_b128 v[192:195], v147 offset:34816
	ds_read_b128 v[196:199], v147 offset:35840
	ds_read_b128 v[200:203], v147 offset:36864
	ds_read_b128 v[204:207], v147 offset:37888
	ds_read_b128 v[208:211], v147 offset:38912
	ds_read_b128 v[212:215], v147 offset:39936
	global_load_lds_dwordx4 v128, s[60:61]
	s_mov_b32 m0, s75
	s_nop 0
	global_load_lds_dwordx4 v132, s[60:61]
	s_waitcnt vmcnt(8) lgkmcnt(0)
	s_barrier
	v_mfma_f32_16x16x32_bf16 v[124:127], v[148:151], v[180:183], v[124:127]
	v_mfma_f32_16x16x32_bf16 v[120:123], v[156:159], v[180:183], v[120:123]
	v_mfma_f32_16x16x32_bf16 v[116:119], v[148:151], v[192:195], v[116:119]
	v_mfma_f32_16x16x32_bf16 v[108:111], v[156:159], v[192:195], v[108:111]
	v_mfma_f32_16x16x32_bf16 v[100:103], v[148:151], v[200:203], v[100:103]
	v_mfma_f32_16x16x32_bf16 v[92:95], v[156:159], v[200:203], v[92:95]
	v_mfma_f32_16x16x32_bf16 v[84:87], v[148:151], v[208:211], v[84:87]
	v_mfma_f32_16x16x32_bf16 v[76:79], v[156:159], v[208:211], v[76:79]
	v_mfma_f32_16x16x32_bf16 v[124:127], v[152:155], v[184:187], v[124:127]
	v_mfma_f32_16x16x32_bf16 v[120:123], v[160:163], v[184:187], v[120:123]
	v_mfma_f32_16x16x32_bf16 v[116:119], v[152:155], v[196:199], v[116:119]
	v_mfma_f32_16x16x32_bf16 v[108:111], v[160:163], v[196:199], v[108:111]
	v_mfma_f32_16x16x32_bf16 v[100:103], v[152:155], v[204:207], v[100:103]
	v_mfma_f32_16x16x32_bf16 v[92:95], v[160:163], v[204:207], v[92:95]
	v_mfma_f32_16x16x32_bf16 v[84:87], v[152:155], v[212:215], v[84:87]
	v_mfma_f32_16x16x32_bf16 v[76:79], v[160:163], v[212:215], v[76:79]
	v_mfma_f32_16x16x32_bf16 v[112:115], v[164:167], v[180:183], v[112:115]
	v_mfma_f32_16x16x32_bf16 v[104:107], v[172:175], v[180:183], v[104:107]
	v_mfma_f32_16x16x32_bf16 v[96:99], v[164:167], v[192:195], v[96:99]
	v_mfma_f32_16x16x32_bf16 v[88:91], v[172:175], v[192:195], v[88:91]
	v_mfma_f32_16x16x32_bf16 v[80:83], v[164:167], v[200:203], v[80:83]
	v_mfma_f32_16x16x32_bf16 v[72:75], v[172:175], v[200:203], v[72:75]
	v_mfma_f32_16x16x32_bf16 v[68:71], v[164:167], v[208:211], v[68:71]
	v_mfma_f32_16x16x32_bf16 v[64:67], v[172:175], v[208:211], v[64:67]
	v_mfma_f32_16x16x32_bf16 v[112:115], v[168:171], v[184:187], v[112:115]
	v_mfma_f32_16x16x32_bf16 v[104:107], v[176:179], v[184:187], v[104:107]
	v_mfma_f32_16x16x32_bf16 v[96:99], v[168:171], v[196:199], v[96:99]
	v_mfma_f32_16x16x32_bf16 v[88:91], v[176:179], v[196:199], v[88:91]
	v_mfma_f32_16x16x32_bf16 v[80:83], v[168:171], v[204:207], v[80:83]
	v_mfma_f32_16x16x32_bf16 v[72:75], v[176:179], v[204:207], v[72:75]
	v_mfma_f32_16x16x32_bf16 v[68:71], v[168:171], v[212:215], v[68:71]
	v_mfma_f32_16x16x32_bf16 v[64:67], v[176:179], v[212:215], v[64:67]
	s_barrier
	s_mov_b32 m0, s90
	v_lshl_add_u64 v[140:141], v[140:141], 0, s[10:11]
	ds_read_b128 v[180:183], v147 offset:49152
	ds_read_b128 v[184:187], v147 offset:50176
	ds_read_b128 v[192:195], v147 offset:51200
	ds_read_b128 v[196:199], v147 offset:52224
	ds_read_b128 v[200:203], v147 offset:53248
	ds_read_b128 v[204:207], v147 offset:54272
	ds_read_b128 v[208:211], v147 offset:55296
	ds_read_b128 v[212:215], v147 offset:56320
	global_load_lds_dwordx4 v[140:141], off
	v_lshl_add_u64 v[140:141], v[188:189], 0, s[10:11]
	s_mov_b32 m0, s88
	s_nop 0
	global_load_lds_dwordx4 v[140:141], off
	s_mov_b32 m0, s89
	s_nop 0
	global_load_lds_dwordx4 v130, s[42:43]
	s_mov_b32 m0, s87
	s_nop 0
	global_load_lds_dwordx4 v134, s[42:43]
	v_lshl_add_u64 v[140:141], v[216:217], 0, s[10:11]
	s_mov_b32 m0, s77
	s_nop 0
	global_load_lds_dwordx4 v[140:141], off
	v_lshl_add_u64 v[140:141], v[218:219], 0, s[10:11]
	s_mov_b32 m0, s79
	s_nop 0
	global_load_lds_dwordx4 v[140:141], off
	s_waitcnt vmcnt(8) lgkmcnt(0)
	s_barrier
	v_mfma_f32_16x16x32_bf16 v[60:63], v[148:151], v[180:183], v[60:63]
	v_mfma_f32_16x16x32_bf16 v[56:59], v[156:159], v[180:183], v[56:59]
	v_mfma_f32_16x16x32_bf16 v[52:55], v[148:151], v[192:195], v[52:55]
	v_mfma_f32_16x16x32_bf16 v[44:47], v[156:159], v[192:195], v[44:47]
	v_mfma_f32_16x16x32_bf16 v[36:39], v[148:151], v[200:203], v[36:39]
	v_mfma_f32_16x16x32_bf16 v[28:31], v[156:159], v[200:203], v[28:31]
	v_mfma_f32_16x16x32_bf16 v[20:23], v[148:151], v[208:211], v[20:23]
	v_mfma_f32_16x16x32_bf16 v[12:15], v[156:159], v[208:211], v[12:15]
	v_mfma_f32_16x16x32_bf16 v[60:63], v[152:155], v[184:187], v[60:63]
	v_mfma_f32_16x16x32_bf16 v[56:59], v[160:163], v[184:187], v[56:59]
	v_mfma_f32_16x16x32_bf16 v[52:55], v[152:155], v[196:199], v[52:55]
	v_mfma_f32_16x16x32_bf16 v[44:47], v[160:163], v[196:199], v[44:47]
	v_mfma_f32_16x16x32_bf16 v[36:39], v[152:155], v[204:207], v[36:39]
	v_mfma_f32_16x16x32_bf16 v[28:31], v[160:163], v[204:207], v[28:31]
	v_mfma_f32_16x16x32_bf16 v[20:23], v[152:155], v[212:215], v[20:23]
	v_mfma_f32_16x16x32_bf16 v[12:15], v[160:163], v[212:215], v[12:15]
	v_mfma_f32_16x16x32_bf16 v[48:51], v[164:167], v[180:183], v[48:51]
	v_mfma_f32_16x16x32_bf16 v[40:43], v[172:175], v[180:183], v[40:43]
	v_mfma_f32_16x16x32_bf16 v[32:35], v[164:167], v[192:195], v[32:35]
	v_mfma_f32_16x16x32_bf16 v[24:27], v[172:175], v[192:195], v[24:27]
	v_mfma_f32_16x16x32_bf16 v[16:19], v[164:167], v[200:203], v[16:19]
	v_mfma_f32_16x16x32_bf16 v[8:11], v[172:175], v[200:203], v[8:11]
	v_mfma_f32_16x16x32_bf16 v[4:7], v[164:167], v[208:211], v[4:7]
	v_mfma_f32_16x16x32_bf16 v[0:3], v[172:175], v[208:211], v[0:3]
	v_mfma_f32_16x16x32_bf16 v[48:51], v[168:171], v[184:187], v[48:51]
	v_mfma_f32_16x16x32_bf16 v[40:43], v[176:179], v[184:187], v[40:43]
	v_mfma_f32_16x16x32_bf16 v[32:35], v[168:171], v[196:199], v[32:35]
	v_mfma_f32_16x16x32_bf16 v[24:27], v[176:179], v[196:199], v[24:27]
	v_mfma_f32_16x16x32_bf16 v[16:19], v[168:171], v[204:207], v[16:19]
	v_mfma_f32_16x16x32_bf16 v[8:11], v[176:179], v[204:207], v[8:11]
	v_mfma_f32_16x16x32_bf16 v[4:7], v[168:171], v[212:215], v[4:7]
	v_mfma_f32_16x16x32_bf16 v[0:3], v[176:179], v[212:215], v[0:3]
	s_barrier
	s_movk_i32 s60, 0x100
	s_andn2_b64 vcc, exec, s[34:35]
	s_mov_b64 s[42:43], -1
	s_mov_b64 s[34:35], 0
	s_cbranch_vccz .LBB0_1246

.LBB0_1265:
	s_add_u32 s65, s18, 0x100
	s_addc_u32 s66, s19, 0
	s_mov_b32 s67, -2
	ds_read_b128 v[144:147], v151
	ds_read_b128 v[154:157], v151 offset:1024
	ds_read_b128 v[158:161], v151 offset:2048
	ds_read_b128 v[162:165], v151 offset:3072
	ds_read_b128 v[166:169], v152
	ds_read_b128 v[170:173], v152 offset:1024
	ds_read_b128 v[174:177], v152 offset:2048
	ds_read_b128 v[178:181], v152 offset:3072
	s_add_u32 s18, s16, 0x100
	s_addc_u32 s19, s17, 0
	s_cmp_eq_u32 s67, 2
	s_cselect_b32 s23, s5, s19
	s_cselect_b32 s22, s4, s18
	s_cselect_b32 s21, s15, s66
	s_cselect_b32 s20, s14, s65
	v_lshl_add_u64 v[216:217], s[16:17], 0, v[136:137]
	s_add_i32 m0, s31, 0xc000
	ds_read_b128 v[182:185], v153
	ds_read_b128 v[186:189], v153 offset:1024
	ds_read_b128 v[192:195], v153 offset:2048
	ds_read_b128 v[196:199], v153 offset:3072
	ds_read_b128 v[200:203], v153 offset:4096
	ds_read_b128 v[204:207], v153 offset:5120
	ds_read_b128 v[208:211], v153 offset:6144
	ds_read_b128 v[212:215], v153 offset:7168
	global_load_lds_dwordx4 v[216:217], off
	v_lshl_add_u64 v[216:217], s[16:17], 0, v[138:139]
	s_add_i32 m0, s31, 0xe000
	s_nop 0
	global_load_lds_dwordx4 v[216:217], off
	s_waitcnt vmcnt(8) lgkmcnt(0)
	s_barrier
	v_mfma_f32_16x16x32_bf16 v[124:127], v[144:147], v[182:185], 0
	v_mfma_f32_16x16x32_bf16 v[120:123], v[158:161], v[182:185], 0
	v_mfma_f32_16x16x32_bf16 v[116:119], v[144:147], v[192:195], 0
	v_mfma_f32_16x16x32_bf16 v[108:111], v[158:161], v[192:195], 0
	v_mfma_f32_16x16x32_bf16 v[100:103], v[144:147], v[200:203], 0
	v_mfma_f32_16x16x32_bf16 v[92:95], v[158:161], v[200:203], 0
	v_mfma_f32_16x16x32_bf16 v[84:87], v[144:147], v[208:211], 0
	v_mfma_f32_16x16x32_bf16 v[76:79], v[158:161], v[208:211], 0
	v_mfma_f32_16x16x32_bf16 v[124:127], v[154:157], v[186:189], v[124:127]
	v_mfma_f32_16x16x32_bf16 v[120:123], v[162:165], v[186:189], v[120:123]
	v_mfma_f32_16x16x32_bf16 v[116:119], v[154:157], v[196:199], v[116:119]
	v_mfma_f32_16x16x32_bf16 v[108:111], v[162:165], v[196:199], v[108:111]
	v_mfma_f32_16x16x32_bf16 v[100:103], v[154:157], v[204:207], v[100:103]
	v_mfma_f32_16x16x32_bf16 v[92:95], v[162:165], v[204:207], v[92:95]
	v_mfma_f32_16x16x32_bf16 v[84:87], v[154:157], v[212:215], v[84:87]
	v_mfma_f32_16x16x32_bf16 v[76:79], v[162:165], v[212:215], v[76:79]
	v_mfma_f32_16x16x32_bf16 v[112:115], v[166:169], v[182:185], 0
	v_mfma_f32_16x16x32_bf16 v[104:107], v[174:177], v[182:185], 0
	v_mfma_f32_16x16x32_bf16 v[96:99], v[166:169], v[192:195], 0
	v_mfma_f32_16x16x32_bf16 v[88:91], v[174:177], v[192:195], 0
	v_mfma_f32_16x16x32_bf16 v[80:83], v[166:169], v[200:203], 0
	v_mfma_f32_16x16x32_bf16 v[72:75], v[174:177], v[200:203], 0
	v_mfma_f32_16x16x32_bf16 v[68:71], v[166:169], v[208:211], 0
	v_mfma_f32_16x16x32_bf16 v[64:67], v[174:177], v[208:211], 0
	v_mfma_f32_16x16x32_bf16 v[112:115], v[170:173], v[186:189], v[112:115]
	v_mfma_f32_16x16x32_bf16 v[104:107], v[178:181], v[186:189], v[104:107]
	v_mfma_f32_16x16x32_bf16 v[96:99], v[170:173], v[196:199], v[96:99]
	v_mfma_f32_16x16x32_bf16 v[88:91], v[178:181], v[196:199], v[88:91]
	v_mfma_f32_16x16x32_bf16 v[80:83], v[170:173], v[204:207], v[80:83]
	v_mfma_f32_16x16x32_bf16 v[72:75], v[178:181], v[204:207], v[72:75]
	v_mfma_f32_16x16x32_bf16 v[68:71], v[170:173], v[212:215], v[68:71]
	v_mfma_f32_16x16x32_bf16 v[64:67], v[178:181], v[212:215], v[64:67]
	s_barrier
	s_add_i32 s16, s60, s28
	v_lshl_add_u64 v[216:217], s[20:21], 0, v[132:133]
	s_mov_b32 m0, s16
	ds_read_b128 v[182:185], v153 offset:16384
	ds_read_b128 v[186:189], v153 offset:17408
	ds_read_b128 v[192:195], v153 offset:18432
	ds_read_b128 v[196:199], v153 offset:19456
	ds_read_b128 v[200:203], v153 offset:20480
	ds_read_b128 v[204:207], v153 offset:21504
	ds_read_b128 v[208:211], v153 offset:22528
	ds_read_b128 v[212:215], v153 offset:23552
	global_load_lds_dwordx4 v[216:217], off
	s_add_i32 m0, s16, 0x2000
	s_add_u32 s16, s20, 0x18000
	v_lshl_add_u64 v[218:219], s[20:21], 0, v[128:129]
	s_addc_u32 s17, s21, 0
	s_add_i32 s68, s61, s28
	global_load_lds_dwordx4 v[218:219], off
	s_mov_b32 m0, s68
	v_lshl_add_u64 v[222:223], s[22:23], 0, v[130:131]
	global_load_lds_dwordx4 v132, s[16:17]
	s_add_i32 m0, s68, 0x2000
	s_nop 0
	global_load_lds_dwordx4 v128, s[16:17]
	v_lshl_add_u64 v[220:221], s[22:23], 0, v[134:135]
	s_mov_b32 m0, s31
	s_nop 0
	global_load_lds_dwordx4 v[220:221], off
	s_mov_b32 m0, s33
	s_nop 0
	global_load_lds_dwordx4 v[222:223], off
	s_waitcnt vmcnt(8) lgkmcnt(0)
	s_barrier
	v_mfma_f32_16x16x32_bf16 v[60:63], v[144:147], v[182:185], 0
	v_mfma_f32_16x16x32_bf16 v[56:59], v[158:161], v[182:185], 0
	v_mfma_f32_16x16x32_bf16 v[52:55], v[144:147], v[192:195], 0
	v_mfma_f32_16x16x32_bf16 v[44:47], v[158:161], v[192:195], 0
	v_mfma_f32_16x16x32_bf16 v[36:39], v[144:147], v[200:203], 0
	v_mfma_f32_16x16x32_bf16 v[28:31], v[158:161], v[200:203], 0
	v_mfma_f32_16x16x32_bf16 v[20:23], v[144:147], v[208:211], 0
	v_mfma_f32_16x16x32_bf16 v[12:15], v[158:161], v[208:211], 0
	v_mfma_f32_16x16x32_bf16 v[60:63], v[154:157], v[186:189], v[60:63]
	v_mfma_f32_16x16x32_bf16 v[56:59], v[162:165], v[186:189], v[56:59]
	v_mfma_f32_16x16x32_bf16 v[52:55], v[154:157], v[196:199], v[52:55]
	v_mfma_f32_16x16x32_bf16 v[44:47], v[162:165], v[196:199], v[44:47]
	v_mfma_f32_16x16x32_bf16 v[36:39], v[154:157], v[204:207], v[36:39]
	v_mfma_f32_16x16x32_bf16 v[28:31], v[162:165], v[204:207], v[28:31]
	v_mfma_f32_16x16x32_bf16 v[20:23], v[154:157], v[212:215], v[20:23]
	v_mfma_f32_16x16x32_bf16 v[12:15], v[162:165], v[212:215], v[12:15]
	v_mfma_f32_16x16x32_bf16 v[48:51], v[166:169], v[182:185], 0
	v_mfma_f32_16x16x32_bf16 v[40:43], v[174:177], v[182:185], 0
	v_mfma_f32_16x16x32_bf16 v[32:35], v[166:169], v[192:195], 0
	v_mfma_f32_16x16x32_bf16 v[24:27], v[174:177], v[192:195], 0
	v_mfma_f32_16x16x32_bf16 v[16:19], v[166:169], v[200:203], 0
	v_mfma_f32_16x16x32_bf16 v[8:11], v[174:177], v[200:203], 0
	v_mfma_f32_16x16x32_bf16 v[4:7], v[166:169], v[208:211], 0
	v_mfma_f32_16x16x32_bf16 v[0:3], v[174:177], v[208:211], 0
	v_mfma_f32_16x16x32_bf16 v[48:51], v[170:173], v[186:189], v[48:51]
	v_mfma_f32_16x16x32_bf16 v[40:43], v[178:181], v[186:189], v[40:43]
	v_mfma_f32_16x16x32_bf16 v[32:35], v[170:173], v[196:199], v[32:35]
	v_mfma_f32_16x16x32_bf16 v[24:27], v[178:181], v[196:199], v[24:27]
	v_mfma_f32_16x16x32_bf16 v[16:19], v[170:173], v[204:207], v[16:19]
	v_mfma_f32_16x16x32_bf16 v[8:11], v[178:181], v[204:207], v[8:11]
	v_mfma_f32_16x16x32_bf16 v[4:7], v[170:173], v[212:215], v[4:7]
	v_mfma_f32_16x16x32_bf16 v[0:3], v[178:181], v[212:215], v[0:3]
	s_barrier
	s_add_i32 s68, 0, 0x18000
	s_add_i32 s69, 0, 0x1c000
	v_add_u32_e32 v162, s68, v149
	v_add_u32_e32 v178, s69, v149
	ds_read_b128 v[144:147], v162
	ds_read_b128 v[154:157], v162 offset:1024
	ds_read_b128 v[158:161], v162 offset:2048
	ds_read_b128 v[162:165], v162 offset:3072
	ds_read_b128 v[166:169], v178
	ds_read_b128 v[170:173], v178 offset:1024
	ds_read_b128 v[174:177], v178 offset:2048
	ds_read_b128 v[178:181], v178 offset:3072
	s_add_u32 s16, s22, 0x18000
	s_addc_u32 s17, s23, 0
	s_mov_b32 m0, s34
	ds_read_b128 v[182:185], v153 offset:32768
	ds_read_b128 v[186:189], v153 offset:33792
	ds_read_b128 v[192:195], v153 offset:34816
	ds_read_b128 v[196:199], v153 offset:35840
	ds_read_b128 v[200:203], v153 offset:36864
	ds_read_b128 v[204:207], v153 offset:37888
	ds_read_b128 v[208:211], v153 offset:38912
	ds_read_b128 v[212:215], v153 offset:39936
	global_load_lds_dwordx4 v134, s[16:17]
	s_mov_b32 m0, s35
	s_nop 0
	global_load_lds_dwordx4 v130, s[16:17]
	s_waitcnt vmcnt(8) lgkmcnt(0)
	s_barrier
	v_mfma_f32_16x16x32_bf16 v[124:127], v[144:147], v[182:185], v[124:127]
	v_mfma_f32_16x16x32_bf16 v[120:123], v[158:161], v[182:185], v[120:123]
	v_mfma_f32_16x16x32_bf16 v[116:119], v[144:147], v[192:195], v[116:119]
	v_mfma_f32_16x16x32_bf16 v[108:111], v[158:161], v[192:195], v[108:111]
	v_mfma_f32_16x16x32_bf16 v[100:103], v[144:147], v[200:203], v[100:103]
	v_mfma_f32_16x16x32_bf16 v[92:95], v[158:161], v[200:203], v[92:95]
	v_mfma_f32_16x16x32_bf16 v[84:87], v[144:147], v[208:211], v[84:87]
	v_mfma_f32_16x16x32_bf16 v[76:79], v[158:161], v[208:211], v[76:79]
	v_mfma_f32_16x16x32_bf16 v[124:127], v[154:157], v[186:189], v[124:127]
	v_mfma_f32_16x16x32_bf16 v[120:123], v[162:165], v[186:189], v[120:123]
	v_mfma_f32_16x16x32_bf16 v[116:119], v[154:157], v[196:199], v[116:119]
	v_mfma_f32_16x16x32_bf16 v[108:111], v[162:165], v[196:199], v[108:111]
	v_mfma_f32_16x16x32_bf16 v[100:103], v[154:157], v[204:207], v[100:103]
	v_mfma_f32_16x16x32_bf16 v[92:95], v[162:165], v[204:207], v[92:95]
	v_mfma_f32_16x16x32_bf16 v[84:87], v[154:157], v[212:215], v[84:87]
	v_mfma_f32_16x16x32_bf16 v[76:79], v[162:165], v[212:215], v[76:79]
	v_mfma_f32_16x16x32_bf16 v[112:115], v[166:169], v[182:185], v[112:115]
	v_mfma_f32_16x16x32_bf16 v[104:107], v[174:177], v[182:185], v[104:107]
	v_mfma_f32_16x16x32_bf16 v[96:99], v[166:169], v[192:195], v[96:99]
	v_mfma_f32_16x16x32_bf16 v[88:91], v[174:177], v[192:195], v[88:91]
	v_mfma_f32_16x16x32_bf16 v[80:83], v[166:169], v[200:203], v[80:83]
	v_mfma_f32_16x16x32_bf16 v[72:75], v[174:177], v[200:203], v[72:75]
	v_mfma_f32_16x16x32_bf16 v[68:71], v[166:169], v[208:211], v[68:71]
	v_mfma_f32_16x16x32_bf16 v[64:67], v[174:177], v[208:211], v[64:67]
	v_mfma_f32_16x16x32_bf16 v[112:115], v[170:173], v[186:189], v[112:115]
	v_mfma_f32_16x16x32_bf16 v[104:107], v[178:181], v[186:189], v[104:107]
	v_mfma_f32_16x16x32_bf16 v[96:99], v[170:173], v[196:199], v[96:99]
	v_mfma_f32_16x16x32_bf16 v[88:91], v[178:181], v[196:199], v[88:91]
	v_mfma_f32_16x16x32_bf16 v[80:83], v[170:173], v[204:207], v[80:83]
	v_mfma_f32_16x16x32_bf16 v[72:75], v[178:181], v[204:207], v[72:75]
	v_mfma_f32_16x16x32_bf16 v[68:71], v[170:173], v[212:215], v[68:71]
	v_mfma_f32_16x16x32_bf16 v[64:67], v[178:181], v[212:215], v[64:67]
	s_barrier
	s_add_i32 s16, s68, s28
	v_lshl_add_u64 v[216:217], v[216:217], 0, s[10:11]
	s_mov_b32 m0, s16
	ds_read_b128 v[182:185], v153 offset:49152
	ds_read_b128 v[186:189], v153 offset:50176
	ds_read_b128 v[192:195], v153 offset:51200
	ds_read_b128 v[196:199], v153 offset:52224
	ds_read_b128 v[200:203], v153 offset:53248
	ds_read_b128 v[204:207], v153 offset:54272
	ds_read_b128 v[208:211], v153 offset:55296
	ds_read_b128 v[212:215], v153 offset:56320
	global_load_lds_dwordx4 v[216:217], off
	s_add_i32 m0, s16, 0x2000
	s_add_u32 s16, s20, 0x18080
	v_lshl_add_u64 v[216:217], v[218:219], 0, s[10:11]
	s_addc_u32 s17, s21, 0
	s_add_i32 s20, s69, s28
	global_load_lds_dwordx4 v[216:217], off
	s_mov_b32 m0, s20
	s_nop 0
	global_load_lds_dwordx4 v132, s[16:17]
	s_add_i32 m0, s20, 0x2000
	s_nop 0
	global_load_lds_dwordx4 v128, s[16:17]
	v_lshl_add_u64 v[216:217], v[220:221], 0, s[10:11]
	s_mov_b32 m0, s43
	s_nop 0
	global_load_lds_dwordx4 v[216:217], off
	v_lshl_add_u64 v[216:217], v[222:223], 0, s[10:11]
	s_mov_b32 m0, s52
	s_nop 0
	global_load_lds_dwordx4 v[216:217], off
	s_waitcnt vmcnt(8) lgkmcnt(0)
	s_barrier
	v_mfma_f32_16x16x32_bf16 v[60:63], v[144:147], v[182:185], v[60:63]
	v_mfma_f32_16x16x32_bf16 v[56:59], v[158:161], v[182:185], v[56:59]
	v_mfma_f32_16x16x32_bf16 v[52:55], v[144:147], v[192:195], v[52:55]
	v_mfma_f32_16x16x32_bf16 v[44:47], v[158:161], v[192:195], v[44:47]
	v_mfma_f32_16x16x32_bf16 v[36:39], v[144:147], v[200:203], v[36:39]
	v_mfma_f32_16x16x32_bf16 v[28:31], v[158:161], v[200:203], v[28:31]
	v_mfma_f32_16x16x32_bf16 v[20:23], v[144:147], v[208:211], v[20:23]
	v_mfma_f32_16x16x32_bf16 v[12:15], v[158:161], v[208:211], v[12:15]
	v_mfma_f32_16x16x32_bf16 v[60:63], v[154:157], v[186:189], v[60:63]
	v_mfma_f32_16x16x32_bf16 v[56:59], v[162:165], v[186:189], v[56:59]
	v_mfma_f32_16x16x32_bf16 v[52:55], v[154:157], v[196:199], v[52:55]
	v_mfma_f32_16x16x32_bf16 v[44:47], v[162:165], v[196:199], v[44:47]
	v_mfma_f32_16x16x32_bf16 v[36:39], v[154:157], v[204:207], v[36:39]
	v_mfma_f32_16x16x32_bf16 v[28:31], v[162:165], v[204:207], v[28:31]
	v_mfma_f32_16x16x32_bf16 v[20:23], v[154:157], v[212:215], v[20:23]
	v_mfma_f32_16x16x32_bf16 v[12:15], v[162:165], v[212:215], v[12:15]
	v_mfma_f32_16x16x32_bf16 v[48:51], v[166:169], v[182:185], v[48:51]
	v_mfma_f32_16x16x32_bf16 v[40:43], v[174:177], v[182:185], v[40:43]
	v_mfma_f32_16x16x32_bf16 v[32:35], v[166:169], v[192:195], v[32:35]
	v_mfma_f32_16x16x32_bf16 v[24:27], v[174:177], v[192:195], v[24:27]
	v_mfma_f32_16x16x32_bf16 v[16:19], v[166:169], v[200:203], v[16:19]
	v_mfma_f32_16x16x32_bf16 v[8:11], v[174:177], v[200:203], v[8:11]
	v_mfma_f32_16x16x32_bf16 v[4:7], v[166:169], v[208:211], v[4:7]
	v_mfma_f32_16x16x32_bf16 v[0:3], v[174:177], v[208:211], v[0:3]
	v_mfma_f32_16x16x32_bf16 v[48:51], v[170:173], v[186:189], v[48:51]
	v_mfma_f32_16x16x32_bf16 v[40:43], v[178:181], v[186:189], v[40:43]
	v_mfma_f32_16x16x32_bf16 v[32:35], v[170:173], v[196:199], v[32:35]
	v_mfma_f32_16x16x32_bf16 v[24:27], v[178:181], v[196:199], v[24:27]
	v_mfma_f32_16x16x32_bf16 v[16:19], v[170:173], v[204:207], v[16:19]
	v_mfma_f32_16x16x32_bf16 v[8:11], v[178:181], v[204:207], v[8:11]
	v_mfma_f32_16x16x32_bf16 v[4:7], v[170:173], v[212:215], v[4:7]
	v_mfma_f32_16x16x32_bf16 v[0:3], v[178:181], v[212:215], v[0:3]
	s_barrier
	s_add_i32 s67, s67, 2
	s_add_u32 s65, s65, 0x100
	s_addc_u32 s66, s66, 0
	s_cmp_gt_u32 s67, 3
	s_mov_b64 s[16:17], s[18:19]
	s_cbranch_scc0 .LBB0_1266
	s_branch .Lpeel_exit9
.LBB0_1266:
	ds_read_b128 v[144:147], v151
	ds_read_b128 v[154:157], v151 offset:1024
	ds_read_b128 v[158:161], v151 offset:2048
	ds_read_b128 v[162:165], v151 offset:3072
	ds_read_b128 v[166:169], v152
	ds_read_b128 v[170:173], v152 offset:1024
	ds_read_b128 v[174:177], v152 offset:2048
	ds_read_b128 v[178:181], v152 offset:3072
	s_add_u32 s18, s16, 0x100
	s_addc_u32 s19, s17, 0
	s_cmp_eq_u32 s67, 2
	s_cselect_b32 s23, s5, s19
	s_cselect_b32 s22, s4, s18
	s_cselect_b32 s21, s15, s66
	s_cselect_b32 s20, s14, s65
	v_lshl_add_u64 v[216:217], s[16:17], 0, v[136:137]
	s_add_i32 m0, s31, 0xc000
	ds_read_b128 v[182:185], v153
	ds_read_b128 v[186:189], v153 offset:1024
	ds_read_b128 v[192:195], v153 offset:2048
	ds_read_b128 v[196:199], v153 offset:3072
	ds_read_b128 v[200:203], v153 offset:4096
	ds_read_b128 v[204:207], v153 offset:5120
	ds_read_b128 v[208:211], v153 offset:6144
	ds_read_b128 v[212:215], v153 offset:7168
	global_load_lds_dwordx4 v[216:217], off
	v_lshl_add_u64 v[216:217], s[16:17], 0, v[138:139]
	s_add_i32 m0, s31, 0xe000
	s_nop 0
	global_load_lds_dwordx4 v[216:217], off
	s_waitcnt vmcnt(8) lgkmcnt(0)
	s_barrier
	v_mfma_f32_16x16x32_bf16 v[124:127], v[144:147], v[182:185], v[124:127]
	v_mfma_f32_16x16x32_bf16 v[120:123], v[158:161], v[182:185], v[120:123]
	v_mfma_f32_16x16x32_bf16 v[116:119], v[144:147], v[192:195], v[116:119]
	v_mfma_f32_16x16x32_bf16 v[108:111], v[158:161], v[192:195], v[108:111]
	v_mfma_f32_16x16x32_bf16 v[100:103], v[144:147], v[200:203], v[100:103]
	v_mfma_f32_16x16x32_bf16 v[92:95], v[158:161], v[200:203], v[92:95]
	v_mfma_f32_16x16x32_bf16 v[84:87], v[144:147], v[208:211], v[84:87]
	v_mfma_f32_16x16x32_bf16 v[76:79], v[158:161], v[208:211], v[76:79]
	v_mfma_f32_16x16x32_bf16 v[124:127], v[154:157], v[186:189], v[124:127]
	v_mfma_f32_16x16x32_bf16 v[120:123], v[162:165], v[186:189], v[120:123]
	v_mfma_f32_16x16x32_bf16 v[116:119], v[154:157], v[196:199], v[116:119]
	v_mfma_f32_16x16x32_bf16 v[108:111], v[162:165], v[196:199], v[108:111]
	v_mfma_f32_16x16x32_bf16 v[100:103], v[154:157], v[204:207], v[100:103]
	v_mfma_f32_16x16x32_bf16 v[92:95], v[162:165], v[204:207], v[92:95]
	v_mfma_f32_16x16x32_bf16 v[84:87], v[154:157], v[212:215], v[84:87]
	v_mfma_f32_16x16x32_bf16 v[76:79], v[162:165], v[212:215], v[76:79]
	v_mfma_f32_16x16x32_bf16 v[112:115], v[166:169], v[182:185], v[112:115]
	v_mfma_f32_16x16x32_bf16 v[104:107], v[174:177], v[182:185], v[104:107]
	v_mfma_f32_16x16x32_bf16 v[96:99], v[166:169], v[192:195], v[96:99]
	v_mfma_f32_16x16x32_bf16 v[88:91], v[174:177], v[192:195], v[88:91]
	v_mfma_f32_16x16x32_bf16 v[80:83], v[166:169], v[200:203], v[80:83]
	v_mfma_f32_16x16x32_bf16 v[72:75], v[174:177], v[200:203], v[72:75]
	v_mfma_f32_16x16x32_bf16 v[68:71], v[166:169], v[208:211], v[68:71]
	v_mfma_f32_16x16x32_bf16 v[64:67], v[174:177], v[208:211], v[64:67]
	v_mfma_f32_16x16x32_bf16 v[112:115], v[170:173], v[186:189], v[112:115]
	v_mfma_f32_16x16x32_bf16 v[104:107], v[178:181], v[186:189], v[104:107]
	v_mfma_f32_16x16x32_bf16 v[96:99], v[170:173], v[196:199], v[96:99]
	v_mfma_f32_16x16x32_bf16 v[88:91], v[178:181], v[196:199], v[88:91]
	v_mfma_f32_16x16x32_bf16 v[80:83], v[170:173], v[204:207], v[80:83]
	v_mfma_f32_16x16x32_bf16 v[72:75], v[178:181], v[204:207], v[72:75]
	v_mfma_f32_16x16x32_bf16 v[68:71], v[170:173], v[212:215], v[68:71]
	v_mfma_f32_16x16x32_bf16 v[64:67], v[178:181], v[212:215], v[64:67]
	s_barrier
	s_add_i32 s16, s60, s28
	v_lshl_add_u64 v[216:217], s[20:21], 0, v[132:133]
	s_mov_b32 m0, s16
	ds_read_b128 v[182:185], v153 offset:16384
	ds_read_b128 v[186:189], v153 offset:17408
	ds_read_b128 v[192:195], v153 offset:18432
	ds_read_b128 v[196:199], v153 offset:19456
	ds_read_b128 v[200:203], v153 offset:20480
	ds_read_b128 v[204:207], v153 offset:21504
	ds_read_b128 v[208:211], v153 offset:22528
	ds_read_b128 v[212:215], v153 offset:23552
	global_load_lds_dwordx4 v[216:217], off
	s_add_i32 m0, s16, 0x2000
	s_add_u32 s16, s20, 0x18000
	v_lshl_add_u64 v[218:219], s[20:21], 0, v[128:129]
	s_addc_u32 s17, s21, 0
	s_add_i32 s68, s61, s28
	global_load_lds_dwordx4 v[218:219], off
	s_mov_b32 m0, s68
	v_lshl_add_u64 v[222:223], s[22:23], 0, v[130:131]
	global_load_lds_dwordx4 v132, s[16:17]
	s_add_i32 m0, s68, 0x2000
	s_nop 0
	global_load_lds_dwordx4 v128, s[16:17]
	v_lshl_add_u64 v[220:221], s[22:23], 0, v[134:135]
	s_mov_b32 m0, s31
	s_nop 0
	global_load_lds_dwordx4 v[220:221], off
	s_mov_b32 m0, s33
	s_nop 0
	global_load_lds_dwordx4 v[222:223], off
	s_waitcnt vmcnt(8) lgkmcnt(0)
	s_barrier
	v_mfma_f32_16x16x32_bf16 v[60:63], v[144:147], v[182:185], v[60:63]
	v_mfma_f32_16x16x32_bf16 v[56:59], v[158:161], v[182:185], v[56:59]
	v_mfma_f32_16x16x32_bf16 v[52:55], v[144:147], v[192:195], v[52:55]
	v_mfma_f32_16x16x32_bf16 v[44:47], v[158:161], v[192:195], v[44:47]
	v_mfma_f32_16x16x32_bf16 v[36:39], v[144:147], v[200:203], v[36:39]
	v_mfma_f32_16x16x32_bf16 v[28:31], v[158:161], v[200:203], v[28:31]
	v_mfma_f32_16x16x32_bf16 v[20:23], v[144:147], v[208:211], v[20:23]
	v_mfma_f32_16x16x32_bf16 v[12:15], v[158:161], v[208:211], v[12:15]
	v_mfma_f32_16x16x32_bf16 v[60:63], v[154:157], v[186:189], v[60:63]
	v_mfma_f32_16x16x32_bf16 v[56:59], v[162:165], v[186:189], v[56:59]
	v_mfma_f32_16x16x32_bf16 v[52:55], v[154:157], v[196:199], v[52:55]
	v_mfma_f32_16x16x32_bf16 v[44:47], v[162:165], v[196:199], v[44:47]
	v_mfma_f32_16x16x32_bf16 v[36:39], v[154:157], v[204:207], v[36:39]
	v_mfma_f32_16x16x32_bf16 v[28:31], v[162:165], v[204:207], v[28:31]
	v_mfma_f32_16x16x32_bf16 v[20:23], v[154:157], v[212:215], v[20:23]
	v_mfma_f32_16x16x32_bf16 v[12:15], v[162:165], v[212:215], v[12:15]
	v_mfma_f32_16x16x32_bf16 v[48:51], v[166:169], v[182:185], v[48:51]
	v_mfma_f32_16x16x32_bf16 v[40:43], v[174:177], v[182:185], v[40:43]
	v_mfma_f32_16x16x32_bf16 v[32:35], v[166:169], v[192:195], v[32:35]
	v_mfma_f32_16x16x32_bf16 v[24:27], v[174:177], v[192:195], v[24:27]
	v_mfma_f32_16x16x32_bf16 v[16:19], v[166:169], v[200:203], v[16:19]
	v_mfma_f32_16x16x32_bf16 v[8:11], v[174:177], v[200:203], v[8:11]
	v_mfma_f32_16x16x32_bf16 v[4:7], v[166:169], v[208:211], v[4:7]
	v_mfma_f32_16x16x32_bf16 v[0:3], v[174:177], v[208:211], v[0:3]
	v_mfma_f32_16x16x32_bf16 v[48:51], v[170:173], v[186:189], v[48:51]
	v_mfma_f32_16x16x32_bf16 v[40:43], v[178:181], v[186:189], v[40:43]
	v_mfma_f32_16x16x32_bf16 v[32:35], v[170:173], v[196:199], v[32:35]
	v_mfma_f32_16x16x32_bf16 v[24:27], v[178:181], v[196:199], v[24:27]
	v_mfma_f32_16x16x32_bf16 v[16:19], v[170:173], v[204:207], v[16:19]
	v_mfma_f32_16x16x32_bf16 v[8:11], v[178:181], v[204:207], v[8:11]
	v_mfma_f32_16x16x32_bf16 v[4:7], v[170:173], v[212:215], v[4:7]
	v_mfma_f32_16x16x32_bf16 v[0:3], v[178:181], v[212:215], v[0:3]
	s_barrier
	s_add_i32 s68, 0, 0x18000
	s_add_i32 s69, 0, 0x1c000
	v_add_u32_e32 v162, s68, v149
	v_add_u32_e32 v178, s69, v149
	ds_read_b128 v[144:147], v162
	ds_read_b128 v[154:157], v162 offset:1024
	ds_read_b128 v[158:161], v162 offset:2048
	ds_read_b128 v[162:165], v162 offset:3072
	ds_read_b128 v[166:169], v178
	ds_read_b128 v[170:173], v178 offset:1024
	ds_read_b128 v[174:177], v178 offset:2048
	ds_read_b128 v[178:181], v178 offset:3072
	s_add_u32 s16, s22, 0x18000
	s_addc_u32 s17, s23, 0
	s_mov_b32 m0, s34
	ds_read_b128 v[182:185], v153 offset:32768
	ds_read_b128 v[186:189], v153 offset:33792
	ds_read_b128 v[192:195], v153 offset:34816
	ds_read_b128 v[196:199], v153 offset:35840
	ds_read_b128 v[200:203], v153 offset:36864
	ds_read_b128 v[204:207], v153 offset:37888
	ds_read_b128 v[208:211], v153 offset:38912
	ds_read_b128 v[212:215], v153 offset:39936
	global_load_lds_dwordx4 v134, s[16:17]
	s_mov_b32 m0, s35
	s_nop 0
	global_load_lds_dwordx4 v130, s[16:17]
	s_waitcnt vmcnt(8) lgkmcnt(0)
	s_barrier
	v_mfma_f32_16x16x32_bf16 v[124:127], v[144:147], v[182:185], v[124:127]
	v_mfma_f32_16x16x32_bf16 v[120:123], v[158:161], v[182:185], v[120:123]
	v_mfma_f32_16x16x32_bf16 v[116:119], v[144:147], v[192:195], v[116:119]
	v_mfma_f32_16x16x32_bf16 v[108:111], v[158:161], v[192:195], v[108:111]
	v_mfma_f32_16x16x32_bf16 v[100:103], v[144:147], v[200:203], v[100:103]
	v_mfma_f32_16x16x32_bf16 v[92:95], v[158:161], v[200:203], v[92:95]
	v_mfma_f32_16x16x32_bf16 v[84:87], v[144:147], v[208:211], v[84:87]
	v_mfma_f32_16x16x32_bf16 v[76:79], v[158:161], v[208:211], v[76:79]
	v_mfma_f32_16x16x32_bf16 v[124:127], v[154:157], v[186:189], v[124:127]
	v_mfma_f32_16x16x32_bf16 v[120:123], v[162:165], v[186:189], v[120:123]
	v_mfma_f32_16x16x32_bf16 v[116:119], v[154:157], v[196:199], v[116:119]
	v_mfma_f32_16x16x32_bf16 v[108:111], v[162:165], v[196:199], v[108:111]
	v_mfma_f32_16x16x32_bf16 v[100:103], v[154:157], v[204:207], v[100:103]
	v_mfma_f32_16x16x32_bf16 v[92:95], v[162:165], v[204:207], v[92:95]
	v_mfma_f32_16x16x32_bf16 v[84:87], v[154:157], v[212:215], v[84:87]
	v_mfma_f32_16x16x32_bf16 v[76:79], v[162:165], v[212:215], v[76:79]
	v_mfma_f32_16x16x32_bf16 v[112:115], v[166:169], v[182:185], v[112:115]
	v_mfma_f32_16x16x32_bf16 v[104:107], v[174:177], v[182:185], v[104:107]
	v_mfma_f32_16x16x32_bf16 v[96:99], v[166:169], v[192:195], v[96:99]
	v_mfma_f32_16x16x32_bf16 v[88:91], v[174:177], v[192:195], v[88:91]
	v_mfma_f32_16x16x32_bf16 v[80:83], v[166:169], v[200:203], v[80:83]
	v_mfma_f32_16x16x32_bf16 v[72:75], v[174:177], v[200:203], v[72:75]
	v_mfma_f32_16x16x32_bf16 v[68:71], v[166:169], v[208:211], v[68:71]
	v_mfma_f32_16x16x32_bf16 v[64:67], v[174:177], v[208:211], v[64:67]
	v_mfma_f32_16x16x32_bf16 v[112:115], v[170:173], v[186:189], v[112:115]
	v_mfma_f32_16x16x32_bf16 v[104:107], v[178:181], v[186:189], v[104:107]
	v_mfma_f32_16x16x32_bf16 v[96:99], v[170:173], v[196:199], v[96:99]
	v_mfma_f32_16x16x32_bf16 v[88:91], v[178:181], v[196:199], v[88:91]
	v_mfma_f32_16x16x32_bf16 v[80:83], v[170:173], v[204:207], v[80:83]
	v_mfma_f32_16x16x32_bf16 v[72:75], v[178:181], v[204:207], v[72:75]
	v_mfma_f32_16x16x32_bf16 v[68:71], v[170:173], v[212:215], v[68:71]
	v_mfma_f32_16x16x32_bf16 v[64:67], v[178:181], v[212:215], v[64:67]
	s_barrier
	s_add_i32 s16, s68, s28
	v_lshl_add_u64 v[216:217], v[216:217], 0, s[10:11]
	s_mov_b32 m0, s16
	ds_read_b128 v[182:185], v153 offset:49152
	ds_read_b128 v[186:189], v153 offset:50176
	ds_read_b128 v[192:195], v153 offset:51200
	ds_read_b128 v[196:199], v153 offset:52224
	ds_read_b128 v[200:203], v153 offset:53248
	ds_read_b128 v[204:207], v153 offset:54272
	ds_read_b128 v[208:211], v153 offset:55296
	ds_read_b128 v[212:215], v153 offset:56320
	global_load_lds_dwordx4 v[216:217], off
	s_add_i32 m0, s16, 0x2000
	s_add_u32 s16, s20, 0x18080
	v_lshl_add_u64 v[216:217], v[218:219], 0, s[10:11]
	s_addc_u32 s17, s21, 0
	s_add_i32 s20, s69, s28
	global_load_lds_dwordx4 v[216:217], off
	s_mov_b32 m0, s20
	s_nop 0
	global_load_lds_dwordx4 v132, s[16:17]
	s_add_i32 m0, s20, 0x2000
	s_nop 0
	global_load_lds_dwordx4 v128, s[16:17]
	v_lshl_add_u64 v[216:217], v[220:221], 0, s[10:11]
	s_mov_b32 m0, s43
	s_nop 0
	global_load_lds_dwordx4 v[216:217], off
	v_lshl_add_u64 v[216:217], v[222:223], 0, s[10:11]
	s_mov_b32 m0, s52
	s_nop 0
	global_load_lds_dwordx4 v[216:217], off
	s_waitcnt vmcnt(8) lgkmcnt(0)
	s_barrier
	v_mfma_f32_16x16x32_bf16 v[60:63], v[144:147], v[182:185], v[60:63]
	v_mfma_f32_16x16x32_bf16 v[56:59], v[158:161], v[182:185], v[56:59]
	v_mfma_f32_16x16x32_bf16 v[52:55], v[144:147], v[192:195], v[52:55]
	v_mfma_f32_16x16x32_bf16 v[44:47], v[158:161], v[192:195], v[44:47]
	v_mfma_f32_16x16x32_bf16 v[36:39], v[144:147], v[200:203], v[36:39]
	v_mfma_f32_16x16x32_bf16 v[28:31], v[158:161], v[200:203], v[28:31]
	v_mfma_f32_16x16x32_bf16 v[20:23], v[144:147], v[208:211], v[20:23]
	v_mfma_f32_16x16x32_bf16 v[12:15], v[158:161], v[208:211], v[12:15]
	v_mfma_f32_16x16x32_bf16 v[60:63], v[154:157], v[186:189], v[60:63]
	v_mfma_f32_16x16x32_bf16 v[56:59], v[162:165], v[186:189], v[56:59]
	v_mfma_f32_16x16x32_bf16 v[52:55], v[154:157], v[196:199], v[52:55]
	v_mfma_f32_16x16x32_bf16 v[44:47], v[162:165], v[196:199], v[44:47]
	v_mfma_f32_16x16x32_bf16 v[36:39], v[154:157], v[204:207], v[36:39]
	v_mfma_f32_16x16x32_bf16 v[28:31], v[162:165], v[204:207], v[28:31]
	v_mfma_f32_16x16x32_bf16 v[20:23], v[154:157], v[212:215], v[20:23]
	v_mfma_f32_16x16x32_bf16 v[12:15], v[162:165], v[212:215], v[12:15]
	v_mfma_f32_16x16x32_bf16 v[48:51], v[166:169], v[182:185], v[48:51]
	v_mfma_f32_16x16x32_bf16 v[40:43], v[174:177], v[182:185], v[40:43]
	v_mfma_f32_16x16x32_bf16 v[32:35], v[166:169], v[192:195], v[32:35]
	v_mfma_f32_16x16x32_bf16 v[24:27], v[174:177], v[192:195], v[24:27]
	v_mfma_f32_16x16x32_bf16 v[16:19], v[166:169], v[200:203], v[16:19]
	v_mfma_f32_16x16x32_bf16 v[8:11], v[174:177], v[200:203], v[8:11]
	v_mfma_f32_16x16x32_bf16 v[4:7], v[166:169], v[208:211], v[4:7]
	v_mfma_f32_16x16x32_bf16 v[0:3], v[174:177], v[208:211], v[0:3]
	v_mfma_f32_16x16x32_bf16 v[48:51], v[170:173], v[186:189], v[48:51]
	v_mfma_f32_16x16x32_bf16 v[40:43], v[178:181], v[186:189], v[40:43]
	v_mfma_f32_16x16x32_bf16 v[32:35], v[170:173], v[196:199], v[32:35]
	v_mfma_f32_16x16x32_bf16 v[24:27], v[178:181], v[196:199], v[24:27]
	v_mfma_f32_16x16x32_bf16 v[16:19], v[170:173], v[204:207], v[16:19]
	v_mfma_f32_16x16x32_bf16 v[8:11], v[178:181], v[204:207], v[8:11]
	v_mfma_f32_16x16x32_bf16 v[4:7], v[170:173], v[212:215], v[4:7]
	v_mfma_f32_16x16x32_bf16 v[0:3], v[178:181], v[212:215], v[0:3]
	s_barrier
	s_add_i32 s67, s67, 2
	s_add_u32 s65, s65, 0x100
	s_addc_u32 s66, s66, 0
	s_cmp_gt_u32 s67, 3
	s_mov_b64 s[16:17], s[18:19]
	s_cbranch_scc0 .LBB0_1266

.LBB0_1433:
	s_ashr_i32 s23, s22, 31
	s_lshl_b64 s[24:25], s[22:23], 19
	s_add_u32 s24, s56, s24
	s_addc_u32 s25, s57, s25
	s_and_b64 s[26:27], s[0:1], exec
	s_cselect_b32 s23, s25, s31
	s_cselect_b32 s55, s24, s30
	s_ashr_i32 s21, s20, 31
	s_lshl_b64 s[26:27], s[20:21], 19
	s_add_u32 s26, s53, s26
	s_addc_u32 s27, s60, s27
	s_and_b64 s[42:43], s[0:1], exec
	s_cselect_b32 s21, s27, s35
	s_cselect_b32 s74, s26, s34
	s_add_u32 s30, s30, 0x40080
	s_addc_u32 s31, s31, 0
	s_add_u32 s75, s34, 0x100
	s_addc_u32 s76, s35, 0
	s_mov_b32 s77, -2
	ds_read_b128 v[152:155], v149
	ds_read_b128 v[156:159], v149 offset:1024
	ds_read_b128 v[160:163], v149 offset:2048
	ds_read_b128 v[164:167], v149 offset:3072
	ds_read_b128 v[168:171], v150
	ds_read_b128 v[172:175], v150 offset:1024
	ds_read_b128 v[176:179], v150 offset:2048
	ds_read_b128 v[180:183], v150 offset:3072
	s_add_u32 s34, s30, 0xfffc0080
	s_addc_u32 s35, s31, -1
	s_cmp_eq_u32 s77, 12
	s_cselect_b32 s43, s23, s35
	s_cselect_b32 s42, s55, s34
	s_cselect_b32 s35, s21, s76
	s_cselect_b32 s34, s74, s75
	s_add_i32 m0, s29, 0xc000
	ds_read_b128 v[184:187], v151
	ds_read_b128 v[192:195], v151 offset:1024
	ds_read_b128 v[196:199], v151 offset:2048
	ds_read_b128 v[200:203], v151 offset:3072
	ds_read_b128 v[204:207], v151 offset:4096
	ds_read_b128 v[208:211], v151 offset:5120
	ds_read_b128 v[212:215], v151 offset:6144
	ds_read_b128 v[216:219], v151 offset:7168
	global_load_lds_dwordx4 v136, s[30:31]
	s_add_i32 m0, s29, 0xe000
	s_nop 0
	global_load_lds_dwordx4 v138, s[30:31]
	s_waitcnt vmcnt(8) lgkmcnt(0)
	s_barrier
	v_mfma_f32_16x16x32_bf16 v[124:127], v[152:155], v[184:187], 0
	v_mfma_f32_16x16x32_bf16 v[120:123], v[160:163], v[184:187], 0
	v_mfma_f32_16x16x32_bf16 v[116:119], v[152:155], v[196:199], 0
	v_mfma_f32_16x16x32_bf16 v[108:111], v[160:163], v[196:199], 0
	v_mfma_f32_16x16x32_bf16 v[100:103], v[152:155], v[204:207], 0
	v_mfma_f32_16x16x32_bf16 v[92:95], v[160:163], v[204:207], 0
	v_mfma_f32_16x16x32_bf16 v[84:87], v[152:155], v[212:215], 0
	v_mfma_f32_16x16x32_bf16 v[76:79], v[160:163], v[212:215], 0
	v_mfma_f32_16x16x32_bf16 v[124:127], v[156:159], v[192:195], v[124:127]
	v_mfma_f32_16x16x32_bf16 v[120:123], v[164:167], v[192:195], v[120:123]
	v_mfma_f32_16x16x32_bf16 v[116:119], v[156:159], v[200:203], v[116:119]
	v_mfma_f32_16x16x32_bf16 v[108:111], v[164:167], v[200:203], v[108:111]
	v_mfma_f32_16x16x32_bf16 v[100:103], v[156:159], v[208:211], v[100:103]
	v_mfma_f32_16x16x32_bf16 v[92:95], v[164:167], v[208:211], v[92:95]
	v_mfma_f32_16x16x32_bf16 v[84:87], v[156:159], v[216:219], v[84:87]
	v_mfma_f32_16x16x32_bf16 v[76:79], v[164:167], v[216:219], v[76:79]
	v_mfma_f32_16x16x32_bf16 v[112:115], v[168:171], v[184:187], 0
	v_mfma_f32_16x16x32_bf16 v[104:107], v[176:179], v[184:187], 0
	v_mfma_f32_16x16x32_bf16 v[96:99], v[168:171], v[196:199], 0
	v_mfma_f32_16x16x32_bf16 v[88:91], v[176:179], v[196:199], 0
	v_mfma_f32_16x16x32_bf16 v[80:83], v[168:171], v[204:207], 0
	v_mfma_f32_16x16x32_bf16 v[72:75], v[176:179], v[204:207], 0
	v_mfma_f32_16x16x32_bf16 v[68:71], v[168:171], v[212:215], 0
	v_mfma_f32_16x16x32_bf16 v[64:67], v[176:179], v[212:215], 0
	v_mfma_f32_16x16x32_bf16 v[112:115], v[172:175], v[192:195], v[112:115]
	v_mfma_f32_16x16x32_bf16 v[104:107], v[180:183], v[192:195], v[104:107]
	v_mfma_f32_16x16x32_bf16 v[96:99], v[172:175], v[200:203], v[96:99]
	v_mfma_f32_16x16x32_bf16 v[88:91], v[180:183], v[200:203], v[88:91]
	v_mfma_f32_16x16x32_bf16 v[80:83], v[172:175], v[208:211], v[80:83]
	v_mfma_f32_16x16x32_bf16 v[72:75], v[180:183], v[208:211], v[72:75]
	v_mfma_f32_16x16x32_bf16 v[68:71], v[172:175], v[216:219], v[68:71]
	v_mfma_f32_16x16x32_bf16 v[64:67], v[180:183], v[216:219], v[64:67]
	s_barrier
	s_add_i32 s79, s68, s61
	v_lshl_add_u64 v[144:145], s[34:35], 0, v[130:131]
	s_mov_b32 m0, s79
	ds_read_b128 v[184:187], v151 offset:16384
	ds_read_b128 v[192:195], v151 offset:17408
	ds_read_b128 v[196:199], v151 offset:18432
	ds_read_b128 v[200:203], v151 offset:19456
	ds_read_b128 v[204:207], v151 offset:20480
	ds_read_b128 v[208:211], v151 offset:21504
	ds_read_b128 v[212:215], v151 offset:22528
	ds_read_b128 v[216:219], v151 offset:23552
	global_load_lds_dwordx4 v[144:145], off
	s_add_i32 m0, s79, 0x2000
	s_add_u32 s80, s34, 0x40000
	v_lshl_add_u64 v[188:189], s[34:35], 0, v[134:135]
	s_addc_u32 s81, s35, 0
	s_add_i32 s79, s69, s61
	global_load_lds_dwordx4 v[188:189], off
	s_mov_b32 m0, s79
	v_lshl_add_u64 v[222:223], s[42:43], 0, v[132:133]
	global_load_lds_dwordx4 v130, s[80:81]
	s_add_i32 m0, s79, 0x2000
	s_nop 0
	global_load_lds_dwordx4 v134, s[80:81]
	v_lshl_add_u64 v[220:221], s[42:43], 0, v[128:129]
	s_mov_b32 m0, s29
	s_nop 0
	global_load_lds_dwordx4 v[220:221], off
	s_mov_b32 m0, s33
	s_nop 0
	global_load_lds_dwordx4 v[222:223], off
	s_waitcnt vmcnt(8) lgkmcnt(0)
	s_barrier
	v_mfma_f32_16x16x32_bf16 v[60:63], v[152:155], v[184:187], 0
	v_mfma_f32_16x16x32_bf16 v[56:59], v[160:163], v[184:187], 0
	v_mfma_f32_16x16x32_bf16 v[52:55], v[152:155], v[196:199], 0
	v_mfma_f32_16x16x32_bf16 v[44:47], v[160:163], v[196:199], 0
	v_mfma_f32_16x16x32_bf16 v[36:39], v[152:155], v[204:207], 0
	v_mfma_f32_16x16x32_bf16 v[28:31], v[160:163], v[204:207], 0
	v_mfma_f32_16x16x32_bf16 v[20:23], v[152:155], v[212:215], 0
	v_mfma_f32_16x16x32_bf16 v[12:15], v[160:163], v[212:215], 0
	v_mfma_f32_16x16x32_bf16 v[60:63], v[156:159], v[192:195], v[60:63]
	v_mfma_f32_16x16x32_bf16 v[56:59], v[164:167], v[192:195], v[56:59]
	v_mfma_f32_16x16x32_bf16 v[52:55], v[156:159], v[200:203], v[52:55]
	v_mfma_f32_16x16x32_bf16 v[44:47], v[164:167], v[200:203], v[44:47]
	v_mfma_f32_16x16x32_bf16 v[36:39], v[156:159], v[208:211], v[36:39]
	v_mfma_f32_16x16x32_bf16 v[28:31], v[164:167], v[208:211], v[28:31]
	v_mfma_f32_16x16x32_bf16 v[20:23], v[156:159], v[216:219], v[20:23]
	v_mfma_f32_16x16x32_bf16 v[12:15], v[164:167], v[216:219], v[12:15]
	v_mfma_f32_16x16x32_bf16 v[48:51], v[168:171], v[184:187], 0
	v_mfma_f32_16x16x32_bf16 v[40:43], v[176:179], v[184:187], 0
	v_mfma_f32_16x16x32_bf16 v[32:35], v[168:171], v[196:199], 0
	v_mfma_f32_16x16x32_bf16 v[24:27], v[176:179], v[196:199], 0
	v_mfma_f32_16x16x32_bf16 v[16:19], v[168:171], v[204:207], 0
	v_mfma_f32_16x16x32_bf16 v[8:11], v[176:179], v[204:207], 0
	v_mfma_f32_16x16x32_bf16 v[4:7], v[168:171], v[212:215], 0
	v_mfma_f32_16x16x32_bf16 v[0:3], v[176:179], v[212:215], 0
	v_mfma_f32_16x16x32_bf16 v[48:51], v[172:175], v[192:195], v[48:51]
	v_mfma_f32_16x16x32_bf16 v[40:43], v[180:183], v[192:195], v[40:43]
	v_mfma_f32_16x16x32_bf16 v[32:35], v[172:175], v[200:203], v[32:35]
	v_mfma_f32_16x16x32_bf16 v[24:27], v[180:183], v[200:203], v[24:27]
	v_mfma_f32_16x16x32_bf16 v[16:19], v[172:175], v[208:211], v[16:19]
	v_mfma_f32_16x16x32_bf16 v[8:11], v[180:183], v[208:211], v[8:11]
	v_mfma_f32_16x16x32_bf16 v[4:7], v[172:175], v[216:219], v[4:7]
	v_mfma_f32_16x16x32_bf16 v[0:3], v[180:183], v[216:219], v[0:3]
	s_barrier
	s_add_i32 s79, 0, 0x18000
	s_add_i32 s80, 0, 0x1c000
	v_add_u32_e32 v164, s79, v147
	v_add_u32_e32 v180, s80, v147
	ds_read_b128 v[152:155], v164
	ds_read_b128 v[156:159], v164 offset:1024
	ds_read_b128 v[160:163], v164 offset:2048
	ds_read_b128 v[164:167], v164 offset:3072
	ds_read_b128 v[168:171], v180
	ds_read_b128 v[172:175], v180 offset:1024
	ds_read_b128 v[176:179], v180 offset:2048
	ds_read_b128 v[180:183], v180 offset:3072
	s_add_u32 s42, s42, 0x40000
	s_addc_u32 s43, s43, 0
	s_mov_b32 m0, s62
	ds_read_b128 v[184:187], v151 offset:32768
	ds_read_b128 v[192:195], v151 offset:33792
	ds_read_b128 v[196:199], v151 offset:34816
	ds_read_b128 v[200:203], v151 offset:35840
	ds_read_b128 v[204:207], v151 offset:36864
	ds_read_b128 v[208:211], v151 offset:37888
	ds_read_b128 v[212:215], v151 offset:38912
	ds_read_b128 v[216:219], v151 offset:39936
	global_load_lds_dwordx4 v128, s[42:43]
	s_mov_b32 m0, s63
	s_nop 0
	global_load_lds_dwordx4 v132, s[42:43]
	s_waitcnt vmcnt(8) lgkmcnt(0)
	s_barrier
	v_mfma_f32_16x16x32_bf16 v[124:127], v[152:155], v[184:187], v[124:127]
	v_mfma_f32_16x16x32_bf16 v[120:123], v[160:163], v[184:187], v[120:123]
	v_mfma_f32_16x16x32_bf16 v[116:119], v[152:155], v[196:199], v[116:119]
	v_mfma_f32_16x16x32_bf16 v[108:111], v[160:163], v[196:199], v[108:111]
	v_mfma_f32_16x16x32_bf16 v[100:103], v[152:155], v[204:207], v[100:103]
	v_mfma_f32_16x16x32_bf16 v[92:95], v[160:163], v[204:207], v[92:95]
	v_mfma_f32_16x16x32_bf16 v[84:87], v[152:155], v[212:215], v[84:87]
	v_mfma_f32_16x16x32_bf16 v[76:79], v[160:163], v[212:215], v[76:79]
	v_mfma_f32_16x16x32_bf16 v[124:127], v[156:159], v[192:195], v[124:127]
	v_mfma_f32_16x16x32_bf16 v[120:123], v[164:167], v[192:195], v[120:123]
	v_mfma_f32_16x16x32_bf16 v[116:119], v[156:159], v[200:203], v[116:119]
	v_mfma_f32_16x16x32_bf16 v[108:111], v[164:167], v[200:203], v[108:111]
	v_mfma_f32_16x16x32_bf16 v[100:103], v[156:159], v[208:211], v[100:103]
	v_mfma_f32_16x16x32_bf16 v[92:95], v[164:167], v[208:211], v[92:95]
	v_mfma_f32_16x16x32_bf16 v[84:87], v[156:159], v[216:219], v[84:87]
	v_mfma_f32_16x16x32_bf16 v[76:79], v[164:167], v[216:219], v[76:79]
	v_mfma_f32_16x16x32_bf16 v[112:115], v[168:171], v[184:187], v[112:115]
	v_mfma_f32_16x16x32_bf16 v[104:107], v[176:179], v[184:187], v[104:107]
	v_mfma_f32_16x16x32_bf16 v[96:99], v[168:171], v[196:199], v[96:99]
	v_mfma_f32_16x16x32_bf16 v[88:91], v[176:179], v[196:199], v[88:91]
	v_mfma_f32_16x16x32_bf16 v[80:83], v[168:171], v[204:207], v[80:83]
	v_mfma_f32_16x16x32_bf16 v[72:75], v[176:179], v[204:207], v[72:75]
	v_mfma_f32_16x16x32_bf16 v[68:71], v[168:171], v[212:215], v[68:71]
	v_mfma_f32_16x16x32_bf16 v[64:67], v[176:179], v[212:215], v[64:67]
	v_mfma_f32_16x16x32_bf16 v[112:115], v[172:175], v[192:195], v[112:115]
	v_mfma_f32_16x16x32_bf16 v[104:107], v[180:183], v[192:195], v[104:107]
	v_mfma_f32_16x16x32_bf16 v[96:99], v[172:175], v[200:203], v[96:99]
	v_mfma_f32_16x16x32_bf16 v[88:91], v[180:183], v[200:203], v[88:91]
	v_mfma_f32_16x16x32_bf16 v[80:83], v[172:175], v[208:211], v[80:83]
	v_mfma_f32_16x16x32_bf16 v[72:75], v[180:183], v[208:211], v[72:75]
	v_mfma_f32_16x16x32_bf16 v[68:71], v[172:175], v[216:219], v[68:71]
	v_mfma_f32_16x16x32_bf16 v[64:67], v[180:183], v[216:219], v[64:67]
	s_barrier
	s_add_i32 s42, s79, s61
	v_lshl_add_u64 v[144:145], v[144:145], 0, s[10:11]
	s_mov_b32 m0, s42
	ds_read_b128 v[184:187], v151 offset:49152
	ds_read_b128 v[192:195], v151 offset:50176
	ds_read_b128 v[196:199], v151 offset:51200
	ds_read_b128 v[200:203], v151 offset:52224
	ds_read_b128 v[204:207], v151 offset:53248
	ds_read_b128 v[208:211], v151 offset:54272
	ds_read_b128 v[212:215], v151 offset:55296
	ds_read_b128 v[216:219], v151 offset:56320
	global_load_lds_dwordx4 v[144:145], off
	s_add_i32 m0, s42, 0x2000
	s_add_u32 s34, s34, 0x40080
	v_lshl_add_u64 v[144:145], v[188:189], 0, s[10:11]
	s_addc_u32 s35, s35, 0
	s_add_i32 s42, s80, s61
	global_load_lds_dwordx4 v[144:145], off
	s_mov_b32 m0, s42
	s_nop 0
	global_load_lds_dwordx4 v130, s[34:35]
	s_add_i32 m0, s42, 0x2000
	s_nop 0
	global_load_lds_dwordx4 v134, s[34:35]
	v_lshl_add_u64 v[144:145], v[220:221], 0, s[10:11]
	s_mov_b32 m0, s65
	s_nop 0
	global_load_lds_dwordx4 v[144:145], off
	v_lshl_add_u64 v[144:145], v[222:223], 0, s[10:11]
	s_mov_b32 m0, s66
	s_nop 0
	global_load_lds_dwordx4 v[144:145], off
	s_waitcnt vmcnt(8) lgkmcnt(0)
	s_barrier
	v_mfma_f32_16x16x32_bf16 v[60:63], v[152:155], v[184:187], v[60:63]
	v_mfma_f32_16x16x32_bf16 v[56:59], v[160:163], v[184:187], v[56:59]
	v_mfma_f32_16x16x32_bf16 v[52:55], v[152:155], v[196:199], v[52:55]
	v_mfma_f32_16x16x32_bf16 v[44:47], v[160:163], v[196:199], v[44:47]
	v_mfma_f32_16x16x32_bf16 v[36:39], v[152:155], v[204:207], v[36:39]
	v_mfma_f32_16x16x32_bf16 v[28:31], v[160:163], v[204:207], v[28:31]
	v_mfma_f32_16x16x32_bf16 v[20:23], v[152:155], v[212:215], v[20:23]
	v_mfma_f32_16x16x32_bf16 v[12:15], v[160:163], v[212:215], v[12:15]
	v_mfma_f32_16x16x32_bf16 v[60:63], v[156:159], v[192:195], v[60:63]
	v_mfma_f32_16x16x32_bf16 v[56:59], v[164:167], v[192:195], v[56:59]
	v_mfma_f32_16x16x32_bf16 v[52:55], v[156:159], v[200:203], v[52:55]
	v_mfma_f32_16x16x32_bf16 v[44:47], v[164:167], v[200:203], v[44:47]
	v_mfma_f32_16x16x32_bf16 v[36:39], v[156:159], v[208:211], v[36:39]
	v_mfma_f32_16x16x32_bf16 v[28:31], v[164:167], v[208:211], v[28:31]
	v_mfma_f32_16x16x32_bf16 v[20:23], v[156:159], v[216:219], v[20:23]
	v_mfma_f32_16x16x32_bf16 v[12:15], v[164:167], v[216:219], v[12:15]
	v_mfma_f32_16x16x32_bf16 v[48:51], v[168:171], v[184:187], v[48:51]
	v_mfma_f32_16x16x32_bf16 v[40:43], v[176:179], v[184:187], v[40:43]
	v_mfma_f32_16x16x32_bf16 v[32:35], v[168:171], v[196:199], v[32:35]
	v_mfma_f32_16x16x32_bf16 v[24:27], v[176:179], v[196:199], v[24:27]
	v_mfma_f32_16x16x32_bf16 v[16:19], v[168:171], v[204:207], v[16:19]
	v_mfma_f32_16x16x32_bf16 v[8:11], v[176:179], v[204:207], v[8:11]
	v_mfma_f32_16x16x32_bf16 v[4:7], v[168:171], v[212:215], v[4:7]
	v_mfma_f32_16x16x32_bf16 v[0:3], v[176:179], v[212:215], v[0:3]
	v_mfma_f32_16x16x32_bf16 v[48:51], v[172:175], v[192:195], v[48:51]
	v_mfma_f32_16x16x32_bf16 v[40:43], v[180:183], v[192:195], v[40:43]
	v_mfma_f32_16x16x32_bf16 v[32:35], v[172:175], v[200:203], v[32:35]
	v_mfma_f32_16x16x32_bf16 v[24:27], v[180:183], v[200:203], v[24:27]
	v_mfma_f32_16x16x32_bf16 v[16:19], v[172:175], v[208:211], v[16:19]
	v_mfma_f32_16x16x32_bf16 v[8:11], v[180:183], v[208:211], v[8:11]
	v_mfma_f32_16x16x32_bf16 v[4:7], v[172:175], v[216:219], v[4:7]
	v_mfma_f32_16x16x32_bf16 v[0:3], v[180:183], v[216:219], v[0:3]
	s_barrier
	s_add_i32 s77, s77, 2
	s_add_u32 s30, s30, 0x100
	s_addc_u32 s31, s31, 0
	s_add_u32 s75, s75, 0x100
	s_addc_u32 s76, s76, 0
	s_cmp_gt_u32 s77, 13
	s_cbranch_scc0 .LBB0_1434
	s_branch .Lpeel_exit10
.LBB0_1434:
	ds_read_b128 v[152:155], v149
	ds_read_b128 v[156:159], v149 offset:1024
	ds_read_b128 v[160:163], v149 offset:2048
	ds_read_b128 v[164:167], v149 offset:3072
	ds_read_b128 v[168:171], v150
	ds_read_b128 v[172:175], v150 offset:1024
	ds_read_b128 v[176:179], v150 offset:2048
	ds_read_b128 v[180:183], v150 offset:3072
	s_add_u32 s34, s30, 0xfffc0080
	s_addc_u32 s35, s31, -1
	s_cmp_eq_u32 s77, 12
	s_cselect_b32 s43, s23, s35
	s_cselect_b32 s42, s55, s34
	s_cselect_b32 s35, s21, s76
	s_cselect_b32 s34, s74, s75
	s_add_i32 m0, s29, 0xc000
	ds_read_b128 v[184:187], v151
	ds_read_b128 v[192:195], v151 offset:1024
	ds_read_b128 v[196:199], v151 offset:2048
	ds_read_b128 v[200:203], v151 offset:3072
	ds_read_b128 v[204:207], v151 offset:4096
	ds_read_b128 v[208:211], v151 offset:5120
	ds_read_b128 v[212:215], v151 offset:6144
	ds_read_b128 v[216:219], v151 offset:7168
	global_load_lds_dwordx4 v136, s[30:31]
	s_add_i32 m0, s29, 0xe000
	s_nop 0
	global_load_lds_dwordx4 v138, s[30:31]
	s_waitcnt vmcnt(8) lgkmcnt(0)
	s_barrier
	v_mfma_f32_16x16x32_bf16 v[124:127], v[152:155], v[184:187], v[124:127]
	v_mfma_f32_16x16x32_bf16 v[120:123], v[160:163], v[184:187], v[120:123]
	v_mfma_f32_16x16x32_bf16 v[116:119], v[152:155], v[196:199], v[116:119]
	v_mfma_f32_16x16x32_bf16 v[108:111], v[160:163], v[196:199], v[108:111]
	v_mfma_f32_16x16x32_bf16 v[100:103], v[152:155], v[204:207], v[100:103]
	v_mfma_f32_16x16x32_bf16 v[92:95], v[160:163], v[204:207], v[92:95]
	v_mfma_f32_16x16x32_bf16 v[84:87], v[152:155], v[212:215], v[84:87]
	v_mfma_f32_16x16x32_bf16 v[76:79], v[160:163], v[212:215], v[76:79]
	v_mfma_f32_16x16x32_bf16 v[124:127], v[156:159], v[192:195], v[124:127]
	v_mfma_f32_16x16x32_bf16 v[120:123], v[164:167], v[192:195], v[120:123]
	v_mfma_f32_16x16x32_bf16 v[116:119], v[156:159], v[200:203], v[116:119]
	v_mfma_f32_16x16x32_bf16 v[108:111], v[164:167], v[200:203], v[108:111]
	v_mfma_f32_16x16x32_bf16 v[100:103], v[156:159], v[208:211], v[100:103]
	v_mfma_f32_16x16x32_bf16 v[92:95], v[164:167], v[208:211], v[92:95]
	v_mfma_f32_16x16x32_bf16 v[84:87], v[156:159], v[216:219], v[84:87]
	v_mfma_f32_16x16x32_bf16 v[76:79], v[164:167], v[216:219], v[76:79]
	v_mfma_f32_16x16x32_bf16 v[112:115], v[168:171], v[184:187], v[112:115]
	v_mfma_f32_16x16x32_bf16 v[104:107], v[176:179], v[184:187], v[104:107]
	v_mfma_f32_16x16x32_bf16 v[96:99], v[168:171], v[196:199], v[96:99]
	v_mfma_f32_16x16x32_bf16 v[88:91], v[176:179], v[196:199], v[88:91]
	v_mfma_f32_16x16x32_bf16 v[80:83], v[168:171], v[204:207], v[80:83]
	v_mfma_f32_16x16x32_bf16 v[72:75], v[176:179], v[204:207], v[72:75]
	v_mfma_f32_16x16x32_bf16 v[68:71], v[168:171], v[212:215], v[68:71]
	v_mfma_f32_16x16x32_bf16 v[64:67], v[176:179], v[212:215], v[64:67]
	v_mfma_f32_16x16x32_bf16 v[112:115], v[172:175], v[192:195], v[112:115]
	v_mfma_f32_16x16x32_bf16 v[104:107], v[180:183], v[192:195], v[104:107]
	v_mfma_f32_16x16x32_bf16 v[96:99], v[172:175], v[200:203], v[96:99]
	v_mfma_f32_16x16x32_bf16 v[88:91], v[180:183], v[200:203], v[88:91]
	v_mfma_f32_16x16x32_bf16 v[80:83], v[172:175], v[208:211], v[80:83]
	v_mfma_f32_16x16x32_bf16 v[72:75], v[180:183], v[208:211], v[72:75]
	v_mfma_f32_16x16x32_bf16 v[68:71], v[172:175], v[216:219], v[68:71]
	v_mfma_f32_16x16x32_bf16 v[64:67], v[180:183], v[216:219], v[64:67]
	s_barrier
	s_add_i32 s79, s68, s61
	v_lshl_add_u64 v[144:145], s[34:35], 0, v[130:131]
	s_mov_b32 m0, s79
	ds_read_b128 v[184:187], v151 offset:16384
	ds_read_b128 v[192:195], v151 offset:17408
	ds_read_b128 v[196:199], v151 offset:18432
	ds_read_b128 v[200:203], v151 offset:19456
	ds_read_b128 v[204:207], v151 offset:20480
	ds_read_b128 v[208:211], v151 offset:21504
	ds_read_b128 v[212:215], v151 offset:22528
	ds_read_b128 v[216:219], v151 offset:23552
	global_load_lds_dwordx4 v[144:145], off
	s_add_i32 m0, s79, 0x2000
	s_add_u32 s80, s34, 0x40000
	v_lshl_add_u64 v[188:189], s[34:35], 0, v[134:135]
	s_addc_u32 s81, s35, 0
	s_add_i32 s79, s69, s61
	global_load_lds_dwordx4 v[188:189], off
	s_mov_b32 m0, s79
	v_lshl_add_u64 v[222:223], s[42:43], 0, v[132:133]
	global_load_lds_dwordx4 v130, s[80:81]
	s_add_i32 m0, s79, 0x2000
	s_nop 0
	global_load_lds_dwordx4 v134, s[80:81]
	v_lshl_add_u64 v[220:221], s[42:43], 0, v[128:129]
	s_mov_b32 m0, s29
	s_nop 0
	global_load_lds_dwordx4 v[220:221], off
	s_mov_b32 m0, s33
	s_nop 0
	global_load_lds_dwordx4 v[222:223], off
	s_waitcnt vmcnt(8) lgkmcnt(0)
	s_barrier
	v_mfma_f32_16x16x32_bf16 v[60:63], v[152:155], v[184:187], v[60:63]
	v_mfma_f32_16x16x32_bf16 v[56:59], v[160:163], v[184:187], v[56:59]
	v_mfma_f32_16x16x32_bf16 v[52:55], v[152:155], v[196:199], v[52:55]
	v_mfma_f32_16x16x32_bf16 v[44:47], v[160:163], v[196:199], v[44:47]
	v_mfma_f32_16x16x32_bf16 v[36:39], v[152:155], v[204:207], v[36:39]
	v_mfma_f32_16x16x32_bf16 v[28:31], v[160:163], v[204:207], v[28:31]
	v_mfma_f32_16x16x32_bf16 v[20:23], v[152:155], v[212:215], v[20:23]
	v_mfma_f32_16x16x32_bf16 v[12:15], v[160:163], v[212:215], v[12:15]
	v_mfma_f32_16x16x32_bf16 v[60:63], v[156:159], v[192:195], v[60:63]
	v_mfma_f32_16x16x32_bf16 v[56:59], v[164:167], v[192:195], v[56:59]
	v_mfma_f32_16x16x32_bf16 v[52:55], v[156:159], v[200:203], v[52:55]
	v_mfma_f32_16x16x32_bf16 v[44:47], v[164:167], v[200:203], v[44:47]
	v_mfma_f32_16x16x32_bf16 v[36:39], v[156:159], v[208:211], v[36:39]
	v_mfma_f32_16x16x32_bf16 v[28:31], v[164:167], v[208:211], v[28:31]
	v_mfma_f32_16x16x32_bf16 v[20:23], v[156:159], v[216:219], v[20:23]
	v_mfma_f32_16x16x32_bf16 v[12:15], v[164:167], v[216:219], v[12:15]
	v_mfma_f32_16x16x32_bf16 v[48:51], v[168:171], v[184:187], v[48:51]
	v_mfma_f32_16x16x32_bf16 v[40:43], v[176:179], v[184:187], v[40:43]
	v_mfma_f32_16x16x32_bf16 v[32:35], v[168:171], v[196:199], v[32:35]
	v_mfma_f32_16x16x32_bf16 v[24:27], v[176:179], v[196:199], v[24:27]
	v_mfma_f32_16x16x32_bf16 v[16:19], v[168:171], v[204:207], v[16:19]
	v_mfma_f32_16x16x32_bf16 v[8:11], v[176:179], v[204:207], v[8:11]
	v_mfma_f32_16x16x32_bf16 v[4:7], v[168:171], v[212:215], v[4:7]
	v_mfma_f32_16x16x32_bf16 v[0:3], v[176:179], v[212:215], v[0:3]
	v_mfma_f32_16x16x32_bf16 v[48:51], v[172:175], v[192:195], v[48:51]
	v_mfma_f32_16x16x32_bf16 v[40:43], v[180:183], v[192:195], v[40:43]
	v_mfma_f32_16x16x32_bf16 v[32:35], v[172:175], v[200:203], v[32:35]
	v_mfma_f32_16x16x32_bf16 v[24:27], v[180:183], v[200:203], v[24:27]
	v_mfma_f32_16x16x32_bf16 v[16:19], v[172:175], v[208:211], v[16:19]
	v_mfma_f32_16x16x32_bf16 v[8:11], v[180:183], v[208:211], v[8:11]
	v_mfma_f32_16x16x32_bf16 v[4:7], v[172:175], v[216:219], v[4:7]
	v_mfma_f32_16x16x32_bf16 v[0:3], v[180:183], v[216:219], v[0:3]
	s_barrier
	s_add_i32 s79, 0, 0x18000
	s_add_i32 s80, 0, 0x1c000
	v_add_u32_e32 v164, s79, v147
	v_add_u32_e32 v180, s80, v147
	ds_read_b128 v[152:155], v164
	ds_read_b128 v[156:159], v164 offset:1024
	ds_read_b128 v[160:163], v164 offset:2048
	ds_read_b128 v[164:167], v164 offset:3072
	ds_read_b128 v[168:171], v180
	ds_read_b128 v[172:175], v180 offset:1024
	ds_read_b128 v[176:179], v180 offset:2048
	ds_read_b128 v[180:183], v180 offset:3072
	s_add_u32 s42, s42, 0x40000
	s_addc_u32 s43, s43, 0
	s_mov_b32 m0, s62
	ds_read_b128 v[184:187], v151 offset:32768
	ds_read_b128 v[192:195], v151 offset:33792
	ds_read_b128 v[196:199], v151 offset:34816
	ds_read_b128 v[200:203], v151 offset:35840
	ds_read_b128 v[204:207], v151 offset:36864
	ds_read_b128 v[208:211], v151 offset:37888
	ds_read_b128 v[212:215], v151 offset:38912
	ds_read_b128 v[216:219], v151 offset:39936
	global_load_lds_dwordx4 v128, s[42:43]
	s_mov_b32 m0, s63
	s_nop 0
	global_load_lds_dwordx4 v132, s[42:43]
	s_waitcnt vmcnt(8) lgkmcnt(0)
	s_barrier
	v_mfma_f32_16x16x32_bf16 v[124:127], v[152:155], v[184:187], v[124:127]
	v_mfma_f32_16x16x32_bf16 v[120:123], v[160:163], v[184:187], v[120:123]
	v_mfma_f32_16x16x32_bf16 v[116:119], v[152:155], v[196:199], v[116:119]
	v_mfma_f32_16x16x32_bf16 v[108:111], v[160:163], v[196:199], v[108:111]
	v_mfma_f32_16x16x32_bf16 v[100:103], v[152:155], v[204:207], v[100:103]
	v_mfma_f32_16x16x32_bf16 v[92:95], v[160:163], v[204:207], v[92:95]
	v_mfma_f32_16x16x32_bf16 v[84:87], v[152:155], v[212:215], v[84:87]
	v_mfma_f32_16x16x32_bf16 v[76:79], v[160:163], v[212:215], v[76:79]
	v_mfma_f32_16x16x32_bf16 v[124:127], v[156:159], v[192:195], v[124:127]
	v_mfma_f32_16x16x32_bf16 v[120:123], v[164:167], v[192:195], v[120:123]
	v_mfma_f32_16x16x32_bf16 v[116:119], v[156:159], v[200:203], v[116:119]
	v_mfma_f32_16x16x32_bf16 v[108:111], v[164:167], v[200:203], v[108:111]
	v_mfma_f32_16x16x32_bf16 v[100:103], v[156:159], v[208:211], v[100:103]
	v_mfma_f32_16x16x32_bf16 v[92:95], v[164:167], v[208:211], v[92:95]
	v_mfma_f32_16x16x32_bf16 v[84:87], v[156:159], v[216:219], v[84:87]
	v_mfma_f32_16x16x32_bf16 v[76:79], v[164:167], v[216:219], v[76:79]
	v_mfma_f32_16x16x32_bf16 v[112:115], v[168:171], v[184:187], v[112:115]
	v_mfma_f32_16x16x32_bf16 v[104:107], v[176:179], v[184:187], v[104:107]
	v_mfma_f32_16x16x32_bf16 v[96:99], v[168:171], v[196:199], v[96:99]
	v_mfma_f32_16x16x32_bf16 v[88:91], v[176:179], v[196:199], v[88:91]
	v_mfma_f32_16x16x32_bf16 v[80:83], v[168:171], v[204:207], v[80:83]
	v_mfma_f32_16x16x32_bf16 v[72:75], v[176:179], v[204:207], v[72:75]
	v_mfma_f32_16x16x32_bf16 v[68:71], v[168:171], v[212:215], v[68:71]
	v_mfma_f32_16x16x32_bf16 v[64:67], v[176:179], v[212:215], v[64:67]
	v_mfma_f32_16x16x32_bf16 v[112:115], v[172:175], v[192:195], v[112:115]
	v_mfma_f32_16x16x32_bf16 v[104:107], v[180:183], v[192:195], v[104:107]
	v_mfma_f32_16x16x32_bf16 v[96:99], v[172:175], v[200:203], v[96:99]
	v_mfma_f32_16x16x32_bf16 v[88:91], v[180:183], v[200:203], v[88:91]
	v_mfma_f32_16x16x32_bf16 v[80:83], v[172:175], v[208:211], v[80:83]
	v_mfma_f32_16x16x32_bf16 v[72:75], v[180:183], v[208:211], v[72:75]
	v_mfma_f32_16x16x32_bf16 v[68:71], v[172:175], v[216:219], v[68:71]
	v_mfma_f32_16x16x32_bf16 v[64:67], v[180:183], v[216:219], v[64:67]
	s_barrier
	s_add_i32 s42, s79, s61
	v_lshl_add_u64 v[144:145], v[144:145], 0, s[10:11]
	s_mov_b32 m0, s42
	ds_read_b128 v[184:187], v151 offset:49152
	ds_read_b128 v[192:195], v151 offset:50176
	ds_read_b128 v[196:199], v151 offset:51200
	ds_read_b128 v[200:203], v151 offset:52224
	ds_read_b128 v[204:207], v151 offset:53248
	ds_read_b128 v[208:211], v151 offset:54272
	ds_read_b128 v[212:215], v151 offset:55296
	ds_read_b128 v[216:219], v151 offset:56320
	global_load_lds_dwordx4 v[144:145], off
	s_add_i32 m0, s42, 0x2000
	s_add_u32 s34, s34, 0x40080
	v_lshl_add_u64 v[144:145], v[188:189], 0, s[10:11]
	s_addc_u32 s35, s35, 0
	s_add_i32 s42, s80, s61
	global_load_lds_dwordx4 v[144:145], off
	s_mov_b32 m0, s42
	s_nop 0
	global_load_lds_dwordx4 v130, s[34:35]
	s_add_i32 m0, s42, 0x2000
	s_nop 0
	global_load_lds_dwordx4 v134, s[34:35]
	v_lshl_add_u64 v[144:145], v[220:221], 0, s[10:11]
	s_mov_b32 m0, s65
	s_nop 0
	global_load_lds_dwordx4 v[144:145], off
	v_lshl_add_u64 v[144:145], v[222:223], 0, s[10:11]
	s_mov_b32 m0, s66
	s_nop 0
	global_load_lds_dwordx4 v[144:145], off
	s_waitcnt vmcnt(8) lgkmcnt(0)
	s_barrier
	v_mfma_f32_16x16x32_bf16 v[60:63], v[152:155], v[184:187], v[60:63]
	v_mfma_f32_16x16x32_bf16 v[56:59], v[160:163], v[184:187], v[56:59]
	v_mfma_f32_16x16x32_bf16 v[52:55], v[152:155], v[196:199], v[52:55]
	v_mfma_f32_16x16x32_bf16 v[44:47], v[160:163], v[196:199], v[44:47]
	v_mfma_f32_16x16x32_bf16 v[36:39], v[152:155], v[204:207], v[36:39]
	v_mfma_f32_16x16x32_bf16 v[28:31], v[160:163], v[204:207], v[28:31]
	v_mfma_f32_16x16x32_bf16 v[20:23], v[152:155], v[212:215], v[20:23]
	v_mfma_f32_16x16x32_bf16 v[12:15], v[160:163], v[212:215], v[12:15]
	v_mfma_f32_16x16x32_bf16 v[60:63], v[156:159], v[192:195], v[60:63]
	v_mfma_f32_16x16x32_bf16 v[56:59], v[164:167], v[192:195], v[56:59]
	v_mfma_f32_16x16x32_bf16 v[52:55], v[156:159], v[200:203], v[52:55]
	v_mfma_f32_16x16x32_bf16 v[44:47], v[164:167], v[200:203], v[44:47]
	v_mfma_f32_16x16x32_bf16 v[36:39], v[156:159], v[208:211], v[36:39]
	v_mfma_f32_16x16x32_bf16 v[28:31], v[164:167], v[208:211], v[28:31]
	v_mfma_f32_16x16x32_bf16 v[20:23], v[156:159], v[216:219], v[20:23]
	v_mfma_f32_16x16x32_bf16 v[12:15], v[164:167], v[216:219], v[12:15]
	v_mfma_f32_16x16x32_bf16 v[48:51], v[168:171], v[184:187], v[48:51]
	v_mfma_f32_16x16x32_bf16 v[40:43], v[176:179], v[184:187], v[40:43]
	v_mfma_f32_16x16x32_bf16 v[32:35], v[168:171], v[196:199], v[32:35]
	v_mfma_f32_16x16x32_bf16 v[24:27], v[176:179], v[196:199], v[24:27]
	v_mfma_f32_16x16x32_bf16 v[16:19], v[168:171], v[204:207], v[16:19]
	v_mfma_f32_16x16x32_bf16 v[8:11], v[176:179], v[204:207], v[8:11]
	v_mfma_f32_16x16x32_bf16 v[4:7], v[168:171], v[212:215], v[4:7]
	v_mfma_f32_16x16x32_bf16 v[0:3], v[176:179], v[212:215], v[0:3]
	v_mfma_f32_16x16x32_bf16 v[48:51], v[172:175], v[192:195], v[48:51]
	v_mfma_f32_16x16x32_bf16 v[40:43], v[180:183], v[192:195], v[40:43]
	v_mfma_f32_16x16x32_bf16 v[32:35], v[172:175], v[200:203], v[32:35]
	v_mfma_f32_16x16x32_bf16 v[24:27], v[180:183], v[200:203], v[24:27]
	v_mfma_f32_16x16x32_bf16 v[16:19], v[172:175], v[208:211], v[16:19]
	v_mfma_f32_16x16x32_bf16 v[8:11], v[180:183], v[208:211], v[8:11]
	v_mfma_f32_16x16x32_bf16 v[4:7], v[172:175], v[216:219], v[4:7]
	v_mfma_f32_16x16x32_bf16 v[0:3], v[180:183], v[216:219], v[0:3]
	s_barrier
	s_add_i32 s77, s77, 2
	s_add_u32 s30, s30, 0x100
	s_addc_u32 s31, s31, 0
	s_add_u32 s75, s75, 0x100
	s_addc_u32 s76, s76, 0
	s_cmp_gt_u32 s77, 13
	s_cbranch_scc0 .LBB0_1434

.LBB0_1570:
	s_ashr_i32 s23, s22, 31
	s_lshl_b64 s[24:25], s[22:23], 19
	s_add_u32 s24, s58, s24
	s_addc_u32 s25, s59, s25
	s_and_b64 s[26:27], s[0:1], exec
	s_cselect_b32 s23, s25, s31
	s_cselect_b32 s54, s24, s30
	s_ashr_i32 s21, s20, 31
	s_lshl_b64 s[26:27], s[20:21], 19
	s_add_u32 s26, s61, s26
	s_addc_u32 s27, s62, s27
	s_and_b64 s[42:43], s[0:1], exec
	s_cselect_b32 s21, s27, s35
	s_cselect_b32 s55, s26, s34
	s_add_u32 s30, s30, 0x40080
	s_addc_u32 s31, s31, 0
	s_add_u32 s75, s34, 0x100
	s_addc_u32 s76, s35, 0
	s_mov_b32 s77, -2
	ds_read_b128 v[152:155], v149
	ds_read_b128 v[156:159], v149 offset:1024
	ds_read_b128 v[160:163], v149 offset:2048
	ds_read_b128 v[164:167], v149 offset:3072
	ds_read_b128 v[168:171], v150
	ds_read_b128 v[172:175], v150 offset:1024
	ds_read_b128 v[176:179], v150 offset:2048
	ds_read_b128 v[180:183], v150 offset:3072
	s_add_u32 s34, s30, 0xfffc0080
	s_addc_u32 s35, s31, -1
	s_cmp_eq_u32 s77, 12
	s_cselect_b32 s43, s23, s35
	s_cselect_b32 s42, s54, s34
	s_cselect_b32 s35, s21, s76
	s_cselect_b32 s34, s55, s75
	s_add_i32 m0, s29, 0xc000
	ds_read_b128 v[184:187], v151
	ds_read_b128 v[192:195], v151 offset:1024
	ds_read_b128 v[196:199], v151 offset:2048
	ds_read_b128 v[200:203], v151 offset:3072
	ds_read_b128 v[204:207], v151 offset:4096
	ds_read_b128 v[208:211], v151 offset:5120
	ds_read_b128 v[212:215], v151 offset:6144
	ds_read_b128 v[216:219], v151 offset:7168
	global_load_lds_dwordx4 v136, s[30:31]
	s_add_i32 m0, s29, 0xe000
	s_nop 0
	global_load_lds_dwordx4 v138, s[30:31]
	s_waitcnt vmcnt(8) lgkmcnt(0)
	s_barrier
	v_mfma_f32_16x16x32_bf16 v[124:127], v[152:155], v[184:187], 0
	v_mfma_f32_16x16x32_bf16 v[120:123], v[160:163], v[184:187], 0
	v_mfma_f32_16x16x32_bf16 v[108:111], v[152:155], v[196:199], 0
	v_mfma_f32_16x16x32_bf16 v[104:107], v[160:163], v[196:199], 0
	v_mfma_f32_16x16x32_bf16 v[92:95], v[152:155], v[204:207], 0
	v_mfma_f32_16x16x32_bf16 v[88:91], v[160:163], v[204:207], 0
	v_mfma_f32_16x16x32_bf16 v[76:79], v[152:155], v[212:215], 0
	v_mfma_f32_16x16x32_bf16 v[72:75], v[160:163], v[212:215], 0
	v_mfma_f32_16x16x32_bf16 v[124:127], v[156:159], v[192:195], v[124:127]
	v_mfma_f32_16x16x32_bf16 v[120:123], v[164:167], v[192:195], v[120:123]
	v_mfma_f32_16x16x32_bf16 v[108:111], v[156:159], v[200:203], v[108:111]
	v_mfma_f32_16x16x32_bf16 v[104:107], v[164:167], v[200:203], v[104:107]
	v_mfma_f32_16x16x32_bf16 v[92:95], v[156:159], v[208:211], v[92:95]
	v_mfma_f32_16x16x32_bf16 v[88:91], v[164:167], v[208:211], v[88:91]
	v_mfma_f32_16x16x32_bf16 v[76:79], v[156:159], v[216:219], v[76:79]
	v_mfma_f32_16x16x32_bf16 v[72:75], v[164:167], v[216:219], v[72:75]
	v_mfma_f32_16x16x32_bf16 v[116:119], v[168:171], v[184:187], 0
	v_mfma_f32_16x16x32_bf16 v[112:115], v[176:179], v[184:187], 0
	v_mfma_f32_16x16x32_bf16 v[100:103], v[168:171], v[196:199], 0
	v_mfma_f32_16x16x32_bf16 v[96:99], v[176:179], v[196:199], 0
	v_mfma_f32_16x16x32_bf16 v[84:87], v[168:171], v[204:207], 0
	v_mfma_f32_16x16x32_bf16 v[80:83], v[176:179], v[204:207], 0
	v_mfma_f32_16x16x32_bf16 v[68:71], v[168:171], v[212:215], 0
	v_mfma_f32_16x16x32_bf16 v[64:67], v[176:179], v[212:215], 0
	v_mfma_f32_16x16x32_bf16 v[116:119], v[172:175], v[192:195], v[116:119]
	v_mfma_f32_16x16x32_bf16 v[112:115], v[180:183], v[192:195], v[112:115]
	v_mfma_f32_16x16x32_bf16 v[100:103], v[172:175], v[200:203], v[100:103]
	v_mfma_f32_16x16x32_bf16 v[96:99], v[180:183], v[200:203], v[96:99]
	v_mfma_f32_16x16x32_bf16 v[84:87], v[172:175], v[208:211], v[84:87]
	v_mfma_f32_16x16x32_bf16 v[80:83], v[180:183], v[208:211], v[80:83]
	v_mfma_f32_16x16x32_bf16 v[68:71], v[172:175], v[216:219], v[68:71]
	v_mfma_f32_16x16x32_bf16 v[64:67], v[180:183], v[216:219], v[64:67]
	s_barrier
	s_add_i32 s79, s69, s63
	v_lshl_add_u64 v[144:145], s[34:35], 0, v[130:131]
	s_mov_b32 m0, s79
	ds_read_b128 v[184:187], v151 offset:16384
	ds_read_b128 v[192:195], v151 offset:17408
	ds_read_b128 v[196:199], v151 offset:18432
	ds_read_b128 v[200:203], v151 offset:19456
	ds_read_b128 v[204:207], v151 offset:20480
	ds_read_b128 v[208:211], v151 offset:21504
	ds_read_b128 v[212:215], v151 offset:22528
	ds_read_b128 v[216:219], v151 offset:23552
	global_load_lds_dwordx4 v[144:145], off
	s_add_i32 m0, s79, 0x2000
	s_add_u32 s80, s34, 0x40000
	v_lshl_add_u64 v[188:189], s[34:35], 0, v[134:135]
	s_addc_u32 s81, s35, 0
	s_add_i32 s79, s70, s63
	global_load_lds_dwordx4 v[188:189], off
	s_mov_b32 m0, s79
	v_lshl_add_u64 v[222:223], s[42:43], 0, v[132:133]
	global_load_lds_dwordx4 v130, s[80:81]
	s_add_i32 m0, s79, 0x2000
	s_nop 0
	global_load_lds_dwordx4 v134, s[80:81]
	v_lshl_add_u64 v[220:221], s[42:43], 0, v[128:129]
	s_mov_b32 m0, s29
	s_nop 0
	global_load_lds_dwordx4 v[220:221], off
	s_mov_b32 m0, s64
	s_nop 0
	global_load_lds_dwordx4 v[222:223], off
	s_waitcnt vmcnt(8) lgkmcnt(0)
	s_barrier
	v_mfma_f32_16x16x32_bf16 v[60:63], v[152:155], v[184:187], 0
	v_mfma_f32_16x16x32_bf16 v[56:59], v[160:163], v[184:187], 0
	v_mfma_f32_16x16x32_bf16 v[44:47], v[152:155], v[196:199], 0
	v_mfma_f32_16x16x32_bf16 v[40:43], v[160:163], v[196:199], 0
	v_mfma_f32_16x16x32_bf16 v[28:31], v[152:155], v[204:207], 0
	v_mfma_f32_16x16x32_bf16 v[24:27], v[160:163], v[204:207], 0
	v_mfma_f32_16x16x32_bf16 v[12:15], v[152:155], v[212:215], 0
	v_mfma_f32_16x16x32_bf16 v[8:11], v[160:163], v[212:215], 0
	v_mfma_f32_16x16x32_bf16 v[60:63], v[156:159], v[192:195], v[60:63]
	v_mfma_f32_16x16x32_bf16 v[56:59], v[164:167], v[192:195], v[56:59]
	v_mfma_f32_16x16x32_bf16 v[44:47], v[156:159], v[200:203], v[44:47]
	v_mfma_f32_16x16x32_bf16 v[40:43], v[164:167], v[200:203], v[40:43]
	v_mfma_f32_16x16x32_bf16 v[28:31], v[156:159], v[208:211], v[28:31]
	v_mfma_f32_16x16x32_bf16 v[24:27], v[164:167], v[208:211], v[24:27]
	v_mfma_f32_16x16x32_bf16 v[12:15], v[156:159], v[216:219], v[12:15]
	v_mfma_f32_16x16x32_bf16 v[8:11], v[164:167], v[216:219], v[8:11]
	v_mfma_f32_16x16x32_bf16 v[52:55], v[168:171], v[184:187], 0
	v_mfma_f32_16x16x32_bf16 v[48:51], v[176:179], v[184:187], 0
	v_mfma_f32_16x16x32_bf16 v[36:39], v[168:171], v[196:199], 0
	v_mfma_f32_16x16x32_bf16 v[32:35], v[176:179], v[196:199], 0
	v_mfma_f32_16x16x32_bf16 v[20:23], v[168:171], v[204:207], 0
	v_mfma_f32_16x16x32_bf16 v[16:19], v[176:179], v[204:207], 0
	v_mfma_f32_16x16x32_bf16 v[4:7], v[168:171], v[212:215], 0
	v_mfma_f32_16x16x32_bf16 v[0:3], v[176:179], v[212:215], 0
	v_mfma_f32_16x16x32_bf16 v[52:55], v[172:175], v[192:195], v[52:55]
	v_mfma_f32_16x16x32_bf16 v[48:51], v[180:183], v[192:195], v[48:51]
	v_mfma_f32_16x16x32_bf16 v[36:39], v[172:175], v[200:203], v[36:39]
	v_mfma_f32_16x16x32_bf16 v[32:35], v[180:183], v[200:203], v[32:35]
	v_mfma_f32_16x16x32_bf16 v[20:23], v[172:175], v[208:211], v[20:23]
	v_mfma_f32_16x16x32_bf16 v[16:19], v[180:183], v[208:211], v[16:19]
	v_mfma_f32_16x16x32_bf16 v[4:7], v[172:175], v[216:219], v[4:7]
	v_mfma_f32_16x16x32_bf16 v[0:3], v[180:183], v[216:219], v[0:3]
	s_barrier
	s_add_i32 s79, 0, 0x18000
	s_add_i32 s80, 0, 0x1c000
	v_add_u32_e32 v164, s79, v147
	v_add_u32_e32 v180, s80, v147
	ds_read_b128 v[152:155], v164
	ds_read_b128 v[156:159], v164 offset:1024
	ds_read_b128 v[160:163], v164 offset:2048
	ds_read_b128 v[164:167], v164 offset:3072
	ds_read_b128 v[168:171], v180
	ds_read_b128 v[172:175], v180 offset:1024
	ds_read_b128 v[176:179], v180 offset:2048
	ds_read_b128 v[180:183], v180 offset:3072
	s_add_u32 s42, s42, 0x40000
	s_addc_u32 s43, s43, 0
	s_mov_b32 m0, s65
	ds_read_b128 v[184:187], v151 offset:32768
	ds_read_b128 v[192:195], v151 offset:33792
	ds_read_b128 v[196:199], v151 offset:34816
	ds_read_b128 v[200:203], v151 offset:35840
	ds_read_b128 v[204:207], v151 offset:36864
	ds_read_b128 v[208:211], v151 offset:37888
	ds_read_b128 v[212:215], v151 offset:38912
	ds_read_b128 v[216:219], v151 offset:39936
	global_load_lds_dwordx4 v128, s[42:43]
	s_mov_b32 m0, s66
	s_nop 0
	global_load_lds_dwordx4 v132, s[42:43]
	s_waitcnt vmcnt(8) lgkmcnt(0)
	s_barrier
	v_mfma_f32_16x16x32_bf16 v[124:127], v[152:155], v[184:187], v[124:127]
	v_mfma_f32_16x16x32_bf16 v[120:123], v[160:163], v[184:187], v[120:123]
	v_mfma_f32_16x16x32_bf16 v[108:111], v[152:155], v[196:199], v[108:111]
	v_mfma_f32_16x16x32_bf16 v[104:107], v[160:163], v[196:199], v[104:107]
	v_mfma_f32_16x16x32_bf16 v[92:95], v[152:155], v[204:207], v[92:95]
	v_mfma_f32_16x16x32_bf16 v[88:91], v[160:163], v[204:207], v[88:91]
	v_mfma_f32_16x16x32_bf16 v[76:79], v[152:155], v[212:215], v[76:79]
	v_mfma_f32_16x16x32_bf16 v[72:75], v[160:163], v[212:215], v[72:75]
	v_mfma_f32_16x16x32_bf16 v[124:127], v[156:159], v[192:195], v[124:127]
	v_mfma_f32_16x16x32_bf16 v[120:123], v[164:167], v[192:195], v[120:123]
	v_mfma_f32_16x16x32_bf16 v[108:111], v[156:159], v[200:203], v[108:111]
	v_mfma_f32_16x16x32_bf16 v[104:107], v[164:167], v[200:203], v[104:107]
	v_mfma_f32_16x16x32_bf16 v[92:95], v[156:159], v[208:211], v[92:95]
	v_mfma_f32_16x16x32_bf16 v[88:91], v[164:167], v[208:211], v[88:91]
	v_mfma_f32_16x16x32_bf16 v[76:79], v[156:159], v[216:219], v[76:79]
	v_mfma_f32_16x16x32_bf16 v[72:75], v[164:167], v[216:219], v[72:75]
	v_mfma_f32_16x16x32_bf16 v[116:119], v[168:171], v[184:187], v[116:119]
	v_mfma_f32_16x16x32_bf16 v[112:115], v[176:179], v[184:187], v[112:115]
	v_mfma_f32_16x16x32_bf16 v[100:103], v[168:171], v[196:199], v[100:103]
	v_mfma_f32_16x16x32_bf16 v[96:99], v[176:179], v[196:199], v[96:99]
	v_mfma_f32_16x16x32_bf16 v[84:87], v[168:171], v[204:207], v[84:87]
	v_mfma_f32_16x16x32_bf16 v[80:83], v[176:179], v[204:207], v[80:83]
	v_mfma_f32_16x16x32_bf16 v[68:71], v[168:171], v[212:215], v[68:71]
	v_mfma_f32_16x16x32_bf16 v[64:67], v[176:179], v[212:215], v[64:67]
	v_mfma_f32_16x16x32_bf16 v[116:119], v[172:175], v[192:195], v[116:119]
	v_mfma_f32_16x16x32_bf16 v[112:115], v[180:183], v[192:195], v[112:115]
	v_mfma_f32_16x16x32_bf16 v[100:103], v[172:175], v[200:203], v[100:103]
	v_mfma_f32_16x16x32_bf16 v[96:99], v[180:183], v[200:203], v[96:99]
	v_mfma_f32_16x16x32_bf16 v[84:87], v[172:175], v[208:211], v[84:87]
	v_mfma_f32_16x16x32_bf16 v[80:83], v[180:183], v[208:211], v[80:83]
	v_mfma_f32_16x16x32_bf16 v[68:71], v[172:175], v[216:219], v[68:71]
	v_mfma_f32_16x16x32_bf16 v[64:67], v[180:183], v[216:219], v[64:67]
	s_barrier
	s_add_i32 s42, s79, s63
	v_lshl_add_u64 v[144:145], v[144:145], 0, s[8:9]
	s_mov_b32 m0, s42
	ds_read_b128 v[184:187], v151 offset:49152
	ds_read_b128 v[192:195], v151 offset:50176
	ds_read_b128 v[196:199], v151 offset:51200
	ds_read_b128 v[200:203], v151 offset:52224
	ds_read_b128 v[204:207], v151 offset:53248
	ds_read_b128 v[208:211], v151 offset:54272
	ds_read_b128 v[212:215], v151 offset:55296
	ds_read_b128 v[216:219], v151 offset:56320
	global_load_lds_dwordx4 v[144:145], off
	s_add_i32 m0, s42, 0x2000
	s_add_u32 s34, s34, 0x40080
	v_lshl_add_u64 v[144:145], v[188:189], 0, s[8:9]
	s_addc_u32 s35, s35, 0
	s_add_i32 s42, s80, s63
	global_load_lds_dwordx4 v[144:145], off
	s_mov_b32 m0, s42
	s_nop 0
	global_load_lds_dwordx4 v130, s[34:35]
	s_add_i32 m0, s42, 0x2000
	s_nop 0
	global_load_lds_dwordx4 v134, s[34:35]
	v_lshl_add_u64 v[144:145], v[220:221], 0, s[8:9]
	s_mov_b32 m0, s52
	s_nop 0
	global_load_lds_dwordx4 v[144:145], off
	v_lshl_add_u64 v[144:145], v[222:223], 0, s[8:9]
	s_mov_b32 m0, s53
	s_nop 0
	global_load_lds_dwordx4 v[144:145], off
	s_waitcnt vmcnt(8) lgkmcnt(0)
	s_barrier
	v_mfma_f32_16x16x32_bf16 v[60:63], v[152:155], v[184:187], v[60:63]
	v_mfma_f32_16x16x32_bf16 v[56:59], v[160:163], v[184:187], v[56:59]
	v_mfma_f32_16x16x32_bf16 v[44:47], v[152:155], v[196:199], v[44:47]
	v_mfma_f32_16x16x32_bf16 v[40:43], v[160:163], v[196:199], v[40:43]
	v_mfma_f32_16x16x32_bf16 v[28:31], v[152:155], v[204:207], v[28:31]
	v_mfma_f32_16x16x32_bf16 v[24:27], v[160:163], v[204:207], v[24:27]
	v_mfma_f32_16x16x32_bf16 v[12:15], v[152:155], v[212:215], v[12:15]
	v_mfma_f32_16x16x32_bf16 v[8:11], v[160:163], v[212:215], v[8:11]
	v_mfma_f32_16x16x32_bf16 v[60:63], v[156:159], v[192:195], v[60:63]
	v_mfma_f32_16x16x32_bf16 v[56:59], v[164:167], v[192:195], v[56:59]
	v_mfma_f32_16x16x32_bf16 v[44:47], v[156:159], v[200:203], v[44:47]
	v_mfma_f32_16x16x32_bf16 v[40:43], v[164:167], v[200:203], v[40:43]
	v_mfma_f32_16x16x32_bf16 v[28:31], v[156:159], v[208:211], v[28:31]
	v_mfma_f32_16x16x32_bf16 v[24:27], v[164:167], v[208:211], v[24:27]
	v_mfma_f32_16x16x32_bf16 v[12:15], v[156:159], v[216:219], v[12:15]
	v_mfma_f32_16x16x32_bf16 v[8:11], v[164:167], v[216:219], v[8:11]
	v_mfma_f32_16x16x32_bf16 v[52:55], v[168:171], v[184:187], v[52:55]
	v_mfma_f32_16x16x32_bf16 v[48:51], v[176:179], v[184:187], v[48:51]
	v_mfma_f32_16x16x32_bf16 v[36:39], v[168:171], v[196:199], v[36:39]
	v_mfma_f32_16x16x32_bf16 v[32:35], v[176:179], v[196:199], v[32:35]
	v_mfma_f32_16x16x32_bf16 v[20:23], v[168:171], v[204:207], v[20:23]
	v_mfma_f32_16x16x32_bf16 v[16:19], v[176:179], v[204:207], v[16:19]
	v_mfma_f32_16x16x32_bf16 v[4:7], v[168:171], v[212:215], v[4:7]
	v_mfma_f32_16x16x32_bf16 v[0:3], v[176:179], v[212:215], v[0:3]
	v_mfma_f32_16x16x32_bf16 v[52:55], v[172:175], v[192:195], v[52:55]
	v_mfma_f32_16x16x32_bf16 v[48:51], v[180:183], v[192:195], v[48:51]
	v_mfma_f32_16x16x32_bf16 v[36:39], v[172:175], v[200:203], v[36:39]
	v_mfma_f32_16x16x32_bf16 v[32:35], v[180:183], v[200:203], v[32:35]
	v_mfma_f32_16x16x32_bf16 v[20:23], v[172:175], v[208:211], v[20:23]
	v_mfma_f32_16x16x32_bf16 v[16:19], v[180:183], v[208:211], v[16:19]
	v_mfma_f32_16x16x32_bf16 v[4:7], v[172:175], v[216:219], v[4:7]
	v_mfma_f32_16x16x32_bf16 v[0:3], v[180:183], v[216:219], v[0:3]
	s_barrier
	s_add_i32 s77, s77, 2
	s_add_u32 s30, s30, 0x100
	s_addc_u32 s31, s31, 0
	s_add_u32 s75, s75, 0x100
	s_addc_u32 s76, s76, 0
	s_cmp_gt_u32 s77, 13
	s_cbranch_scc0 .LBB0_1571
	s_branch .Lpeel_exit11
.LBB0_1571:
	ds_read_b128 v[152:155], v149
	ds_read_b128 v[156:159], v149 offset:1024
	ds_read_b128 v[160:163], v149 offset:2048
	ds_read_b128 v[164:167], v149 offset:3072
	ds_read_b128 v[168:171], v150
	ds_read_b128 v[172:175], v150 offset:1024
	ds_read_b128 v[176:179], v150 offset:2048
	ds_read_b128 v[180:183], v150 offset:3072
	s_add_u32 s34, s30, 0xfffc0080
	s_addc_u32 s35, s31, -1
	s_cmp_eq_u32 s77, 12
	s_cselect_b32 s43, s23, s35
	s_cselect_b32 s42, s54, s34
	s_cselect_b32 s35, s21, s76
	s_cselect_b32 s34, s55, s75
	s_add_i32 m0, s29, 0xc000
	ds_read_b128 v[184:187], v151
	ds_read_b128 v[192:195], v151 offset:1024
	ds_read_b128 v[196:199], v151 offset:2048
	ds_read_b128 v[200:203], v151 offset:3072
	ds_read_b128 v[204:207], v151 offset:4096
	ds_read_b128 v[208:211], v151 offset:5120
	ds_read_b128 v[212:215], v151 offset:6144
	ds_read_b128 v[216:219], v151 offset:7168
	global_load_lds_dwordx4 v136, s[30:31]
	s_add_i32 m0, s29, 0xe000
	s_nop 0
	global_load_lds_dwordx4 v138, s[30:31]
	s_waitcnt vmcnt(8) lgkmcnt(0)
	s_barrier
	v_mfma_f32_16x16x32_bf16 v[124:127], v[152:155], v[184:187], v[124:127]
	v_mfma_f32_16x16x32_bf16 v[120:123], v[160:163], v[184:187], v[120:123]
	v_mfma_f32_16x16x32_bf16 v[108:111], v[152:155], v[196:199], v[108:111]
	v_mfma_f32_16x16x32_bf16 v[104:107], v[160:163], v[196:199], v[104:107]
	v_mfma_f32_16x16x32_bf16 v[92:95], v[152:155], v[204:207], v[92:95]
	v_mfma_f32_16x16x32_bf16 v[88:91], v[160:163], v[204:207], v[88:91]
	v_mfma_f32_16x16x32_bf16 v[76:79], v[152:155], v[212:215], v[76:79]
	v_mfma_f32_16x16x32_bf16 v[72:75], v[160:163], v[212:215], v[72:75]
	v_mfma_f32_16x16x32_bf16 v[124:127], v[156:159], v[192:195], v[124:127]
	v_mfma_f32_16x16x32_bf16 v[120:123], v[164:167], v[192:195], v[120:123]
	v_mfma_f32_16x16x32_bf16 v[108:111], v[156:159], v[200:203], v[108:111]
	v_mfma_f32_16x16x32_bf16 v[104:107], v[164:167], v[200:203], v[104:107]
	v_mfma_f32_16x16x32_bf16 v[92:95], v[156:159], v[208:211], v[92:95]
	v_mfma_f32_16x16x32_bf16 v[88:91], v[164:167], v[208:211], v[88:91]
	v_mfma_f32_16x16x32_bf16 v[76:79], v[156:159], v[216:219], v[76:79]
	v_mfma_f32_16x16x32_bf16 v[72:75], v[164:167], v[216:219], v[72:75]
	v_mfma_f32_16x16x32_bf16 v[116:119], v[168:171], v[184:187], v[116:119]
	v_mfma_f32_16x16x32_bf16 v[112:115], v[176:179], v[184:187], v[112:115]
	v_mfma_f32_16x16x32_bf16 v[100:103], v[168:171], v[196:199], v[100:103]
	v_mfma_f32_16x16x32_bf16 v[96:99], v[176:179], v[196:199], v[96:99]
	v_mfma_f32_16x16x32_bf16 v[84:87], v[168:171], v[204:207], v[84:87]
	v_mfma_f32_16x16x32_bf16 v[80:83], v[176:179], v[204:207], v[80:83]
	v_mfma_f32_16x16x32_bf16 v[68:71], v[168:171], v[212:215], v[68:71]
	v_mfma_f32_16x16x32_bf16 v[64:67], v[176:179], v[212:215], v[64:67]
	v_mfma_f32_16x16x32_bf16 v[116:119], v[172:175], v[192:195], v[116:119]
	v_mfma_f32_16x16x32_bf16 v[112:115], v[180:183], v[192:195], v[112:115]
	v_mfma_f32_16x16x32_bf16 v[100:103], v[172:175], v[200:203], v[100:103]
	v_mfma_f32_16x16x32_bf16 v[96:99], v[180:183], v[200:203], v[96:99]
	v_mfma_f32_16x16x32_bf16 v[84:87], v[172:175], v[208:211], v[84:87]
	v_mfma_f32_16x16x32_bf16 v[80:83], v[180:183], v[208:211], v[80:83]
	v_mfma_f32_16x16x32_bf16 v[68:71], v[172:175], v[216:219], v[68:71]
	v_mfma_f32_16x16x32_bf16 v[64:67], v[180:183], v[216:219], v[64:67]
	s_barrier
	s_add_i32 s79, s69, s63
	v_lshl_add_u64 v[144:145], s[34:35], 0, v[130:131]
	s_mov_b32 m0, s79
	ds_read_b128 v[184:187], v151 offset:16384
	ds_read_b128 v[192:195], v151 offset:17408
	ds_read_b128 v[196:199], v151 offset:18432
	ds_read_b128 v[200:203], v151 offset:19456
	ds_read_b128 v[204:207], v151 offset:20480
	ds_read_b128 v[208:211], v151 offset:21504
	ds_read_b128 v[212:215], v151 offset:22528
	ds_read_b128 v[216:219], v151 offset:23552
	global_load_lds_dwordx4 v[144:145], off
	s_add_i32 m0, s79, 0x2000
	s_add_u32 s80, s34, 0x40000
	v_lshl_add_u64 v[188:189], s[34:35], 0, v[134:135]
	s_addc_u32 s81, s35, 0
	s_add_i32 s79, s70, s63
	global_load_lds_dwordx4 v[188:189], off
	s_mov_b32 m0, s79
	v_lshl_add_u64 v[222:223], s[42:43], 0, v[132:133]
	global_load_lds_dwordx4 v130, s[80:81]
	s_add_i32 m0, s79, 0x2000
	s_nop 0
	global_load_lds_dwordx4 v134, s[80:81]
	v_lshl_add_u64 v[220:221], s[42:43], 0, v[128:129]
	s_mov_b32 m0, s29
	s_nop 0
	global_load_lds_dwordx4 v[220:221], off
	s_mov_b32 m0, s64
	s_nop 0
	global_load_lds_dwordx4 v[222:223], off
	s_waitcnt vmcnt(8) lgkmcnt(0)
	s_barrier
	v_mfma_f32_16x16x32_bf16 v[60:63], v[152:155], v[184:187], v[60:63]
	v_mfma_f32_16x16x32_bf16 v[56:59], v[160:163], v[184:187], v[56:59]
	v_mfma_f32_16x16x32_bf16 v[44:47], v[152:155], v[196:199], v[44:47]
	v_mfma_f32_16x16x32_bf16 v[40:43], v[160:163], v[196:199], v[40:43]
	v_mfma_f32_16x16x32_bf16 v[28:31], v[152:155], v[204:207], v[28:31]
	v_mfma_f32_16x16x32_bf16 v[24:27], v[160:163], v[204:207], v[24:27]
	v_mfma_f32_16x16x32_bf16 v[12:15], v[152:155], v[212:215], v[12:15]
	v_mfma_f32_16x16x32_bf16 v[8:11], v[160:163], v[212:215], v[8:11]
	v_mfma_f32_16x16x32_bf16 v[60:63], v[156:159], v[192:195], v[60:63]
	v_mfma_f32_16x16x32_bf16 v[56:59], v[164:167], v[192:195], v[56:59]
	v_mfma_f32_16x16x32_bf16 v[44:47], v[156:159], v[200:203], v[44:47]
	v_mfma_f32_16x16x32_bf16 v[40:43], v[164:167], v[200:203], v[40:43]
	v_mfma_f32_16x16x32_bf16 v[28:31], v[156:159], v[208:211], v[28:31]
	v_mfma_f32_16x16x32_bf16 v[24:27], v[164:167], v[208:211], v[24:27]
	v_mfma_f32_16x16x32_bf16 v[12:15], v[156:159], v[216:219], v[12:15]
	v_mfma_f32_16x16x32_bf16 v[8:11], v[164:167], v[216:219], v[8:11]
	v_mfma_f32_16x16x32_bf16 v[52:55], v[168:171], v[184:187], v[52:55]
	v_mfma_f32_16x16x32_bf16 v[48:51], v[176:179], v[184:187], v[48:51]
	v_mfma_f32_16x16x32_bf16 v[36:39], v[168:171], v[196:199], v[36:39]
	v_mfma_f32_16x16x32_bf16 v[32:35], v[176:179], v[196:199], v[32:35]
	v_mfma_f32_16x16x32_bf16 v[20:23], v[168:171], v[204:207], v[20:23]
	v_mfma_f32_16x16x32_bf16 v[16:19], v[176:179], v[204:207], v[16:19]
	v_mfma_f32_16x16x32_bf16 v[4:7], v[168:171], v[212:215], v[4:7]
	v_mfma_f32_16x16x32_bf16 v[0:3], v[176:179], v[212:215], v[0:3]
	v_mfma_f32_16x16x32_bf16 v[52:55], v[172:175], v[192:195], v[52:55]
	v_mfma_f32_16x16x32_bf16 v[48:51], v[180:183], v[192:195], v[48:51]
	v_mfma_f32_16x16x32_bf16 v[36:39], v[172:175], v[200:203], v[36:39]
	v_mfma_f32_16x16x32_bf16 v[32:35], v[180:183], v[200:203], v[32:35]
	v_mfma_f32_16x16x32_bf16 v[20:23], v[172:175], v[208:211], v[20:23]
	v_mfma_f32_16x16x32_bf16 v[16:19], v[180:183], v[208:211], v[16:19]
	v_mfma_f32_16x16x32_bf16 v[4:7], v[172:175], v[216:219], v[4:7]
	v_mfma_f32_16x16x32_bf16 v[0:3], v[180:183], v[216:219], v[0:3]
	s_barrier
	s_add_i32 s79, 0, 0x18000
	s_add_i32 s80, 0, 0x1c000
	v_add_u32_e32 v164, s79, v147
	v_add_u32_e32 v180, s80, v147
	ds_read_b128 v[152:155], v164
	ds_read_b128 v[156:159], v164 offset:1024
	ds_read_b128 v[160:163], v164 offset:2048
	ds_read_b128 v[164:167], v164 offset:3072
	ds_read_b128 v[168:171], v180
	ds_read_b128 v[172:175], v180 offset:1024
	ds_read_b128 v[176:179], v180 offset:2048
	ds_read_b128 v[180:183], v180 offset:3072
	s_add_u32 s42, s42, 0x40000
	s_addc_u32 s43, s43, 0
	s_mov_b32 m0, s65
	ds_read_b128 v[184:187], v151 offset:32768
	ds_read_b128 v[192:195], v151 offset:33792
	ds_read_b128 v[196:199], v151 offset:34816
	ds_read_b128 v[200:203], v151 offset:35840
	ds_read_b128 v[204:207], v151 offset:36864
	ds_read_b128 v[208:211], v151 offset:37888
	ds_read_b128 v[212:215], v151 offset:38912
	ds_read_b128 v[216:219], v151 offset:39936
	global_load_lds_dwordx4 v128, s[42:43]
	s_mov_b32 m0, s66
	s_nop 0
	global_load_lds_dwordx4 v132, s[42:43]
	s_waitcnt vmcnt(8) lgkmcnt(0)
	s_barrier
	v_mfma_f32_16x16x32_bf16 v[124:127], v[152:155], v[184:187], v[124:127]
	v_mfma_f32_16x16x32_bf16 v[120:123], v[160:163], v[184:187], v[120:123]
	v_mfma_f32_16x16x32_bf16 v[108:111], v[152:155], v[196:199], v[108:111]
	v_mfma_f32_16x16x32_bf16 v[104:107], v[160:163], v[196:199], v[104:107]
	v_mfma_f32_16x16x32_bf16 v[92:95], v[152:155], v[204:207], v[92:95]
	v_mfma_f32_16x16x32_bf16 v[88:91], v[160:163], v[204:207], v[88:91]
	v_mfma_f32_16x16x32_bf16 v[76:79], v[152:155], v[212:215], v[76:79]
	v_mfma_f32_16x16x32_bf16 v[72:75], v[160:163], v[212:215], v[72:75]
	v_mfma_f32_16x16x32_bf16 v[124:127], v[156:159], v[192:195], v[124:127]
	v_mfma_f32_16x16x32_bf16 v[120:123], v[164:167], v[192:195], v[120:123]
	v_mfma_f32_16x16x32_bf16 v[108:111], v[156:159], v[200:203], v[108:111]
	v_mfma_f32_16x16x32_bf16 v[104:107], v[164:167], v[200:203], v[104:107]
	v_mfma_f32_16x16x32_bf16 v[92:95], v[156:159], v[208:211], v[92:95]
	v_mfma_f32_16x16x32_bf16 v[88:91], v[164:167], v[208:211], v[88:91]
	v_mfma_f32_16x16x32_bf16 v[76:79], v[156:159], v[216:219], v[76:79]
	v_mfma_f32_16x16x32_bf16 v[72:75], v[164:167], v[216:219], v[72:75]
	v_mfma_f32_16x16x32_bf16 v[116:119], v[168:171], v[184:187], v[116:119]
	v_mfma_f32_16x16x32_bf16 v[112:115], v[176:179], v[184:187], v[112:115]
	v_mfma_f32_16x16x32_bf16 v[100:103], v[168:171], v[196:199], v[100:103]
	v_mfma_f32_16x16x32_bf16 v[96:99], v[176:179], v[196:199], v[96:99]
	v_mfma_f32_16x16x32_bf16 v[84:87], v[168:171], v[204:207], v[84:87]
	v_mfma_f32_16x16x32_bf16 v[80:83], v[176:179], v[204:207], v[80:83]
	v_mfma_f32_16x16x32_bf16 v[68:71], v[168:171], v[212:215], v[68:71]
	v_mfma_f32_16x16x32_bf16 v[64:67], v[176:179], v[212:215], v[64:67]
	v_mfma_f32_16x16x32_bf16 v[116:119], v[172:175], v[192:195], v[116:119]
	v_mfma_f32_16x16x32_bf16 v[112:115], v[180:183], v[192:195], v[112:115]
	v_mfma_f32_16x16x32_bf16 v[100:103], v[172:175], v[200:203], v[100:103]
	v_mfma_f32_16x16x32_bf16 v[96:99], v[180:183], v[200:203], v[96:99]
	v_mfma_f32_16x16x32_bf16 v[84:87], v[172:175], v[208:211], v[84:87]
	v_mfma_f32_16x16x32_bf16 v[80:83], v[180:183], v[208:211], v[80:83]
	v_mfma_f32_16x16x32_bf16 v[68:71], v[172:175], v[216:219], v[68:71]
	v_mfma_f32_16x16x32_bf16 v[64:67], v[180:183], v[216:219], v[64:67]
	s_barrier
	s_add_i32 s42, s79, s63
	v_lshl_add_u64 v[144:145], v[144:145], 0, s[8:9]
	s_mov_b32 m0, s42
	ds_read_b128 v[184:187], v151 offset:49152
	ds_read_b128 v[192:195], v151 offset:50176
	ds_read_b128 v[196:199], v151 offset:51200
	ds_read_b128 v[200:203], v151 offset:52224
	ds_read_b128 v[204:207], v151 offset:53248
	ds_read_b128 v[208:211], v151 offset:54272
	ds_read_b128 v[212:215], v151 offset:55296
	ds_read_b128 v[216:219], v151 offset:56320
	global_load_lds_dwordx4 v[144:145], off
	s_add_i32 m0, s42, 0x2000
	s_add_u32 s34, s34, 0x40080
	v_lshl_add_u64 v[144:145], v[188:189], 0, s[8:9]
	s_addc_u32 s35, s35, 0
	s_add_i32 s42, s80, s63
	global_load_lds_dwordx4 v[144:145], off
	s_mov_b32 m0, s42
	s_nop 0
	global_load_lds_dwordx4 v130, s[34:35]
	s_add_i32 m0, s42, 0x2000
	s_nop 0
	global_load_lds_dwordx4 v134, s[34:35]
	v_lshl_add_u64 v[144:145], v[220:221], 0, s[8:9]
	s_mov_b32 m0, s52
	s_nop 0
	global_load_lds_dwordx4 v[144:145], off
	v_lshl_add_u64 v[144:145], v[222:223], 0, s[8:9]
	s_mov_b32 m0, s53
	s_nop 0
	global_load_lds_dwordx4 v[144:145], off
	s_waitcnt vmcnt(8) lgkmcnt(0)
	s_barrier
	v_mfma_f32_16x16x32_bf16 v[60:63], v[152:155], v[184:187], v[60:63]
	v_mfma_f32_16x16x32_bf16 v[56:59], v[160:163], v[184:187], v[56:59]
	v_mfma_f32_16x16x32_bf16 v[44:47], v[152:155], v[196:199], v[44:47]
	v_mfma_f32_16x16x32_bf16 v[40:43], v[160:163], v[196:199], v[40:43]
	v_mfma_f32_16x16x32_bf16 v[28:31], v[152:155], v[204:207], v[28:31]
	v_mfma_f32_16x16x32_bf16 v[24:27], v[160:163], v[204:207], v[24:27]
	v_mfma_f32_16x16x32_bf16 v[12:15], v[152:155], v[212:215], v[12:15]
	v_mfma_f32_16x16x32_bf16 v[8:11], v[160:163], v[212:215], v[8:11]
	v_mfma_f32_16x16x32_bf16 v[60:63], v[156:159], v[192:195], v[60:63]
	v_mfma_f32_16x16x32_bf16 v[56:59], v[164:167], v[192:195], v[56:59]
	v_mfma_f32_16x16x32_bf16 v[44:47], v[156:159], v[200:203], v[44:47]
	v_mfma_f32_16x16x32_bf16 v[40:43], v[164:167], v[200:203], v[40:43]
	v_mfma_f32_16x16x32_bf16 v[28:31], v[156:159], v[208:211], v[28:31]
	v_mfma_f32_16x16x32_bf16 v[24:27], v[164:167], v[208:211], v[24:27]
	v_mfma_f32_16x16x32_bf16 v[12:15], v[156:159], v[216:219], v[12:15]
	v_mfma_f32_16x16x32_bf16 v[8:11], v[164:167], v[216:219], v[8:11]
	v_mfma_f32_16x16x32_bf16 v[52:55], v[168:171], v[184:187], v[52:55]
	v_mfma_f32_16x16x32_bf16 v[48:51], v[176:179], v[184:187], v[48:51]
	v_mfma_f32_16x16x32_bf16 v[36:39], v[168:171], v[196:199], v[36:39]
	v_mfma_f32_16x16x32_bf16 v[32:35], v[176:179], v[196:199], v[32:35]
	v_mfma_f32_16x16x32_bf16 v[20:23], v[168:171], v[204:207], v[20:23]
	v_mfma_f32_16x16x32_bf16 v[16:19], v[176:179], v[204:207], v[16:19]
	v_mfma_f32_16x16x32_bf16 v[4:7], v[168:171], v[212:215], v[4:7]
	v_mfma_f32_16x16x32_bf16 v[0:3], v[176:179], v[212:215], v[0:3]
	v_mfma_f32_16x16x32_bf16 v[52:55], v[172:175], v[192:195], v[52:55]
	v_mfma_f32_16x16x32_bf16 v[48:51], v[180:183], v[192:195], v[48:51]
	v_mfma_f32_16x16x32_bf16 v[36:39], v[172:175], v[200:203], v[36:39]
	v_mfma_f32_16x16x32_bf16 v[32:35], v[180:183], v[200:203], v[32:35]
	v_mfma_f32_16x16x32_bf16 v[20:23], v[172:175], v[208:211], v[20:23]
	v_mfma_f32_16x16x32_bf16 v[16:19], v[180:183], v[208:211], v[16:19]
	v_mfma_f32_16x16x32_bf16 v[4:7], v[172:175], v[216:219], v[4:7]
	v_mfma_f32_16x16x32_bf16 v[0:3], v[180:183], v[216:219], v[0:3]
	s_barrier
	s_add_i32 s77, s77, 2
	s_add_u32 s30, s30, 0x100
	s_addc_u32 s31, s31, 0
	s_add_u32 s75, s75, 0x100
	s_addc_u32 s76, s76, 0
	s_cmp_gt_u32 s77, 13
	s_cbranch_scc0 .LBB0_1571

.LBB0_1649:
	s_ashr_i32 s23, s22, 31
	s_lshl_b64 s[24:25], s[22:23], 21
	s_add_u32 s24, s56, s24
	s_addc_u32 s25, s57, s25
	s_and_b64 s[26:27], s[0:1], exec
	s_cselect_b32 s23, s25, s31
	s_cselect_b32 s55, s24, s30
	s_ashr_i32 s21, s20, 31
	s_lshl_b64 s[26:27], s[20:21], 21
	s_add_u32 s26, s53, s26
	s_addc_u32 s27, s58, s27
	s_and_b64 s[42:43], s[0:1], exec
	s_cselect_b32 s21, s27, s35
	s_cselect_b32 s72, s26, s34
	s_add_u32 s30, s30, 0x100080
	s_addc_u32 s31, s31, 0
	s_add_u32 s73, s34, 0x100
	s_addc_u32 s74, s35, 0
	s_mov_b32 s75, -2
	ds_read_b128 v[152:155], v149
	ds_read_b128 v[156:159], v149 offset:1024
	ds_read_b128 v[160:163], v149 offset:2048
	ds_read_b128 v[164:167], v149 offset:3072
	ds_read_b128 v[168:171], v150
	ds_read_b128 v[172:175], v150 offset:1024
	ds_read_b128 v[176:179], v150 offset:2048
	ds_read_b128 v[180:183], v150 offset:3072
	s_add_u32 s34, s30, 0xfff00080
	s_addc_u32 s35, s31, -1
	s_cmp_eq_u32 s75, 60
	s_cselect_b32 s43, s23, s35
	s_cselect_b32 s42, s55, s34
	s_cselect_b32 s35, s21, s74
	s_cselect_b32 s34, s72, s73
	s_add_i32 m0, s29, 0xc000
	ds_read_b128 v[184:187], v151
	ds_read_b128 v[192:195], v151 offset:1024
	ds_read_b128 v[196:199], v151 offset:2048
	ds_read_b128 v[200:203], v151 offset:3072
	ds_read_b128 v[204:207], v151 offset:4096
	ds_read_b128 v[208:211], v151 offset:5120
	ds_read_b128 v[212:215], v151 offset:6144
	ds_read_b128 v[216:219], v151 offset:7168
	global_load_lds_dwordx4 v136, s[30:31]
	s_add_i32 m0, s29, 0xe000
	s_nop 0
	global_load_lds_dwordx4 v138, s[30:31]
	s_waitcnt vmcnt(8) lgkmcnt(0)
	s_barrier
	v_mfma_f32_16x16x32_bf16 v[124:127], v[152:155], v[184:187], 0
	v_mfma_f32_16x16x32_bf16 v[120:123], v[160:163], v[184:187], 0
	v_mfma_f32_16x16x32_bf16 v[116:119], v[152:155], v[196:199], 0
	v_mfma_f32_16x16x32_bf16 v[108:111], v[160:163], v[196:199], 0
	v_mfma_f32_16x16x32_bf16 v[100:103], v[152:155], v[204:207], 0
	v_mfma_f32_16x16x32_bf16 v[92:95], v[160:163], v[204:207], 0
	v_mfma_f32_16x16x32_bf16 v[84:87], v[152:155], v[212:215], 0
	v_mfma_f32_16x16x32_bf16 v[76:79], v[160:163], v[212:215], 0
	v_mfma_f32_16x16x32_bf16 v[124:127], v[156:159], v[192:195], v[124:127]
	v_mfma_f32_16x16x32_bf16 v[120:123], v[164:167], v[192:195], v[120:123]
	v_mfma_f32_16x16x32_bf16 v[116:119], v[156:159], v[200:203], v[116:119]
	v_mfma_f32_16x16x32_bf16 v[108:111], v[164:167], v[200:203], v[108:111]
	v_mfma_f32_16x16x32_bf16 v[100:103], v[156:159], v[208:211], v[100:103]
	v_mfma_f32_16x16x32_bf16 v[92:95], v[164:167], v[208:211], v[92:95]
	v_mfma_f32_16x16x32_bf16 v[84:87], v[156:159], v[216:219], v[84:87]
	v_mfma_f32_16x16x32_bf16 v[76:79], v[164:167], v[216:219], v[76:79]
	v_mfma_f32_16x16x32_bf16 v[112:115], v[168:171], v[184:187], 0
	v_mfma_f32_16x16x32_bf16 v[104:107], v[176:179], v[184:187], 0
	v_mfma_f32_16x16x32_bf16 v[96:99], v[168:171], v[196:199], 0
	v_mfma_f32_16x16x32_bf16 v[88:91], v[176:179], v[196:199], 0
	v_mfma_f32_16x16x32_bf16 v[80:83], v[168:171], v[204:207], 0
	v_mfma_f32_16x16x32_bf16 v[72:75], v[176:179], v[204:207], 0
	v_mfma_f32_16x16x32_bf16 v[68:71], v[168:171], v[212:215], 0
	v_mfma_f32_16x16x32_bf16 v[64:67], v[176:179], v[212:215], 0
	v_mfma_f32_16x16x32_bf16 v[112:115], v[172:175], v[192:195], v[112:115]
	v_mfma_f32_16x16x32_bf16 v[104:107], v[180:183], v[192:195], v[104:107]
	v_mfma_f32_16x16x32_bf16 v[96:99], v[172:175], v[200:203], v[96:99]
	v_mfma_f32_16x16x32_bf16 v[88:91], v[180:183], v[200:203], v[88:91]
	v_mfma_f32_16x16x32_bf16 v[80:83], v[172:175], v[208:211], v[80:83]
	v_mfma_f32_16x16x32_bf16 v[72:75], v[180:183], v[208:211], v[72:75]
	v_mfma_f32_16x16x32_bf16 v[68:71], v[172:175], v[216:219], v[68:71]
	v_mfma_f32_16x16x32_bf16 v[64:67], v[180:183], v[216:219], v[64:67]
	s_barrier
	s_add_i32 s76, s66, s59
	v_lshl_add_u64 v[144:145], s[34:35], 0, v[130:131]
	s_mov_b32 m0, s76
	ds_read_b128 v[184:187], v151 offset:16384
	ds_read_b128 v[192:195], v151 offset:17408
	ds_read_b128 v[196:199], v151 offset:18432
	ds_read_b128 v[200:203], v151 offset:19456
	ds_read_b128 v[204:207], v151 offset:20480
	ds_read_b128 v[208:211], v151 offset:21504
	ds_read_b128 v[212:215], v151 offset:22528
	ds_read_b128 v[216:219], v151 offset:23552
	global_load_lds_dwordx4 v[144:145], off
	s_add_i32 m0, s76, 0x2000
	s_add_u32 s76, s34, 0x100000
	v_lshl_add_u64 v[188:189], s[34:35], 0, v[134:135]
	s_addc_u32 s77, s35, 0
	s_add_i32 s79, s67, s59
	global_load_lds_dwordx4 v[188:189], off
	s_mov_b32 m0, s79
	v_lshl_add_u64 v[222:223], s[42:43], 0, v[132:133]
	global_load_lds_dwordx4 v130, s[76:77]
	s_add_i32 m0, s79, 0x2000
	s_nop 0
	global_load_lds_dwordx4 v134, s[76:77]
	v_lshl_add_u64 v[220:221], s[42:43], 0, v[128:129]
	s_mov_b32 m0, s29
	s_nop 0
	global_load_lds_dwordx4 v[220:221], off
	s_mov_b32 m0, s33
	s_nop 0
	global_load_lds_dwordx4 v[222:223], off
	s_waitcnt vmcnt(8) lgkmcnt(0)
	s_barrier
	v_mfma_f32_16x16x32_bf16 v[60:63], v[152:155], v[184:187], 0
	v_mfma_f32_16x16x32_bf16 v[56:59], v[160:163], v[184:187], 0
	v_mfma_f32_16x16x32_bf16 v[52:55], v[152:155], v[196:199], 0
	v_mfma_f32_16x16x32_bf16 v[44:47], v[160:163], v[196:199], 0
	v_mfma_f32_16x16x32_bf16 v[36:39], v[152:155], v[204:207], 0
	v_mfma_f32_16x16x32_bf16 v[28:31], v[160:163], v[204:207], 0
	v_mfma_f32_16x16x32_bf16 v[20:23], v[152:155], v[212:215], 0
	v_mfma_f32_16x16x32_bf16 v[12:15], v[160:163], v[212:215], 0
	v_mfma_f32_16x16x32_bf16 v[60:63], v[156:159], v[192:195], v[60:63]
	v_mfma_f32_16x16x32_bf16 v[56:59], v[164:167], v[192:195], v[56:59]
	v_mfma_f32_16x16x32_bf16 v[52:55], v[156:159], v[200:203], v[52:55]
	v_mfma_f32_16x16x32_bf16 v[44:47], v[164:167], v[200:203], v[44:47]
	v_mfma_f32_16x16x32_bf16 v[36:39], v[156:159], v[208:211], v[36:39]
	v_mfma_f32_16x16x32_bf16 v[28:31], v[164:167], v[208:211], v[28:31]
	v_mfma_f32_16x16x32_bf16 v[20:23], v[156:159], v[216:219], v[20:23]
	v_mfma_f32_16x16x32_bf16 v[12:15], v[164:167], v[216:219], v[12:15]
	v_mfma_f32_16x16x32_bf16 v[48:51], v[168:171], v[184:187], 0
	v_mfma_f32_16x16x32_bf16 v[40:43], v[176:179], v[184:187], 0
	v_mfma_f32_16x16x32_bf16 v[32:35], v[168:171], v[196:199], 0
	v_mfma_f32_16x16x32_bf16 v[24:27], v[176:179], v[196:199], 0
	v_mfma_f32_16x16x32_bf16 v[16:19], v[168:171], v[204:207], 0
	v_mfma_f32_16x16x32_bf16 v[8:11], v[176:179], v[204:207], 0
	v_mfma_f32_16x16x32_bf16 v[4:7], v[168:171], v[212:215], 0
	v_mfma_f32_16x16x32_bf16 v[0:3], v[176:179], v[212:215], 0
	v_mfma_f32_16x16x32_bf16 v[48:51], v[172:175], v[192:195], v[48:51]
	v_mfma_f32_16x16x32_bf16 v[40:43], v[180:183], v[192:195], v[40:43]
	v_mfma_f32_16x16x32_bf16 v[32:35], v[172:175], v[200:203], v[32:35]
	v_mfma_f32_16x16x32_bf16 v[24:27], v[180:183], v[200:203], v[24:27]
	v_mfma_f32_16x16x32_bf16 v[16:19], v[172:175], v[208:211], v[16:19]
	v_mfma_f32_16x16x32_bf16 v[8:11], v[180:183], v[208:211], v[8:11]
	v_mfma_f32_16x16x32_bf16 v[4:7], v[172:175], v[216:219], v[4:7]
	v_mfma_f32_16x16x32_bf16 v[0:3], v[180:183], v[216:219], v[0:3]
	s_barrier
	s_add_i32 s76, 0, 0x18000
	s_add_i32 s77, 0, 0x1c000
	v_add_u32_e32 v164, s76, v147
	v_add_u32_e32 v180, s77, v147
	ds_read_b128 v[152:155], v164
	ds_read_b128 v[156:159], v164 offset:1024
	ds_read_b128 v[160:163], v164 offset:2048
	ds_read_b128 v[164:167], v164 offset:3072
	ds_read_b128 v[168:171], v180
	ds_read_b128 v[172:175], v180 offset:1024
	ds_read_b128 v[176:179], v180 offset:2048
	ds_read_b128 v[180:183], v180 offset:3072
	s_add_u32 s42, s42, 0x100000
	s_addc_u32 s43, s43, 0
	s_mov_b32 m0, s60
	ds_read_b128 v[184:187], v151 offset:32768
	ds_read_b128 v[192:195], v151 offset:33792
	ds_read_b128 v[196:199], v151 offset:34816
	ds_read_b128 v[200:203], v151 offset:35840
	ds_read_b128 v[204:207], v151 offset:36864
	ds_read_b128 v[208:211], v151 offset:37888
	ds_read_b128 v[212:215], v151 offset:38912
	ds_read_b128 v[216:219], v151 offset:39936
	global_load_lds_dwordx4 v128, s[42:43]
	s_mov_b32 m0, s61
	s_nop 0
	global_load_lds_dwordx4 v132, s[42:43]
	s_waitcnt vmcnt(8) lgkmcnt(0)
	s_barrier
	v_mfma_f32_16x16x32_bf16 v[124:127], v[152:155], v[184:187], v[124:127]
	v_mfma_f32_16x16x32_bf16 v[120:123], v[160:163], v[184:187], v[120:123]
	v_mfma_f32_16x16x32_bf16 v[116:119], v[152:155], v[196:199], v[116:119]
	v_mfma_f32_16x16x32_bf16 v[108:111], v[160:163], v[196:199], v[108:111]
	v_mfma_f32_16x16x32_bf16 v[100:103], v[152:155], v[204:207], v[100:103]
	v_mfma_f32_16x16x32_bf16 v[92:95], v[160:163], v[204:207], v[92:95]
	v_mfma_f32_16x16x32_bf16 v[84:87], v[152:155], v[212:215], v[84:87]
	v_mfma_f32_16x16x32_bf16 v[76:79], v[160:163], v[212:215], v[76:79]
	v_mfma_f32_16x16x32_bf16 v[124:127], v[156:159], v[192:195], v[124:127]
	v_mfma_f32_16x16x32_bf16 v[120:123], v[164:167], v[192:195], v[120:123]
	v_mfma_f32_16x16x32_bf16 v[116:119], v[156:159], v[200:203], v[116:119]
	v_mfma_f32_16x16x32_bf16 v[108:111], v[164:167], v[200:203], v[108:111]
	v_mfma_f32_16x16x32_bf16 v[100:103], v[156:159], v[208:211], v[100:103]
	v_mfma_f32_16x16x32_bf16 v[92:95], v[164:167], v[208:211], v[92:95]
	v_mfma_f32_16x16x32_bf16 v[84:87], v[156:159], v[216:219], v[84:87]
	v_mfma_f32_16x16x32_bf16 v[76:79], v[164:167], v[216:219], v[76:79]
	v_mfma_f32_16x16x32_bf16 v[112:115], v[168:171], v[184:187], v[112:115]
	v_mfma_f32_16x16x32_bf16 v[104:107], v[176:179], v[184:187], v[104:107]
	v_mfma_f32_16x16x32_bf16 v[96:99], v[168:171], v[196:199], v[96:99]
	v_mfma_f32_16x16x32_bf16 v[88:91], v[176:179], v[196:199], v[88:91]
	v_mfma_f32_16x16x32_bf16 v[80:83], v[168:171], v[204:207], v[80:83]
	v_mfma_f32_16x16x32_bf16 v[72:75], v[176:179], v[204:207], v[72:75]
	v_mfma_f32_16x16x32_bf16 v[68:71], v[168:171], v[212:215], v[68:71]
	v_mfma_f32_16x16x32_bf16 v[64:67], v[176:179], v[212:215], v[64:67]
	v_mfma_f32_16x16x32_bf16 v[112:115], v[172:175], v[192:195], v[112:115]
	v_mfma_f32_16x16x32_bf16 v[104:107], v[180:183], v[192:195], v[104:107]
	v_mfma_f32_16x16x32_bf16 v[96:99], v[172:175], v[200:203], v[96:99]
	v_mfma_f32_16x16x32_bf16 v[88:91], v[180:183], v[200:203], v[88:91]
	v_mfma_f32_16x16x32_bf16 v[80:83], v[172:175], v[208:211], v[80:83]
	v_mfma_f32_16x16x32_bf16 v[72:75], v[180:183], v[208:211], v[72:75]
	v_mfma_f32_16x16x32_bf16 v[68:71], v[172:175], v[216:219], v[68:71]
	v_mfma_f32_16x16x32_bf16 v[64:67], v[180:183], v[216:219], v[64:67]
	s_barrier
	s_add_i32 s42, s76, s59
	v_lshl_add_u64 v[144:145], v[144:145], 0, s[8:9]
	s_mov_b32 m0, s42
	ds_read_b128 v[184:187], v151 offset:49152
	ds_read_b128 v[192:195], v151 offset:50176
	ds_read_b128 v[196:199], v151 offset:51200
	ds_read_b128 v[200:203], v151 offset:52224
	ds_read_b128 v[204:207], v151 offset:53248
	ds_read_b128 v[208:211], v151 offset:54272
	ds_read_b128 v[212:215], v151 offset:55296
	ds_read_b128 v[216:219], v151 offset:56320
	global_load_lds_dwordx4 v[144:145], off
	s_add_i32 m0, s42, 0x2000
	s_add_u32 s34, s34, 0x100080
	v_lshl_add_u64 v[144:145], v[188:189], 0, s[8:9]
	s_addc_u32 s35, s35, 0
	s_add_i32 s42, s77, s59
	global_load_lds_dwordx4 v[144:145], off
	s_mov_b32 m0, s42
	s_nop 0
	global_load_lds_dwordx4 v130, s[34:35]
	s_add_i32 m0, s42, 0x2000
	s_nop 0
	global_load_lds_dwordx4 v134, s[34:35]
	v_lshl_add_u64 v[144:145], v[220:221], 0, s[8:9]
	s_mov_b32 m0, s63
	s_nop 0
	global_load_lds_dwordx4 v[144:145], off
	v_lshl_add_u64 v[144:145], v[222:223], 0, s[8:9]
	s_mov_b32 m0, s64
	s_nop 0
	global_load_lds_dwordx4 v[144:145], off
	s_waitcnt vmcnt(8) lgkmcnt(0)
	s_barrier
	v_mfma_f32_16x16x32_bf16 v[60:63], v[152:155], v[184:187], v[60:63]
	v_mfma_f32_16x16x32_bf16 v[56:59], v[160:163], v[184:187], v[56:59]
	v_mfma_f32_16x16x32_bf16 v[52:55], v[152:155], v[196:199], v[52:55]
	v_mfma_f32_16x16x32_bf16 v[44:47], v[160:163], v[196:199], v[44:47]
	v_mfma_f32_16x16x32_bf16 v[36:39], v[152:155], v[204:207], v[36:39]
	v_mfma_f32_16x16x32_bf16 v[28:31], v[160:163], v[204:207], v[28:31]
	v_mfma_f32_16x16x32_bf16 v[20:23], v[152:155], v[212:215], v[20:23]
	v_mfma_f32_16x16x32_bf16 v[12:15], v[160:163], v[212:215], v[12:15]
	v_mfma_f32_16x16x32_bf16 v[60:63], v[156:159], v[192:195], v[60:63]
	v_mfma_f32_16x16x32_bf16 v[56:59], v[164:167], v[192:195], v[56:59]
	v_mfma_f32_16x16x32_bf16 v[52:55], v[156:159], v[200:203], v[52:55]
	v_mfma_f32_16x16x32_bf16 v[44:47], v[164:167], v[200:203], v[44:47]
	v_mfma_f32_16x16x32_bf16 v[36:39], v[156:159], v[208:211], v[36:39]
	v_mfma_f32_16x16x32_bf16 v[28:31], v[164:167], v[208:211], v[28:31]
	v_mfma_f32_16x16x32_bf16 v[20:23], v[156:159], v[216:219], v[20:23]
	v_mfma_f32_16x16x32_bf16 v[12:15], v[164:167], v[216:219], v[12:15]
	v_mfma_f32_16x16x32_bf16 v[48:51], v[168:171], v[184:187], v[48:51]
	v_mfma_f32_16x16x32_bf16 v[40:43], v[176:179], v[184:187], v[40:43]
	v_mfma_f32_16x16x32_bf16 v[32:35], v[168:171], v[196:199], v[32:35]
	v_mfma_f32_16x16x32_bf16 v[24:27], v[176:179], v[196:199], v[24:27]
	v_mfma_f32_16x16x32_bf16 v[16:19], v[168:171], v[204:207], v[16:19]
	v_mfma_f32_16x16x32_bf16 v[8:11], v[176:179], v[204:207], v[8:11]
	v_mfma_f32_16x16x32_bf16 v[4:7], v[168:171], v[212:215], v[4:7]
	v_mfma_f32_16x16x32_bf16 v[0:3], v[176:179], v[212:215], v[0:3]
	v_mfma_f32_16x16x32_bf16 v[48:51], v[172:175], v[192:195], v[48:51]
	v_mfma_f32_16x16x32_bf16 v[40:43], v[180:183], v[192:195], v[40:43]
	v_mfma_f32_16x16x32_bf16 v[32:35], v[172:175], v[200:203], v[32:35]
	v_mfma_f32_16x16x32_bf16 v[24:27], v[180:183], v[200:203], v[24:27]
	v_mfma_f32_16x16x32_bf16 v[16:19], v[172:175], v[208:211], v[16:19]
	v_mfma_f32_16x16x32_bf16 v[8:11], v[180:183], v[208:211], v[8:11]
	v_mfma_f32_16x16x32_bf16 v[4:7], v[172:175], v[216:219], v[4:7]
	v_mfma_f32_16x16x32_bf16 v[0:3], v[180:183], v[216:219], v[0:3]
	s_barrier
	s_add_i32 s75, s75, 2
	s_add_u32 s30, s30, 0x100
	s_addc_u32 s31, s31, 0
	s_add_u32 s73, s73, 0x100
	s_addc_u32 s74, s74, 0
	s_cmp_gt_u32 s75, 61
	s_cbranch_scc0 .LBB0_1650
	s_branch .Lpeel_exit12
.LBB0_1650:
	ds_read_b128 v[152:155], v149
	ds_read_b128 v[156:159], v149 offset:1024
	ds_read_b128 v[160:163], v149 offset:2048
	ds_read_b128 v[164:167], v149 offset:3072
	ds_read_b128 v[168:171], v150
	ds_read_b128 v[172:175], v150 offset:1024
	ds_read_b128 v[176:179], v150 offset:2048
	ds_read_b128 v[180:183], v150 offset:3072
	s_add_u32 s34, s30, 0xfff00080
	s_addc_u32 s35, s31, -1
	s_cmp_eq_u32 s75, 60
	s_cselect_b32 s43, s23, s35
	s_cselect_b32 s42, s55, s34
	s_cselect_b32 s35, s21, s74
	s_cselect_b32 s34, s72, s73
	s_add_i32 m0, s29, 0xc000
	ds_read_b128 v[184:187], v151
	ds_read_b128 v[192:195], v151 offset:1024
	ds_read_b128 v[196:199], v151 offset:2048
	ds_read_b128 v[200:203], v151 offset:3072
	ds_read_b128 v[204:207], v151 offset:4096
	ds_read_b128 v[208:211], v151 offset:5120
	ds_read_b128 v[212:215], v151 offset:6144
	ds_read_b128 v[216:219], v151 offset:7168
	global_load_lds_dwordx4 v136, s[30:31]
	s_add_i32 m0, s29, 0xe000
	s_nop 0
	global_load_lds_dwordx4 v138, s[30:31]
	s_waitcnt vmcnt(8) lgkmcnt(0)
	s_barrier
	v_mfma_f32_16x16x32_bf16 v[124:127], v[152:155], v[184:187], v[124:127]
	v_mfma_f32_16x16x32_bf16 v[120:123], v[160:163], v[184:187], v[120:123]
	v_mfma_f32_16x16x32_bf16 v[116:119], v[152:155], v[196:199], v[116:119]
	v_mfma_f32_16x16x32_bf16 v[108:111], v[160:163], v[196:199], v[108:111]
	v_mfma_f32_16x16x32_bf16 v[100:103], v[152:155], v[204:207], v[100:103]
	v_mfma_f32_16x16x32_bf16 v[92:95], v[160:163], v[204:207], v[92:95]
	v_mfma_f32_16x16x32_bf16 v[84:87], v[152:155], v[212:215], v[84:87]
	v_mfma_f32_16x16x32_bf16 v[76:79], v[160:163], v[212:215], v[76:79]
	v_mfma_f32_16x16x32_bf16 v[124:127], v[156:159], v[192:195], v[124:127]
	v_mfma_f32_16x16x32_bf16 v[120:123], v[164:167], v[192:195], v[120:123]
	v_mfma_f32_16x16x32_bf16 v[116:119], v[156:159], v[200:203], v[116:119]
	v_mfma_f32_16x16x32_bf16 v[108:111], v[164:167], v[200:203], v[108:111]
	v_mfma_f32_16x16x32_bf16 v[100:103], v[156:159], v[208:211], v[100:103]
	v_mfma_f32_16x16x32_bf16 v[92:95], v[164:167], v[208:211], v[92:95]
	v_mfma_f32_16x16x32_bf16 v[84:87], v[156:159], v[216:219], v[84:87]
	v_mfma_f32_16x16x32_bf16 v[76:79], v[164:167], v[216:219], v[76:79]
	v_mfma_f32_16x16x32_bf16 v[112:115], v[168:171], v[184:187], v[112:115]
	v_mfma_f32_16x16x32_bf16 v[104:107], v[176:179], v[184:187], v[104:107]
	v_mfma_f32_16x16x32_bf16 v[96:99], v[168:171], v[196:199], v[96:99]
	v_mfma_f32_16x16x32_bf16 v[88:91], v[176:179], v[196:199], v[88:91]
	v_mfma_f32_16x16x32_bf16 v[80:83], v[168:171], v[204:207], v[80:83]
	v_mfma_f32_16x16x32_bf16 v[72:75], v[176:179], v[204:207], v[72:75]
	v_mfma_f32_16x16x32_bf16 v[68:71], v[168:171], v[212:215], v[68:71]
	v_mfma_f32_16x16x32_bf16 v[64:67], v[176:179], v[212:215], v[64:67]
	v_mfma_f32_16x16x32_bf16 v[112:115], v[172:175], v[192:195], v[112:115]
	v_mfma_f32_16x16x32_bf16 v[104:107], v[180:183], v[192:195], v[104:107]
	v_mfma_f32_16x16x32_bf16 v[96:99], v[172:175], v[200:203], v[96:99]
	v_mfma_f32_16x16x32_bf16 v[88:91], v[180:183], v[200:203], v[88:91]
	v_mfma_f32_16x16x32_bf16 v[80:83], v[172:175], v[208:211], v[80:83]
	v_mfma_f32_16x16x32_bf16 v[72:75], v[180:183], v[208:211], v[72:75]
	v_mfma_f32_16x16x32_bf16 v[68:71], v[172:175], v[216:219], v[68:71]
	v_mfma_f32_16x16x32_bf16 v[64:67], v[180:183], v[216:219], v[64:67]
	s_barrier
	s_add_i32 s76, s66, s59
	v_lshl_add_u64 v[144:145], s[34:35], 0, v[130:131]
	s_mov_b32 m0, s76
	ds_read_b128 v[184:187], v151 offset:16384
	ds_read_b128 v[192:195], v151 offset:17408
	ds_read_b128 v[196:199], v151 offset:18432
	ds_read_b128 v[200:203], v151 offset:19456
	ds_read_b128 v[204:207], v151 offset:20480
	ds_read_b128 v[208:211], v151 offset:21504
	ds_read_b128 v[212:215], v151 offset:22528
	ds_read_b128 v[216:219], v151 offset:23552
	global_load_lds_dwordx4 v[144:145], off
	s_add_i32 m0, s76, 0x2000
	s_add_u32 s76, s34, 0x100000
	v_lshl_add_u64 v[188:189], s[34:35], 0, v[134:135]
	s_addc_u32 s77, s35, 0
	s_add_i32 s79, s67, s59
	global_load_lds_dwordx4 v[188:189], off
	s_mov_b32 m0, s79
	v_lshl_add_u64 v[222:223], s[42:43], 0, v[132:133]
	global_load_lds_dwordx4 v130, s[76:77]
	s_add_i32 m0, s79, 0x2000
	s_nop 0
	global_load_lds_dwordx4 v134, s[76:77]
	v_lshl_add_u64 v[220:221], s[42:43], 0, v[128:129]
	s_mov_b32 m0, s29
	s_nop 0
	global_load_lds_dwordx4 v[220:221], off
	s_mov_b32 m0, s33
	s_nop 0
	global_load_lds_dwordx4 v[222:223], off
	s_waitcnt vmcnt(8) lgkmcnt(0)
	s_barrier
	v_mfma_f32_16x16x32_bf16 v[60:63], v[152:155], v[184:187], v[60:63]
	v_mfma_f32_16x16x32_bf16 v[56:59], v[160:163], v[184:187], v[56:59]
	v_mfma_f32_16x16x32_bf16 v[52:55], v[152:155], v[196:199], v[52:55]
	v_mfma_f32_16x16x32_bf16 v[44:47], v[160:163], v[196:199], v[44:47]
	v_mfma_f32_16x16x32_bf16 v[36:39], v[152:155], v[204:207], v[36:39]
	v_mfma_f32_16x16x32_bf16 v[28:31], v[160:163], v[204:207], v[28:31]
	v_mfma_f32_16x16x32_bf16 v[20:23], v[152:155], v[212:215], v[20:23]
	v_mfma_f32_16x16x32_bf16 v[12:15], v[160:163], v[212:215], v[12:15]
	v_mfma_f32_16x16x32_bf16 v[60:63], v[156:159], v[192:195], v[60:63]
	v_mfma_f32_16x16x32_bf16 v[56:59], v[164:167], v[192:195], v[56:59]
	v_mfma_f32_16x16x32_bf16 v[52:55], v[156:159], v[200:203], v[52:55]
	v_mfma_f32_16x16x32_bf16 v[44:47], v[164:167], v[200:203], v[44:47]
	v_mfma_f32_16x16x32_bf16 v[36:39], v[156:159], v[208:211], v[36:39]
	v_mfma_f32_16x16x32_bf16 v[28:31], v[164:167], v[208:211], v[28:31]
	v_mfma_f32_16x16x32_bf16 v[20:23], v[156:159], v[216:219], v[20:23]
	v_mfma_f32_16x16x32_bf16 v[12:15], v[164:167], v[216:219], v[12:15]
	v_mfma_f32_16x16x32_bf16 v[48:51], v[168:171], v[184:187], v[48:51]
	v_mfma_f32_16x16x32_bf16 v[40:43], v[176:179], v[184:187], v[40:43]
	v_mfma_f32_16x16x32_bf16 v[32:35], v[168:171], v[196:199], v[32:35]
	v_mfma_f32_16x16x32_bf16 v[24:27], v[176:179], v[196:199], v[24:27]
	v_mfma_f32_16x16x32_bf16 v[16:19], v[168:171], v[204:207], v[16:19]
	v_mfma_f32_16x16x32_bf16 v[8:11], v[176:179], v[204:207], v[8:11]
	v_mfma_f32_16x16x32_bf16 v[4:7], v[168:171], v[212:215], v[4:7]
	v_mfma_f32_16x16x32_bf16 v[0:3], v[176:179], v[212:215], v[0:3]
	v_mfma_f32_16x16x32_bf16 v[48:51], v[172:175], v[192:195], v[48:51]
	v_mfma_f32_16x16x32_bf16 v[40:43], v[180:183], v[192:195], v[40:43]
	v_mfma_f32_16x16x32_bf16 v[32:35], v[172:175], v[200:203], v[32:35]
	v_mfma_f32_16x16x32_bf16 v[24:27], v[180:183], v[200:203], v[24:27]
	v_mfma_f32_16x16x32_bf16 v[16:19], v[172:175], v[208:211], v[16:19]
	v_mfma_f32_16x16x32_bf16 v[8:11], v[180:183], v[208:211], v[8:11]
	v_mfma_f32_16x16x32_bf16 v[4:7], v[172:175], v[216:219], v[4:7]
	v_mfma_f32_16x16x32_bf16 v[0:3], v[180:183], v[216:219], v[0:3]
	s_barrier
	s_add_i32 s76, 0, 0x18000
	s_add_i32 s77, 0, 0x1c000
	v_add_u32_e32 v164, s76, v147
	v_add_u32_e32 v180, s77, v147
	ds_read_b128 v[152:155], v164
	ds_read_b128 v[156:159], v164 offset:1024
	ds_read_b128 v[160:163], v164 offset:2048
	ds_read_b128 v[164:167], v164 offset:3072
	ds_read_b128 v[168:171], v180
	ds_read_b128 v[172:175], v180 offset:1024
	ds_read_b128 v[176:179], v180 offset:2048
	ds_read_b128 v[180:183], v180 offset:3072
	s_add_u32 s42, s42, 0x100000
	s_addc_u32 s43, s43, 0
	s_mov_b32 m0, s60
	ds_read_b128 v[184:187], v151 offset:32768
	ds_read_b128 v[192:195], v151 offset:33792
	ds_read_b128 v[196:199], v151 offset:34816
	ds_read_b128 v[200:203], v151 offset:35840
	ds_read_b128 v[204:207], v151 offset:36864
	ds_read_b128 v[208:211], v151 offset:37888
	ds_read_b128 v[212:215], v151 offset:38912
	ds_read_b128 v[216:219], v151 offset:39936
	global_load_lds_dwordx4 v128, s[42:43]
	s_mov_b32 m0, s61
	s_nop 0
	global_load_lds_dwordx4 v132, s[42:43]
	s_waitcnt vmcnt(8) lgkmcnt(0)
	s_barrier
	v_mfma_f32_16x16x32_bf16 v[124:127], v[152:155], v[184:187], v[124:127]
	v_mfma_f32_16x16x32_bf16 v[120:123], v[160:163], v[184:187], v[120:123]
	v_mfma_f32_16x16x32_bf16 v[116:119], v[152:155], v[196:199], v[116:119]
	v_mfma_f32_16x16x32_bf16 v[108:111], v[160:163], v[196:199], v[108:111]
	v_mfma_f32_16x16x32_bf16 v[100:103], v[152:155], v[204:207], v[100:103]
	v_mfma_f32_16x16x32_bf16 v[92:95], v[160:163], v[204:207], v[92:95]
	v_mfma_f32_16x16x32_bf16 v[84:87], v[152:155], v[212:215], v[84:87]
	v_mfma_f32_16x16x32_bf16 v[76:79], v[160:163], v[212:215], v[76:79]
	v_mfma_f32_16x16x32_bf16 v[124:127], v[156:159], v[192:195], v[124:127]
	v_mfma_f32_16x16x32_bf16 v[120:123], v[164:167], v[192:195], v[120:123]
	v_mfma_f32_16x16x32_bf16 v[116:119], v[156:159], v[200:203], v[116:119]
	v_mfma_f32_16x16x32_bf16 v[108:111], v[164:167], v[200:203], v[108:111]
	v_mfma_f32_16x16x32_bf16 v[100:103], v[156:159], v[208:211], v[100:103]
	v_mfma_f32_16x16x32_bf16 v[92:95], v[164:167], v[208:211], v[92:95]
	v_mfma_f32_16x16x32_bf16 v[84:87], v[156:159], v[216:219], v[84:87]
	v_mfma_f32_16x16x32_bf16 v[76:79], v[164:167], v[216:219], v[76:79]
	v_mfma_f32_16x16x32_bf16 v[112:115], v[168:171], v[184:187], v[112:115]
	v_mfma_f32_16x16x32_bf16 v[104:107], v[176:179], v[184:187], v[104:107]
	v_mfma_f32_16x16x32_bf16 v[96:99], v[168:171], v[196:199], v[96:99]
	v_mfma_f32_16x16x32_bf16 v[88:91], v[176:179], v[196:199], v[88:91]
	v_mfma_f32_16x16x32_bf16 v[80:83], v[168:171], v[204:207], v[80:83]
	v_mfma_f32_16x16x32_bf16 v[72:75], v[176:179], v[204:207], v[72:75]
	v_mfma_f32_16x16x32_bf16 v[68:71], v[168:171], v[212:215], v[68:71]
	v_mfma_f32_16x16x32_bf16 v[64:67], v[176:179], v[212:215], v[64:67]
	v_mfma_f32_16x16x32_bf16 v[112:115], v[172:175], v[192:195], v[112:115]
	v_mfma_f32_16x16x32_bf16 v[104:107], v[180:183], v[192:195], v[104:107]
	v_mfma_f32_16x16x32_bf16 v[96:99], v[172:175], v[200:203], v[96:99]
	v_mfma_f32_16x16x32_bf16 v[88:91], v[180:183], v[200:203], v[88:91]
	v_mfma_f32_16x16x32_bf16 v[80:83], v[172:175], v[208:211], v[80:83]
	v_mfma_f32_16x16x32_bf16 v[72:75], v[180:183], v[208:211], v[72:75]
	v_mfma_f32_16x16x32_bf16 v[68:71], v[172:175], v[216:219], v[68:71]
	v_mfma_f32_16x16x32_bf16 v[64:67], v[180:183], v[216:219], v[64:67]
	s_barrier
	s_add_i32 s42, s76, s59
	v_lshl_add_u64 v[144:145], v[144:145], 0, s[8:9]
	s_mov_b32 m0, s42
	ds_read_b128 v[184:187], v151 offset:49152
	ds_read_b128 v[192:195], v151 offset:50176
	ds_read_b128 v[196:199], v151 offset:51200
	ds_read_b128 v[200:203], v151 offset:52224
	ds_read_b128 v[204:207], v151 offset:53248
	ds_read_b128 v[208:211], v151 offset:54272
	ds_read_b128 v[212:215], v151 offset:55296
	ds_read_b128 v[216:219], v151 offset:56320
	global_load_lds_dwordx4 v[144:145], off
	s_add_i32 m0, s42, 0x2000
	s_add_u32 s34, s34, 0x100080
	v_lshl_add_u64 v[144:145], v[188:189], 0, s[8:9]
	s_addc_u32 s35, s35, 0
	s_add_i32 s42, s77, s59
	global_load_lds_dwordx4 v[144:145], off
	s_mov_b32 m0, s42
	s_nop 0
	global_load_lds_dwordx4 v130, s[34:35]
	s_add_i32 m0, s42, 0x2000
	s_nop 0
	global_load_lds_dwordx4 v134, s[34:35]
	v_lshl_add_u64 v[144:145], v[220:221], 0, s[8:9]
	s_mov_b32 m0, s63
	s_nop 0
	global_load_lds_dwordx4 v[144:145], off
	v_lshl_add_u64 v[144:145], v[222:223], 0, s[8:9]
	s_mov_b32 m0, s64
	s_nop 0
	global_load_lds_dwordx4 v[144:145], off
	s_waitcnt vmcnt(8) lgkmcnt(0)
	s_barrier
	v_mfma_f32_16x16x32_bf16 v[60:63], v[152:155], v[184:187], v[60:63]
	v_mfma_f32_16x16x32_bf16 v[56:59], v[160:163], v[184:187], v[56:59]
	v_mfma_f32_16x16x32_bf16 v[52:55], v[152:155], v[196:199], v[52:55]
	v_mfma_f32_16x16x32_bf16 v[44:47], v[160:163], v[196:199], v[44:47]
	v_mfma_f32_16x16x32_bf16 v[36:39], v[152:155], v[204:207], v[36:39]
	v_mfma_f32_16x16x32_bf16 v[28:31], v[160:163], v[204:207], v[28:31]
	v_mfma_f32_16x16x32_bf16 v[20:23], v[152:155], v[212:215], v[20:23]
	v_mfma_f32_16x16x32_bf16 v[12:15], v[160:163], v[212:215], v[12:15]
	v_mfma_f32_16x16x32_bf16 v[60:63], v[156:159], v[192:195], v[60:63]
	v_mfma_f32_16x16x32_bf16 v[56:59], v[164:167], v[192:195], v[56:59]
	v_mfma_f32_16x16x32_bf16 v[52:55], v[156:159], v[200:203], v[52:55]
	v_mfma_f32_16x16x32_bf16 v[44:47], v[164:167], v[200:203], v[44:47]
	v_mfma_f32_16x16x32_bf16 v[36:39], v[156:159], v[208:211], v[36:39]
	v_mfma_f32_16x16x32_bf16 v[28:31], v[164:167], v[208:211], v[28:31]
	v_mfma_f32_16x16x32_bf16 v[20:23], v[156:159], v[216:219], v[20:23]
	v_mfma_f32_16x16x32_bf16 v[12:15], v[164:167], v[216:219], v[12:15]
	v_mfma_f32_16x16x32_bf16 v[48:51], v[168:171], v[184:187], v[48:51]
	v_mfma_f32_16x16x32_bf16 v[40:43], v[176:179], v[184:187], v[40:43]
	v_mfma_f32_16x16x32_bf16 v[32:35], v[168:171], v[196:199], v[32:35]
	v_mfma_f32_16x16x32_bf16 v[24:27], v[176:179], v[196:199], v[24:27]
	v_mfma_f32_16x16x32_bf16 v[16:19], v[168:171], v[204:207], v[16:19]
	v_mfma_f32_16x16x32_bf16 v[8:11], v[176:179], v[204:207], v[8:11]
	v_mfma_f32_16x16x32_bf16 v[4:7], v[168:171], v[212:215], v[4:7]
	v_mfma_f32_16x16x32_bf16 v[0:3], v[176:179], v[212:215], v[0:3]
	v_mfma_f32_16x16x32_bf16 v[48:51], v[172:175], v[192:195], v[48:51]
	v_mfma_f32_16x16x32_bf16 v[40:43], v[180:183], v[192:195], v[40:43]
	v_mfma_f32_16x16x32_bf16 v[32:35], v[172:175], v[200:203], v[32:35]
	v_mfma_f32_16x16x32_bf16 v[24:27], v[180:183], v[200:203], v[24:27]
	v_mfma_f32_16x16x32_bf16 v[16:19], v[172:175], v[208:211], v[16:19]
	v_mfma_f32_16x16x32_bf16 v[8:11], v[180:183], v[208:211], v[8:11]
	v_mfma_f32_16x16x32_bf16 v[4:7], v[172:175], v[216:219], v[4:7]
	v_mfma_f32_16x16x32_bf16 v[0:3], v[180:183], v[216:219], v[0:3]
	s_barrier
	s_add_i32 s75, s75, 2
	s_add_u32 s30, s30, 0x100
	s_addc_u32 s31, s31, 0
	s_add_u32 s73, s73, 0x100
	s_addc_u32 s74, s74, 0
	s_cmp_gt_u32 s75, 61
	s_cbranch_scc0 .LBB0_1650
